# x3 plus removal of the s_setprio 0/1 pair in the middle of each 32-MFMA run of the K-loops
# baseline (speedup 1.0000x reference)
; #define PG8_STAGE(bufoff, gbase, voff) do { _Pragma("unroll") for (int _i = 0; _i < 2; ++_i) \
;         __builtin_amdgcn_global_load_lds((const unsigned*)((const char*)(gbase) + (voff)[_i]), (LAS unsigned*)(lds + (bufoff) + ldsw + _i * 8192), 16, 0, 0); } while (0)
; #define PG8_LDA(dst, b, h) do { _Pragma("unroll") for (int m = 0; m < 4; ++m) _Pragma("unroll") for (int k = 0; k < 2; ++k) dst[m][k] = *(const LAS bf16x8*)(lds + PG8_SA(b, h) + aoff + m * 2048 + k * 1024); } while (0)
; #define PG8_MMA(ai, bj, At, Bt) do { __builtin_amdgcn_s_setprio(1); _Pragma("unroll") for (int m = 0; m < 4; ++m) _Pragma("unroll") for (int n = 0; n < 2; ++n) _Pragma("unroll") for (int k = 0; k < 2; ++k) \
;         acc[ai][bj][m][n] = __builtin_amdgcn_mfma_f32_16x16x32_bf16(Bt[n][k], At[m][k], acc[ai][bj][m][n], 0, 0, 0); __builtin_amdgcn_s_setprio(0); } while (0)
; #define PG8_WAIT_V(n) asm volatile("s_waitcnt vmcnt(" #n ")" ::: "memory")
; #define PG8_WAIT_L(n) asm volatile("s_waitcnt lgkmcnt(" #n ")" ::: "memory")
; #define PG8_BAR __builtin_amdgcn_s_barrier()
; #define PG8_WAIT_RELAX(flag, n) asm volatile("s_cmp_eq_u32 %0, 0\n\ts_cbranch_scc1 .Lrw%=\n\ts_waitcnt vmcnt(8)\n.Lrw%=:\n\ts_waitcnt vmcnt(%1)" :: "s"(flag), "n"(n) : "scc", "memory")
; #define PG8_SCHED __builtin_amdgcn_sched_barrier(0)
; template <class Epi, bool ALIGN_EPI = true>
; __device__ __forceinline__ void gemm_phase(LAS unsigned char* lds, const Gemm g, const Sched& S, const Epi& E) {
;     ...
;             if constexpr (Epi::NSTORES > 0) PG8_WAIT_RELAX(rflag, 8 + Epi::NSTORES); else PG8_WAIT_V(8);
;             PG8_WAIT_L(0); PG8_BAR; PG8_MMA(0, 0, At, B0); PG8_MMA(0, 1, At, B1); PG8_BAR; PG8_SCHED;
;             PG8_LDA(At, 0, 1); PG8_STAGE(PG8_SB(0, 0), b2, voffB); PG8_STAGE(PG8_SB(0, 1), b2 + hstepB, voffB); PG8_STAGE(PG8_SA(0, 0), a2, voffA);
;             if constexpr (Epi::NSTORES > 0) PG8_WAIT_RELAX(rflag, 8 + Epi::NSTORES); else PG8_WAIT_V(8);
;             PG8_WAIT_L(0); PG8_BAR; PG8_MMA(1, 0, At, B0); PG8_MMA(1, 1, At, B1); PG8_BAR; PG8_SCHED;
.Lrw0:
	s_waitcnt vmcnt(24)
	s_waitcnt lgkmcnt(0)
	s_barrier
	s_setprio 1
	s_waitcnt lgkmcnt(0)
	v_mfma_f32_16x16x32_bf16 v[122:125], v[154:157], v[186:189], v[122:125]
	v_mfma_f32_16x16x32_bf16 v[126:129], v[162:165], v[186:189], v[126:129]
	v_mfma_f32_16x16x32_bf16 v[110:113], v[154:157], v[194:197], v[110:113]
	v_mfma_f32_16x16x32_bf16 v[106:109], v[162:165], v[194:197], v[106:109]
	v_mfma_f32_16x16x32_bf16 v[94:97], v[154:157], v[202:205], v[94:97]
	v_mfma_f32_16x16x32_bf16 v[90:93], v[162:165], v[202:205], v[90:93]
	v_mfma_f32_16x16x32_bf16 v[78:81], v[154:157], v[210:213], v[78:81]
	v_mfma_f32_16x16x32_bf16 v[74:77], v[162:165], v[210:213], v[74:77]
	v_mfma_f32_16x16x32_bf16 v[122:125], v[158:161], v[190:193], v[122:125]
	v_mfma_f32_16x16x32_bf16 v[126:129], v[166:169], v[190:193], v[126:129]
	v_mfma_f32_16x16x32_bf16 v[110:113], v[158:161], v[198:201], v[110:113]
	v_mfma_f32_16x16x32_bf16 v[106:109], v[166:169], v[198:201], v[106:109]
	v_mfma_f32_16x16x32_bf16 v[94:97], v[158:161], v[206:209], v[94:97]
	v_mfma_f32_16x16x32_bf16 v[90:93], v[166:169], v[206:209], v[90:93]
	v_mfma_f32_16x16x32_bf16 v[78:81], v[158:161], v[214:217], v[78:81]
	v_mfma_f32_16x16x32_bf16 v[74:77], v[166:169], v[214:217], v[74:77]
	v_mfma_f32_16x16x32_bf16 v[118:121], v[170:173], v[186:189], v[118:121]
	v_mfma_f32_16x16x32_bf16 v[114:117], v[178:181], v[186:189], v[114:117]
	v_mfma_f32_16x16x32_bf16 v[102:105], v[170:173], v[194:197], v[102:105]
	v_mfma_f32_16x16x32_bf16 v[98:101], v[178:181], v[194:197], v[98:101]
	v_mfma_f32_16x16x32_bf16 v[86:89], v[170:173], v[202:205], v[86:89]
	v_mfma_f32_16x16x32_bf16 v[82:85], v[178:181], v[202:205], v[82:85]
	v_mfma_f32_16x16x32_bf16 v[70:73], v[170:173], v[210:213], v[70:73]
	v_mfma_f32_16x16x32_bf16 v[66:69], v[178:181], v[210:213], v[66:69]
	v_mfma_f32_16x16x32_bf16 v[118:121], v[174:177], v[190:193], v[118:121]
	v_mfma_f32_16x16x32_bf16 v[114:117], v[182:185], v[190:193], v[114:117]
	v_mfma_f32_16x16x32_bf16 v[102:105], v[174:177], v[198:201], v[102:105]
	v_mfma_f32_16x16x32_bf16 v[98:101], v[182:185], v[198:201], v[98:101]
	v_mfma_f32_16x16x32_bf16 v[86:89], v[174:177], v[206:209], v[86:89]
	v_mfma_f32_16x16x32_bf16 v[82:85], v[182:185], v[206:209], v[82:85]
	v_mfma_f32_16x16x32_bf16 v[70:73], v[174:177], v[214:217], v[70:73]
	v_mfma_f32_16x16x32_bf16 v[66:69], v[182:185], v[214:217], v[66:69]
	s_setprio 0
	s_barrier
	s_add_i32 s50, s72, s58
	s_mov_b32 m0, s50
	ds_read_b128 v[186:189], v153 offset:16384
	ds_read_b128 v[190:193], v153 offset:17408
	ds_read_b128 v[194:197], v153 offset:18432
	ds_read_b128 v[198:201], v153 offset:19456
	ds_read_b128 v[202:205], v153 offset:20480
	ds_read_b128 v[206:209], v153 offset:21504
	ds_read_b128 v[210:213], v153 offset:22528
	ds_read_b128 v[214:217], v153 offset:23552
	global_load_lds_dwordx4 v132, s[42:43]
	s_add_i32 m0, s50, 0x2000
	s_add_u32 s50, s42, 0x80000
	s_addc_u32 s51, s43, 0
	s_add_i32 s53, s73, s58
	global_load_lds_dwordx4 v136, s[42:43]
	s_mov_b32 m0, s53
	s_nop 0
	global_load_lds_dwordx4 v132, s[50:51]
	s_add_i32 m0, s53, 0x2000
	s_nop 0
	global_load_lds_dwordx4 v136, s[50:51]
	s_cmp_eq_u32 s52, 0
	s_cbranch_scc1 .Lrw1
	s_waitcnt vmcnt(6)
.Lrw1:
	s_waitcnt vmcnt(6)
	s_waitcnt lgkmcnt(0)
	s_barrier
	s_setprio 1
	s_waitcnt lgkmcnt(0)
	v_mfma_f32_16x16x32_bf16 v[62:65], v[154:157], v[186:189], v[62:65]
	v_mfma_f32_16x16x32_bf16 v[58:61], v[162:165], v[186:189], v[58:61]
	v_mfma_f32_16x16x32_bf16 v[46:49], v[154:157], v[194:197], v[46:49]
	v_mfma_f32_16x16x32_bf16 v[42:45], v[162:165], v[194:197], v[42:45]
	v_mfma_f32_16x16x32_bf16 v[30:33], v[154:157], v[202:205], v[30:33]
	v_mfma_f32_16x16x32_bf16 v[26:29], v[162:165], v[202:205], v[26:29]
	v_mfma_f32_16x16x32_bf16 v[14:17], v[154:157], v[210:213], v[14:17]
	v_mfma_f32_16x16x32_bf16 v[10:13], v[162:165], v[210:213], v[10:13]
	v_mfma_f32_16x16x32_bf16 v[62:65], v[158:161], v[190:193], v[62:65]
	v_mfma_f32_16x16x32_bf16 v[58:61], v[166:169], v[190:193], v[58:61]
	v_mfma_f32_16x16x32_bf16 v[46:49], v[158:161], v[198:201], v[46:49]
	v_mfma_f32_16x16x32_bf16 v[42:45], v[166:169], v[198:201], v[42:45]
	v_mfma_f32_16x16x32_bf16 v[30:33], v[158:161], v[206:209], v[30:33]
	v_mfma_f32_16x16x32_bf16 v[26:29], v[166:169], v[206:209], v[26:29]
	v_mfma_f32_16x16x32_bf16 v[14:17], v[158:161], v[214:217], v[14:17]
	v_mfma_f32_16x16x32_bf16 v[10:13], v[166:169], v[214:217], v[10:13]
	v_mfma_f32_16x16x32_bf16 v[54:57], v[170:173], v[186:189], v[54:57]
	v_mfma_f32_16x16x32_bf16 v[50:53], v[178:181], v[186:189], v[50:53]
	v_mfma_f32_16x16x32_bf16 v[38:41], v[170:173], v[194:197], v[38:41]
	v_mfma_f32_16x16x32_bf16 v[34:37], v[178:181], v[194:197], v[34:37]
	v_mfma_f32_16x16x32_bf16 v[22:25], v[170:173], v[202:205], v[22:25]
	v_mfma_f32_16x16x32_bf16 v[18:21], v[178:181], v[202:205], v[18:21]
	v_mfma_f32_16x16x32_bf16 v[6:9], v[170:173], v[210:213], v[6:9]
	v_mfma_f32_16x16x32_bf16 v[2:5], v[178:181], v[210:213], v[2:5]
	v_mfma_f32_16x16x32_bf16 v[54:57], v[174:177], v[190:193], v[54:57]
	v_mfma_f32_16x16x32_bf16 v[50:53], v[182:185], v[190:193], v[50:53]
	v_mfma_f32_16x16x32_bf16 v[38:41], v[174:177], v[198:201], v[38:41]
	v_mfma_f32_16x16x32_bf16 v[34:37], v[182:185], v[198:201], v[34:37]
	v_mfma_f32_16x16x32_bf16 v[22:25], v[174:177], v[206:209], v[22:25]
	v_mfma_f32_16x16x32_bf16 v[18:21], v[182:185], v[206:209], v[18:21]
	v_mfma_f32_16x16x32_bf16 v[6:9], v[174:177], v[214:217], v[6:9]
	v_mfma_f32_16x16x32_bf16 v[2:5], v[182:185], v[214:217], v[2:5]
	s_setprio 0
	s_barrier
; #define PG8_STAGE(bufoff, gbase, voff) do { _Pragma("unroll") for (int _i = 0; _i < 2; ++_i) \
;         __builtin_amdgcn_global_load_lds((const unsigned*)((const char*)(gbase) + (voff)[_i]), (LAS unsigned*)(lds + (bufoff) + ldsw + _i * 8192), 16, 0, 0); } while (0)
; #define PG8_LDA(dst, b, h) do { _Pragma("unroll") for (int m = 0; m < 4; ++m) _Pragma("unroll") for (int k = 0; k < 2; ++k) dst[m][k] = *(const LAS bf16x8*)(lds + PG8_SA(b, h) + aoff + m * 2048 + k * 1024); } while (0)
; #define PG8_LDB(dst, b, h) do { _Pragma("unroll") for (int n = 0; n < 2; ++n) _Pragma("unroll") for (int k = 0; k < 2; ++k) dst[n][k] = *(const LAS bf16x8*)(lds + PG8_SB(b, h) + boff + n * 2048 + k * 1024); } while (0)
; #define PG8_MMA(ai, bj, At, Bt) do { __builtin_amdgcn_s_setprio(1); _Pragma("unroll") for (int m = 0; m < 4; ++m) _Pragma("unroll") for (int n = 0; n < 2; ++n) _Pragma("unroll") for (int k = 0; k < 2; ++k) \
;         acc[ai][bj][m][n] = __builtin_amdgcn_mfma_f32_16x16x32_bf16(Bt[n][k], At[m][k], acc[ai][bj][m][n], 0, 0, 0); __builtin_amdgcn_s_setprio(0); } while (0)
; #define PG8_WAIT_V(n) asm volatile("s_waitcnt vmcnt(" #n ")" ::: "memory")
; #define PG8_WAIT_L(n) asm volatile("s_waitcnt lgkmcnt(" #n ")" ::: "memory")
; #define PG8_BAR __builtin_amdgcn_s_barrier()
; #define PG8_SCHED __builtin_amdgcn_sched_barrier(0)
; template <class Epi, bool ALIGN_EPI = true>
; __device__ __forceinline__ void gemm_phase(LAS unsigned char* lds, const Gemm g, const Sched& S, const Epi& E) {
;     ...
;             PG8_LDB(B0, 1, 0); PG8_LDB(B1, 1, 1); PG8_SCHED; PG8_LDA(At, 1, 0); PG8_STAGE(PG8_SA(0, 1), a2 + hstepA, voffA);
;             PG8_WAIT_V(8); PG8_WAIT_L(0); PG8_BAR; PG8_MMA(0, 0, At, B0); PG8_MMA(0, 1, At, B1); PG8_BAR; PG8_SCHED;
;             PG8_LDA(At, 1, 1); PG8_STAGE(PG8_SB(1, 0), b3, voffB); PG8_STAGE(PG8_SB(1, 1), b3 + hstepB, voffB); PG8_STAGE(PG8_SA(1, 0), a3, voffA);
;             PG8_WAIT_V(8); PG8_WAIT_L(0); PG8_BAR; PG8_MMA(1, 0, At, B0); PG8_MMA(1, 1, At, B1); PG8_BAR; PG8_SCHED;
;         }
	s_add_i32 s50, 0, 0x18000
	v_add_u32_e32 v146, s50, v147
	s_add_i32 s51, 0, 0x1c000
	ds_read_b128 v[154:157], v146
	ds_read_b128 v[158:161], v146 offset:1024
	ds_read_b128 v[162:165], v146 offset:2048
	ds_read_b128 v[166:169], v146 offset:3072
	v_add_u32_e32 v146, s51, v147
	ds_read_b128 v[170:173], v146
	ds_read_b128 v[174:177], v146 offset:1024
	ds_read_b128 v[178:181], v146 offset:2048
	ds_read_b128 v[182:185], v146 offset:3072
	s_add_u32 s44, s44, 0x80000
	s_addc_u32 s45, s45, 0
	s_mov_b32 m0, s61
	ds_read_b128 v[186:189], v153 offset:32768
	ds_read_b128 v[190:193], v153 offset:33792
	ds_read_b128 v[194:197], v153 offset:34816
	ds_read_b128 v[198:201], v153 offset:35840
	ds_read_b128 v[202:205], v153 offset:36864
	ds_read_b128 v[206:209], v153 offset:37888
	ds_read_b128 v[210:213], v153 offset:38912
	ds_read_b128 v[214:217], v153 offset:39936
	s_add_u32 s100, s44, 0xfff80000
	s_addc_u32 s101, s45, -1
	s_mov_b32 m0, s59
	s_nop 0
	global_load_lds_dwordx4 v130, s[100:101]
	s_mov_b32 m0, s60
	s_nop 0
	global_load_lds_dwordx4 v134, s[100:101]
	s_mov_b32 m0, s61
	s_nop 0
	global_load_lds_dwordx4 v130, s[44:45]
	s_mov_b32 m0, s62
	s_nop 0
	global_load_lds_dwordx4 v134, s[44:45]
	s_waitcnt vmcnt(8)
	s_waitcnt lgkmcnt(0)
	s_barrier
	s_setprio 1
	s_waitcnt lgkmcnt(0)
	v_mfma_f32_16x16x32_bf16 v[122:125], v[154:157], v[186:189], v[122:125]
	v_mfma_f32_16x16x32_bf16 v[126:129], v[162:165], v[186:189], v[126:129]
	v_mfma_f32_16x16x32_bf16 v[110:113], v[154:157], v[194:197], v[110:113]
	v_mfma_f32_16x16x32_bf16 v[106:109], v[162:165], v[194:197], v[106:109]
	v_mfma_f32_16x16x32_bf16 v[94:97], v[154:157], v[202:205], v[94:97]
	v_mfma_f32_16x16x32_bf16 v[90:93], v[162:165], v[202:205], v[90:93]
	v_mfma_f32_16x16x32_bf16 v[78:81], v[154:157], v[210:213], v[78:81]
	v_mfma_f32_16x16x32_bf16 v[74:77], v[162:165], v[210:213], v[74:77]
	v_mfma_f32_16x16x32_bf16 v[122:125], v[158:161], v[190:193], v[122:125]
	v_mfma_f32_16x16x32_bf16 v[126:129], v[166:169], v[190:193], v[126:129]
	v_mfma_f32_16x16x32_bf16 v[110:113], v[158:161], v[198:201], v[110:113]
	v_mfma_f32_16x16x32_bf16 v[106:109], v[166:169], v[198:201], v[106:109]
	v_mfma_f32_16x16x32_bf16 v[94:97], v[158:161], v[206:209], v[94:97]
	v_mfma_f32_16x16x32_bf16 v[90:93], v[166:169], v[206:209], v[90:93]
	v_mfma_f32_16x16x32_bf16 v[78:81], v[158:161], v[214:217], v[78:81]
	v_mfma_f32_16x16x32_bf16 v[74:77], v[166:169], v[214:217], v[74:77]
	v_mfma_f32_16x16x32_bf16 v[118:121], v[170:173], v[186:189], v[118:121]
	v_mfma_f32_16x16x32_bf16 v[114:117], v[178:181], v[186:189], v[114:117]
	v_mfma_f32_16x16x32_bf16 v[102:105], v[170:173], v[194:197], v[102:105]
	v_mfma_f32_16x16x32_bf16 v[98:101], v[178:181], v[194:197], v[98:101]
	v_mfma_f32_16x16x32_bf16 v[86:89], v[170:173], v[202:205], v[86:89]
	v_mfma_f32_16x16x32_bf16 v[82:85], v[178:181], v[202:205], v[82:85]
	v_mfma_f32_16x16x32_bf16 v[70:73], v[170:173], v[210:213], v[70:73]
	v_mfma_f32_16x16x32_bf16 v[66:69], v[178:181], v[210:213], v[66:69]
	v_mfma_f32_16x16x32_bf16 v[118:121], v[174:177], v[190:193], v[118:121]
	v_mfma_f32_16x16x32_bf16 v[114:117], v[182:185], v[190:193], v[114:117]
	v_mfma_f32_16x16x32_bf16 v[102:105], v[174:177], v[198:201], v[102:105]
	v_mfma_f32_16x16x32_bf16 v[98:101], v[182:185], v[198:201], v[98:101]
	v_mfma_f32_16x16x32_bf16 v[86:89], v[174:177], v[206:209], v[86:89]
	v_mfma_f32_16x16x32_bf16 v[82:85], v[182:185], v[206:209], v[82:85]
	v_mfma_f32_16x16x32_bf16 v[70:73], v[174:177], v[214:217], v[70:73]
	v_mfma_f32_16x16x32_bf16 v[66:69], v[182:185], v[214:217], v[66:69]
	s_setprio 0
	s_barrier
	s_add_u32 s100, s42, 0x80
	s_addc_u32 s101, s43, 0
	s_add_i32 s44, s50, s58
	s_mov_b32 m0, s44
	ds_read_b128 v[186:189], v153 offset:49152
	ds_read_b128 v[190:193], v153 offset:50176
	ds_read_b128 v[194:197], v153 offset:51200
	ds_read_b128 v[198:201], v153 offset:52224
	ds_read_b128 v[202:205], v153 offset:53248
	ds_read_b128 v[206:209], v153 offset:54272
	ds_read_b128 v[210:213], v153 offset:55296
	ds_read_b128 v[214:217], v153 offset:56320
	global_load_lds_dwordx4 v132, s[100:101]
	s_add_i32 m0, s44, 0x2000
	s_add_u32 s42, s42, 0x80080
	s_addc_u32 s43, s43, 0
	s_add_i32 s44, s51, s58
	global_load_lds_dwordx4 v136, s[100:101]
	s_mov_b32 m0, s44
	s_nop 0
	global_load_lds_dwordx4 v132, s[42:43]
	s_add_i32 m0, s44, 0x2000
	s_nop 0
	global_load_lds_dwordx4 v136, s[42:43]
	s_waitcnt vmcnt(6)
	s_waitcnt lgkmcnt(0)
	s_barrier
	s_setprio 1
	s_waitcnt lgkmcnt(0)
	v_mfma_f32_16x16x32_bf16 v[62:65], v[154:157], v[186:189], v[62:65]
	v_mfma_f32_16x16x32_bf16 v[58:61], v[162:165], v[186:189], v[58:61]
	v_mfma_f32_16x16x32_bf16 v[46:49], v[154:157], v[194:197], v[46:49]
	v_mfma_f32_16x16x32_bf16 v[42:45], v[162:165], v[194:197], v[42:45]
	v_mfma_f32_16x16x32_bf16 v[30:33], v[154:157], v[202:205], v[30:33]
	v_mfma_f32_16x16x32_bf16 v[26:29], v[162:165], v[202:205], v[26:29]
	v_mfma_f32_16x16x32_bf16 v[14:17], v[154:157], v[210:213], v[14:17]
	v_mfma_f32_16x16x32_bf16 v[10:13], v[162:165], v[210:213], v[10:13]
	v_mfma_f32_16x16x32_bf16 v[62:65], v[158:161], v[190:193], v[62:65]
	v_mfma_f32_16x16x32_bf16 v[58:61], v[166:169], v[190:193], v[58:61]
	v_mfma_f32_16x16x32_bf16 v[46:49], v[158:161], v[198:201], v[46:49]
	v_mfma_f32_16x16x32_bf16 v[42:45], v[166:169], v[198:201], v[42:45]
	v_mfma_f32_16x16x32_bf16 v[30:33], v[158:161], v[206:209], v[30:33]
	v_mfma_f32_16x16x32_bf16 v[26:29], v[166:169], v[206:209], v[26:29]
	v_mfma_f32_16x16x32_bf16 v[14:17], v[158:161], v[214:217], v[14:17]
	v_mfma_f32_16x16x32_bf16 v[10:13], v[166:169], v[214:217], v[10:13]
	v_mfma_f32_16x16x32_bf16 v[54:57], v[170:173], v[186:189], v[54:57]
	v_mfma_f32_16x16x32_bf16 v[50:53], v[178:181], v[186:189], v[50:53]
	v_mfma_f32_16x16x32_bf16 v[38:41], v[170:173], v[194:197], v[38:41]
	v_mfma_f32_16x16x32_bf16 v[34:37], v[178:181], v[194:197], v[34:37]
	v_mfma_f32_16x16x32_bf16 v[22:25], v[170:173], v[202:205], v[22:25]
	v_mfma_f32_16x16x32_bf16 v[18:21], v[178:181], v[202:205], v[18:21]
	v_mfma_f32_16x16x32_bf16 v[6:9], v[170:173], v[210:213], v[6:9]
	v_mfma_f32_16x16x32_bf16 v[2:5], v[178:181], v[210:213], v[2:5]
	v_mfma_f32_16x16x32_bf16 v[54:57], v[174:177], v[190:193], v[54:57]
	v_mfma_f32_16x16x32_bf16 v[50:53], v[182:185], v[190:193], v[50:53]
	v_mfma_f32_16x16x32_bf16 v[38:41], v[174:177], v[198:201], v[38:41]
	v_mfma_f32_16x16x32_bf16 v[34:37], v[182:185], v[198:201], v[34:37]
	v_mfma_f32_16x16x32_bf16 v[22:25], v[174:177], v[206:209], v[22:25]
	v_mfma_f32_16x16x32_bf16 v[18:21], v[182:185], v[206:209], v[18:21]
	v_mfma_f32_16x16x32_bf16 v[6:9], v[174:177], v[214:217], v[6:9]
	v_mfma_f32_16x16x32_bf16 v[2:5], v[182:185], v[214:217], v[2:5]
	s_setprio 0
	s_barrier
	s_add_u32 s40, s40, 0x100
	s_addc_u32 s41, s41, 0
	s_add_u32 s47, s47, 0x100
	s_addc_u32 s48, s48, 0
	s_cmp_ge_i32 s49, s65
	s_mov_b32 s44, s49
	s_cbranch_scc0 .LBB0_314

; #define PG8_STAGE(bufoff, gbase, voff) do { _Pragma("unroll") for (int _i = 0; _i < 2; ++_i) \
;         __builtin_amdgcn_global_load_lds((const unsigned*)((const char*)(gbase) + (voff)[_i]), (LAS unsigned*)(lds + (bufoff) + ldsw + _i * 8192), 16, 0, 0); } while (0)
; #define PG8_LDA(dst, b, h) do { _Pragma("unroll") for (int m = 0; m < 4; ++m) _Pragma("unroll") for (int k = 0; k < 2; ++k) dst[m][k] = *(const LAS bf16x8*)(lds + PG8_SA(b, h) + aoff + m * 2048 + k * 1024); } while (0)
; #define PG8_LDB(dst, b, h) do { _Pragma("unroll") for (int n = 0; n < 2; ++n) _Pragma("unroll") for (int k = 0; k < 2; ++k) dst[n][k] = *(const LAS bf16x8*)(lds + PG8_SB(b, h) + boff + n * 2048 + k * 1024); } while (0)
; #define PG8_MMA(ai, bj, At, Bt) do { __builtin_amdgcn_s_setprio(1); _Pragma("unroll") for (int m = 0; m < 4; ++m) _Pragma("unroll") for (int n = 0; n < 2; ++n) _Pragma("unroll") for (int k = 0; k < 2; ++k) \
;         acc[ai][bj][m][n] = __builtin_amdgcn_mfma_f32_16x16x32_bf16(Bt[n][k], At[m][k], acc[ai][bj][m][n], 0, 0, 0); __builtin_amdgcn_s_setprio(0); } while (0)
; #define PG8_WAIT_V(n) asm volatile("s_waitcnt vmcnt(" #n ")" ::: "memory")
; #define PG8_WAIT_L(n) asm volatile("s_waitcnt lgkmcnt(" #n ")" ::: "memory")
; #define PG8_BAR __builtin_amdgcn_s_barrier()
; #define PG8_WAIT_RELAX(flag, n) asm volatile("s_cmp_eq_u32 %0, 0\n\ts_cbranch_scc1 .Lrw%=\n\ts_waitcnt vmcnt(8)\n.Lrw%=:\n\ts_waitcnt vmcnt(%1)" :: "s"(flag), "n"(n) : "scc", "memory")
; #define PG8_SCHED __builtin_amdgcn_sched_barrier(0)
; template <class Epi, bool ALIGN_EPI = true>
; __device__ __forceinline__ void gemm_phase(LAS unsigned char* lds, const Gemm g, const Sched& S, const Epi& E) {
;     ...
;             PG8_LDB(B0, 0, 0); PG8_LDB(B1, 0, 1); PG8_SCHED; PG8_LDA(At, 0, 0); PG8_STAGE(PG8_SA(1, 1), a1 + hstepA, voffA);
;             if constexpr (Epi::NSTORES > 0) PG8_WAIT_RELAX(rflag, 8 + Epi::NSTORES); else PG8_WAIT_V(8);
;             PG8_WAIT_L(0); PG8_BAR; PG8_MMA(0, 0, At, B0); PG8_MMA(0, 1, At, B1); PG8_BAR; PG8_SCHED;
;             PG8_LDA(At, 0, 1); PG8_STAGE(PG8_SB(0, 0), b2, voffB); PG8_STAGE(PG8_SB(0, 1), b2 + hstepB, voffB); PG8_STAGE(PG8_SA(0, 0), a2, voffA);
;             if constexpr (Epi::NSTORES > 0) PG8_WAIT_RELAX(rflag, 8 + Epi::NSTORES); else PG8_WAIT_V(8);
;             PG8_WAIT_L(0); PG8_BAR; PG8_MMA(1, 0, At, B0); PG8_MMA(1, 1, At, B1); PG8_BAR; PG8_SCHED;
.Lrw2:
	s_waitcnt vmcnt(24)
	s_waitcnt lgkmcnt(0)
	s_barrier
	s_setprio 1
	s_waitcnt lgkmcnt(0)
	v_mfma_f32_16x16x32_bf16 v[122:125], v[150:153], v[182:185], v[122:125]
	v_mfma_f32_16x16x32_bf16 v[126:129], v[158:161], v[182:185], v[126:129]
	v_mfma_f32_16x16x32_bf16 v[110:113], v[150:153], v[190:193], v[110:113]
	v_mfma_f32_16x16x32_bf16 v[106:109], v[158:161], v[190:193], v[106:109]
	v_mfma_f32_16x16x32_bf16 v[94:97], v[150:153], v[198:201], v[94:97]
	v_mfma_f32_16x16x32_bf16 v[90:93], v[158:161], v[198:201], v[90:93]
	v_mfma_f32_16x16x32_bf16 v[78:81], v[150:153], v[206:209], v[78:81]
	v_mfma_f32_16x16x32_bf16 v[74:77], v[158:161], v[206:209], v[74:77]
	v_mfma_f32_16x16x32_bf16 v[122:125], v[154:157], v[186:189], v[122:125]
	v_mfma_f32_16x16x32_bf16 v[126:129], v[162:165], v[186:189], v[126:129]
	v_mfma_f32_16x16x32_bf16 v[110:113], v[154:157], v[194:197], v[110:113]
	v_mfma_f32_16x16x32_bf16 v[106:109], v[162:165], v[194:197], v[106:109]
	v_mfma_f32_16x16x32_bf16 v[94:97], v[154:157], v[202:205], v[94:97]
	v_mfma_f32_16x16x32_bf16 v[90:93], v[162:165], v[202:205], v[90:93]
	v_mfma_f32_16x16x32_bf16 v[78:81], v[154:157], v[210:213], v[78:81]
	v_mfma_f32_16x16x32_bf16 v[74:77], v[162:165], v[210:213], v[74:77]
	v_mfma_f32_16x16x32_bf16 v[118:121], v[166:169], v[182:185], v[118:121]
	v_mfma_f32_16x16x32_bf16 v[114:117], v[174:177], v[182:185], v[114:117]
	v_mfma_f32_16x16x32_bf16 v[102:105], v[166:169], v[190:193], v[102:105]
	v_mfma_f32_16x16x32_bf16 v[98:101], v[174:177], v[190:193], v[98:101]
	v_mfma_f32_16x16x32_bf16 v[86:89], v[166:169], v[198:201], v[86:89]
	v_mfma_f32_16x16x32_bf16 v[82:85], v[174:177], v[198:201], v[82:85]
	v_mfma_f32_16x16x32_bf16 v[70:73], v[166:169], v[206:209], v[70:73]
	v_mfma_f32_16x16x32_bf16 v[66:69], v[174:177], v[206:209], v[66:69]
	v_mfma_f32_16x16x32_bf16 v[118:121], v[170:173], v[186:189], v[118:121]
	v_mfma_f32_16x16x32_bf16 v[114:117], v[178:181], v[186:189], v[114:117]
	v_mfma_f32_16x16x32_bf16 v[102:105], v[170:173], v[194:197], v[102:105]
	v_mfma_f32_16x16x32_bf16 v[98:101], v[178:181], v[194:197], v[98:101]
	v_mfma_f32_16x16x32_bf16 v[86:89], v[170:173], v[202:205], v[86:89]
	v_mfma_f32_16x16x32_bf16 v[82:85], v[178:181], v[202:205], v[82:85]
	v_mfma_f32_16x16x32_bf16 v[70:73], v[170:173], v[210:213], v[70:73]
	v_mfma_f32_16x16x32_bf16 v[66:69], v[178:181], v[210:213], v[66:69]
	s_setprio 0
	s_barrier
	s_add_i32 s74, s61, s46
	s_mov_b32 m0, s74
	ds_read_b128 v[182:185], v147 offset:16384
	ds_read_b128 v[186:189], v147 offset:17408
	ds_read_b128 v[190:193], v147 offset:18432
	ds_read_b128 v[194:197], v147 offset:19456
	ds_read_b128 v[198:201], v147 offset:20480
	ds_read_b128 v[202:205], v147 offset:21504
	ds_read_b128 v[206:209], v147 offset:22528
	ds_read_b128 v[210:213], v147 offset:23552
	global_load_lds_dwordx4 v134, s[36:37]
	s_add_i32 m0, s74, 0x2000
	s_add_u32 s74, s36, 0x400000
	s_addc_u32 s75, s37, 0
	s_add_i32 s76, s62, s46
	global_load_lds_dwordx4 v130, s[36:37]
	s_mov_b32 m0, s76
	s_nop 0
	global_load_lds_dwordx4 v134, s[74:75]
	s_add_i32 m0, s76, 0x2000
	s_nop 0
	global_load_lds_dwordx4 v130, s[74:75]
	s_cmp_eq_u32 s73, 0
	s_cbranch_scc1 .Lrw3
	s_waitcnt vmcnt(6)
.Lrw3:
	s_waitcnt vmcnt(6)
	s_waitcnt lgkmcnt(0)
	s_barrier
	s_setprio 1
	s_waitcnt lgkmcnt(0)
	v_mfma_f32_16x16x32_bf16 v[62:65], v[150:153], v[182:185], v[62:65]
	v_mfma_f32_16x16x32_bf16 v[58:61], v[158:161], v[182:185], v[58:61]
	v_mfma_f32_16x16x32_bf16 v[46:49], v[150:153], v[190:193], v[46:49]
	v_mfma_f32_16x16x32_bf16 v[42:45], v[158:161], v[190:193], v[42:45]
	v_mfma_f32_16x16x32_bf16 v[30:33], v[150:153], v[198:201], v[30:33]
	v_mfma_f32_16x16x32_bf16 v[26:29], v[158:161], v[198:201], v[26:29]
	v_mfma_f32_16x16x32_bf16 v[14:17], v[150:153], v[206:209], v[14:17]
	v_mfma_f32_16x16x32_bf16 v[10:13], v[158:161], v[206:209], v[10:13]
	v_mfma_f32_16x16x32_bf16 v[62:65], v[154:157], v[186:189], v[62:65]
	v_mfma_f32_16x16x32_bf16 v[58:61], v[162:165], v[186:189], v[58:61]
	v_mfma_f32_16x16x32_bf16 v[46:49], v[154:157], v[194:197], v[46:49]
	v_mfma_f32_16x16x32_bf16 v[42:45], v[162:165], v[194:197], v[42:45]
	v_mfma_f32_16x16x32_bf16 v[30:33], v[154:157], v[202:205], v[30:33]
	v_mfma_f32_16x16x32_bf16 v[26:29], v[162:165], v[202:205], v[26:29]
	v_mfma_f32_16x16x32_bf16 v[14:17], v[154:157], v[210:213], v[14:17]
	v_mfma_f32_16x16x32_bf16 v[10:13], v[162:165], v[210:213], v[10:13]
	v_mfma_f32_16x16x32_bf16 v[54:57], v[166:169], v[182:185], v[54:57]
	v_mfma_f32_16x16x32_bf16 v[50:53], v[174:177], v[182:185], v[50:53]
	v_mfma_f32_16x16x32_bf16 v[38:41], v[166:169], v[190:193], v[38:41]
	v_mfma_f32_16x16x32_bf16 v[34:37], v[174:177], v[190:193], v[34:37]
	v_mfma_f32_16x16x32_bf16 v[22:25], v[166:169], v[198:201], v[22:25]
	v_mfma_f32_16x16x32_bf16 v[18:21], v[174:177], v[198:201], v[18:21]
	v_mfma_f32_16x16x32_bf16 v[6:9], v[166:169], v[206:209], v[6:9]
	v_mfma_f32_16x16x32_bf16 v[2:5], v[174:177], v[206:209], v[2:5]
	v_mfma_f32_16x16x32_bf16 v[54:57], v[170:173], v[186:189], v[54:57]
	v_mfma_f32_16x16x32_bf16 v[50:53], v[178:181], v[186:189], v[50:53]
	v_mfma_f32_16x16x32_bf16 v[38:41], v[170:173], v[194:197], v[38:41]
	v_mfma_f32_16x16x32_bf16 v[34:37], v[178:181], v[194:197], v[34:37]
	v_mfma_f32_16x16x32_bf16 v[22:25], v[170:173], v[202:205], v[22:25]
	v_mfma_f32_16x16x32_bf16 v[18:21], v[178:181], v[202:205], v[18:21]
	v_mfma_f32_16x16x32_bf16 v[6:9], v[170:173], v[210:213], v[6:9]
	v_mfma_f32_16x16x32_bf16 v[2:5], v[178:181], v[210:213], v[2:5]
	s_setprio 0
	s_barrier
; #define PG8_STAGE(bufoff, gbase, voff) do { _Pragma("unroll") for (int _i = 0; _i < 2; ++_i) \
;         __builtin_amdgcn_global_load_lds((const unsigned*)((const char*)(gbase) + (voff)[_i]), (LAS unsigned*)(lds + (bufoff) + ldsw + _i * 8192), 16, 0, 0); } while (0)
; #define PG8_LDA(dst, b, h) do { _Pragma("unroll") for (int m = 0; m < 4; ++m) _Pragma("unroll") for (int k = 0; k < 2; ++k) dst[m][k] = *(const LAS bf16x8*)(lds + PG8_SA(b, h) + aoff + m * 2048 + k * 1024); } while (0)
; #define PG8_LDB(dst, b, h) do { _Pragma("unroll") for (int n = 0; n < 2; ++n) _Pragma("unroll") for (int k = 0; k < 2; ++k) dst[n][k] = *(const LAS bf16x8*)(lds + PG8_SB(b, h) + boff + n * 2048 + k * 1024); } while (0)
; #define PG8_MMA(ai, bj, At, Bt) do { __builtin_amdgcn_s_setprio(1); _Pragma("unroll") for (int m = 0; m < 4; ++m) _Pragma("unroll") for (int n = 0; n < 2; ++n) _Pragma("unroll") for (int k = 0; k < 2; ++k) \
;         acc[ai][bj][m][n] = __builtin_amdgcn_mfma_f32_16x16x32_bf16(Bt[n][k], At[m][k], acc[ai][bj][m][n], 0, 0, 0); __builtin_amdgcn_s_setprio(0); } while (0)
; #define PG8_WAIT_V(n) asm volatile("s_waitcnt vmcnt(" #n ")" ::: "memory")
; #define PG8_WAIT_L(n) asm volatile("s_waitcnt lgkmcnt(" #n ")" ::: "memory")
; #define PG8_BAR __builtin_amdgcn_s_barrier()
; #define PG8_SCHED __builtin_amdgcn_sched_barrier(0)
; template <class Epi, bool ALIGN_EPI = true>
; __device__ __forceinline__ void gemm_phase(LAS unsigned char* lds, const Gemm g, const Sched& S, const Epi& E) {
;     ...
;             PG8_LDB(B0, 1, 0); PG8_LDB(B1, 1, 1); PG8_SCHED; PG8_LDA(At, 1, 0); PG8_STAGE(PG8_SA(0, 1), a2 + hstepA, voffA);
;             PG8_WAIT_V(8); PG8_WAIT_L(0); PG8_BAR; PG8_MMA(0, 0, At, B0); PG8_MMA(0, 1, At, B1); PG8_BAR; PG8_SCHED;
;             PG8_LDA(At, 1, 1); PG8_STAGE(PG8_SB(1, 0), b3, voffB); PG8_STAGE(PG8_SB(1, 1), b3 + hstepB, voffB); PG8_STAGE(PG8_SA(1, 0), a3, voffA);
;             PG8_WAIT_V(8); PG8_WAIT_L(0); PG8_BAR; PG8_MMA(1, 0, At, B0); PG8_MMA(1, 1, At, B1); PG8_BAR; PG8_SCHED;
	s_add_i32 s73, 0, 0x18000
	v_add_u32_e32 v149, s73, v144
	s_add_i32 s74, 0, 0x1c000
	ds_read_b128 v[150:153], v149
	ds_read_b128 v[154:157], v149 offset:1024
	ds_read_b128 v[158:161], v149 offset:2048
	ds_read_b128 v[162:165], v149 offset:3072
	v_add_u32_e32 v149, s74, v144
	ds_read_b128 v[166:169], v149
	ds_read_b128 v[170:173], v149 offset:1024
	ds_read_b128 v[174:177], v149 offset:2048
	ds_read_b128 v[178:181], v149 offset:3072
	s_add_u32 s40, s40, 0x80000
	s_addc_u32 s41, s41, 0
	s_mov_b32 m0, s49
	ds_read_b128 v[182:185], v147 offset:32768
	ds_read_b128 v[186:189], v147 offset:33792
	ds_read_b128 v[190:193], v147 offset:34816
	ds_read_b128 v[194:197], v147 offset:35840
	ds_read_b128 v[198:201], v147 offset:36864
	ds_read_b128 v[202:205], v147 offset:37888
	ds_read_b128 v[206:209], v147 offset:38912
	ds_read_b128 v[210:213], v147 offset:39936
	s_add_u32 s100, s40, 0xfff80000
	s_addc_u32 s101, s41, -1
	s_mov_b32 m0, s47
	s_nop 0
	global_load_lds_dwordx4 v136, s[100:101]
	s_mov_b32 m0, s48
	s_nop 0
	global_load_lds_dwordx4 v132, s[100:101]
	s_mov_b32 m0, s49
	s_nop 0
	global_load_lds_dwordx4 v136, s[40:41]
	s_mov_b32 m0, s50
	s_nop 0
	global_load_lds_dwordx4 v132, s[40:41]
	s_waitcnt vmcnt(8)
	s_waitcnt lgkmcnt(0)
	s_barrier
	s_setprio 1
	s_waitcnt lgkmcnt(0)
	v_mfma_f32_16x16x32_bf16 v[122:125], v[150:153], v[182:185], v[122:125]
	v_mfma_f32_16x16x32_bf16 v[126:129], v[158:161], v[182:185], v[126:129]
	v_mfma_f32_16x16x32_bf16 v[110:113], v[150:153], v[190:193], v[110:113]
	v_mfma_f32_16x16x32_bf16 v[106:109], v[158:161], v[190:193], v[106:109]
	v_mfma_f32_16x16x32_bf16 v[94:97], v[150:153], v[198:201], v[94:97]
	v_mfma_f32_16x16x32_bf16 v[90:93], v[158:161], v[198:201], v[90:93]
	v_mfma_f32_16x16x32_bf16 v[78:81], v[150:153], v[206:209], v[78:81]
	v_mfma_f32_16x16x32_bf16 v[74:77], v[158:161], v[206:209], v[74:77]
	v_mfma_f32_16x16x32_bf16 v[122:125], v[154:157], v[186:189], v[122:125]
	v_mfma_f32_16x16x32_bf16 v[126:129], v[162:165], v[186:189], v[126:129]
	v_mfma_f32_16x16x32_bf16 v[110:113], v[154:157], v[194:197], v[110:113]
	v_mfma_f32_16x16x32_bf16 v[106:109], v[162:165], v[194:197], v[106:109]
	v_mfma_f32_16x16x32_bf16 v[94:97], v[154:157], v[202:205], v[94:97]
	v_mfma_f32_16x16x32_bf16 v[90:93], v[162:165], v[202:205], v[90:93]
	v_mfma_f32_16x16x32_bf16 v[78:81], v[154:157], v[210:213], v[78:81]
	v_mfma_f32_16x16x32_bf16 v[74:77], v[162:165], v[210:213], v[74:77]
	v_mfma_f32_16x16x32_bf16 v[118:121], v[166:169], v[182:185], v[118:121]
	v_mfma_f32_16x16x32_bf16 v[114:117], v[174:177], v[182:185], v[114:117]
	v_mfma_f32_16x16x32_bf16 v[102:105], v[166:169], v[190:193], v[102:105]
	v_mfma_f32_16x16x32_bf16 v[98:101], v[174:177], v[190:193], v[98:101]
	v_mfma_f32_16x16x32_bf16 v[86:89], v[166:169], v[198:201], v[86:89]
	v_mfma_f32_16x16x32_bf16 v[82:85], v[174:177], v[198:201], v[82:85]
	v_mfma_f32_16x16x32_bf16 v[70:73], v[166:169], v[206:209], v[70:73]
	v_mfma_f32_16x16x32_bf16 v[66:69], v[174:177], v[206:209], v[66:69]
	v_mfma_f32_16x16x32_bf16 v[118:121], v[170:173], v[186:189], v[118:121]
	v_mfma_f32_16x16x32_bf16 v[114:117], v[178:181], v[186:189], v[114:117]
	v_mfma_f32_16x16x32_bf16 v[102:105], v[170:173], v[194:197], v[102:105]
	v_mfma_f32_16x16x32_bf16 v[98:101], v[178:181], v[194:197], v[98:101]
	v_mfma_f32_16x16x32_bf16 v[86:89], v[170:173], v[202:205], v[86:89]
	v_mfma_f32_16x16x32_bf16 v[82:85], v[178:181], v[202:205], v[82:85]
	v_mfma_f32_16x16x32_bf16 v[70:73], v[170:173], v[210:213], v[70:73]
	v_mfma_f32_16x16x32_bf16 v[66:69], v[178:181], v[210:213], v[66:69]
	s_setprio 0
	s_barrier
	s_add_u32 s100, s36, 0x80
	s_addc_u32 s101, s37, 0
	s_add_i32 s40, s73, s46
	s_mov_b32 m0, s40
	ds_read_b128 v[182:185], v147 offset:49152
	ds_read_b128 v[186:189], v147 offset:50176
	ds_read_b128 v[190:193], v147 offset:51200
	ds_read_b128 v[194:197], v147 offset:52224
	ds_read_b128 v[198:201], v147 offset:53248
	ds_read_b128 v[202:205], v147 offset:54272
	ds_read_b128 v[206:209], v147 offset:55296
	ds_read_b128 v[210:213], v147 offset:56320
	global_load_lds_dwordx4 v134, s[100:101]
	s_add_i32 m0, s40, 0x2000
	s_add_u32 s36, s36, 0x400080
	s_addc_u32 s37, s37, 0
	s_add_i32 s40, s74, s46
	global_load_lds_dwordx4 v130, s[100:101]
	s_mov_b32 m0, s40
	s_nop 0
	global_load_lds_dwordx4 v134, s[36:37]
	s_add_i32 m0, s40, 0x2000
	s_nop 0
	global_load_lds_dwordx4 v130, s[36:37]
	s_waitcnt vmcnt(6)
	s_waitcnt lgkmcnt(0)
	s_barrier
	s_setprio 1
	s_waitcnt lgkmcnt(0)
	v_mfma_f32_16x16x32_bf16 v[62:65], v[150:153], v[182:185], v[62:65]
	v_mfma_f32_16x16x32_bf16 v[58:61], v[158:161], v[182:185], v[58:61]
	v_mfma_f32_16x16x32_bf16 v[46:49], v[150:153], v[190:193], v[46:49]
	v_mfma_f32_16x16x32_bf16 v[42:45], v[158:161], v[190:193], v[42:45]
	v_mfma_f32_16x16x32_bf16 v[30:33], v[150:153], v[198:201], v[30:33]
	v_mfma_f32_16x16x32_bf16 v[26:29], v[158:161], v[198:201], v[26:29]
	v_mfma_f32_16x16x32_bf16 v[14:17], v[150:153], v[206:209], v[14:17]
	v_mfma_f32_16x16x32_bf16 v[10:13], v[158:161], v[206:209], v[10:13]
	v_mfma_f32_16x16x32_bf16 v[62:65], v[154:157], v[186:189], v[62:65]
	v_mfma_f32_16x16x32_bf16 v[58:61], v[162:165], v[186:189], v[58:61]
	v_mfma_f32_16x16x32_bf16 v[46:49], v[154:157], v[194:197], v[46:49]
	v_mfma_f32_16x16x32_bf16 v[42:45], v[162:165], v[194:197], v[42:45]
	v_mfma_f32_16x16x32_bf16 v[30:33], v[154:157], v[202:205], v[30:33]
	v_mfma_f32_16x16x32_bf16 v[26:29], v[162:165], v[202:205], v[26:29]
	v_mfma_f32_16x16x32_bf16 v[14:17], v[154:157], v[210:213], v[14:17]
	v_mfma_f32_16x16x32_bf16 v[10:13], v[162:165], v[210:213], v[10:13]
	v_mfma_f32_16x16x32_bf16 v[54:57], v[166:169], v[182:185], v[54:57]
	v_mfma_f32_16x16x32_bf16 v[50:53], v[174:177], v[182:185], v[50:53]
	v_mfma_f32_16x16x32_bf16 v[38:41], v[166:169], v[190:193], v[38:41]
	v_mfma_f32_16x16x32_bf16 v[34:37], v[174:177], v[190:193], v[34:37]
	v_mfma_f32_16x16x32_bf16 v[22:25], v[166:169], v[198:201], v[22:25]
	v_mfma_f32_16x16x32_bf16 v[18:21], v[174:177], v[198:201], v[18:21]
	v_mfma_f32_16x16x32_bf16 v[6:9], v[166:169], v[206:209], v[6:9]
	v_mfma_f32_16x16x32_bf16 v[2:5], v[174:177], v[206:209], v[2:5]
	v_mfma_f32_16x16x32_bf16 v[54:57], v[170:173], v[186:189], v[54:57]
	v_mfma_f32_16x16x32_bf16 v[50:53], v[178:181], v[186:189], v[50:53]
	v_mfma_f32_16x16x32_bf16 v[38:41], v[170:173], v[194:197], v[38:41]
	v_mfma_f32_16x16x32_bf16 v[34:37], v[178:181], v[194:197], v[34:37]
	v_mfma_f32_16x16x32_bf16 v[22:25], v[170:173], v[202:205], v[22:25]
	v_mfma_f32_16x16x32_bf16 v[18:21], v[178:181], v[202:205], v[18:21]
	v_mfma_f32_16x16x32_bf16 v[6:9], v[170:173], v[210:213], v[6:9]
	v_mfma_f32_16x16x32_bf16 v[2:5], v[178:181], v[210:213], v[2:5]
	s_setprio 0
	s_barrier
	s_add_u32 s34, s34, 0x100
	s_addc_u32 s35, s35, 0
	s_add_u32 s70, s70, 0x100
	s_addc_u32 s71, s71, 0
	s_cmp_ge_i32 s72, s54
	s_mov_b32 s40, s72
	s_cbranch_scc0 .LBB0_388

; #define PG8_STAGE(bufoff, gbase, voff) do { _Pragma("unroll") for (int _i = 0; _i < 2; ++_i) \
;         __builtin_amdgcn_global_load_lds((const unsigned*)((const char*)(gbase) + (voff)[_i]), (LAS unsigned*)(lds + (bufoff) + ldsw + _i * 8192), 16, 0, 0); } while (0)
; #define PG8_LDA(dst, b, h) do { _Pragma("unroll") for (int m = 0; m < 4; ++m) _Pragma("unroll") for (int k = 0; k < 2; ++k) dst[m][k] = *(const LAS bf16x8*)(lds + PG8_SA(b, h) + aoff + m * 2048 + k * 1024); } while (0)
; #define PG8_LDB(dst, b, h) do { _Pragma("unroll") for (int n = 0; n < 2; ++n) _Pragma("unroll") for (int k = 0; k < 2; ++k) dst[n][k] = *(const LAS bf16x8*)(lds + PG8_SB(b, h) + boff + n * 2048 + k * 1024); } while (0)
; #define PG8_MMA(ai, bj, At, Bt) do { __builtin_amdgcn_s_setprio(1); _Pragma("unroll") for (int m = 0; m < 4; ++m) _Pragma("unroll") for (int n = 0; n < 2; ++n) _Pragma("unroll") for (int k = 0; k < 2; ++k) \
;         acc[ai][bj][m][n] = __builtin_amdgcn_mfma_f32_16x16x32_bf16(Bt[n][k], At[m][k], acc[ai][bj][m][n], 0, 0, 0); __builtin_amdgcn_s_setprio(0); } while (0)
; #define PG8_WAIT_V(n) asm volatile("s_waitcnt vmcnt(" #n ")" ::: "memory")
; #define PG8_WAIT_L(n) asm volatile("s_waitcnt lgkmcnt(" #n ")" ::: "memory")
; #define PG8_BAR __builtin_amdgcn_s_barrier()
; #define PG8_WAIT_RELAX(flag, n) asm volatile("s_cmp_eq_u32 %0, 0\n\ts_cbranch_scc1 .Lrw%=\n\ts_waitcnt vmcnt(8)\n.Lrw%=:\n\ts_waitcnt vmcnt(%1)" :: "s"(flag), "n"(n) : "scc", "memory")
; #define PG8_SCHED __builtin_amdgcn_sched_barrier(0)
; template <class Epi, bool ALIGN_EPI = true>
; __device__ __forceinline__ void gemm_phase(LAS unsigned char* lds, const Gemm g, const Sched& S, const Epi& E) {
;     ...
;             PG8_LDB(B0, 0, 0); PG8_LDB(B1, 0, 1); PG8_SCHED; PG8_LDA(At, 0, 0); PG8_STAGE(PG8_SA(1, 1), a1 + hstepA, voffA);
;             if constexpr (Epi::NSTORES > 0) PG8_WAIT_RELAX(rflag, 8 + Epi::NSTORES); else PG8_WAIT_V(8);
;             PG8_WAIT_L(0); PG8_BAR; PG8_MMA(0, 0, At, B0); PG8_MMA(0, 1, At, B1); PG8_BAR; PG8_SCHED;
;             PG8_LDA(At, 0, 1); PG8_STAGE(PG8_SB(0, 0), b2, voffB); PG8_STAGE(PG8_SB(0, 1), b2 + hstepB, voffB); PG8_STAGE(PG8_SA(0, 0), a2, voffA);
;             if constexpr (Epi::NSTORES > 0) PG8_WAIT_RELAX(rflag, 8 + Epi::NSTORES); else PG8_WAIT_V(8);
;             PG8_WAIT_L(0); PG8_BAR; PG8_MMA(1, 0, At, B0); PG8_MMA(1, 1, At, B1); PG8_BAR; PG8_SCHED;
.Lrw4:
	s_waitcnt vmcnt(24)
	s_waitcnt lgkmcnt(0)
	s_barrier
	s_setprio 1
	s_waitcnt lgkmcnt(0)
	v_mfma_f32_16x16x32_bf16 v[122:125], v[150:153], v[182:185], v[122:125]
	v_mfma_f32_16x16x32_bf16 v[126:129], v[158:161], v[182:185], v[126:129]
	v_mfma_f32_16x16x32_bf16 v[110:113], v[150:153], v[190:193], v[110:113]
	v_mfma_f32_16x16x32_bf16 v[106:109], v[158:161], v[190:193], v[106:109]
	v_mfma_f32_16x16x32_bf16 v[94:97], v[150:153], v[198:201], v[94:97]
	v_mfma_f32_16x16x32_bf16 v[90:93], v[158:161], v[198:201], v[90:93]
	v_mfma_f32_16x16x32_bf16 v[78:81], v[150:153], v[206:209], v[78:81]
	v_mfma_f32_16x16x32_bf16 v[74:77], v[158:161], v[206:209], v[74:77]
	v_mfma_f32_16x16x32_bf16 v[122:125], v[154:157], v[186:189], v[122:125]
	v_mfma_f32_16x16x32_bf16 v[126:129], v[162:165], v[186:189], v[126:129]
	v_mfma_f32_16x16x32_bf16 v[110:113], v[154:157], v[194:197], v[110:113]
	v_mfma_f32_16x16x32_bf16 v[106:109], v[162:165], v[194:197], v[106:109]
	v_mfma_f32_16x16x32_bf16 v[94:97], v[154:157], v[202:205], v[94:97]
	v_mfma_f32_16x16x32_bf16 v[90:93], v[162:165], v[202:205], v[90:93]
	v_mfma_f32_16x16x32_bf16 v[78:81], v[154:157], v[210:213], v[78:81]
	v_mfma_f32_16x16x32_bf16 v[74:77], v[162:165], v[210:213], v[74:77]
	v_mfma_f32_16x16x32_bf16 v[118:121], v[166:169], v[182:185], v[118:121]
	v_mfma_f32_16x16x32_bf16 v[114:117], v[174:177], v[182:185], v[114:117]
	v_mfma_f32_16x16x32_bf16 v[102:105], v[166:169], v[190:193], v[102:105]
	v_mfma_f32_16x16x32_bf16 v[98:101], v[174:177], v[190:193], v[98:101]
	v_mfma_f32_16x16x32_bf16 v[86:89], v[166:169], v[198:201], v[86:89]
	v_mfma_f32_16x16x32_bf16 v[82:85], v[174:177], v[198:201], v[82:85]
	v_mfma_f32_16x16x32_bf16 v[70:73], v[166:169], v[206:209], v[70:73]
	v_mfma_f32_16x16x32_bf16 v[66:69], v[174:177], v[206:209], v[66:69]
	v_mfma_f32_16x16x32_bf16 v[118:121], v[170:173], v[186:189], v[118:121]
	v_mfma_f32_16x16x32_bf16 v[114:117], v[178:181], v[186:189], v[114:117]
	v_mfma_f32_16x16x32_bf16 v[102:105], v[170:173], v[194:197], v[102:105]
	v_mfma_f32_16x16x32_bf16 v[98:101], v[178:181], v[194:197], v[98:101]
	v_mfma_f32_16x16x32_bf16 v[86:89], v[170:173], v[202:205], v[86:89]
	v_mfma_f32_16x16x32_bf16 v[82:85], v[178:181], v[202:205], v[82:85]
	v_mfma_f32_16x16x32_bf16 v[70:73], v[170:173], v[210:213], v[70:73]
	v_mfma_f32_16x16x32_bf16 v[66:69], v[178:181], v[210:213], v[66:69]
	s_setprio 0
	s_barrier
	s_add_i32 s70, s58, s44
	s_mov_b32 m0, s70
	ds_read_b128 v[182:185], v147 offset:16384
	ds_read_b128 v[186:189], v147 offset:17408
	ds_read_b128 v[190:193], v147 offset:18432
	ds_read_b128 v[194:197], v147 offset:19456
	ds_read_b128 v[198:201], v147 offset:20480
	ds_read_b128 v[202:205], v147 offset:21504
	ds_read_b128 v[206:209], v147 offset:22528
	ds_read_b128 v[210:213], v147 offset:23552
	global_load_lds_dwordx4 v132, s[34:35]
	s_add_i32 m0, s70, 0x2000
	s_add_u32 s70, s34, 0x80000
	s_addc_u32 s71, s35, 0
	s_add_i32 s73, s59, s44
	global_load_lds_dwordx4 v136, s[34:35]
	s_mov_b32 m0, s73
	s_nop 0
	global_load_lds_dwordx4 v132, s[70:71]
	s_add_i32 m0, s73, 0x2000
	s_nop 0
	global_load_lds_dwordx4 v136, s[70:71]
	s_cmp_eq_u32 s72, 0
	s_cbranch_scc1 .Lrw5
	s_waitcnt vmcnt(6)
.Lrw5:
	s_waitcnt vmcnt(6)
	s_waitcnt lgkmcnt(0)
	s_barrier
	s_setprio 1
	s_waitcnt lgkmcnt(0)
	v_mfma_f32_16x16x32_bf16 v[62:65], v[150:153], v[182:185], v[62:65]
	v_mfma_f32_16x16x32_bf16 v[58:61], v[158:161], v[182:185], v[58:61]
	v_mfma_f32_16x16x32_bf16 v[46:49], v[150:153], v[190:193], v[46:49]
	v_mfma_f32_16x16x32_bf16 v[42:45], v[158:161], v[190:193], v[42:45]
	v_mfma_f32_16x16x32_bf16 v[30:33], v[150:153], v[198:201], v[30:33]
	v_mfma_f32_16x16x32_bf16 v[26:29], v[158:161], v[198:201], v[26:29]
	v_mfma_f32_16x16x32_bf16 v[14:17], v[150:153], v[206:209], v[14:17]
	v_mfma_f32_16x16x32_bf16 v[10:13], v[158:161], v[206:209], v[10:13]
	v_mfma_f32_16x16x32_bf16 v[62:65], v[154:157], v[186:189], v[62:65]
	v_mfma_f32_16x16x32_bf16 v[58:61], v[162:165], v[186:189], v[58:61]
	v_mfma_f32_16x16x32_bf16 v[46:49], v[154:157], v[194:197], v[46:49]
	v_mfma_f32_16x16x32_bf16 v[42:45], v[162:165], v[194:197], v[42:45]
	v_mfma_f32_16x16x32_bf16 v[30:33], v[154:157], v[202:205], v[30:33]
	v_mfma_f32_16x16x32_bf16 v[26:29], v[162:165], v[202:205], v[26:29]
	v_mfma_f32_16x16x32_bf16 v[14:17], v[154:157], v[210:213], v[14:17]
	v_mfma_f32_16x16x32_bf16 v[10:13], v[162:165], v[210:213], v[10:13]
	v_mfma_f32_16x16x32_bf16 v[54:57], v[166:169], v[182:185], v[54:57]
	v_mfma_f32_16x16x32_bf16 v[50:53], v[174:177], v[182:185], v[50:53]
	v_mfma_f32_16x16x32_bf16 v[38:41], v[166:169], v[190:193], v[38:41]
	v_mfma_f32_16x16x32_bf16 v[34:37], v[174:177], v[190:193], v[34:37]
	v_mfma_f32_16x16x32_bf16 v[22:25], v[166:169], v[198:201], v[22:25]
	v_mfma_f32_16x16x32_bf16 v[18:21], v[174:177], v[198:201], v[18:21]
	v_mfma_f32_16x16x32_bf16 v[6:9], v[166:169], v[206:209], v[6:9]
	v_mfma_f32_16x16x32_bf16 v[2:5], v[174:177], v[206:209], v[2:5]
	v_mfma_f32_16x16x32_bf16 v[54:57], v[170:173], v[186:189], v[54:57]
	v_mfma_f32_16x16x32_bf16 v[50:53], v[178:181], v[186:189], v[50:53]
	v_mfma_f32_16x16x32_bf16 v[38:41], v[170:173], v[194:197], v[38:41]
	v_mfma_f32_16x16x32_bf16 v[34:37], v[178:181], v[194:197], v[34:37]
	v_mfma_f32_16x16x32_bf16 v[22:25], v[170:173], v[202:205], v[22:25]
	v_mfma_f32_16x16x32_bf16 v[18:21], v[178:181], v[202:205], v[18:21]
	v_mfma_f32_16x16x32_bf16 v[6:9], v[170:173], v[210:213], v[6:9]
	v_mfma_f32_16x16x32_bf16 v[2:5], v[178:181], v[210:213], v[2:5]
	s_setprio 0
	s_barrier
; #define PG8_STAGE(bufoff, gbase, voff) do { _Pragma("unroll") for (int _i = 0; _i < 2; ++_i) \
;         __builtin_amdgcn_global_load_lds((const unsigned*)((const char*)(gbase) + (voff)[_i]), (LAS unsigned*)(lds + (bufoff) + ldsw + _i * 8192), 16, 0, 0); } while (0)
; #define PG8_LDA(dst, b, h) do { _Pragma("unroll") for (int m = 0; m < 4; ++m) _Pragma("unroll") for (int k = 0; k < 2; ++k) dst[m][k] = *(const LAS bf16x8*)(lds + PG8_SA(b, h) + aoff + m * 2048 + k * 1024); } while (0)
; #define PG8_LDB(dst, b, h) do { _Pragma("unroll") for (int n = 0; n < 2; ++n) _Pragma("unroll") for (int k = 0; k < 2; ++k) dst[n][k] = *(const LAS bf16x8*)(lds + PG8_SB(b, h) + boff + n * 2048 + k * 1024); } while (0)
; #define PG8_MMA(ai, bj, At, Bt) do { __builtin_amdgcn_s_setprio(1); _Pragma("unroll") for (int m = 0; m < 4; ++m) _Pragma("unroll") for (int n = 0; n < 2; ++n) _Pragma("unroll") for (int k = 0; k < 2; ++k) \
;         acc[ai][bj][m][n] = __builtin_amdgcn_mfma_f32_16x16x32_bf16(Bt[n][k], At[m][k], acc[ai][bj][m][n], 0, 0, 0); __builtin_amdgcn_s_setprio(0); } while (0)
; #define PG8_WAIT_V(n) asm volatile("s_waitcnt vmcnt(" #n ")" ::: "memory")
; #define PG8_WAIT_L(n) asm volatile("s_waitcnt lgkmcnt(" #n ")" ::: "memory")
; #define PG8_BAR __builtin_amdgcn_s_barrier()
; #define PG8_SCHED __builtin_amdgcn_sched_barrier(0)
; template <class Epi, bool ALIGN_EPI = true>
; __device__ __forceinline__ void gemm_phase(LAS unsigned char* lds, const Gemm g, const Sched& S, const Epi& E) {
;     ...
;             PG8_LDB(B0, 1, 0); PG8_LDB(B1, 1, 1); PG8_SCHED; PG8_LDA(At, 1, 0); PG8_STAGE(PG8_SA(0, 1), a2 + hstepA, voffA);
;             PG8_WAIT_V(8); PG8_WAIT_L(0); PG8_BAR; PG8_MMA(0, 0, At, B0); PG8_MMA(0, 1, At, B1); PG8_BAR; PG8_SCHED;
;             PG8_LDA(At, 1, 1); PG8_STAGE(PG8_SB(1, 0), b3, voffB); PG8_STAGE(PG8_SB(1, 1), b3 + hstepB, voffB); PG8_STAGE(PG8_SA(1, 0), a3, voffA);
;             PG8_WAIT_V(8); PG8_WAIT_L(0); PG8_BAR; PG8_MMA(1, 0, At, B0); PG8_MMA(1, 1, At, B1); PG8_BAR; PG8_SCHED;
	s_add_i32 s70, 0, 0x18000
	v_add_u32_e32 v149, s70, v144
	s_add_i32 s71, 0, 0x1c000
	ds_read_b128 v[150:153], v149
	ds_read_b128 v[154:157], v149 offset:1024
	ds_read_b128 v[158:161], v149 offset:2048
	ds_read_b128 v[162:165], v149 offset:3072
	v_add_u32_e32 v149, s71, v144
	ds_read_b128 v[166:169], v149
	ds_read_b128 v[170:173], v149 offset:1024
	ds_read_b128 v[174:177], v149 offset:2048
	ds_read_b128 v[178:181], v149 offset:3072
	s_add_u32 s36, s36, 0x400000
	s_addc_u32 s37, s37, 0
	s_mov_b32 m0, s47
	ds_read_b128 v[182:185], v147 offset:32768
	ds_read_b128 v[186:189], v147 offset:33792
	ds_read_b128 v[190:193], v147 offset:34816
	ds_read_b128 v[194:197], v147 offset:35840
	ds_read_b128 v[198:201], v147 offset:36864
	ds_read_b128 v[202:205], v147 offset:37888
	ds_read_b128 v[206:209], v147 offset:38912
	ds_read_b128 v[210:213], v147 offset:39936
	s_add_u32 s100, s36, 0xffc00000
	s_addc_u32 s101, s37, -1
	s_mov_b32 m0, s45
	s_nop 0
	global_load_lds_dwordx4 v130, s[100:101]
	s_mov_b32 m0, s46
	s_nop 0
	global_load_lds_dwordx4 v134, s[100:101]
	s_mov_b32 m0, s47
	s_nop 0
	global_load_lds_dwordx4 v130, s[36:37]
	s_mov_b32 m0, s48
	s_nop 0
	global_load_lds_dwordx4 v134, s[36:37]
	s_waitcnt vmcnt(8)
	s_waitcnt lgkmcnt(0)
	s_barrier
	s_setprio 1
	s_waitcnt lgkmcnt(0)
	v_mfma_f32_16x16x32_bf16 v[122:125], v[150:153], v[182:185], v[122:125]
	v_mfma_f32_16x16x32_bf16 v[126:129], v[158:161], v[182:185], v[126:129]
	v_mfma_f32_16x16x32_bf16 v[110:113], v[150:153], v[190:193], v[110:113]
	v_mfma_f32_16x16x32_bf16 v[106:109], v[158:161], v[190:193], v[106:109]
	v_mfma_f32_16x16x32_bf16 v[94:97], v[150:153], v[198:201], v[94:97]
	v_mfma_f32_16x16x32_bf16 v[90:93], v[158:161], v[198:201], v[90:93]
	v_mfma_f32_16x16x32_bf16 v[78:81], v[150:153], v[206:209], v[78:81]
	v_mfma_f32_16x16x32_bf16 v[74:77], v[158:161], v[206:209], v[74:77]
	v_mfma_f32_16x16x32_bf16 v[122:125], v[154:157], v[186:189], v[122:125]
	v_mfma_f32_16x16x32_bf16 v[126:129], v[162:165], v[186:189], v[126:129]
	v_mfma_f32_16x16x32_bf16 v[110:113], v[154:157], v[194:197], v[110:113]
	v_mfma_f32_16x16x32_bf16 v[106:109], v[162:165], v[194:197], v[106:109]
	v_mfma_f32_16x16x32_bf16 v[94:97], v[154:157], v[202:205], v[94:97]
	v_mfma_f32_16x16x32_bf16 v[90:93], v[162:165], v[202:205], v[90:93]
	v_mfma_f32_16x16x32_bf16 v[78:81], v[154:157], v[210:213], v[78:81]
	v_mfma_f32_16x16x32_bf16 v[74:77], v[162:165], v[210:213], v[74:77]
	v_mfma_f32_16x16x32_bf16 v[118:121], v[166:169], v[182:185], v[118:121]
	v_mfma_f32_16x16x32_bf16 v[114:117], v[174:177], v[182:185], v[114:117]
	v_mfma_f32_16x16x32_bf16 v[102:105], v[166:169], v[190:193], v[102:105]
	v_mfma_f32_16x16x32_bf16 v[98:101], v[174:177], v[190:193], v[98:101]
	v_mfma_f32_16x16x32_bf16 v[86:89], v[166:169], v[198:201], v[86:89]
	v_mfma_f32_16x16x32_bf16 v[82:85], v[174:177], v[198:201], v[82:85]
	v_mfma_f32_16x16x32_bf16 v[70:73], v[166:169], v[206:209], v[70:73]
	v_mfma_f32_16x16x32_bf16 v[66:69], v[174:177], v[206:209], v[66:69]
	v_mfma_f32_16x16x32_bf16 v[118:121], v[170:173], v[186:189], v[118:121]
	v_mfma_f32_16x16x32_bf16 v[114:117], v[178:181], v[186:189], v[114:117]
	v_mfma_f32_16x16x32_bf16 v[102:105], v[170:173], v[194:197], v[102:105]
	v_mfma_f32_16x16x32_bf16 v[98:101], v[178:181], v[194:197], v[98:101]
	v_mfma_f32_16x16x32_bf16 v[86:89], v[170:173], v[202:205], v[86:89]
	v_mfma_f32_16x16x32_bf16 v[82:85], v[178:181], v[202:205], v[82:85]
	v_mfma_f32_16x16x32_bf16 v[70:73], v[170:173], v[210:213], v[70:73]
	v_mfma_f32_16x16x32_bf16 v[66:69], v[178:181], v[210:213], v[66:69]
	s_setprio 0
	s_barrier
	s_add_u32 s100, s34, 0x80
	s_addc_u32 s101, s35, 0
	s_add_i32 s36, s70, s44
	s_mov_b32 m0, s36
	ds_read_b128 v[182:185], v147 offset:49152
	ds_read_b128 v[186:189], v147 offset:50176
	ds_read_b128 v[190:193], v147 offset:51200
	ds_read_b128 v[194:197], v147 offset:52224
	ds_read_b128 v[198:201], v147 offset:53248
	ds_read_b128 v[202:205], v147 offset:54272
	ds_read_b128 v[206:209], v147 offset:55296
	ds_read_b128 v[210:213], v147 offset:56320
	global_load_lds_dwordx4 v132, s[100:101]
	s_add_i32 m0, s36, 0x2000
	s_add_u32 s34, s34, 0x80080
	s_addc_u32 s35, s35, 0
	s_add_i32 s36, s71, s44
	global_load_lds_dwordx4 v136, s[100:101]
	s_mov_b32 m0, s36
	s_nop 0
	global_load_lds_dwordx4 v132, s[34:35]
	s_add_i32 m0, s36, 0x2000
	s_nop 0
	global_load_lds_dwordx4 v136, s[34:35]
	s_waitcnt vmcnt(6)
	s_waitcnt lgkmcnt(0)
	s_barrier
	s_setprio 1
	s_waitcnt lgkmcnt(0)
	v_mfma_f32_16x16x32_bf16 v[62:65], v[150:153], v[182:185], v[62:65]
	v_mfma_f32_16x16x32_bf16 v[58:61], v[158:161], v[182:185], v[58:61]
	v_mfma_f32_16x16x32_bf16 v[46:49], v[150:153], v[190:193], v[46:49]
	v_mfma_f32_16x16x32_bf16 v[42:45], v[158:161], v[190:193], v[42:45]
	v_mfma_f32_16x16x32_bf16 v[30:33], v[150:153], v[198:201], v[30:33]
	v_mfma_f32_16x16x32_bf16 v[26:29], v[158:161], v[198:201], v[26:29]
	v_mfma_f32_16x16x32_bf16 v[14:17], v[150:153], v[206:209], v[14:17]
	v_mfma_f32_16x16x32_bf16 v[10:13], v[158:161], v[206:209], v[10:13]
	v_mfma_f32_16x16x32_bf16 v[62:65], v[154:157], v[186:189], v[62:65]
	v_mfma_f32_16x16x32_bf16 v[58:61], v[162:165], v[186:189], v[58:61]
	v_mfma_f32_16x16x32_bf16 v[46:49], v[154:157], v[194:197], v[46:49]
	v_mfma_f32_16x16x32_bf16 v[42:45], v[162:165], v[194:197], v[42:45]
	v_mfma_f32_16x16x32_bf16 v[30:33], v[154:157], v[202:205], v[30:33]
	v_mfma_f32_16x16x32_bf16 v[26:29], v[162:165], v[202:205], v[26:29]
	v_mfma_f32_16x16x32_bf16 v[14:17], v[154:157], v[210:213], v[14:17]
	v_mfma_f32_16x16x32_bf16 v[10:13], v[162:165], v[210:213], v[10:13]
	v_mfma_f32_16x16x32_bf16 v[54:57], v[166:169], v[182:185], v[54:57]
	v_mfma_f32_16x16x32_bf16 v[50:53], v[174:177], v[182:185], v[50:53]
	v_mfma_f32_16x16x32_bf16 v[38:41], v[166:169], v[190:193], v[38:41]
	v_mfma_f32_16x16x32_bf16 v[34:37], v[174:177], v[190:193], v[34:37]
	v_mfma_f32_16x16x32_bf16 v[22:25], v[166:169], v[198:201], v[22:25]
	v_mfma_f32_16x16x32_bf16 v[18:21], v[174:177], v[198:201], v[18:21]
	v_mfma_f32_16x16x32_bf16 v[6:9], v[166:169], v[206:209], v[6:9]
	v_mfma_f32_16x16x32_bf16 v[2:5], v[174:177], v[206:209], v[2:5]
	v_mfma_f32_16x16x32_bf16 v[54:57], v[170:173], v[186:189], v[54:57]
	v_mfma_f32_16x16x32_bf16 v[50:53], v[178:181], v[186:189], v[50:53]
	v_mfma_f32_16x16x32_bf16 v[38:41], v[170:173], v[194:197], v[38:41]
	v_mfma_f32_16x16x32_bf16 v[34:37], v[178:181], v[194:197], v[34:37]
	v_mfma_f32_16x16x32_bf16 v[22:25], v[170:173], v[202:205], v[22:25]
	v_mfma_f32_16x16x32_bf16 v[18:21], v[178:181], v[202:205], v[18:21]
	v_mfma_f32_16x16x32_bf16 v[6:9], v[170:173], v[210:213], v[6:9]
	v_mfma_f32_16x16x32_bf16 v[2:5], v[178:181], v[210:213], v[2:5]
	s_setprio 0
	s_barrier
	s_add_u32 s30, s30, 0x100
	s_addc_u32 s31, s31, 0
	s_add_u32 s67, s67, 0x100
	s_addc_u32 s68, s68, 0
	s_cmp_ge_i32 s69, s51
	s_mov_b32 s36, s69
	s_cbranch_scc0 .LBB0_415

; #define PG8_STAGE(bufoff, gbase, voff) do { _Pragma("unroll") for (int _i = 0; _i < 2; ++_i) \
;         __builtin_amdgcn_global_load_lds((const unsigned*)((const char*)(gbase) + (voff)[_i]), (LAS unsigned*)(lds + (bufoff) + ldsw + _i * 8192), 16, 0, 0); } while (0)
; #define PG8_LDA(dst, b, h) do { _Pragma("unroll") for (int m = 0; m < 4; ++m) _Pragma("unroll") for (int k = 0; k < 2; ++k) dst[m][k] = *(const LAS bf16x8*)(lds + PG8_SA(b, h) + aoff + m * 2048 + k * 1024); } while (0)
; #define PG8_LDB(dst, b, h) do { _Pragma("unroll") for (int n = 0; n < 2; ++n) _Pragma("unroll") for (int k = 0; k < 2; ++k) dst[n][k] = *(const LAS bf16x8*)(lds + PG8_SB(b, h) + boff + n * 2048 + k * 1024); } while (0)
; #define PG8_MMA(ai, bj, At, Bt) do { __builtin_amdgcn_s_setprio(1); _Pragma("unroll") for (int m = 0; m < 4; ++m) _Pragma("unroll") for (int n = 0; n < 2; ++n) _Pragma("unroll") for (int k = 0; k < 2; ++k) \
;         acc[ai][bj][m][n] = __builtin_amdgcn_mfma_f32_16x16x32_bf16(Bt[n][k], At[m][k], acc[ai][bj][m][n], 0, 0, 0); __builtin_amdgcn_s_setprio(0); } while (0)
; #define PG8_WAIT_V(n) asm volatile("s_waitcnt vmcnt(" #n ")" ::: "memory")
; #define PG8_WAIT_L(n) asm volatile("s_waitcnt lgkmcnt(" #n ")" ::: "memory")
; #define PG8_BAR __builtin_amdgcn_s_barrier()
; #define PG8_WAIT_RELAX(flag, n) asm volatile("s_cmp_eq_u32 %0, 0\n\ts_cbranch_scc1 .Lrw%=\n\ts_waitcnt vmcnt(8)\n.Lrw%=:\n\ts_waitcnt vmcnt(%1)" :: "s"(flag), "n"(n) : "scc", "memory")
; #define PG8_SCHED __builtin_amdgcn_sched_barrier(0)
; template <class Epi, bool ALIGN_EPI = true>
; __device__ __forceinline__ void gemm_phase(LAS unsigned char* lds, const Gemm g, const Sched& S, const Epi& E) {
;     ...
;             PG8_LDB(B0, 0, 0); PG8_LDB(B1, 0, 1); PG8_SCHED; PG8_LDA(At, 0, 0); PG8_STAGE(PG8_SA(1, 1), a1 + hstepA, voffA);
;             if constexpr (Epi::NSTORES > 0) PG8_WAIT_RELAX(rflag, 8 + Epi::NSTORES); else PG8_WAIT_V(8);
;             PG8_WAIT_L(0); PG8_BAR; PG8_MMA(0, 0, At, B0); PG8_MMA(0, 1, At, B1); PG8_BAR; PG8_SCHED;
;             PG8_LDA(At, 0, 1); PG8_STAGE(PG8_SB(0, 0), b2, voffB); PG8_STAGE(PG8_SB(0, 1), b2 + hstepB, voffB); PG8_STAGE(PG8_SA(0, 0), a2, voffA);
;             if constexpr (Epi::NSTORES > 0) PG8_WAIT_RELAX(rflag, 8 + Epi::NSTORES); else PG8_WAIT_V(8);
;             PG8_WAIT_L(0); PG8_BAR; PG8_MMA(1, 0, At, B0); PG8_MMA(1, 1, At, B1); PG8_BAR; PG8_SCHED;
.Lrw6:
	s_waitcnt vmcnt(24)
	s_waitcnt lgkmcnt(0)
	s_barrier
	s_setprio 1
	s_waitcnt lgkmcnt(0)
	v_mfma_f32_16x16x32_bf16 v[130:133], v[134:137], v[178:181], v[130:133]
	v_mfma_f32_16x16x32_bf16 v[126:129], v[142:145], v[178:181], v[126:129]
	v_mfma_f32_16x16x32_bf16 v[122:125], v[134:137], v[192:195], v[122:125]
	v_mfma_f32_16x16x32_bf16 v[118:121], v[142:145], v[192:195], v[118:121]
	v_mfma_f32_16x16x32_bf16 v[114:117], v[134:137], v[224:227], v[114:117]
	v_mfma_f32_16x16x32_bf16 v[110:113], v[142:145], v[224:227], v[110:113]
	v_mfma_f32_16x16x32_bf16 v[106:109], v[134:137], v[232:235], v[106:109]
	v_mfma_f32_16x16x32_bf16 v[102:105], v[142:145], v[232:235], v[102:105]
	v_mfma_f32_16x16x32_bf16 v[130:133], v[138:141], v[188:191], v[130:133]
	v_mfma_f32_16x16x32_bf16 v[126:129], v[146:149], v[188:191], v[126:129]
	v_mfma_f32_16x16x32_bf16 v[122:125], v[138:141], v[206:209], v[122:125]
	v_mfma_f32_16x16x32_bf16 v[118:121], v[146:149], v[206:209], v[118:121]
	v_mfma_f32_16x16x32_bf16 v[114:117], v[138:141], v[228:231], v[114:117]
	v_mfma_f32_16x16x32_bf16 v[110:113], v[146:149], v[228:231], v[110:113]
	v_mfma_f32_16x16x32_bf16 v[106:109], v[138:141], v[236:239], v[106:109]
	v_mfma_f32_16x16x32_bf16 v[102:105], v[146:149], v[236:239], v[102:105]
	v_mfma_f32_16x16x32_bf16 v[98:101], v[162:165], v[178:181], v[98:101]
	v_mfma_f32_16x16x32_bf16 v[94:97], v[170:173], v[178:181], v[94:97]
	v_mfma_f32_16x16x32_bf16 v[90:93], v[162:165], v[192:195], v[90:93]
	v_mfma_f32_16x16x32_bf16 v[86:89], v[170:173], v[192:195], v[86:89]
	v_mfma_f32_16x16x32_bf16 v[82:85], v[162:165], v[224:227], v[82:85]
	v_mfma_f32_16x16x32_bf16 v[78:81], v[170:173], v[224:227], v[78:81]
	v_mfma_f32_16x16x32_bf16 v[74:77], v[162:165], v[232:235], v[74:77]
	v_mfma_f32_16x16x32_bf16 v[70:73], v[170:173], v[232:235], v[70:73]
	v_mfma_f32_16x16x32_bf16 v[98:101], v[166:169], v[188:191], v[98:101]
	v_mfma_f32_16x16x32_bf16 v[94:97], v[174:177], v[188:191], v[94:97]
	v_mfma_f32_16x16x32_bf16 v[90:93], v[166:169], v[206:209], v[90:93]
	v_mfma_f32_16x16x32_bf16 v[86:89], v[174:177], v[206:209], v[86:89]
	v_mfma_f32_16x16x32_bf16 v[82:85], v[166:169], v[228:231], v[82:85]
	v_mfma_f32_16x16x32_bf16 v[78:81], v[174:177], v[228:231], v[78:81]
	v_mfma_f32_16x16x32_bf16 v[74:77], v[166:169], v[236:239], v[74:77]
	v_mfma_f32_16x16x32_bf16 v[70:73], v[174:177], v[236:239], v[70:73]
	s_setprio 0
	s_barrier
	s_add_i32 s23, s23, s27
	s_mov_b32 m0, s23
	ds_read_b128 v[178:181], v186 offset:16384
	ds_read_b128 v[188:191], v186 offset:17408
	ds_read_b128 v[192:195], v186 offset:18432
	ds_read_b128 v[206:209], v186 offset:19456
	ds_read_b128 v[224:227], v186 offset:20480
	ds_read_b128 v[228:231], v186 offset:21504
	ds_read_b128 v[232:235], v186 offset:22528
	ds_read_b128 v[236:239], v186 offset:23552
	global_load_lds_dwordx4 v152, s[6:7]
	s_add_i32 m0, s23, 0x2000
	s_add_u32 s24, s6, 0x80000
	s_addc_u32 s25, s7, 0
	s_add_i32 s23, s52, s27
	global_load_lds_dwordx4 v156, s[6:7]
	s_mov_b32 m0, s23
	s_nop 0
	global_load_lds_dwordx4 v152, s[24:25]
	s_add_i32 m0, s23, 0x2000
	s_nop 0
	global_load_lds_dwordx4 v156, s[24:25]
	s_cmp_eq_u32 s53, 0
	s_cbranch_scc1 .Lrw7
	s_waitcnt vmcnt(6)
.Lrw7:
	s_waitcnt vmcnt(6)
	s_waitcnt lgkmcnt(0)
	s_barrier
	s_setprio 1
	s_waitcnt lgkmcnt(0)
	v_mfma_f32_16x16x32_bf16 v[66:69], v[134:137], v[178:181], v[66:69]
	v_mfma_f32_16x16x32_bf16 v[62:65], v[142:145], v[178:181], v[62:65]
	v_mfma_f32_16x16x32_bf16 v[58:61], v[134:137], v[192:195], v[58:61]
	v_mfma_f32_16x16x32_bf16 v[54:57], v[142:145], v[192:195], v[54:57]
	v_mfma_f32_16x16x32_bf16 v[50:53], v[134:137], v[224:227], v[50:53]
	v_mfma_f32_16x16x32_bf16 v[46:49], v[142:145], v[224:227], v[46:49]
	v_mfma_f32_16x16x32_bf16 v[42:45], v[134:137], v[232:235], v[42:45]
	v_mfma_f32_16x16x32_bf16 v[38:41], v[142:145], v[232:235], v[38:41]
	v_mfma_f32_16x16x32_bf16 v[66:69], v[138:141], v[188:191], v[66:69]
	v_mfma_f32_16x16x32_bf16 v[62:65], v[146:149], v[188:191], v[62:65]
	v_mfma_f32_16x16x32_bf16 v[58:61], v[138:141], v[206:209], v[58:61]
	v_mfma_f32_16x16x32_bf16 v[54:57], v[146:149], v[206:209], v[54:57]
	v_mfma_f32_16x16x32_bf16 v[50:53], v[138:141], v[228:231], v[50:53]
	v_mfma_f32_16x16x32_bf16 v[46:49], v[146:149], v[228:231], v[46:49]
	v_mfma_f32_16x16x32_bf16 v[42:45], v[138:141], v[236:239], v[42:45]
	v_mfma_f32_16x16x32_bf16 v[38:41], v[146:149], v[236:239], v[38:41]
	v_mfma_f32_16x16x32_bf16 v[34:37], v[162:165], v[178:181], v[34:37]
	v_mfma_f32_16x16x32_bf16 v[30:33], v[170:173], v[178:181], v[30:33]
	v_mfma_f32_16x16x32_bf16 v[26:29], v[162:165], v[192:195], v[26:29]
	v_mfma_f32_16x16x32_bf16 v[22:25], v[170:173], v[192:195], v[22:25]
	v_mfma_f32_16x16x32_bf16 v[18:21], v[162:165], v[224:227], v[18:21]
	v_mfma_f32_16x16x32_bf16 v[14:17], v[170:173], v[224:227], v[14:17]
	v_mfma_f32_16x16x32_bf16 v[10:13], v[162:165], v[232:235], v[10:13]
	v_mfma_f32_16x16x32_bf16 v[4:7], v[170:173], v[232:235], v[6:9]
	v_mfma_f32_16x16x32_bf16 v[34:37], v[166:169], v[188:191], v[34:37]
	v_mfma_f32_16x16x32_bf16 v[30:33], v[174:177], v[188:191], v[30:33]
	v_mfma_f32_16x16x32_bf16 v[26:29], v[166:169], v[206:209], v[26:29]
	v_mfma_f32_16x16x32_bf16 v[22:25], v[174:177], v[206:209], v[22:25]
	v_mfma_f32_16x16x32_bf16 v[18:21], v[166:169], v[228:231], v[18:21]
	v_mfma_f32_16x16x32_bf16 v[14:17], v[174:177], v[228:231], v[14:17]
	v_mfma_f32_16x16x32_bf16 v[10:13], v[166:169], v[236:239], v[10:13]
	v_mfma_f32_16x16x32_bf16 v[4:7], v[174:177], v[236:239], v[4:7]
	s_setprio 0
	s_barrier
; #define PG8_STAGE(bufoff, gbase, voff) do { _Pragma("unroll") for (int _i = 0; _i < 2; ++_i) \
;         __builtin_amdgcn_global_load_lds((const unsigned*)((const char*)(gbase) + (voff)[_i]), (LAS unsigned*)(lds + (bufoff) + ldsw + _i * 8192), 16, 0, 0); } while (0)
; #define PG8_LDA(dst, b, h) do { _Pragma("unroll") for (int m = 0; m < 4; ++m) _Pragma("unroll") for (int k = 0; k < 2; ++k) dst[m][k] = *(const LAS bf16x8*)(lds + PG8_SA(b, h) + aoff + m * 2048 + k * 1024); } while (0)
; #define PG8_LDB(dst, b, h) do { _Pragma("unroll") for (int n = 0; n < 2; ++n) _Pragma("unroll") for (int k = 0; k < 2; ++k) dst[n][k] = *(const LAS bf16x8*)(lds + PG8_SB(b, h) + boff + n * 2048 + k * 1024); } while (0)
; #define PG8_MMA(ai, bj, At, Bt) do { __builtin_amdgcn_s_setprio(1); _Pragma("unroll") for (int m = 0; m < 4; ++m) _Pragma("unroll") for (int n = 0; n < 2; ++n) _Pragma("unroll") for (int k = 0; k < 2; ++k) \
;         acc[ai][bj][m][n] = __builtin_amdgcn_mfma_f32_16x16x32_bf16(Bt[n][k], At[m][k], acc[ai][bj][m][n], 0, 0, 0); __builtin_amdgcn_s_setprio(0); } while (0)
; #define PG8_WAIT_V(n) asm volatile("s_waitcnt vmcnt(" #n ")" ::: "memory")
; #define PG8_WAIT_L(n) asm volatile("s_waitcnt lgkmcnt(" #n ")" ::: "memory")
; #define PG8_BAR __builtin_amdgcn_s_barrier()
; #define PG8_SCHED __builtin_amdgcn_sched_barrier(0)
; template <class Epi, bool ALIGN_EPI = true>
; __device__ __forceinline__ void gemm_phase(LAS unsigned char* lds, const Gemm g, const Sched& S, const Epi& E) {
;     ...
;             PG8_LDB(B0, 1, 0); PG8_LDB(B1, 1, 1); PG8_SCHED; PG8_LDA(At, 1, 0); PG8_STAGE(PG8_SA(0, 1), a2 + hstepA, voffA);
;             PG8_WAIT_V(8); PG8_WAIT_L(0); PG8_BAR; PG8_MMA(0, 0, At, B0); PG8_MMA(0, 1, At, B1); PG8_BAR; PG8_SCHED;
;             PG8_LDA(At, 1, 1); PG8_STAGE(PG8_SB(1, 0), b3, voffB); PG8_STAGE(PG8_SB(1, 1), b3 + hstepB, voffB); PG8_STAGE(PG8_SA(1, 0), a3, voffA);
;             PG8_WAIT_V(8); PG8_WAIT_L(0); PG8_BAR; PG8_MMA(1, 0, At, B0); PG8_MMA(1, 1, At, B1); PG8_BAR; PG8_SCHED;
	s_add_i32 s23, 0, 0x18000
	v_add_u32_e32 v8, s23, v185
	s_add_i32 s24, 0, 0x1c000
	ds_read_b128 v[134:137], v8
	ds_read_b128 v[138:141], v8 offset:1024
	ds_read_b128 v[142:145], v8 offset:2048
	ds_read_b128 v[146:149], v8 offset:3072
	v_add_u32_e32 v8, s24, v185
	ds_read_b128 v[162:165], v8
	ds_read_b128 v[166:169], v8 offset:1024
	ds_read_b128 v[170:173], v8 offset:2048
	ds_read_b128 v[174:177], v8 offset:3072
	s_add_u32 s14, s14, 0x80000
	s_addc_u32 s15, s15, 0
	s_mov_b32 m0, s36
	ds_read_b128 v[178:181], v186 offset:32768
	ds_read_b128 v[188:191], v186 offset:33792
	ds_read_b128 v[192:195], v186 offset:34816
	ds_read_b128 v[206:209], v186 offset:35840
	ds_read_b128 v[224:227], v186 offset:36864
	ds_read_b128 v[228:231], v186 offset:37888
	ds_read_b128 v[232:235], v186 offset:38912
	ds_read_b128 v[236:239], v186 offset:39936
	s_add_u32 s100, s14, 0xfff80000
	s_addc_u32 s101, s15, -1
	s_mov_b32 m0, s50
	s_nop 0
	global_load_lds_dwordx4 v150, s[100:101]
	s_mov_b32 m0, s51
	s_nop 0
	global_load_lds_dwordx4 v154, s[100:101]
	s_mov_b32 m0, s36
	s_nop 0
	global_load_lds_dwordx4 v150, s[14:15]
	s_mov_b32 m0, s37
	s_nop 0
	global_load_lds_dwordx4 v154, s[14:15]
	s_waitcnt vmcnt(8)
	s_waitcnt lgkmcnt(0)
	s_barrier
	s_setprio 1
	s_waitcnt lgkmcnt(0)
	v_mfma_f32_16x16x32_bf16 v[130:133], v[134:137], v[178:181], v[130:133]
	v_mfma_f32_16x16x32_bf16 v[126:129], v[142:145], v[178:181], v[126:129]
	v_mfma_f32_16x16x32_bf16 v[122:125], v[134:137], v[192:195], v[122:125]
	v_mfma_f32_16x16x32_bf16 v[118:121], v[142:145], v[192:195], v[118:121]
	v_mfma_f32_16x16x32_bf16 v[114:117], v[134:137], v[224:227], v[114:117]
	v_mfma_f32_16x16x32_bf16 v[110:113], v[142:145], v[224:227], v[110:113]
	v_mfma_f32_16x16x32_bf16 v[106:109], v[134:137], v[232:235], v[106:109]
	v_mfma_f32_16x16x32_bf16 v[102:105], v[142:145], v[232:235], v[102:105]
	v_mfma_f32_16x16x32_bf16 v[130:133], v[138:141], v[188:191], v[130:133]
	v_mfma_f32_16x16x32_bf16 v[126:129], v[146:149], v[188:191], v[126:129]
	v_mfma_f32_16x16x32_bf16 v[122:125], v[138:141], v[206:209], v[122:125]
	v_mfma_f32_16x16x32_bf16 v[118:121], v[146:149], v[206:209], v[118:121]
	v_mfma_f32_16x16x32_bf16 v[114:117], v[138:141], v[228:231], v[114:117]
	v_mfma_f32_16x16x32_bf16 v[110:113], v[146:149], v[228:231], v[110:113]
	v_mfma_f32_16x16x32_bf16 v[106:109], v[138:141], v[236:239], v[106:109]
	v_mfma_f32_16x16x32_bf16 v[102:105], v[146:149], v[236:239], v[102:105]
	v_mfma_f32_16x16x32_bf16 v[98:101], v[162:165], v[178:181], v[98:101]
	v_mfma_f32_16x16x32_bf16 v[94:97], v[170:173], v[178:181], v[94:97]
	v_mfma_f32_16x16x32_bf16 v[90:93], v[162:165], v[192:195], v[90:93]
	v_mfma_f32_16x16x32_bf16 v[86:89], v[170:173], v[192:195], v[86:89]
	v_mfma_f32_16x16x32_bf16 v[82:85], v[162:165], v[224:227], v[82:85]
	v_mfma_f32_16x16x32_bf16 v[78:81], v[170:173], v[224:227], v[78:81]
	v_mfma_f32_16x16x32_bf16 v[74:77], v[162:165], v[232:235], v[74:77]
	v_mfma_f32_16x16x32_bf16 v[70:73], v[170:173], v[232:235], v[70:73]
	v_mfma_f32_16x16x32_bf16 v[98:101], v[166:169], v[188:191], v[98:101]
	v_mfma_f32_16x16x32_bf16 v[94:97], v[174:177], v[188:191], v[94:97]
	v_mfma_f32_16x16x32_bf16 v[90:93], v[166:169], v[206:209], v[90:93]
	v_mfma_f32_16x16x32_bf16 v[86:89], v[174:177], v[206:209], v[86:89]
	v_mfma_f32_16x16x32_bf16 v[82:85], v[166:169], v[228:231], v[82:85]
	v_mfma_f32_16x16x32_bf16 v[78:81], v[174:177], v[228:231], v[78:81]
	v_mfma_f32_16x16x32_bf16 v[74:77], v[166:169], v[236:239], v[74:77]
	v_mfma_f32_16x16x32_bf16 v[70:73], v[174:177], v[236:239], v[70:73]
	s_setprio 0
	s_barrier
	s_add_u32 s100, s6, 0x80
	s_addc_u32 s101, s7, 0
	s_add_i32 s14, s23, s27
	s_mov_b32 m0, s14
	ds_read_b128 v[178:181], v186 offset:49152
	ds_read_b128 v[188:191], v186 offset:50176
	ds_read_b128 v[192:195], v186 offset:51200
	ds_read_b128 v[206:209], v186 offset:52224
	ds_read_b128 v[224:227], v186 offset:53248
	ds_read_b128 v[228:231], v186 offset:54272
	ds_read_b128 v[232:235], v186 offset:55296
	ds_read_b128 v[236:239], v186 offset:56320
	global_load_lds_dwordx4 v152, s[100:101]
	s_add_i32 m0, s14, 0x2000
	s_add_u32 s6, s6, 0x80080
	s_addc_u32 s7, s7, 0
	s_add_i32 s14, s24, s27
	global_load_lds_dwordx4 v156, s[100:101]
	s_mov_b32 m0, s14
	s_nop 0
	global_load_lds_dwordx4 v152, s[6:7]
	s_add_i32 m0, s14, 0x2000
	s_nop 0
	global_load_lds_dwordx4 v156, s[6:7]
	s_waitcnt vmcnt(6)
	s_waitcnt lgkmcnt(0)
	s_barrier
	s_setprio 1
	s_waitcnt lgkmcnt(0)
	v_mfma_f32_16x16x32_bf16 v[66:69], v[134:137], v[178:181], v[66:69]
	v_mfma_f32_16x16x32_bf16 v[62:65], v[142:145], v[178:181], v[62:65]
	v_mfma_f32_16x16x32_bf16 v[58:61], v[134:137], v[192:195], v[58:61]
	v_mfma_f32_16x16x32_bf16 v[54:57], v[142:145], v[192:195], v[54:57]
	v_mfma_f32_16x16x32_bf16 v[50:53], v[134:137], v[224:227], v[50:53]
	v_mfma_f32_16x16x32_bf16 v[46:49], v[142:145], v[224:227], v[46:49]
	v_mfma_f32_16x16x32_bf16 v[42:45], v[134:137], v[232:235], v[42:45]
	v_mfma_f32_16x16x32_bf16 v[38:41], v[142:145], v[232:235], v[38:41]
	v_mfma_f32_16x16x32_bf16 v[66:69], v[138:141], v[188:191], v[66:69]
	v_mfma_f32_16x16x32_bf16 v[62:65], v[146:149], v[188:191], v[62:65]
	v_mfma_f32_16x16x32_bf16 v[58:61], v[138:141], v[206:209], v[58:61]
	v_mfma_f32_16x16x32_bf16 v[54:57], v[146:149], v[206:209], v[54:57]
	v_mfma_f32_16x16x32_bf16 v[50:53], v[138:141], v[228:231], v[50:53]
	v_mfma_f32_16x16x32_bf16 v[46:49], v[146:149], v[228:231], v[46:49]
	v_mfma_f32_16x16x32_bf16 v[42:45], v[138:141], v[236:239], v[42:45]
	v_mfma_f32_16x16x32_bf16 v[38:41], v[146:149], v[236:239], v[38:41]
	v_mfma_f32_16x16x32_bf16 v[34:37], v[162:165], v[178:181], v[34:37]
	v_mfma_f32_16x16x32_bf16 v[30:33], v[170:173], v[178:181], v[30:33]
	v_mfma_f32_16x16x32_bf16 v[26:29], v[162:165], v[192:195], v[26:29]
	v_mfma_f32_16x16x32_bf16 v[22:25], v[170:173], v[192:195], v[22:25]
	v_mfma_f32_16x16x32_bf16 v[18:21], v[162:165], v[224:227], v[18:21]
	v_mfma_f32_16x16x32_bf16 v[14:17], v[170:173], v[224:227], v[14:17]
	v_mfma_f32_16x16x32_bf16 v[8:11], v[162:165], v[232:235], v[10:13]
	v_mfma_f32_16x16x32_bf16 v[4:7], v[170:173], v[232:235], v[4:7]
	v_mfma_f32_16x16x32_bf16 v[34:37], v[166:169], v[188:191], v[34:37]
	v_mfma_f32_16x16x32_bf16 v[30:33], v[174:177], v[188:191], v[30:33]
	v_mfma_f32_16x16x32_bf16 v[26:29], v[166:169], v[206:209], v[26:29]
	v_mfma_f32_16x16x32_bf16 v[22:25], v[174:177], v[206:209], v[22:25]
	v_mfma_f32_16x16x32_bf16 v[18:21], v[166:169], v[228:231], v[18:21]
	v_mfma_f32_16x16x32_bf16 v[14:17], v[174:177], v[228:231], v[14:17]
	v_mfma_f32_16x16x32_bf16 v[10:13], v[166:169], v[236:239], v[8:11]
	v_mfma_f32_16x16x32_bf16 v[6:9], v[174:177], v[236:239], v[4:7]
	s_setprio 0
	s_barrier
	s_add_u32 s4, s4, 0x100
	s_addc_u32 s5, s5, 0
	s_add_u32 s20, s20, 0x100
	s_addc_u32 s21, s21, 0
	s_cmp_ge_i32 s22, s46
	s_mov_b32 s6, s22
	s_cbranch_scc0 .LBB0_500

; #define PG8_STAGE(bufoff, gbase, voff) do { _Pragma("unroll") for (int _i = 0; _i < 2; ++_i) \
;         __builtin_amdgcn_global_load_lds((const unsigned*)((const char*)(gbase) + (voff)[_i]), (LAS unsigned*)(lds + (bufoff) + ldsw + _i * 8192), 16, 0, 0); } while (0)
; #define PG8_LDA(dst, b, h) do { _Pragma("unroll") for (int m = 0; m < 4; ++m) _Pragma("unroll") for (int k = 0; k < 2; ++k) dst[m][k] = *(const LAS bf16x8*)(lds + PG8_SA(b, h) + aoff + m * 2048 + k * 1024); } while (0)
; #define PG8_LDB(dst, b, h) do { _Pragma("unroll") for (int n = 0; n < 2; ++n) _Pragma("unroll") for (int k = 0; k < 2; ++k) dst[n][k] = *(const LAS bf16x8*)(lds + PG8_SB(b, h) + boff + n * 2048 + k * 1024); } while (0)
; #define PG8_MMA(ai, bj, At, Bt) do { __builtin_amdgcn_s_setprio(1); _Pragma("unroll") for (int m = 0; m < 4; ++m) _Pragma("unroll") for (int n = 0; n < 2; ++n) _Pragma("unroll") for (int k = 0; k < 2; ++k) \
;         acc[ai][bj][m][n] = __builtin_amdgcn_mfma_f32_16x16x32_bf16(Bt[n][k], At[m][k], acc[ai][bj][m][n], 0, 0, 0); __builtin_amdgcn_s_setprio(0); } while (0)
; #define PG8_WAIT_V(n) asm volatile("s_waitcnt vmcnt(" #n ")" ::: "memory")
; #define PG8_WAIT_L(n) asm volatile("s_waitcnt lgkmcnt(" #n ")" ::: "memory")
; #define PG8_BAR __builtin_amdgcn_s_barrier()
; #define PG8_WAIT_RELAX(flag, n) asm volatile("s_cmp_eq_u32 %0, 0\n\ts_cbranch_scc1 .Lrw%=\n\ts_waitcnt vmcnt(8)\n.Lrw%=:\n\ts_waitcnt vmcnt(%1)" :: "s"(flag), "n"(n) : "scc", "memory")
; #define PG8_SCHED __builtin_amdgcn_sched_barrier(0)
; template <class Epi, bool ALIGN_EPI = true>
; __device__ __forceinline__ void gemm_phase(LAS unsigned char* lds, const Gemm g, const Sched& S, const Epi& E) {
;     ...
;             PG8_LDB(B0, 0, 0); PG8_LDB(B1, 0, 1); PG8_SCHED; PG8_LDA(At, 0, 0); PG8_STAGE(PG8_SA(1, 1), a1 + hstepA, voffA);
;             if constexpr (Epi::NSTORES > 0) PG8_WAIT_RELAX(rflag, 8 + Epi::NSTORES); else PG8_WAIT_V(8);
;             PG8_WAIT_L(0); PG8_BAR; PG8_MMA(0, 0, At, B0); PG8_MMA(0, 1, At, B1); PG8_BAR; PG8_SCHED;
;             PG8_LDA(At, 0, 1); PG8_STAGE(PG8_SB(0, 0), b2, voffB); PG8_STAGE(PG8_SB(0, 1), b2 + hstepB, voffB); PG8_STAGE(PG8_SA(0, 0), a2, voffA);
;             if constexpr (Epi::NSTORES > 0) PG8_WAIT_RELAX(rflag, 8 + Epi::NSTORES); else PG8_WAIT_V(8);
;             PG8_WAIT_L(0); PG8_BAR; PG8_MMA(1, 0, At, B0); PG8_MMA(1, 1, At, B1); PG8_BAR; PG8_SCHED;
.Lrw8:
	s_waitcnt vmcnt(24)
	s_waitcnt lgkmcnt(0)
	s_barrier
	s_setprio 1
	s_waitcnt lgkmcnt(0)
	v_mfma_f32_16x16x32_bf16 v[128:131], v[134:137], v[182:185], v[128:131]
	v_mfma_f32_16x16x32_bf16 v[124:127], v[142:145], v[182:185], v[124:127]
	v_mfma_f32_16x16x32_bf16 v[112:115], v[134:137], v[190:193], v[112:115]
	v_mfma_f32_16x16x32_bf16 v[108:111], v[142:145], v[190:193], v[108:111]
	v_mfma_f32_16x16x32_bf16 v[96:99], v[134:137], v[206:209], v[96:99]
	v_mfma_f32_16x16x32_bf16 v[92:95], v[142:145], v[206:209], v[92:95]
	v_mfma_f32_16x16x32_bf16 v[80:83], v[134:137], v[228:231], v[80:83]
	v_mfma_f32_16x16x32_bf16 v[76:79], v[142:145], v[228:231], v[76:79]
	v_mfma_f32_16x16x32_bf16 v[128:131], v[138:141], v[186:189], v[128:131]
	v_mfma_f32_16x16x32_bf16 v[124:127], v[158:161], v[186:189], v[124:127]
	v_mfma_f32_16x16x32_bf16 v[112:115], v[138:141], v[194:197], v[112:115]
	v_mfma_f32_16x16x32_bf16 v[108:111], v[158:161], v[194:197], v[108:111]
	v_mfma_f32_16x16x32_bf16 v[96:99], v[138:141], v[224:227], v[96:99]
	v_mfma_f32_16x16x32_bf16 v[92:95], v[158:161], v[224:227], v[92:95]
	v_mfma_f32_16x16x32_bf16 v[80:83], v[138:141], v[232:235], v[80:83]
	v_mfma_f32_16x16x32_bf16 v[76:79], v[158:161], v[232:235], v[76:79]
	v_mfma_f32_16x16x32_bf16 v[120:123], v[166:169], v[182:185], v[120:123]
	v_mfma_f32_16x16x32_bf16 v[116:119], v[174:177], v[182:185], v[116:119]
	v_mfma_f32_16x16x32_bf16 v[104:107], v[166:169], v[190:193], v[104:107]
	v_mfma_f32_16x16x32_bf16 v[100:103], v[174:177], v[190:193], v[100:103]
	v_mfma_f32_16x16x32_bf16 v[88:91], v[166:169], v[206:209], v[88:91]
	v_mfma_f32_16x16x32_bf16 v[84:87], v[174:177], v[206:209], v[84:87]
	v_mfma_f32_16x16x32_bf16 v[72:75], v[166:169], v[228:231], v[72:75]
	v_mfma_f32_16x16x32_bf16 v[68:71], v[174:177], v[228:231], v[68:71]
	v_mfma_f32_16x16x32_bf16 v[120:123], v[170:173], v[186:189], v[120:123]
	v_mfma_f32_16x16x32_bf16 v[116:119], v[178:181], v[186:189], v[116:119]
	v_mfma_f32_16x16x32_bf16 v[104:107], v[170:173], v[194:197], v[104:107]
	v_mfma_f32_16x16x32_bf16 v[100:103], v[178:181], v[194:197], v[100:103]
	v_mfma_f32_16x16x32_bf16 v[88:91], v[170:173], v[224:227], v[88:91]
	v_mfma_f32_16x16x32_bf16 v[84:87], v[178:181], v[224:227], v[84:87]
	v_mfma_f32_16x16x32_bf16 v[72:75], v[170:173], v[232:235], v[72:75]
	v_mfma_f32_16x16x32_bf16 v[68:71], v[178:181], v[232:235], v[68:71]
	s_setprio 0
	s_barrier
	s_add_i32 s70, s70, s35
	s_mov_b32 m0, s70
	ds_read_b128 v[182:185], v164 offset:16384
	ds_read_b128 v[186:189], v164 offset:17408
	ds_read_b128 v[190:193], v164 offset:18432
	ds_read_b128 v[194:197], v164 offset:19456
	ds_read_b128 v[206:209], v164 offset:20480
	ds_read_b128 v[224:227], v164 offset:21504
	ds_read_b128 v[228:231], v164 offset:22528
	ds_read_b128 v[232:235], v164 offset:23552
	global_load_lds_dwordx4 v2, s[26:27]
	s_add_i32 m0, s70, 0x2000
	s_add_u32 s70, s26, 0x10000
	s_addc_u32 s71, s27, 0
	s_add_i32 s72, s72, s35
	global_load_lds_dwordx4 v148, s[26:27]
	s_mov_b32 m0, s72
	s_nop 0
	global_load_lds_dwordx4 v2, s[70:71]
	s_add_i32 m0, s72, 0x2000
	s_nop 0
	global_load_lds_dwordx4 v148, s[70:71]
	s_cmp_eq_u32 s73, 0
	s_cbranch_scc1 .Lrw9
	s_waitcnt vmcnt(6)
.Lrw9:
	s_waitcnt vmcnt(6)
	s_waitcnt lgkmcnt(0)
	s_barrier
	s_setprio 1
	s_waitcnt lgkmcnt(0)
	v_mfma_f32_16x16x32_bf16 v[64:67], v[134:137], v[182:185], v[64:67]
	v_mfma_f32_16x16x32_bf16 v[60:63], v[142:145], v[182:185], v[60:63]
	v_mfma_f32_16x16x32_bf16 v[48:51], v[134:137], v[190:193], v[48:51]
	v_mfma_f32_16x16x32_bf16 v[44:47], v[142:145], v[190:193], v[44:47]
	v_mfma_f32_16x16x32_bf16 v[32:35], v[134:137], v[206:209], v[32:35]
	v_mfma_f32_16x16x32_bf16 v[28:31], v[142:145], v[206:209], v[28:31]
	v_mfma_f32_16x16x32_bf16 v[16:19], v[134:137], v[228:231], v[16:19]
	v_mfma_f32_16x16x32_bf16 v[12:15], v[142:145], v[228:231], v[12:15]
	v_mfma_f32_16x16x32_bf16 v[64:67], v[138:141], v[186:189], v[64:67]
	v_mfma_f32_16x16x32_bf16 v[60:63], v[158:161], v[186:189], v[60:63]
	v_mfma_f32_16x16x32_bf16 v[48:51], v[138:141], v[194:197], v[48:51]
	v_mfma_f32_16x16x32_bf16 v[44:47], v[158:161], v[194:197], v[44:47]
	v_mfma_f32_16x16x32_bf16 v[32:35], v[138:141], v[224:227], v[32:35]
	v_mfma_f32_16x16x32_bf16 v[28:31], v[158:161], v[224:227], v[28:31]
	v_mfma_f32_16x16x32_bf16 v[16:19], v[138:141], v[232:235], v[16:19]
	v_mfma_f32_16x16x32_bf16 v[12:15], v[158:161], v[232:235], v[12:15]
	v_mfma_f32_16x16x32_bf16 v[56:59], v[166:169], v[182:185], v[56:59]
	v_mfma_f32_16x16x32_bf16 v[52:55], v[174:177], v[182:185], v[52:55]
	v_mfma_f32_16x16x32_bf16 v[40:43], v[166:169], v[190:193], v[40:43]
	v_mfma_f32_16x16x32_bf16 v[36:39], v[174:177], v[190:193], v[36:39]
	v_mfma_f32_16x16x32_bf16 v[24:27], v[166:169], v[206:209], v[24:27]
	v_mfma_f32_16x16x32_bf16 v[20:23], v[174:177], v[206:209], v[20:23]
	v_mfma_f32_16x16x32_bf16 v[8:11], v[166:169], v[228:231], v[8:11]
	v_mfma_f32_16x16x32_bf16 v[4:7], v[174:177], v[228:231], v[4:7]
	v_mfma_f32_16x16x32_bf16 v[56:59], v[170:173], v[186:189], v[56:59]
	v_mfma_f32_16x16x32_bf16 v[52:55], v[178:181], v[186:189], v[52:55]
	v_mfma_f32_16x16x32_bf16 v[40:43], v[170:173], v[194:197], v[40:43]
	v_mfma_f32_16x16x32_bf16 v[36:39], v[178:181], v[194:197], v[36:39]
	v_mfma_f32_16x16x32_bf16 v[24:27], v[170:173], v[224:227], v[24:27]
	v_mfma_f32_16x16x32_bf16 v[20:23], v[178:181], v[224:227], v[20:23]
	v_mfma_f32_16x16x32_bf16 v[8:11], v[170:173], v[232:235], v[8:11]
	v_mfma_f32_16x16x32_bf16 v[4:7], v[178:181], v[232:235], v[4:7]
	s_setprio 0
	s_barrier
; #define PG8_STAGE(bufoff, gbase, voff) do { _Pragma("unroll") for (int _i = 0; _i < 2; ++_i) \
;         __builtin_amdgcn_global_load_lds((const unsigned*)((const char*)(gbase) + (voff)[_i]), (LAS unsigned*)(lds + (bufoff) + ldsw + _i * 8192), 16, 0, 0); } while (0)
; #define PG8_LDA(dst, b, h) do { _Pragma("unroll") for (int m = 0; m < 4; ++m) _Pragma("unroll") for (int k = 0; k < 2; ++k) dst[m][k] = *(const LAS bf16x8*)(lds + PG8_SA(b, h) + aoff + m * 2048 + k * 1024); } while (0)
; #define PG8_LDB(dst, b, h) do { _Pragma("unroll") for (int n = 0; n < 2; ++n) _Pragma("unroll") for (int k = 0; k < 2; ++k) dst[n][k] = *(const LAS bf16x8*)(lds + PG8_SB(b, h) + boff + n * 2048 + k * 1024); } while (0)
; #define PG8_MMA(ai, bj, At, Bt) do { __builtin_amdgcn_s_setprio(1); _Pragma("unroll") for (int m = 0; m < 4; ++m) _Pragma("unroll") for (int n = 0; n < 2; ++n) _Pragma("unroll") for (int k = 0; k < 2; ++k) \
;         acc[ai][bj][m][n] = __builtin_amdgcn_mfma_f32_16x16x32_bf16(Bt[n][k], At[m][k], acc[ai][bj][m][n], 0, 0, 0); __builtin_amdgcn_s_setprio(0); } while (0)
; #define PG8_WAIT_V(n) asm volatile("s_waitcnt vmcnt(" #n ")" ::: "memory")
; #define PG8_WAIT_L(n) asm volatile("s_waitcnt lgkmcnt(" #n ")" ::: "memory")
; #define PG8_BAR __builtin_amdgcn_s_barrier()
; #define PG8_SCHED __builtin_amdgcn_sched_barrier(0)
; template <class Epi, bool ALIGN_EPI = true>
; __device__ __forceinline__ void gemm_phase(LAS unsigned char* lds, const Gemm g, const Sched& S, const Epi& E) {
;     ...
;             PG8_LDB(B0, 1, 0); PG8_LDB(B1, 1, 1); PG8_SCHED; PG8_LDA(At, 1, 0); PG8_STAGE(PG8_SA(0, 1), a2 + hstepA, voffA);
;             PG8_WAIT_V(8); PG8_WAIT_L(0); PG8_BAR; PG8_MMA(0, 0, At, B0); PG8_MMA(0, 1, At, B1); PG8_BAR; PG8_SCHED;
;             PG8_LDA(At, 1, 1); PG8_STAGE(PG8_SB(1, 0), b3, voffB); PG8_STAGE(PG8_SB(1, 1), b3 + hstepB, voffB); PG8_STAGE(PG8_SA(1, 0), a3, voffA);
;             PG8_WAIT_V(8); PG8_WAIT_L(0); PG8_BAR; PG8_MMA(1, 0, At, B0); PG8_MMA(1, 1, At, B1); PG8_BAR; PG8_SCHED;
	s_add_i32 s70, 0, 0x18000
	v_add_u32_e32 v133, s70, v163
	s_add_i32 s71, 0, 0x1c000
	ds_read_b128 v[134:137], v133
	ds_read_b128 v[138:141], v133 offset:1024
	ds_read_b128 v[142:145], v133 offset:2048
	ds_read_b128 v[158:161], v133 offset:3072
	v_add_u32_e32 v133, s71, v163
	ds_read_b128 v[166:169], v133
	ds_read_b128 v[170:173], v133 offset:1024
	ds_read_b128 v[174:177], v133 offset:2048
	ds_read_b128 v[178:181], v133 offset:3072
	s_add_u32 s48, s48, 0x40000
	s_addc_u32 s49, s49, 0
	s_mov_b32 m0, s50
	ds_read_b128 v[182:185], v164 offset:32768
	ds_read_b128 v[186:189], v164 offset:33792
	ds_read_b128 v[190:193], v164 offset:34816
	ds_read_b128 v[194:197], v164 offset:35840
	ds_read_b128 v[206:209], v164 offset:36864
	ds_read_b128 v[224:227], v164 offset:37888
	ds_read_b128 v[228:231], v164 offset:38912
	ds_read_b128 v[232:235], v164 offset:39936
	s_add_u32 s100, s48, 0xfffc0000
	s_addc_u32 s101, s49, -1
	s_mov_b32 m0, s36
	s_nop 0
	global_load_lds_dwordx4 v152, s[100:101]
	s_mov_b32 m0, s37
	s_nop 0
	global_load_lds_dwordx4 v150, s[100:101]
	s_mov_b32 m0, s50
	s_nop 0
	global_load_lds_dwordx4 v152, s[48:49]
	s_mov_b32 m0, s51
	s_nop 0
	global_load_lds_dwordx4 v150, s[48:49]
	s_waitcnt vmcnt(8)
	s_waitcnt lgkmcnt(0)
	s_barrier
	s_setprio 1
	s_waitcnt lgkmcnt(0)
	v_mfma_f32_16x16x32_bf16 v[128:131], v[134:137], v[182:185], v[128:131]
	v_mfma_f32_16x16x32_bf16 v[124:127], v[142:145], v[182:185], v[124:127]
	v_mfma_f32_16x16x32_bf16 v[112:115], v[134:137], v[190:193], v[112:115]
	v_mfma_f32_16x16x32_bf16 v[108:111], v[142:145], v[190:193], v[108:111]
	v_mfma_f32_16x16x32_bf16 v[96:99], v[134:137], v[206:209], v[96:99]
	v_mfma_f32_16x16x32_bf16 v[92:95], v[142:145], v[206:209], v[92:95]
	v_mfma_f32_16x16x32_bf16 v[80:83], v[134:137], v[228:231], v[80:83]
	v_mfma_f32_16x16x32_bf16 v[76:79], v[142:145], v[228:231], v[76:79]
	v_mfma_f32_16x16x32_bf16 v[128:131], v[138:141], v[186:189], v[128:131]
	v_mfma_f32_16x16x32_bf16 v[124:127], v[158:161], v[186:189], v[124:127]
	v_mfma_f32_16x16x32_bf16 v[112:115], v[138:141], v[194:197], v[112:115]
	v_mfma_f32_16x16x32_bf16 v[108:111], v[158:161], v[194:197], v[108:111]
	v_mfma_f32_16x16x32_bf16 v[96:99], v[138:141], v[224:227], v[96:99]
	v_mfma_f32_16x16x32_bf16 v[92:95], v[158:161], v[224:227], v[92:95]
	v_mfma_f32_16x16x32_bf16 v[80:83], v[138:141], v[232:235], v[80:83]
	v_mfma_f32_16x16x32_bf16 v[76:79], v[158:161], v[232:235], v[76:79]
	v_mfma_f32_16x16x32_bf16 v[120:123], v[166:169], v[182:185], v[120:123]
	v_mfma_f32_16x16x32_bf16 v[116:119], v[174:177], v[182:185], v[116:119]
	v_mfma_f32_16x16x32_bf16 v[104:107], v[166:169], v[190:193], v[104:107]
	v_mfma_f32_16x16x32_bf16 v[100:103], v[174:177], v[190:193], v[100:103]
	v_mfma_f32_16x16x32_bf16 v[88:91], v[166:169], v[206:209], v[88:91]
	v_mfma_f32_16x16x32_bf16 v[84:87], v[174:177], v[206:209], v[84:87]
	v_mfma_f32_16x16x32_bf16 v[72:75], v[166:169], v[228:231], v[72:75]
	v_mfma_f32_16x16x32_bf16 v[68:71], v[174:177], v[228:231], v[68:71]
	v_mfma_f32_16x16x32_bf16 v[120:123], v[170:173], v[186:189], v[120:123]
	v_mfma_f32_16x16x32_bf16 v[116:119], v[178:181], v[186:189], v[116:119]
	v_mfma_f32_16x16x32_bf16 v[104:107], v[170:173], v[194:197], v[104:107]
	v_mfma_f32_16x16x32_bf16 v[100:103], v[178:181], v[194:197], v[100:103]
	v_mfma_f32_16x16x32_bf16 v[88:91], v[170:173], v[224:227], v[88:91]
	v_mfma_f32_16x16x32_bf16 v[84:87], v[178:181], v[224:227], v[84:87]
	v_mfma_f32_16x16x32_bf16 v[72:75], v[170:173], v[232:235], v[72:75]
	v_mfma_f32_16x16x32_bf16 v[68:71], v[178:181], v[232:235], v[68:71]
	s_setprio 0
	s_barrier
	s_add_u32 s100, s26, 0x80
	s_addc_u32 s101, s27, 0
	s_add_i32 s48, s70, s35
	s_mov_b32 m0, s48
	ds_read_b128 v[182:185], v164 offset:49152
	ds_read_b128 v[186:189], v164 offset:50176
	ds_read_b128 v[190:193], v164 offset:51200
	ds_read_b128 v[194:197], v164 offset:52224
	ds_read_b128 v[206:209], v164 offset:53248
	ds_read_b128 v[224:227], v164 offset:54272
	ds_read_b128 v[228:231], v164 offset:55296
	ds_read_b128 v[232:235], v164 offset:56320
	global_load_lds_dwordx4 v2, s[100:101]
	s_add_i32 m0, s48, 0x2000
	s_add_u32 s26, s26, 0x10080
	s_addc_u32 s27, s27, 0
	s_add_i32 s48, s71, s35
	global_load_lds_dwordx4 v148, s[100:101]
	s_mov_b32 m0, s48
	s_nop 0
	global_load_lds_dwordx4 v2, s[26:27]
	s_add_i32 m0, s48, 0x2000
	s_nop 0
	global_load_lds_dwordx4 v148, s[26:27]
	s_waitcnt vmcnt(6)
	s_waitcnt lgkmcnt(0)
	s_barrier
	s_setprio 1
	s_waitcnt lgkmcnt(0)
	v_mfma_f32_16x16x32_bf16 v[64:67], v[134:137], v[182:185], v[64:67]
	v_mfma_f32_16x16x32_bf16 v[60:63], v[142:145], v[182:185], v[60:63]
	v_mfma_f32_16x16x32_bf16 v[48:51], v[134:137], v[190:193], v[48:51]
	v_mfma_f32_16x16x32_bf16 v[44:47], v[142:145], v[190:193], v[44:47]
	v_mfma_f32_16x16x32_bf16 v[32:35], v[134:137], v[206:209], v[32:35]
	v_mfma_f32_16x16x32_bf16 v[28:31], v[142:145], v[206:209], v[28:31]
	v_mfma_f32_16x16x32_bf16 v[16:19], v[134:137], v[228:231], v[16:19]
	v_mfma_f32_16x16x32_bf16 v[12:15], v[142:145], v[228:231], v[12:15]
	v_mfma_f32_16x16x32_bf16 v[64:67], v[138:141], v[186:189], v[64:67]
	v_mfma_f32_16x16x32_bf16 v[60:63], v[158:161], v[186:189], v[60:63]
	v_mfma_f32_16x16x32_bf16 v[48:51], v[138:141], v[194:197], v[48:51]
	v_mfma_f32_16x16x32_bf16 v[44:47], v[158:161], v[194:197], v[44:47]
	v_mfma_f32_16x16x32_bf16 v[32:35], v[138:141], v[224:227], v[32:35]
	v_mfma_f32_16x16x32_bf16 v[28:31], v[158:161], v[224:227], v[28:31]
	v_mfma_f32_16x16x32_bf16 v[16:19], v[138:141], v[232:235], v[16:19]
	v_mfma_f32_16x16x32_bf16 v[12:15], v[158:161], v[232:235], v[12:15]
	v_mfma_f32_16x16x32_bf16 v[56:59], v[166:169], v[182:185], v[56:59]
	v_mfma_f32_16x16x32_bf16 v[52:55], v[174:177], v[182:185], v[52:55]
	v_mfma_f32_16x16x32_bf16 v[40:43], v[166:169], v[190:193], v[40:43]
	v_mfma_f32_16x16x32_bf16 v[36:39], v[174:177], v[190:193], v[36:39]
	v_mfma_f32_16x16x32_bf16 v[24:27], v[166:169], v[206:209], v[24:27]
	v_mfma_f32_16x16x32_bf16 v[20:23], v[174:177], v[206:209], v[20:23]
	v_mfma_f32_16x16x32_bf16 v[8:11], v[166:169], v[228:231], v[8:11]
	v_mfma_f32_16x16x32_bf16 v[4:7], v[174:177], v[228:231], v[4:7]
	v_mfma_f32_16x16x32_bf16 v[56:59], v[170:173], v[186:189], v[56:59]
	v_mfma_f32_16x16x32_bf16 v[52:55], v[178:181], v[186:189], v[52:55]
	v_mfma_f32_16x16x32_bf16 v[40:43], v[170:173], v[194:197], v[40:43]
	v_mfma_f32_16x16x32_bf16 v[36:39], v[178:181], v[194:197], v[36:39]
	v_mfma_f32_16x16x32_bf16 v[24:27], v[170:173], v[224:227], v[24:27]
	v_mfma_f32_16x16x32_bf16 v[20:23], v[178:181], v[224:227], v[20:23]
	v_mfma_f32_16x16x32_bf16 v[8:11], v[170:173], v[232:235], v[8:11]
	v_mfma_f32_16x16x32_bf16 v[4:7], v[178:181], v[232:235], v[4:7]
	s_setprio 0
	s_barrier
	s_add_u32 s40, s40, 0x100
	s_addc_u32 s41, s41, 0
	s_add_u32 s67, s67, 0x100
	s_addc_u32 s68, s68, 0
	s_cmp_ge_i32 s69, s54
	s_mov_b32 s48, s69
	s_cbranch_scc0 .LBB0_752

; #define PG8_STAGE(bufoff, gbase, voff) do { _Pragma("unroll") for (int _i = 0; _i < 2; ++_i) \
;         __builtin_amdgcn_global_load_lds((const unsigned*)((const char*)(gbase) + (voff)[_i]), (LAS unsigned*)(lds + (bufoff) + ldsw + _i * 8192), 16, 0, 0); } while (0)
; #define PG8_LDA(dst, b, h) do { _Pragma("unroll") for (int m = 0; m < 4; ++m) _Pragma("unroll") for (int k = 0; k < 2; ++k) dst[m][k] = *(const LAS bf16x8*)(lds + PG8_SA(b, h) + aoff + m * 2048 + k * 1024); } while (0)
; #define PG8_LDB(dst, b, h) do { _Pragma("unroll") for (int n = 0; n < 2; ++n) _Pragma("unroll") for (int k = 0; k < 2; ++k) dst[n][k] = *(const LAS bf16x8*)(lds + PG8_SB(b, h) + boff + n * 2048 + k * 1024); } while (0)
; #define PG8_MMA(ai, bj, At, Bt) do { __builtin_amdgcn_s_setprio(1); _Pragma("unroll") for (int m = 0; m < 4; ++m) _Pragma("unroll") for (int n = 0; n < 2; ++n) _Pragma("unroll") for (int k = 0; k < 2; ++k) \
;         acc[ai][bj][m][n] = __builtin_amdgcn_mfma_f32_16x16x32_bf16(Bt[n][k], At[m][k], acc[ai][bj][m][n], 0, 0, 0); __builtin_amdgcn_s_setprio(0); } while (0)
; #define PG8_WAIT_V(n) asm volatile("s_waitcnt vmcnt(" #n ")" ::: "memory")
; #define PG8_WAIT_L(n) asm volatile("s_waitcnt lgkmcnt(" #n ")" ::: "memory")
; #define PG8_BAR __builtin_amdgcn_s_barrier()
; #define PG8_WAIT_RELAX(flag, n) asm volatile("s_cmp_eq_u32 %0, 0\n\ts_cbranch_scc1 .Lrw%=\n\ts_waitcnt vmcnt(8)\n.Lrw%=:\n\ts_waitcnt vmcnt(%1)" :: "s"(flag), "n"(n) : "scc", "memory")
; #define PG8_SCHED __builtin_amdgcn_sched_barrier(0)
; template <class Epi, bool ALIGN_EPI = true>
; __device__ __forceinline__ void gemm_phase(LAS unsigned char* lds, const Gemm g, const Sched& S, const Epi& E) {
;     ...
;             PG8_LDB(B0, 0, 0); PG8_LDB(B1, 0, 1); PG8_SCHED; PG8_LDA(At, 0, 0); PG8_STAGE(PG8_SA(1, 1), a1 + hstepA, voffA);
;             if constexpr (Epi::NSTORES > 0) PG8_WAIT_RELAX(rflag, 8 + Epi::NSTORES); else PG8_WAIT_V(8);
;             PG8_WAIT_L(0); PG8_BAR; PG8_MMA(0, 0, At, B0); PG8_MMA(0, 1, At, B1); PG8_BAR; PG8_SCHED;
;             PG8_LDA(At, 0, 1); PG8_STAGE(PG8_SB(0, 0), b2, voffB); PG8_STAGE(PG8_SB(0, 1), b2 + hstepB, voffB); PG8_STAGE(PG8_SA(0, 0), a2, voffA);
;             if constexpr (Epi::NSTORES > 0) PG8_WAIT_RELAX(rflag, 8 + Epi::NSTORES); else PG8_WAIT_V(8);
;             PG8_WAIT_L(0); PG8_BAR; PG8_MMA(1, 0, At, B0); PG8_MMA(1, 1, At, B1); PG8_BAR; PG8_SCHED;
.Lrw10:
	s_waitcnt vmcnt(24)
	s_waitcnt lgkmcnt(0)
	s_barrier
	s_setprio 1
	s_waitcnt lgkmcnt(0)
	v_mfma_f32_16x16x32_bf16 v[128:131], v[134:137], v[182:185], v[128:131]
	v_mfma_f32_16x16x32_bf16 v[124:127], v[142:145], v[182:185], v[124:127]
	v_mfma_f32_16x16x32_bf16 v[112:115], v[134:137], v[190:193], v[112:115]
	v_mfma_f32_16x16x32_bf16 v[108:111], v[142:145], v[190:193], v[108:111]
	v_mfma_f32_16x16x32_bf16 v[96:99], v[134:137], v[206:209], v[96:99]
	v_mfma_f32_16x16x32_bf16 v[92:95], v[142:145], v[206:209], v[92:95]
	v_mfma_f32_16x16x32_bf16 v[80:83], v[134:137], v[228:231], v[80:83]
	v_mfma_f32_16x16x32_bf16 v[76:79], v[142:145], v[228:231], v[76:79]
	v_mfma_f32_16x16x32_bf16 v[128:131], v[138:141], v[186:189], v[128:131]
	v_mfma_f32_16x16x32_bf16 v[124:127], v[158:161], v[186:189], v[124:127]
	v_mfma_f32_16x16x32_bf16 v[112:115], v[138:141], v[194:197], v[112:115]
	v_mfma_f32_16x16x32_bf16 v[108:111], v[158:161], v[194:197], v[108:111]
	v_mfma_f32_16x16x32_bf16 v[96:99], v[138:141], v[224:227], v[96:99]
	v_mfma_f32_16x16x32_bf16 v[92:95], v[158:161], v[224:227], v[92:95]
	v_mfma_f32_16x16x32_bf16 v[80:83], v[138:141], v[232:235], v[80:83]
	v_mfma_f32_16x16x32_bf16 v[76:79], v[158:161], v[232:235], v[76:79]
	v_mfma_f32_16x16x32_bf16 v[120:123], v[166:169], v[182:185], v[120:123]
	v_mfma_f32_16x16x32_bf16 v[116:119], v[174:177], v[182:185], v[116:119]
	v_mfma_f32_16x16x32_bf16 v[104:107], v[166:169], v[190:193], v[104:107]
	v_mfma_f32_16x16x32_bf16 v[100:103], v[174:177], v[190:193], v[100:103]
	v_mfma_f32_16x16x32_bf16 v[88:91], v[166:169], v[206:209], v[88:91]
	v_mfma_f32_16x16x32_bf16 v[84:87], v[174:177], v[206:209], v[84:87]
	v_mfma_f32_16x16x32_bf16 v[72:75], v[166:169], v[228:231], v[72:75]
	v_mfma_f32_16x16x32_bf16 v[68:71], v[174:177], v[228:231], v[68:71]
	v_mfma_f32_16x16x32_bf16 v[120:123], v[170:173], v[186:189], v[120:123]
	v_mfma_f32_16x16x32_bf16 v[116:119], v[178:181], v[186:189], v[116:119]
	v_mfma_f32_16x16x32_bf16 v[104:107], v[170:173], v[194:197], v[104:107]
	v_mfma_f32_16x16x32_bf16 v[100:103], v[178:181], v[194:197], v[100:103]
	v_mfma_f32_16x16x32_bf16 v[88:91], v[170:173], v[224:227], v[88:91]
	v_mfma_f32_16x16x32_bf16 v[84:87], v[178:181], v[224:227], v[84:87]
	v_mfma_f32_16x16x32_bf16 v[72:75], v[170:173], v[232:235], v[72:75]
	v_mfma_f32_16x16x32_bf16 v[68:71], v[178:181], v[232:235], v[68:71]
	s_setprio 0
	s_barrier
	s_add_i32 s66, s66, s35
	s_mov_b32 m0, s66
	ds_read_b128 v[182:185], v164 offset:16384
	ds_read_b128 v[186:189], v164 offset:17408
	ds_read_b128 v[190:193], v164 offset:18432
	ds_read_b128 v[194:197], v164 offset:19456
	ds_read_b128 v[206:209], v164 offset:20480
	ds_read_b128 v[224:227], v164 offset:21504
	ds_read_b128 v[228:231], v164 offset:22528
	ds_read_b128 v[232:235], v164 offset:23552
	global_load_lds_dwordx4 v2, s[26:27]
	s_add_i32 m0, s66, 0x2000
	s_add_u32 s66, s26, 0x10000
	s_addc_u32 s67, s27, 0
	s_add_i32 s68, s68, s35
	global_load_lds_dwordx4 v148, s[26:27]
	s_mov_b32 m0, s68
	s_nop 0
	global_load_lds_dwordx4 v2, s[66:67]
	s_add_i32 m0, s68, 0x2000
	s_nop 0
	global_load_lds_dwordx4 v148, s[66:67]
	s_cmp_eq_u32 s69, 0
	s_cbranch_scc1 .Lrw11
	s_waitcnt vmcnt(6)
.Lrw11:
	s_waitcnt vmcnt(6)
	s_waitcnt lgkmcnt(0)
	s_barrier
	s_setprio 1
	s_waitcnt lgkmcnt(0)
	v_mfma_f32_16x16x32_bf16 v[64:67], v[134:137], v[182:185], v[64:67]
	v_mfma_f32_16x16x32_bf16 v[60:63], v[142:145], v[182:185], v[60:63]
	v_mfma_f32_16x16x32_bf16 v[48:51], v[134:137], v[190:193], v[48:51]
	v_mfma_f32_16x16x32_bf16 v[44:47], v[142:145], v[190:193], v[44:47]
	v_mfma_f32_16x16x32_bf16 v[32:35], v[134:137], v[206:209], v[32:35]
	v_mfma_f32_16x16x32_bf16 v[28:31], v[142:145], v[206:209], v[28:31]
	v_mfma_f32_16x16x32_bf16 v[16:19], v[134:137], v[228:231], v[16:19]
	v_mfma_f32_16x16x32_bf16 v[12:15], v[142:145], v[228:231], v[12:15]
	v_mfma_f32_16x16x32_bf16 v[64:67], v[138:141], v[186:189], v[64:67]
	v_mfma_f32_16x16x32_bf16 v[60:63], v[158:161], v[186:189], v[60:63]
	v_mfma_f32_16x16x32_bf16 v[48:51], v[138:141], v[194:197], v[48:51]
	v_mfma_f32_16x16x32_bf16 v[44:47], v[158:161], v[194:197], v[44:47]
	v_mfma_f32_16x16x32_bf16 v[32:35], v[138:141], v[224:227], v[32:35]
	v_mfma_f32_16x16x32_bf16 v[28:31], v[158:161], v[224:227], v[28:31]
	v_mfma_f32_16x16x32_bf16 v[16:19], v[138:141], v[232:235], v[16:19]
	v_mfma_f32_16x16x32_bf16 v[12:15], v[158:161], v[232:235], v[12:15]
	v_mfma_f32_16x16x32_bf16 v[56:59], v[166:169], v[182:185], v[56:59]
	v_mfma_f32_16x16x32_bf16 v[52:55], v[174:177], v[182:185], v[52:55]
	v_mfma_f32_16x16x32_bf16 v[40:43], v[166:169], v[190:193], v[40:43]
	v_mfma_f32_16x16x32_bf16 v[36:39], v[174:177], v[190:193], v[36:39]
	v_mfma_f32_16x16x32_bf16 v[24:27], v[166:169], v[206:209], v[24:27]
	v_mfma_f32_16x16x32_bf16 v[20:23], v[174:177], v[206:209], v[20:23]
	v_mfma_f32_16x16x32_bf16 v[8:11], v[166:169], v[228:231], v[8:11]
	v_mfma_f32_16x16x32_bf16 v[4:7], v[174:177], v[228:231], v[4:7]
	v_mfma_f32_16x16x32_bf16 v[56:59], v[170:173], v[186:189], v[56:59]
	v_mfma_f32_16x16x32_bf16 v[52:55], v[178:181], v[186:189], v[52:55]
	v_mfma_f32_16x16x32_bf16 v[40:43], v[170:173], v[194:197], v[40:43]
	v_mfma_f32_16x16x32_bf16 v[36:39], v[178:181], v[194:197], v[36:39]
	v_mfma_f32_16x16x32_bf16 v[24:27], v[170:173], v[224:227], v[24:27]
	v_mfma_f32_16x16x32_bf16 v[20:23], v[178:181], v[224:227], v[20:23]
	v_mfma_f32_16x16x32_bf16 v[8:11], v[170:173], v[232:235], v[8:11]
	v_mfma_f32_16x16x32_bf16 v[4:7], v[178:181], v[232:235], v[4:7]
	s_setprio 0
	s_barrier
; #define PG8_STAGE(bufoff, gbase, voff) do { _Pragma("unroll") for (int _i = 0; _i < 2; ++_i) \
;         __builtin_amdgcn_global_load_lds((const unsigned*)((const char*)(gbase) + (voff)[_i]), (LAS unsigned*)(lds + (bufoff) + ldsw + _i * 8192), 16, 0, 0); } while (0)
; #define PG8_LDA(dst, b, h) do { _Pragma("unroll") for (int m = 0; m < 4; ++m) _Pragma("unroll") for (int k = 0; k < 2; ++k) dst[m][k] = *(const LAS bf16x8*)(lds + PG8_SA(b, h) + aoff + m * 2048 + k * 1024); } while (0)
; #define PG8_LDB(dst, b, h) do { _Pragma("unroll") for (int n = 0; n < 2; ++n) _Pragma("unroll") for (int k = 0; k < 2; ++k) dst[n][k] = *(const LAS bf16x8*)(lds + PG8_SB(b, h) + boff + n * 2048 + k * 1024); } while (0)
; #define PG8_MMA(ai, bj, At, Bt) do { __builtin_amdgcn_s_setprio(1); _Pragma("unroll") for (int m = 0; m < 4; ++m) _Pragma("unroll") for (int n = 0; n < 2; ++n) _Pragma("unroll") for (int k = 0; k < 2; ++k) \
;         acc[ai][bj][m][n] = __builtin_amdgcn_mfma_f32_16x16x32_bf16(Bt[n][k], At[m][k], acc[ai][bj][m][n], 0, 0, 0); __builtin_amdgcn_s_setprio(0); } while (0)
; #define PG8_WAIT_V(n) asm volatile("s_waitcnt vmcnt(" #n ")" ::: "memory")
; #define PG8_WAIT_L(n) asm volatile("s_waitcnt lgkmcnt(" #n ")" ::: "memory")
; #define PG8_BAR __builtin_amdgcn_s_barrier()
; #define PG8_SCHED __builtin_amdgcn_sched_barrier(0)
; template <class Epi, bool ALIGN_EPI = true>
; __device__ __forceinline__ void gemm_phase(LAS unsigned char* lds, const Gemm g, const Sched& S, const Epi& E) {
;     ...
;             PG8_LDB(B0, 1, 0); PG8_LDB(B1, 1, 1); PG8_SCHED; PG8_LDA(At, 1, 0); PG8_STAGE(PG8_SA(0, 1), a2 + hstepA, voffA);
;             PG8_WAIT_V(8); PG8_WAIT_L(0); PG8_BAR; PG8_MMA(0, 0, At, B0); PG8_MMA(0, 1, At, B1); PG8_BAR; PG8_SCHED;
;             PG8_LDA(At, 1, 1); PG8_STAGE(PG8_SB(1, 0), b3, voffB); PG8_STAGE(PG8_SB(1, 1), b3 + hstepB, voffB); PG8_STAGE(PG8_SA(1, 0), a3, voffA);
;             PG8_WAIT_V(8); PG8_WAIT_L(0); PG8_BAR; PG8_MMA(1, 0, At, B0); PG8_MMA(1, 1, At, B1); PG8_BAR; PG8_SCHED;
	s_add_i32 s66, 0, 0x18000
	v_add_u32_e32 v133, s66, v163
	s_add_i32 s67, 0, 0x1c000
	ds_read_b128 v[134:137], v133
	ds_read_b128 v[138:141], v133 offset:1024
	ds_read_b128 v[142:145], v133 offset:2048
	ds_read_b128 v[158:161], v133 offset:3072
	v_add_u32_e32 v133, s67, v163
	ds_read_b128 v[166:169], v133
	ds_read_b128 v[170:173], v133 offset:1024
	ds_read_b128 v[174:177], v133 offset:2048
	ds_read_b128 v[178:181], v133 offset:3072
	s_add_u32 s46, s46, 0x40000
	s_addc_u32 s47, s47, 0
	s_mov_b32 m0, s48
	ds_read_b128 v[182:185], v164 offset:32768
	ds_read_b128 v[186:189], v164 offset:33792
	ds_read_b128 v[190:193], v164 offset:34816
	ds_read_b128 v[194:197], v164 offset:35840
	ds_read_b128 v[206:209], v164 offset:36864
	ds_read_b128 v[224:227], v164 offset:37888
	ds_read_b128 v[228:231], v164 offset:38912
	ds_read_b128 v[232:235], v164 offset:39936
	s_add_u32 s100, s46, 0xfffc0000
	s_addc_u32 s101, s47, -1
	s_mov_b32 m0, s36
	s_nop 0
	global_load_lds_dwordx4 v152, s[100:101]
	s_mov_b32 m0, s37
	s_nop 0
	global_load_lds_dwordx4 v150, s[100:101]
	s_mov_b32 m0, s48
	s_nop 0
	global_load_lds_dwordx4 v152, s[46:47]
	s_mov_b32 m0, s49
	s_nop 0
	global_load_lds_dwordx4 v150, s[46:47]
	s_waitcnt vmcnt(8)
	s_waitcnt lgkmcnt(0)
	s_barrier
	s_setprio 1
	s_waitcnt lgkmcnt(0)
	v_mfma_f32_16x16x32_bf16 v[128:131], v[134:137], v[182:185], v[128:131]
	v_mfma_f32_16x16x32_bf16 v[124:127], v[142:145], v[182:185], v[124:127]
	v_mfma_f32_16x16x32_bf16 v[112:115], v[134:137], v[190:193], v[112:115]
	v_mfma_f32_16x16x32_bf16 v[108:111], v[142:145], v[190:193], v[108:111]
	v_mfma_f32_16x16x32_bf16 v[96:99], v[134:137], v[206:209], v[96:99]
	v_mfma_f32_16x16x32_bf16 v[92:95], v[142:145], v[206:209], v[92:95]
	v_mfma_f32_16x16x32_bf16 v[80:83], v[134:137], v[228:231], v[80:83]
	v_mfma_f32_16x16x32_bf16 v[76:79], v[142:145], v[228:231], v[76:79]
	v_mfma_f32_16x16x32_bf16 v[128:131], v[138:141], v[186:189], v[128:131]
	v_mfma_f32_16x16x32_bf16 v[124:127], v[158:161], v[186:189], v[124:127]
	v_mfma_f32_16x16x32_bf16 v[112:115], v[138:141], v[194:197], v[112:115]
	v_mfma_f32_16x16x32_bf16 v[108:111], v[158:161], v[194:197], v[108:111]
	v_mfma_f32_16x16x32_bf16 v[96:99], v[138:141], v[224:227], v[96:99]
	v_mfma_f32_16x16x32_bf16 v[92:95], v[158:161], v[224:227], v[92:95]
	v_mfma_f32_16x16x32_bf16 v[80:83], v[138:141], v[232:235], v[80:83]
	v_mfma_f32_16x16x32_bf16 v[76:79], v[158:161], v[232:235], v[76:79]
	v_mfma_f32_16x16x32_bf16 v[120:123], v[166:169], v[182:185], v[120:123]
	v_mfma_f32_16x16x32_bf16 v[116:119], v[174:177], v[182:185], v[116:119]
	v_mfma_f32_16x16x32_bf16 v[104:107], v[166:169], v[190:193], v[104:107]
	v_mfma_f32_16x16x32_bf16 v[100:103], v[174:177], v[190:193], v[100:103]
	v_mfma_f32_16x16x32_bf16 v[88:91], v[166:169], v[206:209], v[88:91]
	v_mfma_f32_16x16x32_bf16 v[84:87], v[174:177], v[206:209], v[84:87]
	v_mfma_f32_16x16x32_bf16 v[72:75], v[166:169], v[228:231], v[72:75]
	v_mfma_f32_16x16x32_bf16 v[68:71], v[174:177], v[228:231], v[68:71]
	v_mfma_f32_16x16x32_bf16 v[120:123], v[170:173], v[186:189], v[120:123]
	v_mfma_f32_16x16x32_bf16 v[116:119], v[178:181], v[186:189], v[116:119]
	v_mfma_f32_16x16x32_bf16 v[104:107], v[170:173], v[194:197], v[104:107]
	v_mfma_f32_16x16x32_bf16 v[100:103], v[178:181], v[194:197], v[100:103]
	v_mfma_f32_16x16x32_bf16 v[88:91], v[170:173], v[224:227], v[88:91]
	v_mfma_f32_16x16x32_bf16 v[84:87], v[178:181], v[224:227], v[84:87]
	v_mfma_f32_16x16x32_bf16 v[72:75], v[170:173], v[232:235], v[72:75]
	v_mfma_f32_16x16x32_bf16 v[68:71], v[178:181], v[232:235], v[68:71]
	s_setprio 0
	s_barrier
	s_add_u32 s100, s26, 0x80
	s_addc_u32 s101, s27, 0
	s_add_i32 s46, s66, s35
	s_mov_b32 m0, s46
	ds_read_b128 v[182:185], v164 offset:49152
	ds_read_b128 v[186:189], v164 offset:50176
	ds_read_b128 v[190:193], v164 offset:51200
	ds_read_b128 v[194:197], v164 offset:52224
	ds_read_b128 v[206:209], v164 offset:53248
	ds_read_b128 v[224:227], v164 offset:54272
	ds_read_b128 v[228:231], v164 offset:55296
	ds_read_b128 v[232:235], v164 offset:56320
	global_load_lds_dwordx4 v2, s[100:101]
	s_add_i32 m0, s46, 0x2000
	s_add_u32 s26, s26, 0x10080
	s_addc_u32 s27, s27, 0
	s_add_i32 s46, s67, s35
	global_load_lds_dwordx4 v148, s[100:101]
	s_mov_b32 m0, s46
	s_nop 0
	global_load_lds_dwordx4 v2, s[26:27]
	s_add_i32 m0, s46, 0x2000
	s_nop 0
	global_load_lds_dwordx4 v148, s[26:27]
	s_waitcnt vmcnt(6)
	s_waitcnt lgkmcnt(0)
	s_barrier
	s_setprio 1
	s_waitcnt lgkmcnt(0)
	v_mfma_f32_16x16x32_bf16 v[64:67], v[134:137], v[182:185], v[64:67]
	v_mfma_f32_16x16x32_bf16 v[60:63], v[142:145], v[182:185], v[60:63]
	v_mfma_f32_16x16x32_bf16 v[48:51], v[134:137], v[190:193], v[48:51]
	v_mfma_f32_16x16x32_bf16 v[44:47], v[142:145], v[190:193], v[44:47]
	v_mfma_f32_16x16x32_bf16 v[32:35], v[134:137], v[206:209], v[32:35]
	v_mfma_f32_16x16x32_bf16 v[28:31], v[142:145], v[206:209], v[28:31]
	v_mfma_f32_16x16x32_bf16 v[16:19], v[134:137], v[228:231], v[16:19]
	v_mfma_f32_16x16x32_bf16 v[12:15], v[142:145], v[228:231], v[12:15]
	v_mfma_f32_16x16x32_bf16 v[64:67], v[138:141], v[186:189], v[64:67]
	v_mfma_f32_16x16x32_bf16 v[60:63], v[158:161], v[186:189], v[60:63]
	v_mfma_f32_16x16x32_bf16 v[48:51], v[138:141], v[194:197], v[48:51]
	v_mfma_f32_16x16x32_bf16 v[44:47], v[158:161], v[194:197], v[44:47]
	v_mfma_f32_16x16x32_bf16 v[32:35], v[138:141], v[224:227], v[32:35]
	v_mfma_f32_16x16x32_bf16 v[28:31], v[158:161], v[224:227], v[28:31]
	v_mfma_f32_16x16x32_bf16 v[16:19], v[138:141], v[232:235], v[16:19]
	v_mfma_f32_16x16x32_bf16 v[12:15], v[158:161], v[232:235], v[12:15]
	v_mfma_f32_16x16x32_bf16 v[56:59], v[166:169], v[182:185], v[56:59]
	v_mfma_f32_16x16x32_bf16 v[52:55], v[174:177], v[182:185], v[52:55]
	v_mfma_f32_16x16x32_bf16 v[40:43], v[166:169], v[190:193], v[40:43]
	v_mfma_f32_16x16x32_bf16 v[36:39], v[174:177], v[190:193], v[36:39]
	v_mfma_f32_16x16x32_bf16 v[24:27], v[166:169], v[206:209], v[24:27]
	v_mfma_f32_16x16x32_bf16 v[20:23], v[174:177], v[206:209], v[20:23]
	v_mfma_f32_16x16x32_bf16 v[8:11], v[166:169], v[228:231], v[8:11]
	v_mfma_f32_16x16x32_bf16 v[4:7], v[174:177], v[228:231], v[4:7]
	v_mfma_f32_16x16x32_bf16 v[56:59], v[170:173], v[186:189], v[56:59]
	v_mfma_f32_16x16x32_bf16 v[52:55], v[178:181], v[186:189], v[52:55]
	v_mfma_f32_16x16x32_bf16 v[40:43], v[170:173], v[194:197], v[40:43]
	v_mfma_f32_16x16x32_bf16 v[36:39], v[178:181], v[194:197], v[36:39]
	v_mfma_f32_16x16x32_bf16 v[24:27], v[170:173], v[224:227], v[24:27]
	v_mfma_f32_16x16x32_bf16 v[20:23], v[178:181], v[224:227], v[20:23]
	v_mfma_f32_16x16x32_bf16 v[8:11], v[170:173], v[232:235], v[8:11]
	v_mfma_f32_16x16x32_bf16 v[4:7], v[178:181], v[232:235], v[4:7]
	s_setprio 0
	s_barrier
	s_add_u32 s40, s40, 0x100
	s_addc_u32 s41, s41, 0
	s_add_u32 s63, s63, 0x100
	s_addc_u32 s64, s64, 0
	s_cmp_ge_i32 s65, s52
	s_mov_b32 s46, s65
	s_cbranch_scc0 .LBB0_919

; #define PG8_STAGE(bufoff, gbase, voff) do { _Pragma("unroll") for (int _i = 0; _i < 2; ++_i) \
;         __builtin_amdgcn_global_load_lds((const unsigned*)((const char*)(gbase) + (voff)[_i]), (LAS unsigned*)(lds + (bufoff) + ldsw + _i * 8192), 16, 0, 0); } while (0)
; #define PG8_LDA(dst, b, h) do { _Pragma("unroll") for (int m = 0; m < 4; ++m) _Pragma("unroll") for (int k = 0; k < 2; ++k) dst[m][k] = *(const LAS bf16x8*)(lds + PG8_SA(b, h) + aoff + m * 2048 + k * 1024); } while (0)
; #define PG8_LDB(dst, b, h) do { _Pragma("unroll") for (int n = 0; n < 2; ++n) _Pragma("unroll") for (int k = 0; k < 2; ++k) dst[n][k] = *(const LAS bf16x8*)(lds + PG8_SB(b, h) + boff + n * 2048 + k * 1024); } while (0)
; #define PG8_MMA(ai, bj, At, Bt) do { __builtin_amdgcn_s_setprio(1); _Pragma("unroll") for (int m = 0; m < 4; ++m) _Pragma("unroll") for (int n = 0; n < 2; ++n) _Pragma("unroll") for (int k = 0; k < 2; ++k) \
;         acc[ai][bj][m][n] = __builtin_amdgcn_mfma_f32_16x16x32_bf16(Bt[n][k], At[m][k], acc[ai][bj][m][n], 0, 0, 0); __builtin_amdgcn_s_setprio(0); } while (0)
; #define PG8_WAIT_V(n) asm volatile("s_waitcnt vmcnt(" #n ")" ::: "memory")
; #define PG8_WAIT_L(n) asm volatile("s_waitcnt lgkmcnt(" #n ")" ::: "memory")
; #define PG8_BAR __builtin_amdgcn_s_barrier()
; #define PG8_WAIT_RELAX(flag, n) asm volatile("s_cmp_eq_u32 %0, 0\n\ts_cbranch_scc1 .Lrw%=\n\ts_waitcnt vmcnt(8)\n.Lrw%=:\n\ts_waitcnt vmcnt(%1)" :: "s"(flag), "n"(n) : "scc", "memory")
; #define PG8_SCHED __builtin_amdgcn_sched_barrier(0)
; template <class Epi, bool ALIGN_EPI = true>
; __device__ __forceinline__ void gemm_phase(LAS unsigned char* lds, const Gemm g, const Sched& S, const Epi& E) {
;     ...
;             PG8_LDB(B0, 0, 0); PG8_LDB(B1, 0, 1); PG8_SCHED; PG8_LDA(At, 0, 0); PG8_STAGE(PG8_SA(1, 1), a1 + hstepA, voffA);
;             if constexpr (Epi::NSTORES > 0) PG8_WAIT_RELAX(rflag, 8 + Epi::NSTORES); else PG8_WAIT_V(8);
;             PG8_WAIT_L(0); PG8_BAR; PG8_MMA(0, 0, At, B0); PG8_MMA(0, 1, At, B1); PG8_BAR; PG8_SCHED;
;             PG8_LDA(At, 0, 1); PG8_STAGE(PG8_SB(0, 0), b2, voffB); PG8_STAGE(PG8_SB(0, 1), b2 + hstepB, voffB); PG8_STAGE(PG8_SA(0, 0), a2, voffA);
;             if constexpr (Epi::NSTORES > 0) PG8_WAIT_RELAX(rflag, 8 + Epi::NSTORES); else PG8_WAIT_V(8);
;             PG8_WAIT_L(0); PG8_BAR; PG8_MMA(1, 0, At, B0); PG8_MMA(1, 1, At, B1); PG8_BAR; PG8_SCHED;
.Lrw12:
	s_waitcnt vmcnt(24)
	s_waitcnt lgkmcnt(0)
	s_barrier
	s_setprio 1
	s_waitcnt lgkmcnt(0)
	v_mfma_f32_16x16x32_bf16 v[130:133], v[134:137], v[178:181], v[130:133]
	v_mfma_f32_16x16x32_bf16 v[126:129], v[142:145], v[178:181], v[126:129]
	v_mfma_f32_16x16x32_bf16 v[122:125], v[134:137], v[192:195], v[122:125]
	v_mfma_f32_16x16x32_bf16 v[118:121], v[142:145], v[192:195], v[118:121]
	v_mfma_f32_16x16x32_bf16 v[114:117], v[134:137], v[224:227], v[114:117]
	v_mfma_f32_16x16x32_bf16 v[110:113], v[142:145], v[224:227], v[110:113]
	v_mfma_f32_16x16x32_bf16 v[106:109], v[134:137], v[232:235], v[106:109]
	v_mfma_f32_16x16x32_bf16 v[102:105], v[142:145], v[232:235], v[102:105]
	v_mfma_f32_16x16x32_bf16 v[130:133], v[138:141], v[188:191], v[130:133]
	v_mfma_f32_16x16x32_bf16 v[126:129], v[146:149], v[188:191], v[126:129]
	v_mfma_f32_16x16x32_bf16 v[122:125], v[138:141], v[206:209], v[122:125]
	v_mfma_f32_16x16x32_bf16 v[118:121], v[146:149], v[206:209], v[118:121]
	v_mfma_f32_16x16x32_bf16 v[114:117], v[138:141], v[228:231], v[114:117]
	v_mfma_f32_16x16x32_bf16 v[110:113], v[146:149], v[228:231], v[110:113]
	v_mfma_f32_16x16x32_bf16 v[106:109], v[138:141], v[236:239], v[106:109]
	v_mfma_f32_16x16x32_bf16 v[102:105], v[146:149], v[236:239], v[102:105]
	v_mfma_f32_16x16x32_bf16 v[98:101], v[162:165], v[178:181], v[98:101]
	v_mfma_f32_16x16x32_bf16 v[94:97], v[170:173], v[178:181], v[94:97]
	v_mfma_f32_16x16x32_bf16 v[90:93], v[162:165], v[192:195], v[90:93]
	v_mfma_f32_16x16x32_bf16 v[86:89], v[170:173], v[192:195], v[86:89]
	v_mfma_f32_16x16x32_bf16 v[82:85], v[162:165], v[224:227], v[82:85]
	v_mfma_f32_16x16x32_bf16 v[78:81], v[170:173], v[224:227], v[78:81]
	v_mfma_f32_16x16x32_bf16 v[74:77], v[162:165], v[232:235], v[74:77]
	v_mfma_f32_16x16x32_bf16 v[70:73], v[170:173], v[232:235], v[70:73]
	v_mfma_f32_16x16x32_bf16 v[98:101], v[166:169], v[188:191], v[98:101]
	v_mfma_f32_16x16x32_bf16 v[94:97], v[174:177], v[188:191], v[94:97]
	v_mfma_f32_16x16x32_bf16 v[90:93], v[166:169], v[206:209], v[90:93]
	v_mfma_f32_16x16x32_bf16 v[86:89], v[174:177], v[206:209], v[86:89]
	v_mfma_f32_16x16x32_bf16 v[82:85], v[166:169], v[228:231], v[82:85]
	v_mfma_f32_16x16x32_bf16 v[78:81], v[174:177], v[228:231], v[78:81]
	v_mfma_f32_16x16x32_bf16 v[74:77], v[166:169], v[236:239], v[74:77]
	v_mfma_f32_16x16x32_bf16 v[70:73], v[174:177], v[236:239], v[70:73]
	s_setprio 0
	s_barrier
	s_add_i32 s23, s23, s94
	s_mov_b32 m0, s23
	ds_read_b128 v[178:181], v186 offset:16384
	ds_read_b128 v[188:191], v186 offset:17408
	ds_read_b128 v[192:195], v186 offset:18432
	ds_read_b128 v[206:209], v186 offset:19456
	ds_read_b128 v[224:227], v186 offset:20480
	ds_read_b128 v[228:231], v186 offset:21504
	ds_read_b128 v[232:235], v186 offset:22528
	ds_read_b128 v[236:239], v186 offset:23552
	global_load_lds_dwordx4 v152, s[6:7]
	s_add_i32 m0, s23, 0x2000
	s_add_u32 s24, s6, 0x80000
	s_addc_u32 s25, s7, 0
	s_add_i32 s23, s58, s94
	global_load_lds_dwordx4 v156, s[6:7]
	s_mov_b32 m0, s23
	s_nop 0
	global_load_lds_dwordx4 v152, s[24:25]
	s_add_i32 m0, s23, 0x2000
	s_nop 0
	global_load_lds_dwordx4 v156, s[24:25]
	s_cmp_eq_u32 s59, 0
	s_cbranch_scc1 .Lrw13
	s_waitcnt vmcnt(6)
.Lrw13:
	s_waitcnt vmcnt(6)
	s_waitcnt lgkmcnt(0)
	s_barrier
	s_setprio 1
	s_waitcnt lgkmcnt(0)
	v_mfma_f32_16x16x32_bf16 v[66:69], v[134:137], v[178:181], v[66:69]
	v_mfma_f32_16x16x32_bf16 v[62:65], v[142:145], v[178:181], v[62:65]
	v_mfma_f32_16x16x32_bf16 v[58:61], v[134:137], v[192:195], v[58:61]
	v_mfma_f32_16x16x32_bf16 v[54:57], v[142:145], v[192:195], v[54:57]
	v_mfma_f32_16x16x32_bf16 v[50:53], v[134:137], v[224:227], v[50:53]
	v_mfma_f32_16x16x32_bf16 v[46:49], v[142:145], v[224:227], v[46:49]
	v_mfma_f32_16x16x32_bf16 v[42:45], v[134:137], v[232:235], v[42:45]
	v_mfma_f32_16x16x32_bf16 v[38:41], v[142:145], v[232:235], v[38:41]
	v_mfma_f32_16x16x32_bf16 v[66:69], v[138:141], v[188:191], v[66:69]
	v_mfma_f32_16x16x32_bf16 v[62:65], v[146:149], v[188:191], v[62:65]
	v_mfma_f32_16x16x32_bf16 v[58:61], v[138:141], v[206:209], v[58:61]
	v_mfma_f32_16x16x32_bf16 v[54:57], v[146:149], v[206:209], v[54:57]
	v_mfma_f32_16x16x32_bf16 v[50:53], v[138:141], v[228:231], v[50:53]
	v_mfma_f32_16x16x32_bf16 v[46:49], v[146:149], v[228:231], v[46:49]
	v_mfma_f32_16x16x32_bf16 v[42:45], v[138:141], v[236:239], v[42:45]
	v_mfma_f32_16x16x32_bf16 v[38:41], v[146:149], v[236:239], v[38:41]
	v_mfma_f32_16x16x32_bf16 v[34:37], v[162:165], v[178:181], v[34:37]
	v_mfma_f32_16x16x32_bf16 v[30:33], v[170:173], v[178:181], v[30:33]
	v_mfma_f32_16x16x32_bf16 v[26:29], v[162:165], v[192:195], v[26:29]
	v_mfma_f32_16x16x32_bf16 v[22:25], v[170:173], v[192:195], v[22:25]
	v_mfma_f32_16x16x32_bf16 v[18:21], v[162:165], v[224:227], v[18:21]
	v_mfma_f32_16x16x32_bf16 v[14:17], v[170:173], v[224:227], v[14:17]
	v_mfma_f32_16x16x32_bf16 v[10:13], v[162:165], v[232:235], v[10:13]
	v_mfma_f32_16x16x32_bf16 v[4:7], v[170:173], v[232:235], v[6:9]
	v_mfma_f32_16x16x32_bf16 v[34:37], v[166:169], v[188:191], v[34:37]
	v_mfma_f32_16x16x32_bf16 v[30:33], v[174:177], v[188:191], v[30:33]
	v_mfma_f32_16x16x32_bf16 v[26:29], v[166:169], v[206:209], v[26:29]
	v_mfma_f32_16x16x32_bf16 v[22:25], v[174:177], v[206:209], v[22:25]
	v_mfma_f32_16x16x32_bf16 v[18:21], v[166:169], v[228:231], v[18:21]
	v_mfma_f32_16x16x32_bf16 v[14:17], v[174:177], v[228:231], v[14:17]
	v_mfma_f32_16x16x32_bf16 v[10:13], v[166:169], v[236:239], v[10:13]
	v_mfma_f32_16x16x32_bf16 v[4:7], v[174:177], v[236:239], v[4:7]
	s_setprio 0
	s_barrier
; #define PG8_STAGE(bufoff, gbase, voff) do { _Pragma("unroll") for (int _i = 0; _i < 2; ++_i) \
;         __builtin_amdgcn_global_load_lds((const unsigned*)((const char*)(gbase) + (voff)[_i]), (LAS unsigned*)(lds + (bufoff) + ldsw + _i * 8192), 16, 0, 0); } while (0)
; #define PG8_LDA(dst, b, h) do { _Pragma("unroll") for (int m = 0; m < 4; ++m) _Pragma("unroll") for (int k = 0; k < 2; ++k) dst[m][k] = *(const LAS bf16x8*)(lds + PG8_SA(b, h) + aoff + m * 2048 + k * 1024); } while (0)
; #define PG8_LDB(dst, b, h) do { _Pragma("unroll") for (int n = 0; n < 2; ++n) _Pragma("unroll") for (int k = 0; k < 2; ++k) dst[n][k] = *(const LAS bf16x8*)(lds + PG8_SB(b, h) + boff + n * 2048 + k * 1024); } while (0)
; #define PG8_MMA(ai, bj, At, Bt) do { __builtin_amdgcn_s_setprio(1); _Pragma("unroll") for (int m = 0; m < 4; ++m) _Pragma("unroll") for (int n = 0; n < 2; ++n) _Pragma("unroll") for (int k = 0; k < 2; ++k) \
;         acc[ai][bj][m][n] = __builtin_amdgcn_mfma_f32_16x16x32_bf16(Bt[n][k], At[m][k], acc[ai][bj][m][n], 0, 0, 0); __builtin_amdgcn_s_setprio(0); } while (0)
; #define PG8_WAIT_V(n) asm volatile("s_waitcnt vmcnt(" #n ")" ::: "memory")
; #define PG8_WAIT_L(n) asm volatile("s_waitcnt lgkmcnt(" #n ")" ::: "memory")
; #define PG8_BAR __builtin_amdgcn_s_barrier()
; #define PG8_SCHED __builtin_amdgcn_sched_barrier(0)
; template <class Epi, bool ALIGN_EPI = true>
; __device__ __forceinline__ void gemm_phase(LAS unsigned char* lds, const Gemm g, const Sched& S, const Epi& E) {
;     ...
;             PG8_LDB(B0, 1, 0); PG8_LDB(B1, 1, 1); PG8_SCHED; PG8_LDA(At, 1, 0); PG8_STAGE(PG8_SA(0, 1), a2 + hstepA, voffA);
;             PG8_WAIT_V(8); PG8_WAIT_L(0); PG8_BAR; PG8_MMA(0, 0, At, B0); PG8_MMA(0, 1, At, B1); PG8_BAR; PG8_SCHED;
;             PG8_LDA(At, 1, 1); PG8_STAGE(PG8_SB(1, 0), b3, voffB); PG8_STAGE(PG8_SB(1, 1), b3 + hstepB, voffB); PG8_STAGE(PG8_SA(1, 0), a3, voffA);
;             PG8_WAIT_V(8); PG8_WAIT_L(0); PG8_BAR; PG8_MMA(1, 0, At, B0); PG8_MMA(1, 1, At, B1); PG8_BAR; PG8_SCHED;
	s_add_i32 s23, 0, 0x18000
	v_add_u32_e32 v8, s23, v185
	s_add_i32 s24, 0, 0x1c000
	ds_read_b128 v[134:137], v8
	ds_read_b128 v[138:141], v8 offset:1024
	ds_read_b128 v[142:145], v8 offset:2048
	ds_read_b128 v[146:149], v8 offset:3072
	v_add_u32_e32 v8, s24, v185
	ds_read_b128 v[162:165], v8
	ds_read_b128 v[166:169], v8 offset:1024
	ds_read_b128 v[170:173], v8 offset:2048
	ds_read_b128 v[174:177], v8 offset:3072
	s_add_u32 s14, s14, 0x80000
	s_addc_u32 s15, s15, 0
	s_mov_b32 m0, s46
	ds_read_b128 v[178:181], v186 offset:32768
	ds_read_b128 v[188:191], v186 offset:33792
	ds_read_b128 v[192:195], v186 offset:34816
	ds_read_b128 v[206:209], v186 offset:35840
	ds_read_b128 v[224:227], v186 offset:36864
	ds_read_b128 v[228:231], v186 offset:37888
	ds_read_b128 v[232:235], v186 offset:38912
	ds_read_b128 v[236:239], v186 offset:39936
	s_add_u32 s100, s14, 0xfff80000
	s_addc_u32 s101, s15, -1
	s_mov_b32 m0, s48
	s_nop 0
	global_load_lds_dwordx4 v150, s[100:101]
	s_mov_b32 m0, s49
	s_nop 0
	global_load_lds_dwordx4 v154, s[100:101]
	s_mov_b32 m0, s46
	s_nop 0
	global_load_lds_dwordx4 v150, s[14:15]
	s_mov_b32 m0, s47
	s_nop 0
	global_load_lds_dwordx4 v154, s[14:15]
	s_waitcnt vmcnt(8)
	s_waitcnt lgkmcnt(0)
	s_barrier
	s_setprio 1
	s_waitcnt lgkmcnt(0)
	v_mfma_f32_16x16x32_bf16 v[130:133], v[134:137], v[178:181], v[130:133]
	v_mfma_f32_16x16x32_bf16 v[126:129], v[142:145], v[178:181], v[126:129]
	v_mfma_f32_16x16x32_bf16 v[122:125], v[134:137], v[192:195], v[122:125]
	v_mfma_f32_16x16x32_bf16 v[118:121], v[142:145], v[192:195], v[118:121]
	v_mfma_f32_16x16x32_bf16 v[114:117], v[134:137], v[224:227], v[114:117]
	v_mfma_f32_16x16x32_bf16 v[110:113], v[142:145], v[224:227], v[110:113]
	v_mfma_f32_16x16x32_bf16 v[106:109], v[134:137], v[232:235], v[106:109]
	v_mfma_f32_16x16x32_bf16 v[102:105], v[142:145], v[232:235], v[102:105]
	v_mfma_f32_16x16x32_bf16 v[130:133], v[138:141], v[188:191], v[130:133]
	v_mfma_f32_16x16x32_bf16 v[126:129], v[146:149], v[188:191], v[126:129]
	v_mfma_f32_16x16x32_bf16 v[122:125], v[138:141], v[206:209], v[122:125]
	v_mfma_f32_16x16x32_bf16 v[118:121], v[146:149], v[206:209], v[118:121]
	v_mfma_f32_16x16x32_bf16 v[114:117], v[138:141], v[228:231], v[114:117]
	v_mfma_f32_16x16x32_bf16 v[110:113], v[146:149], v[228:231], v[110:113]
	v_mfma_f32_16x16x32_bf16 v[106:109], v[138:141], v[236:239], v[106:109]
	v_mfma_f32_16x16x32_bf16 v[102:105], v[146:149], v[236:239], v[102:105]
	v_mfma_f32_16x16x32_bf16 v[98:101], v[162:165], v[178:181], v[98:101]
	v_mfma_f32_16x16x32_bf16 v[94:97], v[170:173], v[178:181], v[94:97]
	v_mfma_f32_16x16x32_bf16 v[90:93], v[162:165], v[192:195], v[90:93]
	v_mfma_f32_16x16x32_bf16 v[86:89], v[170:173], v[192:195], v[86:89]
	v_mfma_f32_16x16x32_bf16 v[82:85], v[162:165], v[224:227], v[82:85]
	v_mfma_f32_16x16x32_bf16 v[78:81], v[170:173], v[224:227], v[78:81]
	v_mfma_f32_16x16x32_bf16 v[74:77], v[162:165], v[232:235], v[74:77]
	v_mfma_f32_16x16x32_bf16 v[70:73], v[170:173], v[232:235], v[70:73]
	v_mfma_f32_16x16x32_bf16 v[98:101], v[166:169], v[188:191], v[98:101]
	v_mfma_f32_16x16x32_bf16 v[94:97], v[174:177], v[188:191], v[94:97]
	v_mfma_f32_16x16x32_bf16 v[90:93], v[166:169], v[206:209], v[90:93]
	v_mfma_f32_16x16x32_bf16 v[86:89], v[174:177], v[206:209], v[86:89]
	v_mfma_f32_16x16x32_bf16 v[82:85], v[166:169], v[228:231], v[82:85]
	v_mfma_f32_16x16x32_bf16 v[78:81], v[174:177], v[228:231], v[78:81]
	v_mfma_f32_16x16x32_bf16 v[74:77], v[166:169], v[236:239], v[74:77]
	v_mfma_f32_16x16x32_bf16 v[70:73], v[174:177], v[236:239], v[70:73]
	s_setprio 0
	s_barrier
	s_add_u32 s100, s6, 0x80
	s_addc_u32 s101, s7, 0
	s_add_i32 s14, s23, s94
	s_mov_b32 m0, s14
	ds_read_b128 v[178:181], v186 offset:49152
	ds_read_b128 v[188:191], v186 offset:50176
	ds_read_b128 v[192:195], v186 offset:51200
	ds_read_b128 v[206:209], v186 offset:52224
	ds_read_b128 v[224:227], v186 offset:53248
	ds_read_b128 v[228:231], v186 offset:54272
	ds_read_b128 v[232:235], v186 offset:55296
	ds_read_b128 v[236:239], v186 offset:56320
	global_load_lds_dwordx4 v152, s[100:101]
	s_add_i32 m0, s14, 0x2000
	s_add_u32 s6, s6, 0x80080
	s_addc_u32 s7, s7, 0
	s_add_i32 s14, s24, s94
	global_load_lds_dwordx4 v156, s[100:101]
	s_mov_b32 m0, s14
	s_nop 0
	global_load_lds_dwordx4 v152, s[6:7]
	s_add_i32 m0, s14, 0x2000
	s_nop 0
	global_load_lds_dwordx4 v156, s[6:7]
	s_waitcnt vmcnt(6)
	s_waitcnt lgkmcnt(0)
	s_barrier
	s_setprio 1
	s_waitcnt lgkmcnt(0)
	v_mfma_f32_16x16x32_bf16 v[66:69], v[134:137], v[178:181], v[66:69]
	v_mfma_f32_16x16x32_bf16 v[62:65], v[142:145], v[178:181], v[62:65]
	v_mfma_f32_16x16x32_bf16 v[58:61], v[134:137], v[192:195], v[58:61]
	v_mfma_f32_16x16x32_bf16 v[54:57], v[142:145], v[192:195], v[54:57]
	v_mfma_f32_16x16x32_bf16 v[50:53], v[134:137], v[224:227], v[50:53]
	v_mfma_f32_16x16x32_bf16 v[46:49], v[142:145], v[224:227], v[46:49]
	v_mfma_f32_16x16x32_bf16 v[42:45], v[134:137], v[232:235], v[42:45]
	v_mfma_f32_16x16x32_bf16 v[38:41], v[142:145], v[232:235], v[38:41]
	v_mfma_f32_16x16x32_bf16 v[66:69], v[138:141], v[188:191], v[66:69]
	v_mfma_f32_16x16x32_bf16 v[62:65], v[146:149], v[188:191], v[62:65]
	v_mfma_f32_16x16x32_bf16 v[58:61], v[138:141], v[206:209], v[58:61]
	v_mfma_f32_16x16x32_bf16 v[54:57], v[146:149], v[206:209], v[54:57]
	v_mfma_f32_16x16x32_bf16 v[50:53], v[138:141], v[228:231], v[50:53]
	v_mfma_f32_16x16x32_bf16 v[46:49], v[146:149], v[228:231], v[46:49]
	v_mfma_f32_16x16x32_bf16 v[42:45], v[138:141], v[236:239], v[42:45]
	v_mfma_f32_16x16x32_bf16 v[38:41], v[146:149], v[236:239], v[38:41]
	v_mfma_f32_16x16x32_bf16 v[34:37], v[162:165], v[178:181], v[34:37]
	v_mfma_f32_16x16x32_bf16 v[30:33], v[170:173], v[178:181], v[30:33]
	v_mfma_f32_16x16x32_bf16 v[26:29], v[162:165], v[192:195], v[26:29]
	v_mfma_f32_16x16x32_bf16 v[22:25], v[170:173], v[192:195], v[22:25]
	v_mfma_f32_16x16x32_bf16 v[18:21], v[162:165], v[224:227], v[18:21]
	v_mfma_f32_16x16x32_bf16 v[14:17], v[170:173], v[224:227], v[14:17]
	v_mfma_f32_16x16x32_bf16 v[8:11], v[162:165], v[232:235], v[10:13]
	v_mfma_f32_16x16x32_bf16 v[4:7], v[170:173], v[232:235], v[4:7]
	v_mfma_f32_16x16x32_bf16 v[34:37], v[166:169], v[188:191], v[34:37]
	v_mfma_f32_16x16x32_bf16 v[30:33], v[174:177], v[188:191], v[30:33]
	v_mfma_f32_16x16x32_bf16 v[26:29], v[166:169], v[206:209], v[26:29]
	v_mfma_f32_16x16x32_bf16 v[22:25], v[174:177], v[206:209], v[22:25]
	v_mfma_f32_16x16x32_bf16 v[18:21], v[166:169], v[228:231], v[18:21]
	v_mfma_f32_16x16x32_bf16 v[14:17], v[174:177], v[228:231], v[14:17]
	v_mfma_f32_16x16x32_bf16 v[10:13], v[166:169], v[236:239], v[8:11]
	v_mfma_f32_16x16x32_bf16 v[6:9], v[174:177], v[236:239], v[4:7]
	s_setprio 0
	s_barrier
	s_add_u32 s4, s4, 0x100
	s_addc_u32 s5, s5, 0
	s_add_u32 s20, s20, 0x100
	s_addc_u32 s21, s21, 0
	s_cmp_ge_i32 s22, s31
	s_mov_b32 s6, s22
	s_cbranch_scc0 .LBB0_954

; #define PG8_STAGE(bufoff, gbase, voff) do { _Pragma("unroll") for (int _i = 0; _i < 2; ++_i) \
;         __builtin_amdgcn_global_load_lds((const unsigned*)((const char*)(gbase) + (voff)[_i]), (LAS unsigned*)(lds + (bufoff) + ldsw + _i * 8192), 16, 0, 0); } while (0)
; #define PG8_LDA(dst, b, h) do { _Pragma("unroll") for (int m = 0; m < 4; ++m) _Pragma("unroll") for (int k = 0; k < 2; ++k) dst[m][k] = *(const LAS bf16x8*)(lds + PG8_SA(b, h) + aoff + m * 2048 + k * 1024); } while (0)
; #define PG8_LDB(dst, b, h) do { _Pragma("unroll") for (int n = 0; n < 2; ++n) _Pragma("unroll") for (int k = 0; k < 2; ++k) dst[n][k] = *(const LAS bf16x8*)(lds + PG8_SB(b, h) + boff + n * 2048 + k * 1024); } while (0)
; #define PG8_MMA(ai, bj, At, Bt) do { __builtin_amdgcn_s_setprio(1); _Pragma("unroll") for (int m = 0; m < 4; ++m) _Pragma("unroll") for (int n = 0; n < 2; ++n) _Pragma("unroll") for (int k = 0; k < 2; ++k) \
;         acc[ai][bj][m][n] = __builtin_amdgcn_mfma_f32_16x16x32_bf16(Bt[n][k], At[m][k], acc[ai][bj][m][n], 0, 0, 0); __builtin_amdgcn_s_setprio(0); } while (0)
; template <class Epi, bool ALIGN_EPI = true>
; __device__ __forceinline__ void gemm_phase(LAS unsigned char* lds, const Gemm g, const Sched& S, const Epi& E) {
;     ...
;         for (int t = t_lo; t < t_hi; t += 2) {
;             const bool last = (t == nt - 2);
;             const char* a1 = cA + (size_t)(t + 1) * kstep;
;             const char* a2 = last ? nA : cA + (size_t)(t + 2) * kstep; const char* b2 = last ? nB : cB + (size_t)(t + 2) * kstep;
;             const char* a3 = a2 + kstep; const char* b3 = b2 + kstep;
;             const int rflag = __builtin_amdgcn_readfirstlane(t | (int)(ui == 0));
;             PG8_LDB(B0, 0, 0); PG8_LDB(B1, 0, 1); PG8_SCHED; PG8_LDA(At, 0, 0); PG8_STAGE(PG8_SA(1, 1), a1 + hstepA, voffA);
;             if constexpr (Epi::NSTORES > 0) PG8_WAIT_RELAX(rflag, 8 + Epi::NSTORES); else PG8_WAIT_V(8);
;             PG8_WAIT_L(0); PG8_BAR; PG8_MMA(0, 0, At, B0); PG8_MMA(0, 1, At, B1); PG8_BAR; PG8_SCHED;
;             PG8_LDA(At, 0, 1); PG8_STAGE(PG8_SB(0, 0), b2, voffB); PG8_STAGE(PG8_SB(0, 1), b2 + hstepB, voffB); PG8_STAGE(PG8_SA(0, 0), a2, voffA);
;             if constexpr (Epi::NSTORES > 0) PG8_WAIT_RELAX(rflag, 8 + Epi::NSTORES); else PG8_WAIT_V(8);
;             PG8_WAIT_L(0); PG8_BAR; PG8_MMA(1, 0, At, B0); PG8_MMA(1, 1, At, B1); PG8_BAR; PG8_SCHED;
.LBB0_1237:
	s_add_i32 s94, s24, 1
	s_lshl_b64 s[92:93], s[94:95], 7
	s_add_i32 s94, s24, 2
	s_lshl_b64 s[26:27], s[94:95], 7
	s_add_u32 s25, s56, s26
	s_addc_u32 s91, s57, s27
	s_add_u32 s96, s54, s26
	s_addc_u32 s97, s55, s27
	s_add_i32 vcc_lo, 0, 0x10000
	s_cmp_eq_u32 s85, s24
	s_cselect_b32 s27, s19, s91
	s_cselect_b32 s26, s87, s25
	v_add_u32_e32 v2, vcc_lo, v224
	s_cselect_b32 s25, s88, s97
	s_cselect_b32 s24, s89, s96
	s_add_i32 s91, 0, 0x14000
	ds_read_b128 v[134:137], v2
	ds_read_b128 v[138:141], v2 offset:1024
	ds_read_b128 v[142:145], v2 offset:2048
	ds_read_b128 v[146:149], v2 offset:3072
	v_add_u32_e32 v2, s91, v224
	ds_read_b128 v[150:153], v2
	ds_read_b128 v[154:157], v2 offset:1024
	ds_read_b128 v[158:161], v2 offset:2048
	ds_read_b128 v[162:165], v2 offset:3072
	s_add_u32 s92, s56, s92
	s_addc_u32 s93, s57, s93
	s_add_u32 s92, s92, 0x80000
	s_addc_u32 s93, s93, 0
	s_add_i32 m0, s36, 0xc000
	ds_read_b128 v[166:169], v225
	ds_read_b128 v[170:173], v225 offset:1024
	ds_read_b128 v[174:177], v225 offset:2048
	ds_read_b128 v[178:181], v225 offset:3072
	ds_read_b128 v[182:185], v225 offset:4096
	ds_read_b128 v[186:189], v225 offset:5120
	ds_read_b128 v[190:193], v225 offset:6144
	ds_read_b128 v[226:229], v225 offset:7168
	s_add_u32 s100, s92, 0xfff80000
	s_addc_u32 s101, s93, -1
	s_mov_b32 m0, s81
	s_nop 0
	global_load_lds_dwordx4 v208, s[100:101]
	s_mov_b32 m0, s82
	s_nop 0
	global_load_lds_dwordx4 v196, s[100:101]
	s_add_i32 m0, s36, 0xc000
	s_nop 0
	global_load_lds_dwordx4 v208, s[92:93]
	s_add_i32 m0, s36, 0xe000
	s_nop 0
	global_load_lds_dwordx4 v196, s[92:93]
	s_waitcnt vmcnt(8)
	s_waitcnt lgkmcnt(0)
	s_barrier
	s_setprio 1
	s_waitcnt lgkmcnt(0)
	v_mfma_f32_16x16x32_bf16 v[130:133], v[134:137], v[166:169], v[130:133]
	v_mfma_f32_16x16x32_bf16 v[126:129], v[142:145], v[166:169], v[126:129]
	v_mfma_f32_16x16x32_bf16 v[114:117], v[134:137], v[174:177], v[114:117]
	v_mfma_f32_16x16x32_bf16 v[110:113], v[142:145], v[174:177], v[110:113]
	v_mfma_f32_16x16x32_bf16 v[98:101], v[134:137], v[182:185], v[98:101]
	v_mfma_f32_16x16x32_bf16 v[94:97], v[142:145], v[182:185], v[94:97]
	v_mfma_f32_16x16x32_bf16 v[82:85], v[134:137], v[190:193], v[82:85]
	v_mfma_f32_16x16x32_bf16 v[78:81], v[142:145], v[190:193], v[78:81]
	v_mfma_f32_16x16x32_bf16 v[130:133], v[138:141], v[170:173], v[130:133]
	v_mfma_f32_16x16x32_bf16 v[126:129], v[146:149], v[170:173], v[126:129]
	v_mfma_f32_16x16x32_bf16 v[114:117], v[138:141], v[178:181], v[114:117]
	v_mfma_f32_16x16x32_bf16 v[110:113], v[146:149], v[178:181], v[110:113]
	v_mfma_f32_16x16x32_bf16 v[98:101], v[138:141], v[186:189], v[98:101]
	v_mfma_f32_16x16x32_bf16 v[94:97], v[146:149], v[186:189], v[94:97]
	v_mfma_f32_16x16x32_bf16 v[82:85], v[138:141], v[226:229], v[82:85]
	v_mfma_f32_16x16x32_bf16 v[78:81], v[146:149], v[226:229], v[78:81]
	v_mfma_f32_16x16x32_bf16 v[122:125], v[150:153], v[166:169], v[122:125]
	v_mfma_f32_16x16x32_bf16 v[118:121], v[158:161], v[166:169], v[118:121]
	v_mfma_f32_16x16x32_bf16 v[106:109], v[150:153], v[174:177], v[106:109]
	v_mfma_f32_16x16x32_bf16 v[102:105], v[158:161], v[174:177], v[102:105]
	v_mfma_f32_16x16x32_bf16 v[90:93], v[150:153], v[182:185], v[90:93]
	v_mfma_f32_16x16x32_bf16 v[86:89], v[158:161], v[182:185], v[86:89]
	v_mfma_f32_16x16x32_bf16 v[74:77], v[150:153], v[190:193], v[74:77]
	v_mfma_f32_16x16x32_bf16 v[70:73], v[158:161], v[190:193], v[70:73]
	v_mfma_f32_16x16x32_bf16 v[122:125], v[154:157], v[170:173], v[122:125]
	v_mfma_f32_16x16x32_bf16 v[118:121], v[162:165], v[170:173], v[118:121]
	v_mfma_f32_16x16x32_bf16 v[106:109], v[154:157], v[178:181], v[106:109]
	v_mfma_f32_16x16x32_bf16 v[102:105], v[162:165], v[178:181], v[102:105]
	v_mfma_f32_16x16x32_bf16 v[90:93], v[154:157], v[186:189], v[90:93]
	v_mfma_f32_16x16x32_bf16 v[86:89], v[162:165], v[186:189], v[86:89]
	v_mfma_f32_16x16x32_bf16 v[74:77], v[154:157], v[226:229], v[74:77]
	v_mfma_f32_16x16x32_bf16 v[70:73], v[162:165], v[226:229], v[70:73]
	s_setprio 0
	s_barrier
	s_add_i32 s92, vcc_lo, s35
	s_mov_b32 m0, s92
	ds_read_b128 v[166:169], v225 offset:16384
	ds_read_b128 v[170:173], v225 offset:17408
	ds_read_b128 v[174:177], v225 offset:18432
	ds_read_b128 v[178:181], v225 offset:19456
	ds_read_b128 v[182:185], v225 offset:20480
	ds_read_b128 v[186:189], v225 offset:21504
	ds_read_b128 v[190:193], v225 offset:22528
	ds_read_b128 v[226:229], v225 offset:23552
	global_load_lds_dwordx4 v206, s[24:25]
	s_add_i32 m0, s92, 0x2000
	s_add_u32 s92, s24, 0x80000
	s_addc_u32 s93, s25, 0
	s_add_i32 s91, s91, s35
	global_load_lds_dwordx4 v194, s[24:25]
	s_mov_b32 m0, s91
	s_nop 0
	global_load_lds_dwordx4 v206, s[92:93]
	s_add_i32 m0, s91, 0x2000
	s_nop 0
	global_load_lds_dwordx4 v194, s[92:93]
	s_waitcnt vmcnt(6)
	s_waitcnt lgkmcnt(0)
	s_barrier
; #define PG8_STAGE(bufoff, gbase, voff) do { _Pragma("unroll") for (int _i = 0; _i < 2; ++_i) \
;         __builtin_amdgcn_global_load_lds((const unsigned*)((const char*)(gbase) + (voff)[_i]), (LAS unsigned*)(lds + (bufoff) + ldsw + _i * 8192), 16, 0, 0); } while (0)
; #define PG8_LDA(dst, b, h) do { _Pragma("unroll") for (int m = 0; m < 4; ++m) _Pragma("unroll") for (int k = 0; k < 2; ++k) dst[m][k] = *(const LAS bf16x8*)(lds + PG8_SA(b, h) + aoff + m * 2048 + k * 1024); } while (0)
; #define PG8_LDB(dst, b, h) do { _Pragma("unroll") for (int n = 0; n < 2; ++n) _Pragma("unroll") for (int k = 0; k < 2; ++k) dst[n][k] = *(const LAS bf16x8*)(lds + PG8_SB(b, h) + boff + n * 2048 + k * 1024); } while (0)
; #define PG8_MMA(ai, bj, At, Bt) do { __builtin_amdgcn_s_setprio(1); _Pragma("unroll") for (int m = 0; m < 4; ++m) _Pragma("unroll") for (int n = 0; n < 2; ++n) _Pragma("unroll") for (int k = 0; k < 2; ++k) \
;         acc[ai][bj][m][n] = __builtin_amdgcn_mfma_f32_16x16x32_bf16(Bt[n][k], At[m][k], acc[ai][bj][m][n], 0, 0, 0); __builtin_amdgcn_s_setprio(0); } while (0)
; #define PG8_WAIT_V(n) asm volatile("s_waitcnt vmcnt(" #n ")" ::: "memory")
; #define PG8_WAIT_L(n) asm volatile("s_waitcnt lgkmcnt(" #n ")" ::: "memory")
; #define PG8_BAR __builtin_amdgcn_s_barrier()
; #define PG8_WAIT_RELAX(flag, n) asm volatile("s_cmp_eq_u32 %0, 0\n\ts_cbranch_scc1 .Lrw%=\n\ts_waitcnt vmcnt(8)\n.Lrw%=:\n\ts_waitcnt vmcnt(%1)" :: "s"(flag), "n"(n) : "scc", "memory")
; #define PG8_SCHED __builtin_amdgcn_sched_barrier(0)
; template <class Epi, bool ALIGN_EPI = true>
; __device__ __forceinline__ void gemm_phase(LAS unsigned char* lds, const Gemm g, const Sched& S, const Epi& E) {
;     ...
;             PG8_WAIT_L(0); PG8_BAR; PG8_MMA(0, 0, At, B0); PG8_MMA(0, 1, At, B1); PG8_BAR; PG8_SCHED;
;             PG8_LDA(At, 0, 1); PG8_STAGE(PG8_SB(0, 0), b2, voffB); PG8_STAGE(PG8_SB(0, 1), b2 + hstepB, voffB); PG8_STAGE(PG8_SA(0, 0), a2, voffA);
;             if constexpr (Epi::NSTORES > 0) PG8_WAIT_RELAX(rflag, 8 + Epi::NSTORES); else PG8_WAIT_V(8);
;             PG8_WAIT_L(0); PG8_BAR; PG8_MMA(1, 0, At, B0); PG8_MMA(1, 1, At, B1); PG8_BAR; PG8_SCHED;
;             PG8_LDB(B0, 1, 0); PG8_LDB(B1, 1, 1); PG8_SCHED; PG8_LDA(At, 1, 0); PG8_STAGE(PG8_SA(0, 1), a2 + hstepA, voffA);
;             PG8_WAIT_V(8); PG8_WAIT_L(0); PG8_BAR; PG8_MMA(0, 0, At, B0); PG8_MMA(0, 1, At, B1); PG8_BAR; PG8_SCHED;
	s_setprio 1
	s_waitcnt lgkmcnt(0)
	v_mfma_f32_16x16x32_bf16 v[66:69], v[134:137], v[166:169], v[66:69]
	v_mfma_f32_16x16x32_bf16 v[62:65], v[142:145], v[166:169], v[62:65]
	v_mfma_f32_16x16x32_bf16 v[50:53], v[134:137], v[174:177], v[50:53]
	v_mfma_f32_16x16x32_bf16 v[46:49], v[142:145], v[174:177], v[46:49]
	v_mfma_f32_16x16x32_bf16 v[34:37], v[134:137], v[182:185], v[34:37]
	v_mfma_f32_16x16x32_bf16 v[30:33], v[142:145], v[182:185], v[30:33]
	v_mfma_f32_16x16x32_bf16 v[18:21], v[134:137], v[190:193], v[18:21]
	v_mfma_f32_16x16x32_bf16 v[14:17], v[142:145], v[190:193], v[14:17]
	v_mfma_f32_16x16x32_bf16 v[66:69], v[138:141], v[170:173], v[66:69]
	v_mfma_f32_16x16x32_bf16 v[62:65], v[146:149], v[170:173], v[62:65]
	v_mfma_f32_16x16x32_bf16 v[50:53], v[138:141], v[178:181], v[50:53]
	v_mfma_f32_16x16x32_bf16 v[46:49], v[146:149], v[178:181], v[46:49]
	v_mfma_f32_16x16x32_bf16 v[34:37], v[138:141], v[186:189], v[34:37]
	v_mfma_f32_16x16x32_bf16 v[30:33], v[146:149], v[186:189], v[30:33]
	v_mfma_f32_16x16x32_bf16 v[18:21], v[138:141], v[226:229], v[18:21]
	v_mfma_f32_16x16x32_bf16 v[14:17], v[146:149], v[226:229], v[14:17]
	v_mfma_f32_16x16x32_bf16 v[58:61], v[150:153], v[166:169], v[58:61]
	v_mfma_f32_16x16x32_bf16 v[54:57], v[158:161], v[166:169], v[54:57]
	v_mfma_f32_16x16x32_bf16 v[42:45], v[150:153], v[174:177], v[42:45]
	v_mfma_f32_16x16x32_bf16 v[38:41], v[158:161], v[174:177], v[38:41]
	v_mfma_f32_16x16x32_bf16 v[26:29], v[150:153], v[182:185], v[26:29]
	v_mfma_f32_16x16x32_bf16 v[22:25], v[158:161], v[182:185], v[22:25]
	v_mfma_f32_16x16x32_bf16 v[10:13], v[150:153], v[190:193], v[10:13]
	v_mfma_f32_16x16x32_bf16 v[4:7], v[158:161], v[190:193], v[6:9]
	v_mfma_f32_16x16x32_bf16 v[58:61], v[154:157], v[170:173], v[58:61]
	v_mfma_f32_16x16x32_bf16 v[54:57], v[162:165], v[170:173], v[54:57]
	v_mfma_f32_16x16x32_bf16 v[42:45], v[154:157], v[178:181], v[42:45]
	v_mfma_f32_16x16x32_bf16 v[38:41], v[162:165], v[178:181], v[38:41]
	v_mfma_f32_16x16x32_bf16 v[26:29], v[154:157], v[186:189], v[26:29]
	v_mfma_f32_16x16x32_bf16 v[22:25], v[162:165], v[186:189], v[22:25]
	v_mfma_f32_16x16x32_bf16 v[10:13], v[154:157], v[226:229], v[10:13]
	v_mfma_f32_16x16x32_bf16 v[4:7], v[162:165], v[226:229], v[4:7]
	s_setprio 0
	s_barrier
	s_add_i32 s91, 0, 0x18000
	v_add_u32_e32 v2, s91, v224
	s_add_i32 s92, 0, 0x1c000
	ds_read_b128 v[134:137], v2
	ds_read_b128 v[138:141], v2 offset:1024
	ds_read_b128 v[142:145], v2 offset:2048
	ds_read_b128 v[146:149], v2 offset:3072
	v_add_u32_e32 v2, s92, v224
	ds_read_b128 v[150:153], v2
	ds_read_b128 v[154:157], v2 offset:1024
	ds_read_b128 v[158:161], v2 offset:2048
	ds_read_b128 v[162:165], v2 offset:3072
	s_add_u32 s26, s26, 0x80000
	s_addc_u32 s27, s27, 0
	s_mov_b32 m0, s76
	ds_read_b128 v[166:169], v225 offset:32768
	ds_read_b128 v[170:173], v225 offset:33792
	ds_read_b128 v[174:177], v225 offset:34816
	ds_read_b128 v[178:181], v225 offset:35840
	ds_read_b128 v[182:185], v225 offset:36864
	ds_read_b128 v[186:189], v225 offset:37888
	ds_read_b128 v[190:193], v225 offset:38912
	ds_read_b128 v[226:229], v225 offset:39936
	s_add_u32 s100, s26, 0xfff80000
	s_addc_u32 s101, s27, -1
	s_mov_b32 m0, s36
	s_nop 0
	global_load_lds_dwordx4 v208, s[100:101]
	s_mov_b32 m0, s37
	s_nop 0
	global_load_lds_dwordx4 v196, s[100:101]
	s_mov_b32 m0, s76
	s_nop 0
	global_load_lds_dwordx4 v208, s[26:27]
	s_mov_b32 m0, s77
	s_nop 0
	global_load_lds_dwordx4 v196, s[26:27]
	s_waitcnt vmcnt(8)
	s_waitcnt lgkmcnt(0)
	s_barrier
; #define PG8_STAGE(bufoff, gbase, voff) do { _Pragma("unroll") for (int _i = 0; _i < 2; ++_i) \
;         __builtin_amdgcn_global_load_lds((const unsigned*)((const char*)(gbase) + (voff)[_i]), (LAS unsigned*)(lds + (bufoff) + ldsw + _i * 8192), 16, 0, 0); } while (0)
; #define PG8_LDA(dst, b, h) do { _Pragma("unroll") for (int m = 0; m < 4; ++m) _Pragma("unroll") for (int k = 0; k < 2; ++k) dst[m][k] = *(const LAS bf16x8*)(lds + PG8_SA(b, h) + aoff + m * 2048 + k * 1024); } while (0)
; #define PG8_MMA(ai, bj, At, Bt) do { __builtin_amdgcn_s_setprio(1); _Pragma("unroll") for (int m = 0; m < 4; ++m) _Pragma("unroll") for (int n = 0; n < 2; ++n) _Pragma("unroll") for (int k = 0; k < 2; ++k) \
;         acc[ai][bj][m][n] = __builtin_amdgcn_mfma_f32_16x16x32_bf16(Bt[n][k], At[m][k], acc[ai][bj][m][n], 0, 0, 0); __builtin_amdgcn_s_setprio(0); } while (0)
; #define PG8_WAIT_V(n) asm volatile("s_waitcnt vmcnt(" #n ")" ::: "memory")
; #define PG8_WAIT_L(n) asm volatile("s_waitcnt lgkmcnt(" #n ")" ::: "memory")
; #define PG8_BAR __builtin_amdgcn_s_barrier()
; #define PG8_SCHED __builtin_amdgcn_sched_barrier(0)
; template <class Epi, bool ALIGN_EPI = true>
; __device__ __forceinline__ void gemm_phase(LAS unsigned char* lds, const Gemm g, const Sched& S, const Epi& E) {
;     ...
;             PG8_WAIT_V(8); PG8_WAIT_L(0); PG8_BAR; PG8_MMA(0, 0, At, B0); PG8_MMA(0, 1, At, B1); PG8_BAR; PG8_SCHED;
;             PG8_LDA(At, 1, 1); PG8_STAGE(PG8_SB(1, 0), b3, voffB); PG8_STAGE(PG8_SB(1, 1), b3 + hstepB, voffB); PG8_STAGE(PG8_SA(1, 0), a3, voffA);
;             PG8_WAIT_V(8); PG8_WAIT_L(0); PG8_BAR; PG8_MMA(1, 0, At, B0); PG8_MMA(1, 1, At, B1); PG8_BAR; PG8_SCHED;
	s_setprio 1
	s_waitcnt lgkmcnt(0)
	v_mfma_f32_16x16x32_bf16 v[130:133], v[134:137], v[166:169], v[130:133]
	v_mfma_f32_16x16x32_bf16 v[126:129], v[142:145], v[166:169], v[126:129]
	v_mfma_f32_16x16x32_bf16 v[114:117], v[134:137], v[174:177], v[114:117]
	v_mfma_f32_16x16x32_bf16 v[110:113], v[142:145], v[174:177], v[110:113]
	v_mfma_f32_16x16x32_bf16 v[98:101], v[134:137], v[182:185], v[98:101]
	v_mfma_f32_16x16x32_bf16 v[94:97], v[142:145], v[182:185], v[94:97]
	v_mfma_f32_16x16x32_bf16 v[82:85], v[134:137], v[190:193], v[82:85]
	v_mfma_f32_16x16x32_bf16 v[78:81], v[142:145], v[190:193], v[78:81]
	v_mfma_f32_16x16x32_bf16 v[130:133], v[138:141], v[170:173], v[130:133]
	v_mfma_f32_16x16x32_bf16 v[126:129], v[146:149], v[170:173], v[126:129]
	v_mfma_f32_16x16x32_bf16 v[114:117], v[138:141], v[178:181], v[114:117]
	v_mfma_f32_16x16x32_bf16 v[110:113], v[146:149], v[178:181], v[110:113]
	v_mfma_f32_16x16x32_bf16 v[98:101], v[138:141], v[186:189], v[98:101]
	v_mfma_f32_16x16x32_bf16 v[94:97], v[146:149], v[186:189], v[94:97]
	v_mfma_f32_16x16x32_bf16 v[82:85], v[138:141], v[226:229], v[82:85]
	v_mfma_f32_16x16x32_bf16 v[78:81], v[146:149], v[226:229], v[78:81]
	v_mfma_f32_16x16x32_bf16 v[122:125], v[150:153], v[166:169], v[122:125]
	v_mfma_f32_16x16x32_bf16 v[118:121], v[158:161], v[166:169], v[118:121]
	v_mfma_f32_16x16x32_bf16 v[106:109], v[150:153], v[174:177], v[106:109]
	v_mfma_f32_16x16x32_bf16 v[102:105], v[158:161], v[174:177], v[102:105]
	v_mfma_f32_16x16x32_bf16 v[90:93], v[150:153], v[182:185], v[90:93]
	v_mfma_f32_16x16x32_bf16 v[86:89], v[158:161], v[182:185], v[86:89]
	v_mfma_f32_16x16x32_bf16 v[74:77], v[150:153], v[190:193], v[74:77]
	v_mfma_f32_16x16x32_bf16 v[70:73], v[158:161], v[190:193], v[70:73]
	v_mfma_f32_16x16x32_bf16 v[122:125], v[154:157], v[170:173], v[122:125]
	v_mfma_f32_16x16x32_bf16 v[118:121], v[162:165], v[170:173], v[118:121]
	v_mfma_f32_16x16x32_bf16 v[106:109], v[154:157], v[178:181], v[106:109]
	v_mfma_f32_16x16x32_bf16 v[102:105], v[162:165], v[178:181], v[102:105]
	v_mfma_f32_16x16x32_bf16 v[90:93], v[154:157], v[186:189], v[90:93]
	v_mfma_f32_16x16x32_bf16 v[86:89], v[162:165], v[186:189], v[86:89]
	v_mfma_f32_16x16x32_bf16 v[74:77], v[154:157], v[226:229], v[74:77]
	v_mfma_f32_16x16x32_bf16 v[70:73], v[162:165], v[226:229], v[70:73]
	s_setprio 0
	s_barrier
	s_add_u32 s100, s24, 0x80
	s_addc_u32 s101, s25, 0
	s_add_i32 s26, s91, s35
	s_mov_b32 m0, s26
	ds_read_b128 v[166:169], v225 offset:49152
	ds_read_b128 v[170:173], v225 offset:50176
	ds_read_b128 v[174:177], v225 offset:51200
	ds_read_b128 v[178:181], v225 offset:52224
	ds_read_b128 v[182:185], v225 offset:53248
	ds_read_b128 v[186:189], v225 offset:54272
	ds_read_b128 v[190:193], v225 offset:55296
	ds_read_b128 v[226:229], v225 offset:56320
	global_load_lds_dwordx4 v206, s[100:101]
	s_add_i32 m0, s26, 0x2000
	s_add_u32 s24, s24, 0x80080
	s_addc_u32 s25, s25, 0
	s_add_i32 s26, s92, s35
	global_load_lds_dwordx4 v194, s[100:101]
	s_mov_b32 m0, s26
	s_nop 0
	global_load_lds_dwordx4 v206, s[24:25]
	s_add_i32 m0, s26, 0x2000
	s_nop 0
	global_load_lds_dwordx4 v194, s[24:25]
	s_waitcnt vmcnt(6)
	s_waitcnt lgkmcnt(0)
	s_barrier
	s_setprio 1
	s_waitcnt lgkmcnt(0)
	v_mfma_f32_16x16x32_bf16 v[66:69], v[134:137], v[166:169], v[66:69]
	v_mfma_f32_16x16x32_bf16 v[62:65], v[142:145], v[166:169], v[62:65]
	v_mfma_f32_16x16x32_bf16 v[50:53], v[134:137], v[174:177], v[50:53]
	v_mfma_f32_16x16x32_bf16 v[46:49], v[142:145], v[174:177], v[46:49]
	v_mfma_f32_16x16x32_bf16 v[34:37], v[134:137], v[182:185], v[34:37]
	v_mfma_f32_16x16x32_bf16 v[30:33], v[142:145], v[182:185], v[30:33]
	v_mfma_f32_16x16x32_bf16 v[18:21], v[134:137], v[190:193], v[18:21]
	v_mfma_f32_16x16x32_bf16 v[14:17], v[142:145], v[190:193], v[14:17]
	v_mfma_f32_16x16x32_bf16 v[66:69], v[138:141], v[170:173], v[66:69]
	v_mfma_f32_16x16x32_bf16 v[62:65], v[146:149], v[170:173], v[62:65]
	v_mfma_f32_16x16x32_bf16 v[50:53], v[138:141], v[178:181], v[50:53]
	v_mfma_f32_16x16x32_bf16 v[46:49], v[146:149], v[178:181], v[46:49]
	v_mfma_f32_16x16x32_bf16 v[34:37], v[138:141], v[186:189], v[34:37]
	v_mfma_f32_16x16x32_bf16 v[30:33], v[146:149], v[186:189], v[30:33]
	v_mfma_f32_16x16x32_bf16 v[18:21], v[138:141], v[226:229], v[18:21]
	v_mfma_f32_16x16x32_bf16 v[14:17], v[146:149], v[226:229], v[14:17]
	v_mfma_f32_16x16x32_bf16 v[58:61], v[150:153], v[166:169], v[58:61]
	v_mfma_f32_16x16x32_bf16 v[54:57], v[158:161], v[166:169], v[54:57]
	v_mfma_f32_16x16x32_bf16 v[42:45], v[150:153], v[174:177], v[42:45]
	v_mfma_f32_16x16x32_bf16 v[38:41], v[158:161], v[174:177], v[38:41]
	v_mfma_f32_16x16x32_bf16 v[26:29], v[150:153], v[182:185], v[26:29]
	v_mfma_f32_16x16x32_bf16 v[22:25], v[158:161], v[182:185], v[22:25]
	v_mfma_f32_16x16x32_bf16 v[8:11], v[150:153], v[190:193], v[10:13]
	v_mfma_f32_16x16x32_bf16 v[4:7], v[158:161], v[190:193], v[4:7]
	v_mfma_f32_16x16x32_bf16 v[58:61], v[154:157], v[170:173], v[58:61]
	v_mfma_f32_16x16x32_bf16 v[54:57], v[162:165], v[170:173], v[54:57]
	v_mfma_f32_16x16x32_bf16 v[42:45], v[154:157], v[178:181], v[42:45]
	v_mfma_f32_16x16x32_bf16 v[38:41], v[162:165], v[178:181], v[38:41]
	v_mfma_f32_16x16x32_bf16 v[26:29], v[154:157], v[186:189], v[26:29]
	v_mfma_f32_16x16x32_bf16 v[22:25], v[162:165], v[186:189], v[22:25]
	v_mfma_f32_16x16x32_bf16 v[10:13], v[154:157], v[226:229], v[8:11]
	v_mfma_f32_16x16x32_bf16 v[6:9], v[162:165], v[226:229], v[4:7]
	s_setprio 0
	s_barrier
	s_cmp_ge_i32 s94, s90
	s_mov_b32 s24, s94
	s_cbranch_scc0 .LBB0_1237
	s_branch .LBB0_1232

; #define PG8_STAGE(bufoff, gbase, voff) do { _Pragma("unroll") for (int _i = 0; _i < 2; ++_i) \
;         __builtin_amdgcn_global_load_lds((const unsigned*)((const char*)(gbase) + (voff)[_i]), (LAS unsigned*)(lds + (bufoff) + ldsw + _i * 8192), 16, 0, 0); } while (0)
; #define PG8_LDA(dst, b, h) do { _Pragma("unroll") for (int m = 0; m < 4; ++m) _Pragma("unroll") for (int k = 0; k < 2; ++k) dst[m][k] = *(const LAS bf16x8*)(lds + PG8_SA(b, h) + aoff + m * 2048 + k * 1024); } while (0)
; #define PG8_LDB(dst, b, h) do { _Pragma("unroll") for (int n = 0; n < 2; ++n) _Pragma("unroll") for (int k = 0; k < 2; ++k) dst[n][k] = *(const LAS bf16x8*)(lds + PG8_SB(b, h) + boff + n * 2048 + k * 1024); } while (0)
; #define PG8_MMA(ai, bj, At, Bt) do { __builtin_amdgcn_s_setprio(1); _Pragma("unroll") for (int m = 0; m < 4; ++m) _Pragma("unroll") for (int n = 0; n < 2; ++n) _Pragma("unroll") for (int k = 0; k < 2; ++k) \
;         acc[ai][bj][m][n] = __builtin_amdgcn_mfma_f32_16x16x32_bf16(Bt[n][k], At[m][k], acc[ai][bj][m][n], 0, 0, 0); __builtin_amdgcn_s_setprio(0); } while (0)
; template <class Epi, bool ALIGN_EPI = true>
; __device__ __forceinline__ void gemm_phase(LAS unsigned char* lds, const Gemm g, const Sched& S, const Epi& E) {
;     ...
;         for (int t = t_lo; t < t_hi; t += 2) {
;             const bool last = (t == nt - 2);
;             const char* a1 = cA + (size_t)(t + 1) * kstep;
;             const char* a2 = last ? nA : cA + (size_t)(t + 2) * kstep; const char* b2 = last ? nB : cB + (size_t)(t + 2) * kstep;
;             const char* a3 = a2 + kstep; const char* b3 = b2 + kstep;
;             const int rflag = __builtin_amdgcn_readfirstlane(t | (int)(ui == 0));
;             PG8_LDB(B0, 0, 0); PG8_LDB(B1, 0, 1); PG8_SCHED; PG8_LDA(At, 0, 0); PG8_STAGE(PG8_SA(1, 1), a1 + hstepA, voffA);
;             if constexpr (Epi::NSTORES > 0) PG8_WAIT_RELAX(rflag, 8 + Epi::NSTORES); else PG8_WAIT_V(8);
;             PG8_WAIT_L(0); PG8_BAR; PG8_MMA(0, 0, At, B0); PG8_MMA(0, 1, At, B1); PG8_BAR; PG8_SCHED;
;             PG8_LDA(At, 0, 1); PG8_STAGE(PG8_SB(0, 0), b2, voffB); PG8_STAGE(PG8_SB(0, 1), b2 + hstepB, voffB); PG8_STAGE(PG8_SA(0, 0), a2, voffA);
;             if constexpr (Epi::NSTORES > 0) PG8_WAIT_RELAX(rflag, 8 + Epi::NSTORES); else PG8_WAIT_V(8);
;             PG8_WAIT_L(0); PG8_BAR; PG8_MMA(1, 0, At, B0); PG8_MMA(1, 1, At, B1); PG8_BAR; PG8_SCHED;
.LBB0_1311:
	s_add_i32 s67, s48, 2
	s_add_u32 s49, s46, 0xfff80080
	s_addc_u32 s50, s47, -1
	s_add_i32 s68, 0, 0x10000
	s_cmp_eq_u32 s59, s48
	s_cselect_b32 s51, s21, s50
	s_cselect_b32 s50, s23, s49
	v_add_u32_e32 v2, s68, v147
	s_cselect_b32 s49, s63, s66
	s_cselect_b32 s48, s64, s65
	s_add_i32 s70, 0, 0x14000
	ds_read_b128 v[150:153], v2
	ds_read_b128 v[154:157], v2 offset:1024
	ds_read_b128 v[158:161], v2 offset:2048
	ds_read_b128 v[162:165], v2 offset:3072
	v_add_u32_e32 v2, s70, v147
	ds_read_b128 v[166:169], v2
	ds_read_b128 v[170:173], v2 offset:1024
	ds_read_b128 v[174:177], v2 offset:2048
	ds_read_b128 v[178:181], v2 offset:3072
	s_add_i32 m0, s52, 0xc000
	ds_read_b128 v[182:185], v148
	ds_read_b128 v[186:189], v148 offset:1024
	ds_read_b128 v[190:193], v148 offset:2048
	ds_read_b128 v[194:197], v148 offset:3072
	ds_read_b128 v[206:209], v148 offset:4096
	ds_read_b128 v[224:227], v148 offset:5120
	ds_read_b128 v[228:231], v148 offset:6144
	ds_read_b128 v[232:235], v148 offset:7168
	s_add_u32 s100, s46, 0xfff80000
	s_addc_u32 s101, s47, -1
	s_mov_b32 m0, s57
	s_nop 0
	global_load_lds_dwordx4 v142, s[100:101]
	s_mov_b32 m0, s58
	s_nop 0
	global_load_lds_dwordx4 v144, s[100:101]
	s_add_i32 m0, s52, 0xc000
	s_nop 0
	global_load_lds_dwordx4 v142, s[46:47]
	s_add_i32 m0, s52, 0xe000
	s_nop 0
	global_load_lds_dwordx4 v144, s[46:47]
	s_waitcnt vmcnt(8)
	s_waitcnt lgkmcnt(0)
	s_barrier
	s_setprio 1
	s_waitcnt lgkmcnt(0)
	v_mfma_f32_16x16x32_bf16 v[130:133], v[150:153], v[182:185], v[130:133]
	v_mfma_f32_16x16x32_bf16 v[126:129], v[158:161], v[182:185], v[126:129]
	v_mfma_f32_16x16x32_bf16 v[114:117], v[150:153], v[190:193], v[114:117]
	v_mfma_f32_16x16x32_bf16 v[110:113], v[158:161], v[190:193], v[110:113]
	v_mfma_f32_16x16x32_bf16 v[98:101], v[150:153], v[206:209], v[98:101]
	v_mfma_f32_16x16x32_bf16 v[94:97], v[158:161], v[206:209], v[94:97]
	v_mfma_f32_16x16x32_bf16 v[82:85], v[150:153], v[228:231], v[82:85]
	v_mfma_f32_16x16x32_bf16 v[78:81], v[158:161], v[228:231], v[78:81]
	v_mfma_f32_16x16x32_bf16 v[130:133], v[154:157], v[186:189], v[130:133]
	v_mfma_f32_16x16x32_bf16 v[126:129], v[162:165], v[186:189], v[126:129]
	v_mfma_f32_16x16x32_bf16 v[114:117], v[154:157], v[194:197], v[114:117]
	v_mfma_f32_16x16x32_bf16 v[110:113], v[162:165], v[194:197], v[110:113]
	v_mfma_f32_16x16x32_bf16 v[98:101], v[154:157], v[224:227], v[98:101]
	v_mfma_f32_16x16x32_bf16 v[94:97], v[162:165], v[224:227], v[94:97]
	v_mfma_f32_16x16x32_bf16 v[82:85], v[154:157], v[232:235], v[82:85]
	v_mfma_f32_16x16x32_bf16 v[78:81], v[162:165], v[232:235], v[78:81]
	v_mfma_f32_16x16x32_bf16 v[122:125], v[166:169], v[182:185], v[122:125]
	v_mfma_f32_16x16x32_bf16 v[118:121], v[174:177], v[182:185], v[118:121]
	v_mfma_f32_16x16x32_bf16 v[106:109], v[166:169], v[190:193], v[106:109]
	v_mfma_f32_16x16x32_bf16 v[102:105], v[174:177], v[190:193], v[102:105]
	v_mfma_f32_16x16x32_bf16 v[90:93], v[166:169], v[206:209], v[90:93]
	v_mfma_f32_16x16x32_bf16 v[86:89], v[174:177], v[206:209], v[86:89]
	v_mfma_f32_16x16x32_bf16 v[74:77], v[166:169], v[228:231], v[74:77]
	v_mfma_f32_16x16x32_bf16 v[70:73], v[174:177], v[228:231], v[70:73]
	v_mfma_f32_16x16x32_bf16 v[122:125], v[170:173], v[186:189], v[122:125]
	v_mfma_f32_16x16x32_bf16 v[118:121], v[178:181], v[186:189], v[118:121]
	v_mfma_f32_16x16x32_bf16 v[106:109], v[170:173], v[194:197], v[106:109]
	v_mfma_f32_16x16x32_bf16 v[102:105], v[178:181], v[194:197], v[102:105]
	v_mfma_f32_16x16x32_bf16 v[90:93], v[170:173], v[224:227], v[90:93]
	v_mfma_f32_16x16x32_bf16 v[86:89], v[178:181], v[224:227], v[86:89]
	v_mfma_f32_16x16x32_bf16 v[74:77], v[170:173], v[232:235], v[74:77]
	v_mfma_f32_16x16x32_bf16 v[70:73], v[178:181], v[232:235], v[70:73]
	s_setprio 0
	s_barrier
	s_add_i32 s68, s68, s37
	s_mov_b32 m0, s68
	ds_read_b128 v[182:185], v148 offset:16384
	ds_read_b128 v[186:189], v148 offset:17408
	ds_read_b128 v[190:193], v148 offset:18432
	ds_read_b128 v[194:197], v148 offset:19456
	ds_read_b128 v[206:209], v148 offset:20480
	ds_read_b128 v[224:227], v148 offset:21504
	ds_read_b128 v[228:231], v148 offset:22528
	ds_read_b128 v[232:235], v148 offset:23552
	global_load_lds_dwordx4 v138, s[48:49]
	s_add_i32 m0, s68, 0x2000
	s_add_u32 s68, s48, 0x80000
	s_addc_u32 s69, s49, 0
	s_add_i32 s70, s70, s37
	global_load_lds_dwordx4 v134, s[48:49]
	s_mov_b32 m0, s70
	s_nop 0
	global_load_lds_dwordx4 v138, s[68:69]
	s_add_i32 m0, s70, 0x2000
	s_nop 0
	global_load_lds_dwordx4 v134, s[68:69]
	s_waitcnt vmcnt(6)
	s_waitcnt lgkmcnt(0)
	s_barrier
; #define PG8_STAGE(bufoff, gbase, voff) do { _Pragma("unroll") for (int _i = 0; _i < 2; ++_i) \
;         __builtin_amdgcn_global_load_lds((const unsigned*)((const char*)(gbase) + (voff)[_i]), (LAS unsigned*)(lds + (bufoff) + ldsw + _i * 8192), 16, 0, 0); } while (0)
; #define PG8_LDA(dst, b, h) do { _Pragma("unroll") for (int m = 0; m < 4; ++m) _Pragma("unroll") for (int k = 0; k < 2; ++k) dst[m][k] = *(const LAS bf16x8*)(lds + PG8_SA(b, h) + aoff + m * 2048 + k * 1024); } while (0)
; #define PG8_LDB(dst, b, h) do { _Pragma("unroll") for (int n = 0; n < 2; ++n) _Pragma("unroll") for (int k = 0; k < 2; ++k) dst[n][k] = *(const LAS bf16x8*)(lds + PG8_SB(b, h) + boff + n * 2048 + k * 1024); } while (0)
; #define PG8_MMA(ai, bj, At, Bt) do { __builtin_amdgcn_s_setprio(1); _Pragma("unroll") for (int m = 0; m < 4; ++m) _Pragma("unroll") for (int n = 0; n < 2; ++n) _Pragma("unroll") for (int k = 0; k < 2; ++k) \
;         acc[ai][bj][m][n] = __builtin_amdgcn_mfma_f32_16x16x32_bf16(Bt[n][k], At[m][k], acc[ai][bj][m][n], 0, 0, 0); __builtin_amdgcn_s_setprio(0); } while (0)
; #define PG8_WAIT_V(n) asm volatile("s_waitcnt vmcnt(" #n ")" ::: "memory")
; #define PG8_WAIT_L(n) asm volatile("s_waitcnt lgkmcnt(" #n ")" ::: "memory")
; #define PG8_BAR __builtin_amdgcn_s_barrier()
; #define PG8_WAIT_RELAX(flag, n) asm volatile("s_cmp_eq_u32 %0, 0\n\ts_cbranch_scc1 .Lrw%=\n\ts_waitcnt vmcnt(8)\n.Lrw%=:\n\ts_waitcnt vmcnt(%1)" :: "s"(flag), "n"(n) : "scc", "memory")
; #define PG8_SCHED __builtin_amdgcn_sched_barrier(0)
; template <class Epi, bool ALIGN_EPI = true>
; __device__ __forceinline__ void gemm_phase(LAS unsigned char* lds, const Gemm g, const Sched& S, const Epi& E) {
;     ...
;             PG8_WAIT_L(0); PG8_BAR; PG8_MMA(0, 0, At, B0); PG8_MMA(0, 1, At, B1); PG8_BAR; PG8_SCHED;
;             PG8_LDA(At, 0, 1); PG8_STAGE(PG8_SB(0, 0), b2, voffB); PG8_STAGE(PG8_SB(0, 1), b2 + hstepB, voffB); PG8_STAGE(PG8_SA(0, 0), a2, voffA);
;             if constexpr (Epi::NSTORES > 0) PG8_WAIT_RELAX(rflag, 8 + Epi::NSTORES); else PG8_WAIT_V(8);
;             PG8_WAIT_L(0); PG8_BAR; PG8_MMA(1, 0, At, B0); PG8_MMA(1, 1, At, B1); PG8_BAR; PG8_SCHED;
;             PG8_LDB(B0, 1, 0); PG8_LDB(B1, 1, 1); PG8_SCHED; PG8_LDA(At, 1, 0); PG8_STAGE(PG8_SA(0, 1), a2 + hstepA, voffA);
;             PG8_WAIT_V(8); PG8_WAIT_L(0); PG8_BAR; PG8_MMA(0, 0, At, B0); PG8_MMA(0, 1, At, B1); PG8_BAR; PG8_SCHED;
	s_setprio 1
	s_waitcnt lgkmcnt(0)
	v_mfma_f32_16x16x32_bf16 v[66:69], v[150:153], v[182:185], v[66:69]
	v_mfma_f32_16x16x32_bf16 v[62:65], v[158:161], v[182:185], v[62:65]
	v_mfma_f32_16x16x32_bf16 v[50:53], v[150:153], v[190:193], v[50:53]
	v_mfma_f32_16x16x32_bf16 v[46:49], v[158:161], v[190:193], v[46:49]
	v_mfma_f32_16x16x32_bf16 v[34:37], v[150:153], v[206:209], v[34:37]
	v_mfma_f32_16x16x32_bf16 v[30:33], v[158:161], v[206:209], v[30:33]
	v_mfma_f32_16x16x32_bf16 v[18:21], v[150:153], v[228:231], v[18:21]
	v_mfma_f32_16x16x32_bf16 v[14:17], v[158:161], v[228:231], v[14:17]
	v_mfma_f32_16x16x32_bf16 v[66:69], v[154:157], v[186:189], v[66:69]
	v_mfma_f32_16x16x32_bf16 v[62:65], v[162:165], v[186:189], v[62:65]
	v_mfma_f32_16x16x32_bf16 v[50:53], v[154:157], v[194:197], v[50:53]
	v_mfma_f32_16x16x32_bf16 v[46:49], v[162:165], v[194:197], v[46:49]
	v_mfma_f32_16x16x32_bf16 v[34:37], v[154:157], v[224:227], v[34:37]
	v_mfma_f32_16x16x32_bf16 v[30:33], v[162:165], v[224:227], v[30:33]
	v_mfma_f32_16x16x32_bf16 v[18:21], v[154:157], v[232:235], v[18:21]
	v_mfma_f32_16x16x32_bf16 v[14:17], v[162:165], v[232:235], v[14:17]
	v_mfma_f32_16x16x32_bf16 v[58:61], v[166:169], v[182:185], v[58:61]
	v_mfma_f32_16x16x32_bf16 v[54:57], v[174:177], v[182:185], v[54:57]
	v_mfma_f32_16x16x32_bf16 v[42:45], v[166:169], v[190:193], v[42:45]
	v_mfma_f32_16x16x32_bf16 v[38:41], v[174:177], v[190:193], v[38:41]
	v_mfma_f32_16x16x32_bf16 v[26:29], v[166:169], v[206:209], v[26:29]
	v_mfma_f32_16x16x32_bf16 v[22:25], v[174:177], v[206:209], v[22:25]
	v_mfma_f32_16x16x32_bf16 v[10:13], v[166:169], v[228:231], v[10:13]
	v_mfma_f32_16x16x32_bf16 v[4:7], v[174:177], v[228:231], v[6:9]
	v_mfma_f32_16x16x32_bf16 v[58:61], v[170:173], v[186:189], v[58:61]
	v_mfma_f32_16x16x32_bf16 v[54:57], v[178:181], v[186:189], v[54:57]
	v_mfma_f32_16x16x32_bf16 v[42:45], v[170:173], v[194:197], v[42:45]
	v_mfma_f32_16x16x32_bf16 v[38:41], v[178:181], v[194:197], v[38:41]
	v_mfma_f32_16x16x32_bf16 v[26:29], v[170:173], v[224:227], v[26:29]
	v_mfma_f32_16x16x32_bf16 v[22:25], v[178:181], v[224:227], v[22:25]
	v_mfma_f32_16x16x32_bf16 v[10:13], v[170:173], v[232:235], v[10:13]
	v_mfma_f32_16x16x32_bf16 v[4:7], v[178:181], v[232:235], v[4:7]
	s_setprio 0
	s_barrier
	s_add_i32 s68, 0, 0x18000
	v_add_u32_e32 v2, s68, v147
	s_add_i32 s69, 0, 0x1c000
	ds_read_b128 v[150:153], v2
	ds_read_b128 v[154:157], v2 offset:1024
	ds_read_b128 v[158:161], v2 offset:2048
	ds_read_b128 v[162:165], v2 offset:3072
	v_add_u32_e32 v2, s69, v147
	ds_read_b128 v[166:169], v2
	ds_read_b128 v[170:173], v2 offset:1024
	ds_read_b128 v[174:177], v2 offset:2048
	ds_read_b128 v[178:181], v2 offset:3072
	s_add_u32 s50, s50, 0x80000
	s_addc_u32 s51, s51, 0
	s_mov_b32 m0, s54
	ds_read_b128 v[182:185], v148 offset:32768
	ds_read_b128 v[186:189], v148 offset:33792
	ds_read_b128 v[190:193], v148 offset:34816
	ds_read_b128 v[194:197], v148 offset:35840
	ds_read_b128 v[206:209], v148 offset:36864
	ds_read_b128 v[224:227], v148 offset:37888
	ds_read_b128 v[228:231], v148 offset:38912
	ds_read_b128 v[232:235], v148 offset:39936
	s_add_u32 s100, s50, 0xfff80000
	s_addc_u32 s101, s51, -1
	s_mov_b32 m0, s52
	s_nop 0
	global_load_lds_dwordx4 v140, s[100:101]
	s_mov_b32 m0, s53
	s_nop 0
	global_load_lds_dwordx4 v136, s[100:101]
	s_mov_b32 m0, s54
	s_nop 0
	global_load_lds_dwordx4 v140, s[50:51]
	s_mov_b32 m0, s55
	s_nop 0
	global_load_lds_dwordx4 v136, s[50:51]
	s_waitcnt vmcnt(8)
	s_waitcnt lgkmcnt(0)
	s_barrier
; #define PG8_STAGE(bufoff, gbase, voff) do { _Pragma("unroll") for (int _i = 0; _i < 2; ++_i) \
;         __builtin_amdgcn_global_load_lds((const unsigned*)((const char*)(gbase) + (voff)[_i]), (LAS unsigned*)(lds + (bufoff) + ldsw + _i * 8192), 16, 0, 0); } while (0)
; #define PG8_LDA(dst, b, h) do { _Pragma("unroll") for (int m = 0; m < 4; ++m) _Pragma("unroll") for (int k = 0; k < 2; ++k) dst[m][k] = *(const LAS bf16x8*)(lds + PG8_SA(b, h) + aoff + m * 2048 + k * 1024); } while (0)
; #define PG8_MMA(ai, bj, At, Bt) do { __builtin_amdgcn_s_setprio(1); _Pragma("unroll") for (int m = 0; m < 4; ++m) _Pragma("unroll") for (int n = 0; n < 2; ++n) _Pragma("unroll") for (int k = 0; k < 2; ++k) \
;         acc[ai][bj][m][n] = __builtin_amdgcn_mfma_f32_16x16x32_bf16(Bt[n][k], At[m][k], acc[ai][bj][m][n], 0, 0, 0); __builtin_amdgcn_s_setprio(0); } while (0)
; #define PG8_WAIT_V(n) asm volatile("s_waitcnt vmcnt(" #n ")" ::: "memory")
; #define PG8_WAIT_L(n) asm volatile("s_waitcnt lgkmcnt(" #n ")" ::: "memory")
; #define PG8_BAR __builtin_amdgcn_s_barrier()
; #define PG8_SCHED __builtin_amdgcn_sched_barrier(0)
; template <class Epi, bool ALIGN_EPI = true>
; __device__ __forceinline__ void gemm_phase(LAS unsigned char* lds, const Gemm g, const Sched& S, const Epi& E) {
;     ...
;             PG8_WAIT_V(8); PG8_WAIT_L(0); PG8_BAR; PG8_MMA(0, 0, At, B0); PG8_MMA(0, 1, At, B1); PG8_BAR; PG8_SCHED;
;             PG8_LDA(At, 1, 1); PG8_STAGE(PG8_SB(1, 0), b3, voffB); PG8_STAGE(PG8_SB(1, 1), b3 + hstepB, voffB); PG8_STAGE(PG8_SA(1, 0), a3, voffA);
;             PG8_WAIT_V(8); PG8_WAIT_L(0); PG8_BAR; PG8_MMA(1, 0, At, B0); PG8_MMA(1, 1, At, B1); PG8_BAR; PG8_SCHED;
	s_setprio 1
	s_waitcnt lgkmcnt(0)
	v_mfma_f32_16x16x32_bf16 v[130:133], v[150:153], v[182:185], v[130:133]
	v_mfma_f32_16x16x32_bf16 v[126:129], v[158:161], v[182:185], v[126:129]
	v_mfma_f32_16x16x32_bf16 v[114:117], v[150:153], v[190:193], v[114:117]
	v_mfma_f32_16x16x32_bf16 v[110:113], v[158:161], v[190:193], v[110:113]
	v_mfma_f32_16x16x32_bf16 v[98:101], v[150:153], v[206:209], v[98:101]
	v_mfma_f32_16x16x32_bf16 v[94:97], v[158:161], v[206:209], v[94:97]
	v_mfma_f32_16x16x32_bf16 v[82:85], v[150:153], v[228:231], v[82:85]
	v_mfma_f32_16x16x32_bf16 v[78:81], v[158:161], v[228:231], v[78:81]
	v_mfma_f32_16x16x32_bf16 v[130:133], v[154:157], v[186:189], v[130:133]
	v_mfma_f32_16x16x32_bf16 v[126:129], v[162:165], v[186:189], v[126:129]
	v_mfma_f32_16x16x32_bf16 v[114:117], v[154:157], v[194:197], v[114:117]
	v_mfma_f32_16x16x32_bf16 v[110:113], v[162:165], v[194:197], v[110:113]
	v_mfma_f32_16x16x32_bf16 v[98:101], v[154:157], v[224:227], v[98:101]
	v_mfma_f32_16x16x32_bf16 v[94:97], v[162:165], v[224:227], v[94:97]
	v_mfma_f32_16x16x32_bf16 v[82:85], v[154:157], v[232:235], v[82:85]
	v_mfma_f32_16x16x32_bf16 v[78:81], v[162:165], v[232:235], v[78:81]
	v_mfma_f32_16x16x32_bf16 v[122:125], v[166:169], v[182:185], v[122:125]
	v_mfma_f32_16x16x32_bf16 v[118:121], v[174:177], v[182:185], v[118:121]
	v_mfma_f32_16x16x32_bf16 v[106:109], v[166:169], v[190:193], v[106:109]
	v_mfma_f32_16x16x32_bf16 v[102:105], v[174:177], v[190:193], v[102:105]
	v_mfma_f32_16x16x32_bf16 v[90:93], v[166:169], v[206:209], v[90:93]
	v_mfma_f32_16x16x32_bf16 v[86:89], v[174:177], v[206:209], v[86:89]
	v_mfma_f32_16x16x32_bf16 v[74:77], v[166:169], v[228:231], v[74:77]
	v_mfma_f32_16x16x32_bf16 v[70:73], v[174:177], v[228:231], v[70:73]
	v_mfma_f32_16x16x32_bf16 v[122:125], v[170:173], v[186:189], v[122:125]
	v_mfma_f32_16x16x32_bf16 v[118:121], v[178:181], v[186:189], v[118:121]
	v_mfma_f32_16x16x32_bf16 v[106:109], v[170:173], v[194:197], v[106:109]
	v_mfma_f32_16x16x32_bf16 v[102:105], v[178:181], v[194:197], v[102:105]
	v_mfma_f32_16x16x32_bf16 v[90:93], v[170:173], v[224:227], v[90:93]
	v_mfma_f32_16x16x32_bf16 v[86:89], v[178:181], v[224:227], v[86:89]
	v_mfma_f32_16x16x32_bf16 v[74:77], v[170:173], v[232:235], v[74:77]
	v_mfma_f32_16x16x32_bf16 v[70:73], v[178:181], v[232:235], v[70:73]
	s_setprio 0
	s_barrier
	s_add_u32 s100, s48, 0x80
	s_addc_u32 s101, s49, 0
	s_add_i32 s50, s68, s37
	s_mov_b32 m0, s50
	ds_read_b128 v[182:185], v148 offset:49152
	ds_read_b128 v[186:189], v148 offset:50176
	ds_read_b128 v[190:193], v148 offset:51200
	ds_read_b128 v[194:197], v148 offset:52224
	ds_read_b128 v[206:209], v148 offset:53248
	ds_read_b128 v[224:227], v148 offset:54272
	ds_read_b128 v[228:231], v148 offset:55296
	ds_read_b128 v[232:235], v148 offset:56320
	global_load_lds_dwordx4 v138, s[100:101]
	s_add_i32 m0, s50, 0x2000
	s_add_u32 s48, s48, 0x80080
	s_addc_u32 s49, s49, 0
	s_add_i32 s50, s69, s37
	global_load_lds_dwordx4 v134, s[100:101]
	s_mov_b32 m0, s50
	s_nop 0
	global_load_lds_dwordx4 v138, s[48:49]
	s_add_i32 m0, s50, 0x2000
	s_nop 0
	global_load_lds_dwordx4 v134, s[48:49]
	s_waitcnt vmcnt(6)
	s_waitcnt lgkmcnt(0)
	s_barrier
	s_setprio 1
	s_waitcnt lgkmcnt(0)
	v_mfma_f32_16x16x32_bf16 v[66:69], v[150:153], v[182:185], v[66:69]
	v_mfma_f32_16x16x32_bf16 v[62:65], v[158:161], v[182:185], v[62:65]
	v_mfma_f32_16x16x32_bf16 v[50:53], v[150:153], v[190:193], v[50:53]
	v_mfma_f32_16x16x32_bf16 v[46:49], v[158:161], v[190:193], v[46:49]
	v_mfma_f32_16x16x32_bf16 v[34:37], v[150:153], v[206:209], v[34:37]
	v_mfma_f32_16x16x32_bf16 v[30:33], v[158:161], v[206:209], v[30:33]
	v_mfma_f32_16x16x32_bf16 v[18:21], v[150:153], v[228:231], v[18:21]
	v_mfma_f32_16x16x32_bf16 v[14:17], v[158:161], v[228:231], v[14:17]
	v_mfma_f32_16x16x32_bf16 v[66:69], v[154:157], v[186:189], v[66:69]
	v_mfma_f32_16x16x32_bf16 v[62:65], v[162:165], v[186:189], v[62:65]
	v_mfma_f32_16x16x32_bf16 v[50:53], v[154:157], v[194:197], v[50:53]
	v_mfma_f32_16x16x32_bf16 v[46:49], v[162:165], v[194:197], v[46:49]
	v_mfma_f32_16x16x32_bf16 v[34:37], v[154:157], v[224:227], v[34:37]
	v_mfma_f32_16x16x32_bf16 v[30:33], v[162:165], v[224:227], v[30:33]
	v_mfma_f32_16x16x32_bf16 v[18:21], v[154:157], v[232:235], v[18:21]
	v_mfma_f32_16x16x32_bf16 v[14:17], v[162:165], v[232:235], v[14:17]
	v_mfma_f32_16x16x32_bf16 v[58:61], v[166:169], v[182:185], v[58:61]
	v_mfma_f32_16x16x32_bf16 v[54:57], v[174:177], v[182:185], v[54:57]
	v_mfma_f32_16x16x32_bf16 v[42:45], v[166:169], v[190:193], v[42:45]
	v_mfma_f32_16x16x32_bf16 v[38:41], v[174:177], v[190:193], v[38:41]
	v_mfma_f32_16x16x32_bf16 v[26:29], v[166:169], v[206:209], v[26:29]
	v_mfma_f32_16x16x32_bf16 v[22:25], v[174:177], v[206:209], v[22:25]
	v_mfma_f32_16x16x32_bf16 v[8:11], v[166:169], v[228:231], v[10:13]
	v_mfma_f32_16x16x32_bf16 v[4:7], v[174:177], v[228:231], v[4:7]
	v_mfma_f32_16x16x32_bf16 v[58:61], v[170:173], v[186:189], v[58:61]
	v_mfma_f32_16x16x32_bf16 v[54:57], v[178:181], v[186:189], v[54:57]
	v_mfma_f32_16x16x32_bf16 v[42:45], v[170:173], v[194:197], v[42:45]
	v_mfma_f32_16x16x32_bf16 v[38:41], v[178:181], v[194:197], v[38:41]
	v_mfma_f32_16x16x32_bf16 v[26:29], v[170:173], v[224:227], v[26:29]
	v_mfma_f32_16x16x32_bf16 v[22:25], v[178:181], v[224:227], v[22:25]
	v_mfma_f32_16x16x32_bf16 v[10:13], v[170:173], v[232:235], v[8:11]
	v_mfma_f32_16x16x32_bf16 v[6:9], v[178:181], v[232:235], v[4:7]
	s_setprio 0
	s_barrier
	s_add_u32 s46, s46, 0x100
	s_addc_u32 s47, s47, 0
	s_add_u32 s65, s65, 0x100
	s_addc_u32 s66, s66, 0
	s_cmp_ge_i32 s67, s56
	s_mov_b32 s48, s67
	s_cbranch_scc0 .LBB0_1311

; #define PG8_STAGE(bufoff, gbase, voff) do { _Pragma("unroll") for (int _i = 0; _i < 2; ++_i) \
;         __builtin_amdgcn_global_load_lds((const unsigned*)((const char*)(gbase) + (voff)[_i]), (LAS unsigned*)(lds + (bufoff) + ldsw + _i * 8192), 16, 0, 0); } while (0)
; #define PG8_LDA(dst, b, h) do { _Pragma("unroll") for (int m = 0; m < 4; ++m) _Pragma("unroll") for (int k = 0; k < 2; ++k) dst[m][k] = *(const LAS bf16x8*)(lds + PG8_SA(b, h) + aoff + m * 2048 + k * 1024); } while (0)
; #define PG8_LDB(dst, b, h) do { _Pragma("unroll") for (int n = 0; n < 2; ++n) _Pragma("unroll") for (int k = 0; k < 2; ++k) dst[n][k] = *(const LAS bf16x8*)(lds + PG8_SB(b, h) + boff + n * 2048 + k * 1024); } while (0)
; #define PG8_MMA(ai, bj, At, Bt) do { __builtin_amdgcn_s_setprio(1); _Pragma("unroll") for (int m = 0; m < 4; ++m) _Pragma("unroll") for (int n = 0; n < 2; ++n) _Pragma("unroll") for (int k = 0; k < 2; ++k) \
;         acc[ai][bj][m][n] = __builtin_amdgcn_mfma_f32_16x16x32_bf16(Bt[n][k], At[m][k], acc[ai][bj][m][n], 0, 0, 0); __builtin_amdgcn_s_setprio(0); } while (0)
; template <class Epi, bool ALIGN_EPI = true>
; __device__ __forceinline__ void gemm_phase(LAS unsigned char* lds, const Gemm g, const Sched& S, const Epi& E) {
;     ...
;         for (int t = t_lo; t < t_hi; t += 2) {
;             const bool last = (t == nt - 2);
;             const char* a1 = cA + (size_t)(t + 1) * kstep;
;             const char* a2 = last ? nA : cA + (size_t)(t + 2) * kstep; const char* b2 = last ? nB : cB + (size_t)(t + 2) * kstep;
;             const char* a3 = a2 + kstep; const char* b3 = b2 + kstep;
;             const int rflag = __builtin_amdgcn_readfirstlane(t | (int)(ui == 0));
;             PG8_LDB(B0, 0, 0); PG8_LDB(B1, 0, 1); PG8_SCHED; PG8_LDA(At, 0, 0); PG8_STAGE(PG8_SA(1, 1), a1 + hstepA, voffA);
;             if constexpr (Epi::NSTORES > 0) PG8_WAIT_RELAX(rflag, 8 + Epi::NSTORES); else PG8_WAIT_V(8);
;             PG8_WAIT_L(0); PG8_BAR; PG8_MMA(0, 0, At, B0); PG8_MMA(0, 1, At, B1); PG8_BAR; PG8_SCHED;
;             PG8_LDA(At, 0, 1); PG8_STAGE(PG8_SB(0, 0), b2, voffB); PG8_STAGE(PG8_SB(0, 1), b2 + hstepB, voffB); PG8_STAGE(PG8_SA(0, 0), a2, voffA);
;             if constexpr (Epi::NSTORES > 0) PG8_WAIT_RELAX(rflag, 8 + Epi::NSTORES); else PG8_WAIT_V(8);
;             PG8_WAIT_L(0); PG8_BAR; PG8_MMA(1, 0, At, B0); PG8_MMA(1, 1, At, B1); PG8_BAR; PG8_SCHED;
.LBB0_1402:
	s_add_i32 s67, s46, 2
	s_add_u32 s47, s44, 0xfff80080
	s_addc_u32 s48, s45, -1
	s_add_i32 s68, 0, 0x10000
	s_cmp_eq_u32 s59, s46
	s_cselect_b32 s49, s19, s48
	s_cselect_b32 s48, s21, s47
	v_add_u32_e32 v2, s68, v147
	s_cselect_b32 s47, s63, s66
	s_cselect_b32 s46, s64, s65
	s_add_i32 s70, 0, 0x14000
	ds_read_b128 v[150:153], v2
	ds_read_b128 v[154:157], v2 offset:1024
	ds_read_b128 v[158:161], v2 offset:2048
	ds_read_b128 v[162:165], v2 offset:3072
	v_add_u32_e32 v2, s70, v147
	ds_read_b128 v[166:169], v2
	ds_read_b128 v[170:173], v2 offset:1024
	ds_read_b128 v[174:177], v2 offset:2048
	ds_read_b128 v[178:181], v2 offset:3072
	s_add_i32 m0, s52, 0xc000
	ds_read_b128 v[182:185], v148
	ds_read_b128 v[186:189], v148 offset:1024
	ds_read_b128 v[190:193], v148 offset:2048
	ds_read_b128 v[194:197], v148 offset:3072
	ds_read_b128 v[206:209], v148 offset:4096
	ds_read_b128 v[224:227], v148 offset:5120
	ds_read_b128 v[228:231], v148 offset:6144
	ds_read_b128 v[232:235], v148 offset:7168
	s_add_u32 s100, s44, 0xfff80000
	s_addc_u32 s101, s45, -1
	s_mov_b32 m0, s57
	s_nop 0
	global_load_lds_dwordx4 v142, s[100:101]
	s_mov_b32 m0, s58
	s_nop 0
	global_load_lds_dwordx4 v144, s[100:101]
	s_add_i32 m0, s52, 0xc000
	s_nop 0
	global_load_lds_dwordx4 v142, s[44:45]
	s_add_i32 m0, s52, 0xe000
	s_nop 0
	global_load_lds_dwordx4 v144, s[44:45]
	s_waitcnt vmcnt(8)
	s_waitcnt lgkmcnt(0)
	s_barrier
	s_setprio 1
	s_waitcnt lgkmcnt(0)
	v_mfma_f32_16x16x32_bf16 v[130:133], v[150:153], v[182:185], v[130:133]
	v_mfma_f32_16x16x32_bf16 v[126:129], v[158:161], v[182:185], v[126:129]
	v_mfma_f32_16x16x32_bf16 v[114:117], v[150:153], v[190:193], v[114:117]
	v_mfma_f32_16x16x32_bf16 v[110:113], v[158:161], v[190:193], v[110:113]
	v_mfma_f32_16x16x32_bf16 v[98:101], v[150:153], v[206:209], v[98:101]
	v_mfma_f32_16x16x32_bf16 v[94:97], v[158:161], v[206:209], v[94:97]
	v_mfma_f32_16x16x32_bf16 v[82:85], v[150:153], v[228:231], v[82:85]
	v_mfma_f32_16x16x32_bf16 v[78:81], v[158:161], v[228:231], v[78:81]
	v_mfma_f32_16x16x32_bf16 v[130:133], v[154:157], v[186:189], v[130:133]
	v_mfma_f32_16x16x32_bf16 v[126:129], v[162:165], v[186:189], v[126:129]
	v_mfma_f32_16x16x32_bf16 v[114:117], v[154:157], v[194:197], v[114:117]
	v_mfma_f32_16x16x32_bf16 v[110:113], v[162:165], v[194:197], v[110:113]
	v_mfma_f32_16x16x32_bf16 v[98:101], v[154:157], v[224:227], v[98:101]
	v_mfma_f32_16x16x32_bf16 v[94:97], v[162:165], v[224:227], v[94:97]
	v_mfma_f32_16x16x32_bf16 v[82:85], v[154:157], v[232:235], v[82:85]
	v_mfma_f32_16x16x32_bf16 v[78:81], v[162:165], v[232:235], v[78:81]
	v_mfma_f32_16x16x32_bf16 v[122:125], v[166:169], v[182:185], v[122:125]
	v_mfma_f32_16x16x32_bf16 v[118:121], v[174:177], v[182:185], v[118:121]
	v_mfma_f32_16x16x32_bf16 v[106:109], v[166:169], v[190:193], v[106:109]
	v_mfma_f32_16x16x32_bf16 v[102:105], v[174:177], v[190:193], v[102:105]
	v_mfma_f32_16x16x32_bf16 v[90:93], v[166:169], v[206:209], v[90:93]
	v_mfma_f32_16x16x32_bf16 v[86:89], v[174:177], v[206:209], v[86:89]
	v_mfma_f32_16x16x32_bf16 v[74:77], v[166:169], v[228:231], v[74:77]
	v_mfma_f32_16x16x32_bf16 v[70:73], v[174:177], v[228:231], v[70:73]
	v_mfma_f32_16x16x32_bf16 v[122:125], v[170:173], v[186:189], v[122:125]
	v_mfma_f32_16x16x32_bf16 v[118:121], v[178:181], v[186:189], v[118:121]
	v_mfma_f32_16x16x32_bf16 v[106:109], v[170:173], v[194:197], v[106:109]
	v_mfma_f32_16x16x32_bf16 v[102:105], v[178:181], v[194:197], v[102:105]
	v_mfma_f32_16x16x32_bf16 v[90:93], v[170:173], v[224:227], v[90:93]
	v_mfma_f32_16x16x32_bf16 v[86:89], v[178:181], v[224:227], v[86:89]
	v_mfma_f32_16x16x32_bf16 v[74:77], v[170:173], v[232:235], v[74:77]
	v_mfma_f32_16x16x32_bf16 v[70:73], v[178:181], v[232:235], v[70:73]
	s_setprio 0
	s_barrier
	s_add_i32 s68, s68, s51
	s_mov_b32 m0, s68
	ds_read_b128 v[182:185], v148 offset:16384
	ds_read_b128 v[186:189], v148 offset:17408
	ds_read_b128 v[190:193], v148 offset:18432
	ds_read_b128 v[194:197], v148 offset:19456
	ds_read_b128 v[206:209], v148 offset:20480
	ds_read_b128 v[224:227], v148 offset:21504
	ds_read_b128 v[228:231], v148 offset:22528
	ds_read_b128 v[232:235], v148 offset:23552
	global_load_lds_dwordx4 v138, s[46:47]
	s_add_i32 m0, s68, 0x2000
	s_add_u32 s68, s46, 0x80000
	s_addc_u32 s69, s47, 0
	s_add_i32 s70, s70, s51
	global_load_lds_dwordx4 v134, s[46:47]
	s_mov_b32 m0, s70
	s_nop 0
	global_load_lds_dwordx4 v138, s[68:69]
	s_add_i32 m0, s70, 0x2000
	s_nop 0
	global_load_lds_dwordx4 v134, s[68:69]
	s_waitcnt vmcnt(6)
	s_waitcnt lgkmcnt(0)
	s_barrier
; #define PG8_STAGE(bufoff, gbase, voff) do { _Pragma("unroll") for (int _i = 0; _i < 2; ++_i) \
;         __builtin_amdgcn_global_load_lds((const unsigned*)((const char*)(gbase) + (voff)[_i]), (LAS unsigned*)(lds + (bufoff) + ldsw + _i * 8192), 16, 0, 0); } while (0)
; #define PG8_LDA(dst, b, h) do { _Pragma("unroll") for (int m = 0; m < 4; ++m) _Pragma("unroll") for (int k = 0; k < 2; ++k) dst[m][k] = *(const LAS bf16x8*)(lds + PG8_SA(b, h) + aoff + m * 2048 + k * 1024); } while (0)
; #define PG8_LDB(dst, b, h) do { _Pragma("unroll") for (int n = 0; n < 2; ++n) _Pragma("unroll") for (int k = 0; k < 2; ++k) dst[n][k] = *(const LAS bf16x8*)(lds + PG8_SB(b, h) + boff + n * 2048 + k * 1024); } while (0)
; #define PG8_MMA(ai, bj, At, Bt) do { __builtin_amdgcn_s_setprio(1); _Pragma("unroll") for (int m = 0; m < 4; ++m) _Pragma("unroll") for (int n = 0; n < 2; ++n) _Pragma("unroll") for (int k = 0; k < 2; ++k) \
;         acc[ai][bj][m][n] = __builtin_amdgcn_mfma_f32_16x16x32_bf16(Bt[n][k], At[m][k], acc[ai][bj][m][n], 0, 0, 0); __builtin_amdgcn_s_setprio(0); } while (0)
; #define PG8_WAIT_V(n) asm volatile("s_waitcnt vmcnt(" #n ")" ::: "memory")
; #define PG8_WAIT_L(n) asm volatile("s_waitcnt lgkmcnt(" #n ")" ::: "memory")
; #define PG8_BAR __builtin_amdgcn_s_barrier()
; #define PG8_WAIT_RELAX(flag, n) asm volatile("s_cmp_eq_u32 %0, 0\n\ts_cbranch_scc1 .Lrw%=\n\ts_waitcnt vmcnt(8)\n.Lrw%=:\n\ts_waitcnt vmcnt(%1)" :: "s"(flag), "n"(n) : "scc", "memory")
; #define PG8_SCHED __builtin_amdgcn_sched_barrier(0)
; template <class Epi, bool ALIGN_EPI = true>
; __device__ __forceinline__ void gemm_phase(LAS unsigned char* lds, const Gemm g, const Sched& S, const Epi& E) {
;     ...
;             PG8_WAIT_L(0); PG8_BAR; PG8_MMA(0, 0, At, B0); PG8_MMA(0, 1, At, B1); PG8_BAR; PG8_SCHED;
;             PG8_LDA(At, 0, 1); PG8_STAGE(PG8_SB(0, 0), b2, voffB); PG8_STAGE(PG8_SB(0, 1), b2 + hstepB, voffB); PG8_STAGE(PG8_SA(0, 0), a2, voffA);
;             if constexpr (Epi::NSTORES > 0) PG8_WAIT_RELAX(rflag, 8 + Epi::NSTORES); else PG8_WAIT_V(8);
;             PG8_WAIT_L(0); PG8_BAR; PG8_MMA(1, 0, At, B0); PG8_MMA(1, 1, At, B1); PG8_BAR; PG8_SCHED;
;             PG8_LDB(B0, 1, 0); PG8_LDB(B1, 1, 1); PG8_SCHED; PG8_LDA(At, 1, 0); PG8_STAGE(PG8_SA(0, 1), a2 + hstepA, voffA);
;             PG8_WAIT_V(8); PG8_WAIT_L(0); PG8_BAR; PG8_MMA(0, 0, At, B0); PG8_MMA(0, 1, At, B1); PG8_BAR; PG8_SCHED;
	s_setprio 1
	s_waitcnt lgkmcnt(0)
	v_mfma_f32_16x16x32_bf16 v[66:69], v[150:153], v[182:185], v[66:69]
	v_mfma_f32_16x16x32_bf16 v[62:65], v[158:161], v[182:185], v[62:65]
	v_mfma_f32_16x16x32_bf16 v[50:53], v[150:153], v[190:193], v[50:53]
	v_mfma_f32_16x16x32_bf16 v[46:49], v[158:161], v[190:193], v[46:49]
	v_mfma_f32_16x16x32_bf16 v[34:37], v[150:153], v[206:209], v[34:37]
	v_mfma_f32_16x16x32_bf16 v[30:33], v[158:161], v[206:209], v[30:33]
	v_mfma_f32_16x16x32_bf16 v[18:21], v[150:153], v[228:231], v[18:21]
	v_mfma_f32_16x16x32_bf16 v[14:17], v[158:161], v[228:231], v[14:17]
	v_mfma_f32_16x16x32_bf16 v[66:69], v[154:157], v[186:189], v[66:69]
	v_mfma_f32_16x16x32_bf16 v[62:65], v[162:165], v[186:189], v[62:65]
	v_mfma_f32_16x16x32_bf16 v[50:53], v[154:157], v[194:197], v[50:53]
	v_mfma_f32_16x16x32_bf16 v[46:49], v[162:165], v[194:197], v[46:49]
	v_mfma_f32_16x16x32_bf16 v[34:37], v[154:157], v[224:227], v[34:37]
	v_mfma_f32_16x16x32_bf16 v[30:33], v[162:165], v[224:227], v[30:33]
	v_mfma_f32_16x16x32_bf16 v[18:21], v[154:157], v[232:235], v[18:21]
	v_mfma_f32_16x16x32_bf16 v[14:17], v[162:165], v[232:235], v[14:17]
	v_mfma_f32_16x16x32_bf16 v[58:61], v[166:169], v[182:185], v[58:61]
	v_mfma_f32_16x16x32_bf16 v[54:57], v[174:177], v[182:185], v[54:57]
	v_mfma_f32_16x16x32_bf16 v[42:45], v[166:169], v[190:193], v[42:45]
	v_mfma_f32_16x16x32_bf16 v[38:41], v[174:177], v[190:193], v[38:41]
	v_mfma_f32_16x16x32_bf16 v[26:29], v[166:169], v[206:209], v[26:29]
	v_mfma_f32_16x16x32_bf16 v[22:25], v[174:177], v[206:209], v[22:25]
	v_mfma_f32_16x16x32_bf16 v[10:13], v[166:169], v[228:231], v[10:13]
	v_mfma_f32_16x16x32_bf16 v[4:7], v[174:177], v[228:231], v[6:9]
	v_mfma_f32_16x16x32_bf16 v[58:61], v[170:173], v[186:189], v[58:61]
	v_mfma_f32_16x16x32_bf16 v[54:57], v[178:181], v[186:189], v[54:57]
	v_mfma_f32_16x16x32_bf16 v[42:45], v[170:173], v[194:197], v[42:45]
	v_mfma_f32_16x16x32_bf16 v[38:41], v[178:181], v[194:197], v[38:41]
	v_mfma_f32_16x16x32_bf16 v[26:29], v[170:173], v[224:227], v[26:29]
	v_mfma_f32_16x16x32_bf16 v[22:25], v[178:181], v[224:227], v[22:25]
	v_mfma_f32_16x16x32_bf16 v[10:13], v[170:173], v[232:235], v[10:13]
	v_mfma_f32_16x16x32_bf16 v[4:7], v[178:181], v[232:235], v[4:7]
	s_setprio 0
	s_barrier
	s_add_i32 s68, 0, 0x18000
	v_add_u32_e32 v2, s68, v147
	s_add_i32 s69, 0, 0x1c000
	ds_read_b128 v[150:153], v2
	ds_read_b128 v[154:157], v2 offset:1024
	ds_read_b128 v[158:161], v2 offset:2048
	ds_read_b128 v[162:165], v2 offset:3072
	v_add_u32_e32 v2, s69, v147
	ds_read_b128 v[166:169], v2
	ds_read_b128 v[170:173], v2 offset:1024
	ds_read_b128 v[174:177], v2 offset:2048
	ds_read_b128 v[178:181], v2 offset:3072
	s_add_u32 s48, s48, 0x80000
	s_addc_u32 s49, s49, 0
	s_mov_b32 m0, s54
	ds_read_b128 v[182:185], v148 offset:32768
	ds_read_b128 v[186:189], v148 offset:33792
	ds_read_b128 v[190:193], v148 offset:34816
	ds_read_b128 v[194:197], v148 offset:35840
	ds_read_b128 v[206:209], v148 offset:36864
	ds_read_b128 v[224:227], v148 offset:37888
	ds_read_b128 v[228:231], v148 offset:38912
	ds_read_b128 v[232:235], v148 offset:39936
	s_add_u32 s100, s48, 0xfff80000
	s_addc_u32 s101, s49, -1
	s_mov_b32 m0, s52
	s_nop 0
	global_load_lds_dwordx4 v140, s[100:101]
	s_mov_b32 m0, s53
	s_nop 0
	global_load_lds_dwordx4 v136, s[100:101]
	s_mov_b32 m0, s54
	s_nop 0
	global_load_lds_dwordx4 v140, s[48:49]
	s_mov_b32 m0, s55
	s_nop 0
	global_load_lds_dwordx4 v136, s[48:49]
	s_waitcnt vmcnt(8)
	s_waitcnt lgkmcnt(0)
	s_barrier
; #define PG8_STAGE(bufoff, gbase, voff) do { _Pragma("unroll") for (int _i = 0; _i < 2; ++_i) \
;         __builtin_amdgcn_global_load_lds((const unsigned*)((const char*)(gbase) + (voff)[_i]), (LAS unsigned*)(lds + (bufoff) + ldsw + _i * 8192), 16, 0, 0); } while (0)
; #define PG8_LDA(dst, b, h) do { _Pragma("unroll") for (int m = 0; m < 4; ++m) _Pragma("unroll") for (int k = 0; k < 2; ++k) dst[m][k] = *(const LAS bf16x8*)(lds + PG8_SA(b, h) + aoff + m * 2048 + k * 1024); } while (0)
; #define PG8_MMA(ai, bj, At, Bt) do { __builtin_amdgcn_s_setprio(1); _Pragma("unroll") for (int m = 0; m < 4; ++m) _Pragma("unroll") for (int n = 0; n < 2; ++n) _Pragma("unroll") for (int k = 0; k < 2; ++k) \
;         acc[ai][bj][m][n] = __builtin_amdgcn_mfma_f32_16x16x32_bf16(Bt[n][k], At[m][k], acc[ai][bj][m][n], 0, 0, 0); __builtin_amdgcn_s_setprio(0); } while (0)
; #define PG8_WAIT_V(n) asm volatile("s_waitcnt vmcnt(" #n ")" ::: "memory")
; #define PG8_WAIT_L(n) asm volatile("s_waitcnt lgkmcnt(" #n ")" ::: "memory")
; #define PG8_BAR __builtin_amdgcn_s_barrier()
; #define PG8_SCHED __builtin_amdgcn_sched_barrier(0)
; template <class Epi, bool ALIGN_EPI = true>
; __device__ __forceinline__ void gemm_phase(LAS unsigned char* lds, const Gemm g, const Sched& S, const Epi& E) {
;     ...
;             PG8_WAIT_V(8); PG8_WAIT_L(0); PG8_BAR; PG8_MMA(0, 0, At, B0); PG8_MMA(0, 1, At, B1); PG8_BAR; PG8_SCHED;
;             PG8_LDA(At, 1, 1); PG8_STAGE(PG8_SB(1, 0), b3, voffB); PG8_STAGE(PG8_SB(1, 1), b3 + hstepB, voffB); PG8_STAGE(PG8_SA(1, 0), a3, voffA);
;             PG8_WAIT_V(8); PG8_WAIT_L(0); PG8_BAR; PG8_MMA(1, 0, At, B0); PG8_MMA(1, 1, At, B1); PG8_BAR; PG8_SCHED;
	s_setprio 1
	s_waitcnt lgkmcnt(0)
	v_mfma_f32_16x16x32_bf16 v[130:133], v[150:153], v[182:185], v[130:133]
	v_mfma_f32_16x16x32_bf16 v[126:129], v[158:161], v[182:185], v[126:129]
	v_mfma_f32_16x16x32_bf16 v[114:117], v[150:153], v[190:193], v[114:117]
	v_mfma_f32_16x16x32_bf16 v[110:113], v[158:161], v[190:193], v[110:113]
	v_mfma_f32_16x16x32_bf16 v[98:101], v[150:153], v[206:209], v[98:101]
	v_mfma_f32_16x16x32_bf16 v[94:97], v[158:161], v[206:209], v[94:97]
	v_mfma_f32_16x16x32_bf16 v[82:85], v[150:153], v[228:231], v[82:85]
	v_mfma_f32_16x16x32_bf16 v[78:81], v[158:161], v[228:231], v[78:81]
	v_mfma_f32_16x16x32_bf16 v[130:133], v[154:157], v[186:189], v[130:133]
	v_mfma_f32_16x16x32_bf16 v[126:129], v[162:165], v[186:189], v[126:129]
	v_mfma_f32_16x16x32_bf16 v[114:117], v[154:157], v[194:197], v[114:117]
	v_mfma_f32_16x16x32_bf16 v[110:113], v[162:165], v[194:197], v[110:113]
	v_mfma_f32_16x16x32_bf16 v[98:101], v[154:157], v[224:227], v[98:101]
	v_mfma_f32_16x16x32_bf16 v[94:97], v[162:165], v[224:227], v[94:97]
	v_mfma_f32_16x16x32_bf16 v[82:85], v[154:157], v[232:235], v[82:85]
	v_mfma_f32_16x16x32_bf16 v[78:81], v[162:165], v[232:235], v[78:81]
	v_mfma_f32_16x16x32_bf16 v[122:125], v[166:169], v[182:185], v[122:125]
	v_mfma_f32_16x16x32_bf16 v[118:121], v[174:177], v[182:185], v[118:121]
	v_mfma_f32_16x16x32_bf16 v[106:109], v[166:169], v[190:193], v[106:109]
	v_mfma_f32_16x16x32_bf16 v[102:105], v[174:177], v[190:193], v[102:105]
	v_mfma_f32_16x16x32_bf16 v[90:93], v[166:169], v[206:209], v[90:93]
	v_mfma_f32_16x16x32_bf16 v[86:89], v[174:177], v[206:209], v[86:89]
	v_mfma_f32_16x16x32_bf16 v[74:77], v[166:169], v[228:231], v[74:77]
	v_mfma_f32_16x16x32_bf16 v[70:73], v[174:177], v[228:231], v[70:73]
	v_mfma_f32_16x16x32_bf16 v[122:125], v[170:173], v[186:189], v[122:125]
	v_mfma_f32_16x16x32_bf16 v[118:121], v[178:181], v[186:189], v[118:121]
	v_mfma_f32_16x16x32_bf16 v[106:109], v[170:173], v[194:197], v[106:109]
	v_mfma_f32_16x16x32_bf16 v[102:105], v[178:181], v[194:197], v[102:105]
	v_mfma_f32_16x16x32_bf16 v[90:93], v[170:173], v[224:227], v[90:93]
	v_mfma_f32_16x16x32_bf16 v[86:89], v[178:181], v[224:227], v[86:89]
	v_mfma_f32_16x16x32_bf16 v[74:77], v[170:173], v[232:235], v[74:77]
	v_mfma_f32_16x16x32_bf16 v[70:73], v[178:181], v[232:235], v[70:73]
	s_setprio 0
	s_barrier
	s_add_u32 s100, s46, 0x80
	s_addc_u32 s101, s47, 0
	s_add_i32 s48, s68, s51
	s_mov_b32 m0, s48
	ds_read_b128 v[182:185], v148 offset:49152
	ds_read_b128 v[186:189], v148 offset:50176
	ds_read_b128 v[190:193], v148 offset:51200
	ds_read_b128 v[194:197], v148 offset:52224
	ds_read_b128 v[206:209], v148 offset:53248
	ds_read_b128 v[224:227], v148 offset:54272
	ds_read_b128 v[228:231], v148 offset:55296
	ds_read_b128 v[232:235], v148 offset:56320
	global_load_lds_dwordx4 v138, s[100:101]
	s_add_i32 m0, s48, 0x2000
	s_add_u32 s46, s46, 0x80080
	s_addc_u32 s47, s47, 0
	s_add_i32 s48, s69, s51
	global_load_lds_dwordx4 v134, s[100:101]
	s_mov_b32 m0, s48
	s_nop 0
	global_load_lds_dwordx4 v138, s[46:47]
	s_add_i32 m0, s48, 0x2000
	s_nop 0
	global_load_lds_dwordx4 v134, s[46:47]
	s_waitcnt vmcnt(6)
	s_waitcnt lgkmcnt(0)
	s_barrier
	s_setprio 1
	s_waitcnt lgkmcnt(0)
	v_mfma_f32_16x16x32_bf16 v[66:69], v[150:153], v[182:185], v[66:69]
	v_mfma_f32_16x16x32_bf16 v[62:65], v[158:161], v[182:185], v[62:65]
	v_mfma_f32_16x16x32_bf16 v[50:53], v[150:153], v[190:193], v[50:53]
	v_mfma_f32_16x16x32_bf16 v[46:49], v[158:161], v[190:193], v[46:49]
	v_mfma_f32_16x16x32_bf16 v[34:37], v[150:153], v[206:209], v[34:37]
	v_mfma_f32_16x16x32_bf16 v[30:33], v[158:161], v[206:209], v[30:33]
	v_mfma_f32_16x16x32_bf16 v[18:21], v[150:153], v[228:231], v[18:21]
	v_mfma_f32_16x16x32_bf16 v[14:17], v[158:161], v[228:231], v[14:17]
	v_mfma_f32_16x16x32_bf16 v[66:69], v[154:157], v[186:189], v[66:69]
	v_mfma_f32_16x16x32_bf16 v[62:65], v[162:165], v[186:189], v[62:65]
	v_mfma_f32_16x16x32_bf16 v[50:53], v[154:157], v[194:197], v[50:53]
	v_mfma_f32_16x16x32_bf16 v[46:49], v[162:165], v[194:197], v[46:49]
	v_mfma_f32_16x16x32_bf16 v[34:37], v[154:157], v[224:227], v[34:37]
	v_mfma_f32_16x16x32_bf16 v[30:33], v[162:165], v[224:227], v[30:33]
	v_mfma_f32_16x16x32_bf16 v[18:21], v[154:157], v[232:235], v[18:21]
	v_mfma_f32_16x16x32_bf16 v[14:17], v[162:165], v[232:235], v[14:17]
	v_mfma_f32_16x16x32_bf16 v[58:61], v[166:169], v[182:185], v[58:61]
	v_mfma_f32_16x16x32_bf16 v[54:57], v[174:177], v[182:185], v[54:57]
	v_mfma_f32_16x16x32_bf16 v[42:45], v[166:169], v[190:193], v[42:45]
	v_mfma_f32_16x16x32_bf16 v[38:41], v[174:177], v[190:193], v[38:41]
	v_mfma_f32_16x16x32_bf16 v[26:29], v[166:169], v[206:209], v[26:29]
	v_mfma_f32_16x16x32_bf16 v[22:25], v[174:177], v[206:209], v[22:25]
	v_mfma_f32_16x16x32_bf16 v[8:11], v[166:169], v[228:231], v[10:13]
	v_mfma_f32_16x16x32_bf16 v[4:7], v[174:177], v[228:231], v[4:7]
	v_mfma_f32_16x16x32_bf16 v[58:61], v[170:173], v[186:189], v[58:61]
	v_mfma_f32_16x16x32_bf16 v[54:57], v[178:181], v[186:189], v[54:57]
	v_mfma_f32_16x16x32_bf16 v[42:45], v[170:173], v[194:197], v[42:45]
	v_mfma_f32_16x16x32_bf16 v[38:41], v[178:181], v[194:197], v[38:41]
	v_mfma_f32_16x16x32_bf16 v[26:29], v[170:173], v[224:227], v[26:29]
	v_mfma_f32_16x16x32_bf16 v[22:25], v[178:181], v[224:227], v[22:25]
	v_mfma_f32_16x16x32_bf16 v[10:13], v[170:173], v[232:235], v[8:11]
	v_mfma_f32_16x16x32_bf16 v[6:9], v[178:181], v[232:235], v[4:7]
	s_setprio 0
	s_barrier
	s_add_u32 s44, s44, 0x100
	s_addc_u32 s45, s45, 0
	s_add_u32 s65, s65, 0x100
	s_addc_u32 s66, s66, 0
	s_cmp_ge_i32 s67, s56
	s_mov_b32 s46, s67
	s_cbranch_scc0 .LBB0_1402

; #define PG8_STAGE(bufoff, gbase, voff) do { _Pragma("unroll") for (int _i = 0; _i < 2; ++_i) \
;         __builtin_amdgcn_global_load_lds((const unsigned*)((const char*)(gbase) + (voff)[_i]), (LAS unsigned*)(lds + (bufoff) + ldsw + _i * 8192), 16, 0, 0); } while (0)
; #define PG8_LDA(dst, b, h) do { _Pragma("unroll") for (int m = 0; m < 4; ++m) _Pragma("unroll") for (int k = 0; k < 2; ++k) dst[m][k] = *(const LAS bf16x8*)(lds + PG8_SA(b, h) + aoff + m * 2048 + k * 1024); } while (0)
; #define PG8_LDB(dst, b, h) do { _Pragma("unroll") for (int n = 0; n < 2; ++n) _Pragma("unroll") for (int k = 0; k < 2; ++k) dst[n][k] = *(const LAS bf16x8*)(lds + PG8_SB(b, h) + boff + n * 2048 + k * 1024); } while (0)
; #define PG8_MMA(ai, bj, At, Bt) do { __builtin_amdgcn_s_setprio(1); _Pragma("unroll") for (int m = 0; m < 4; ++m) _Pragma("unroll") for (int n = 0; n < 2; ++n) _Pragma("unroll") for (int k = 0; k < 2; ++k) \
;         acc[ai][bj][m][n] = __builtin_amdgcn_mfma_f32_16x16x32_bf16(Bt[n][k], At[m][k], acc[ai][bj][m][n], 0, 0, 0); __builtin_amdgcn_s_setprio(0); } while (0)
; #define PG8_WAIT_V(n) asm volatile("s_waitcnt vmcnt(" #n ")" ::: "memory")
; #define PG8_WAIT_L(n) asm volatile("s_waitcnt lgkmcnt(" #n ")" ::: "memory")
; #define PG8_BAR __builtin_amdgcn_s_barrier()
; #define PG8_WAIT_RELAX(flag, n) asm volatile("s_cmp_eq_u32 %0, 0\n\ts_cbranch_scc1 .Lrw%=\n\ts_waitcnt vmcnt(8)\n.Lrw%=:\n\ts_waitcnt vmcnt(%1)" :: "s"(flag), "n"(n) : "scc", "memory")
; #define PG8_SCHED __builtin_amdgcn_sched_barrier(0)
; template <class Epi, bool ALIGN_EPI = true>
; __device__ __forceinline__ void gemm_phase(LAS unsigned char* lds, const Gemm g, const Sched& S, const Epi& E) {
;     ...
;             PG8_LDB(B0, 0, 0); PG8_LDB(B1, 0, 1); PG8_SCHED; PG8_LDA(At, 0, 0); PG8_STAGE(PG8_SA(1, 1), a1 + hstepA, voffA);
;             if constexpr (Epi::NSTORES > 0) PG8_WAIT_RELAX(rflag, 8 + Epi::NSTORES); else PG8_WAIT_V(8);
;             PG8_WAIT_L(0); PG8_BAR; PG8_MMA(0, 0, At, B0); PG8_MMA(0, 1, At, B1); PG8_BAR; PG8_SCHED;
;             PG8_LDA(At, 0, 1); PG8_STAGE(PG8_SB(0, 0), b2, voffB); PG8_STAGE(PG8_SB(0, 1), b2 + hstepB, voffB); PG8_STAGE(PG8_SA(0, 0), a2, voffA);
;             if constexpr (Epi::NSTORES > 0) PG8_WAIT_RELAX(rflag, 8 + Epi::NSTORES); else PG8_WAIT_V(8);
;             PG8_WAIT_L(0); PG8_BAR; PG8_MMA(1, 0, At, B0); PG8_MMA(1, 1, At, B1); PG8_BAR; PG8_SCHED;
.Lrw14:
	s_waitcnt vmcnt(24)
	s_waitcnt lgkmcnt(0)
	s_barrier
	s_setprio 1
	s_waitcnt lgkmcnt(0)
	v_mfma_f32_16x16x32_bf16 v[124:127], v[146:149], v[178:181], v[124:127]
	v_mfma_f32_16x16x32_bf16 v[128:131], v[154:157], v[178:181], v[128:131]
	v_mfma_f32_16x16x32_bf16 v[112:115], v[146:149], v[186:189], v[112:115]
	v_mfma_f32_16x16x32_bf16 v[108:111], v[154:157], v[186:189], v[108:111]
	v_mfma_f32_16x16x32_bf16 v[96:99], v[146:149], v[194:197], v[96:99]
	v_mfma_f32_16x16x32_bf16 v[92:95], v[154:157], v[194:197], v[92:95]
	v_mfma_f32_16x16x32_bf16 v[80:83], v[146:149], v[224:227], v[80:83]
	v_mfma_f32_16x16x32_bf16 v[76:79], v[154:157], v[224:227], v[76:79]
	v_mfma_f32_16x16x32_bf16 v[124:127], v[150:153], v[182:185], v[124:127]
	v_mfma_f32_16x16x32_bf16 v[128:131], v[158:161], v[182:185], v[128:131]
	v_mfma_f32_16x16x32_bf16 v[112:115], v[150:153], v[190:193], v[112:115]
	v_mfma_f32_16x16x32_bf16 v[108:111], v[158:161], v[190:193], v[108:111]
	v_mfma_f32_16x16x32_bf16 v[96:99], v[150:153], v[206:209], v[96:99]
	v_mfma_f32_16x16x32_bf16 v[92:95], v[158:161], v[206:209], v[92:95]
	v_mfma_f32_16x16x32_bf16 v[80:83], v[150:153], v[228:231], v[80:83]
	v_mfma_f32_16x16x32_bf16 v[76:79], v[158:161], v[228:231], v[76:79]
	v_mfma_f32_16x16x32_bf16 v[120:123], v[162:165], v[178:181], v[120:123]
	v_mfma_f32_16x16x32_bf16 v[116:119], v[170:173], v[178:181], v[116:119]
	v_mfma_f32_16x16x32_bf16 v[104:107], v[162:165], v[186:189], v[104:107]
	v_mfma_f32_16x16x32_bf16 v[100:103], v[170:173], v[186:189], v[100:103]
	v_mfma_f32_16x16x32_bf16 v[88:91], v[162:165], v[194:197], v[88:91]
	v_mfma_f32_16x16x32_bf16 v[84:87], v[170:173], v[194:197], v[84:87]
	v_mfma_f32_16x16x32_bf16 v[72:75], v[162:165], v[224:227], v[72:75]
	v_mfma_f32_16x16x32_bf16 v[68:71], v[170:173], v[224:227], v[68:71]
	v_mfma_f32_16x16x32_bf16 v[120:123], v[166:169], v[182:185], v[120:123]
	v_mfma_f32_16x16x32_bf16 v[116:119], v[174:177], v[182:185], v[116:119]
	v_mfma_f32_16x16x32_bf16 v[104:107], v[166:169], v[190:193], v[104:107]
	v_mfma_f32_16x16x32_bf16 v[100:103], v[174:177], v[190:193], v[100:103]
	v_mfma_f32_16x16x32_bf16 v[88:91], v[166:169], v[206:209], v[88:91]
	v_mfma_f32_16x16x32_bf16 v[84:87], v[174:177], v[206:209], v[84:87]
	v_mfma_f32_16x16x32_bf16 v[72:75], v[166:169], v[228:231], v[72:75]
	v_mfma_f32_16x16x32_bf16 v[68:71], v[174:177], v[228:231], v[68:71]
	s_setprio 0
	s_barrier
	s_add_i32 s70, s70, s37
	s_mov_b32 m0, s70
	ds_read_b128 v[178:181], v144 offset:16384
	ds_read_b128 v[182:185], v144 offset:17408
	ds_read_b128 v[186:189], v144 offset:18432
	ds_read_b128 v[190:193], v144 offset:19456
	ds_read_b128 v[194:197], v144 offset:20480
	ds_read_b128 v[206:209], v144 offset:21504
	ds_read_b128 v[224:227], v144 offset:22528
	ds_read_b128 v[228:231], v144 offset:23552
	global_load_lds_dwordx4 v2, s[26:27]
	s_add_i32 m0, s70, 0x2000
	s_add_u32 s70, s26, 0x80000
	s_addc_u32 s71, s27, 0
	s_add_i32 s72, s72, s37
	global_load_lds_dwordx4 v132, s[26:27]
	s_mov_b32 m0, s72
	s_nop 0
	global_load_lds_dwordx4 v2, s[70:71]
	s_add_i32 m0, s72, 0x2000
	s_nop 0
	global_load_lds_dwordx4 v132, s[70:71]
	s_cmp_eq_u32 s73, 0
	s_cbranch_scc1 .Lrw15
	s_waitcnt vmcnt(6)
.Lrw15:
	s_waitcnt vmcnt(6)
	s_waitcnt lgkmcnt(0)
	s_barrier
	s_setprio 1
	s_waitcnt lgkmcnt(0)
	v_mfma_f32_16x16x32_bf16 v[64:67], v[146:149], v[178:181], v[64:67]
	v_mfma_f32_16x16x32_bf16 v[60:63], v[154:157], v[178:181], v[60:63]
	v_mfma_f32_16x16x32_bf16 v[48:51], v[146:149], v[186:189], v[48:51]
	v_mfma_f32_16x16x32_bf16 v[44:47], v[154:157], v[186:189], v[44:47]
	v_mfma_f32_16x16x32_bf16 v[32:35], v[146:149], v[194:197], v[32:35]
	v_mfma_f32_16x16x32_bf16 v[28:31], v[154:157], v[194:197], v[28:31]
	v_mfma_f32_16x16x32_bf16 v[16:19], v[146:149], v[224:227], v[16:19]
	v_mfma_f32_16x16x32_bf16 v[12:15], v[154:157], v[224:227], v[12:15]
	v_mfma_f32_16x16x32_bf16 v[64:67], v[150:153], v[182:185], v[64:67]
	v_mfma_f32_16x16x32_bf16 v[60:63], v[158:161], v[182:185], v[60:63]
	v_mfma_f32_16x16x32_bf16 v[48:51], v[150:153], v[190:193], v[48:51]
	v_mfma_f32_16x16x32_bf16 v[44:47], v[158:161], v[190:193], v[44:47]
	v_mfma_f32_16x16x32_bf16 v[32:35], v[150:153], v[206:209], v[32:35]
	v_mfma_f32_16x16x32_bf16 v[28:31], v[158:161], v[206:209], v[28:31]
	v_mfma_f32_16x16x32_bf16 v[16:19], v[150:153], v[228:231], v[16:19]
	v_mfma_f32_16x16x32_bf16 v[12:15], v[158:161], v[228:231], v[12:15]
	v_mfma_f32_16x16x32_bf16 v[56:59], v[162:165], v[178:181], v[56:59]
	v_mfma_f32_16x16x32_bf16 v[52:55], v[170:173], v[178:181], v[52:55]
	v_mfma_f32_16x16x32_bf16 v[40:43], v[162:165], v[186:189], v[40:43]
	v_mfma_f32_16x16x32_bf16 v[36:39], v[170:173], v[186:189], v[36:39]
	v_mfma_f32_16x16x32_bf16 v[24:27], v[162:165], v[194:197], v[24:27]
	v_mfma_f32_16x16x32_bf16 v[20:23], v[170:173], v[194:197], v[20:23]
	v_mfma_f32_16x16x32_bf16 v[8:11], v[162:165], v[224:227], v[8:11]
	v_mfma_f32_16x16x32_bf16 v[4:7], v[170:173], v[224:227], v[4:7]
	v_mfma_f32_16x16x32_bf16 v[56:59], v[166:169], v[182:185], v[56:59]
	v_mfma_f32_16x16x32_bf16 v[52:55], v[174:177], v[182:185], v[52:55]
	v_mfma_f32_16x16x32_bf16 v[40:43], v[166:169], v[190:193], v[40:43]
	v_mfma_f32_16x16x32_bf16 v[36:39], v[174:177], v[190:193], v[36:39]
	v_mfma_f32_16x16x32_bf16 v[24:27], v[166:169], v[206:209], v[24:27]
	v_mfma_f32_16x16x32_bf16 v[20:23], v[174:177], v[206:209], v[20:23]
	v_mfma_f32_16x16x32_bf16 v[8:11], v[166:169], v[228:231], v[8:11]
	v_mfma_f32_16x16x32_bf16 v[4:7], v[174:177], v[228:231], v[4:7]
	s_setprio 0
	s_barrier
; #define PG8_STAGE(bufoff, gbase, voff) do { _Pragma("unroll") for (int _i = 0; _i < 2; ++_i) \
;         __builtin_amdgcn_global_load_lds((const unsigned*)((const char*)(gbase) + (voff)[_i]), (LAS unsigned*)(lds + (bufoff) + ldsw + _i * 8192), 16, 0, 0); } while (0)
; #define PG8_LDA(dst, b, h) do { _Pragma("unroll") for (int m = 0; m < 4; ++m) _Pragma("unroll") for (int k = 0; k < 2; ++k) dst[m][k] = *(const LAS bf16x8*)(lds + PG8_SA(b, h) + aoff + m * 2048 + k * 1024); } while (0)
; #define PG8_LDB(dst, b, h) do { _Pragma("unroll") for (int n = 0; n < 2; ++n) _Pragma("unroll") for (int k = 0; k < 2; ++k) dst[n][k] = *(const LAS bf16x8*)(lds + PG8_SB(b, h) + boff + n * 2048 + k * 1024); } while (0)
; #define PG8_WAIT_V(n) asm volatile("s_waitcnt vmcnt(" #n ")" ::: "memory")
; #define PG8_WAIT_L(n) asm volatile("s_waitcnt lgkmcnt(" #n ")" ::: "memory")
; #define PG8_BAR __builtin_amdgcn_s_barrier()
; #define PG8_SCHED __builtin_amdgcn_sched_barrier(0)
; template <class Epi, bool ALIGN_EPI = true>
; __device__ __forceinline__ void gemm_phase(LAS unsigned char* lds, const Gemm g, const Sched& S, const Epi& E) {
;     ...
;             PG8_LDB(B0, 0, 0); PG8_LDB(B1, 0, 1); PG8_SCHED; PG8_LDA(At, 0, 0); PG8_STAGE(PG8_SA(1, 1), a1 + hstepA, voffA);
;             if constexpr (Epi::NSTORES > 0) PG8_WAIT_RELAX(rflag, 8 + Epi::NSTORES); else PG8_WAIT_V(8);
;             PG8_WAIT_L(0); PG8_BAR; PG8_MMA(0, 0, At, B0); PG8_MMA(0, 1, At, B1); PG8_BAR; PG8_SCHED;
;             PG8_LDA(At, 0, 1); PG8_STAGE(PG8_SB(0, 0), b2, voffB); PG8_STAGE(PG8_SB(0, 1), b2 + hstepB, voffB); PG8_STAGE(PG8_SA(0, 0), a2, voffA);
;             if constexpr (Epi::NSTORES > 0) PG8_WAIT_RELAX(rflag, 8 + Epi::NSTORES); else PG8_WAIT_V(8);
;             PG8_WAIT_L(0); PG8_BAR; PG8_MMA(1, 0, At, B0); PG8_MMA(1, 1, At, B1); PG8_BAR; PG8_SCHED;
;             PG8_LDB(B0, 1, 0); PG8_LDB(B1, 1, 1); PG8_SCHED; PG8_LDA(At, 1, 0); PG8_STAGE(PG8_SA(0, 1), a2 + hstepA, voffA);
;             PG8_WAIT_V(8); PG8_WAIT_L(0); PG8_BAR; PG8_MMA(0, 0, At, B0); PG8_MMA(0, 1, At, B1); PG8_BAR; PG8_SCHED;
;             PG8_LDA(At, 1, 1); PG8_STAGE(PG8_SB(1, 0), b3, voffB); PG8_STAGE(PG8_SB(1, 1), b3 + hstepB, voffB); PG8_STAGE(PG8_SA(1, 0), a3, voffA);
;             PG8_WAIT_V(8); PG8_WAIT_L(0); PG8_BAR; PG8_MMA(1, 0, At, B0); PG8_MMA(1, 1, At, B1); PG8_BAR; PG8_SCHED;
	s_add_i32 s70, 0, 0x18000
	s_add_i32 s71, 0, 0x1c000
	v_add_u32_e32 v158, s70, v143
	v_add_u32_e32 v174, s71, v143
	ds_read_b128 v[146:149], v158
	ds_read_b128 v[150:153], v158 offset:1024
	ds_read_b128 v[154:157], v158 offset:2048
	ds_read_b128 v[158:161], v158 offset:3072
	ds_read_b128 v[162:165], v174
	ds_read_b128 v[166:169], v174 offset:1024
	ds_read_b128 v[170:173], v174 offset:2048
	ds_read_b128 v[174:177], v174 offset:3072
	s_add_u32 s46, s46, 0x400000
	s_addc_u32 s47, s47, 0
	s_mov_b32 m0, s50
	ds_read_b128 v[178:181], v144 offset:32768
	ds_read_b128 v[182:185], v144 offset:33792
	ds_read_b128 v[186:189], v144 offset:34816
	ds_read_b128 v[190:193], v144 offset:35840
	ds_read_b128 v[194:197], v144 offset:36864
	ds_read_b128 v[206:209], v144 offset:37888
	ds_read_b128 v[224:227], v144 offset:38912
	ds_read_b128 v[228:231], v144 offset:39936
	s_add_u32 s100, s46, 0xffc00000
	s_addc_u32 s101, s47, -1
	s_mov_b32 m0, s48
	s_nop 0
	global_load_lds_dwordx4 v136, s[100:101]
	s_mov_b32 m0, s49
	s_nop 0
	global_load_lds_dwordx4 v134, s[100:101]
	s_mov_b32 m0, s50
	s_nop 0
	global_load_lds_dwordx4 v136, s[46:47]
	s_mov_b32 m0, s51
	s_nop 0
	global_load_lds_dwordx4 v134, s[46:47]
	s_waitcnt vmcnt(8)
	s_waitcnt lgkmcnt(0)
	s_barrier
	s_setprio 1
	s_waitcnt lgkmcnt(0)
	v_mfma_f32_16x16x32_bf16 v[124:127], v[146:149], v[178:181], v[124:127]
	v_mfma_f32_16x16x32_bf16 v[128:131], v[154:157], v[178:181], v[128:131]
	v_mfma_f32_16x16x32_bf16 v[112:115], v[146:149], v[186:189], v[112:115]
	v_mfma_f32_16x16x32_bf16 v[108:111], v[154:157], v[186:189], v[108:111]
	v_mfma_f32_16x16x32_bf16 v[96:99], v[146:149], v[194:197], v[96:99]
	v_mfma_f32_16x16x32_bf16 v[92:95], v[154:157], v[194:197], v[92:95]
	v_mfma_f32_16x16x32_bf16 v[80:83], v[146:149], v[224:227], v[80:83]
	v_mfma_f32_16x16x32_bf16 v[76:79], v[154:157], v[224:227], v[76:79]
	v_mfma_f32_16x16x32_bf16 v[124:127], v[150:153], v[182:185], v[124:127]
	v_mfma_f32_16x16x32_bf16 v[128:131], v[158:161], v[182:185], v[128:131]
	v_mfma_f32_16x16x32_bf16 v[112:115], v[150:153], v[190:193], v[112:115]
	v_mfma_f32_16x16x32_bf16 v[108:111], v[158:161], v[190:193], v[108:111]
	v_mfma_f32_16x16x32_bf16 v[96:99], v[150:153], v[206:209], v[96:99]
	v_mfma_f32_16x16x32_bf16 v[92:95], v[158:161], v[206:209], v[92:95]
	v_mfma_f32_16x16x32_bf16 v[80:83], v[150:153], v[228:231], v[80:83]
	v_mfma_f32_16x16x32_bf16 v[76:79], v[158:161], v[228:231], v[76:79]
	v_mfma_f32_16x16x32_bf16 v[120:123], v[162:165], v[178:181], v[120:123]
	v_mfma_f32_16x16x32_bf16 v[116:119], v[170:173], v[178:181], v[116:119]
	v_mfma_f32_16x16x32_bf16 v[104:107], v[162:165], v[186:189], v[104:107]
	v_mfma_f32_16x16x32_bf16 v[100:103], v[170:173], v[186:189], v[100:103]
	v_mfma_f32_16x16x32_bf16 v[88:91], v[162:165], v[194:197], v[88:91]
	v_mfma_f32_16x16x32_bf16 v[84:87], v[170:173], v[194:197], v[84:87]
	v_mfma_f32_16x16x32_bf16 v[72:75], v[162:165], v[224:227], v[72:75]
	v_mfma_f32_16x16x32_bf16 v[68:71], v[170:173], v[224:227], v[68:71]
	v_mfma_f32_16x16x32_bf16 v[120:123], v[166:169], v[182:185], v[120:123]
	v_mfma_f32_16x16x32_bf16 v[116:119], v[174:177], v[182:185], v[116:119]
	v_mfma_f32_16x16x32_bf16 v[104:107], v[166:169], v[190:193], v[104:107]
	v_mfma_f32_16x16x32_bf16 v[100:103], v[174:177], v[190:193], v[100:103]
	v_mfma_f32_16x16x32_bf16 v[88:91], v[166:169], v[206:209], v[88:91]
	v_mfma_f32_16x16x32_bf16 v[84:87], v[174:177], v[206:209], v[84:87]
	v_mfma_f32_16x16x32_bf16 v[72:75], v[166:169], v[228:231], v[72:75]
	v_mfma_f32_16x16x32_bf16 v[68:71], v[174:177], v[228:231], v[68:71]
	s_setprio 0
	s_barrier
	s_add_u32 s100, s26, 0x80
	s_addc_u32 s101, s27, 0
	s_add_i32 s46, s70, s37
	s_mov_b32 m0, s46
	ds_read_b128 v[178:181], v144 offset:49152
	ds_read_b128 v[182:185], v144 offset:50176
	ds_read_b128 v[186:189], v144 offset:51200
	ds_read_b128 v[190:193], v144 offset:52224
	ds_read_b128 v[194:197], v144 offset:53248
	ds_read_b128 v[206:209], v144 offset:54272
	ds_read_b128 v[224:227], v144 offset:55296
	ds_read_b128 v[228:231], v144 offset:56320
	global_load_lds_dwordx4 v2, s[100:101]
	s_add_i32 m0, s46, 0x2000
	s_add_u32 s26, s26, 0x80080
	s_addc_u32 s27, s27, 0
	s_add_i32 s46, s71, s37
	global_load_lds_dwordx4 v132, s[100:101]
	s_mov_b32 m0, s46
	s_nop 0
	global_load_lds_dwordx4 v2, s[26:27]
	s_add_i32 m0, s46, 0x2000
	s_nop 0
	global_load_lds_dwordx4 v132, s[26:27]
	s_waitcnt vmcnt(6)
	s_waitcnt lgkmcnt(0)
	s_barrier
	s_setprio 1
	s_waitcnt lgkmcnt(0)
	v_mfma_f32_16x16x32_bf16 v[64:67], v[146:149], v[178:181], v[64:67]
	v_mfma_f32_16x16x32_bf16 v[60:63], v[154:157], v[178:181], v[60:63]
	v_mfma_f32_16x16x32_bf16 v[48:51], v[146:149], v[186:189], v[48:51]
	v_mfma_f32_16x16x32_bf16 v[44:47], v[154:157], v[186:189], v[44:47]
	v_mfma_f32_16x16x32_bf16 v[32:35], v[146:149], v[194:197], v[32:35]
	v_mfma_f32_16x16x32_bf16 v[28:31], v[154:157], v[194:197], v[28:31]
	v_mfma_f32_16x16x32_bf16 v[16:19], v[146:149], v[224:227], v[16:19]
	v_mfma_f32_16x16x32_bf16 v[12:15], v[154:157], v[224:227], v[12:15]
	v_mfma_f32_16x16x32_bf16 v[64:67], v[150:153], v[182:185], v[64:67]
	v_mfma_f32_16x16x32_bf16 v[60:63], v[158:161], v[182:185], v[60:63]
	v_mfma_f32_16x16x32_bf16 v[48:51], v[150:153], v[190:193], v[48:51]
	v_mfma_f32_16x16x32_bf16 v[44:47], v[158:161], v[190:193], v[44:47]
	v_mfma_f32_16x16x32_bf16 v[32:35], v[150:153], v[206:209], v[32:35]
	v_mfma_f32_16x16x32_bf16 v[28:31], v[158:161], v[206:209], v[28:31]
	v_mfma_f32_16x16x32_bf16 v[16:19], v[150:153], v[228:231], v[16:19]
	v_mfma_f32_16x16x32_bf16 v[12:15], v[158:161], v[228:231], v[12:15]
	v_mfma_f32_16x16x32_bf16 v[56:59], v[162:165], v[178:181], v[56:59]
	v_mfma_f32_16x16x32_bf16 v[52:55], v[170:173], v[178:181], v[52:55]
	v_mfma_f32_16x16x32_bf16 v[40:43], v[162:165], v[186:189], v[40:43]
	v_mfma_f32_16x16x32_bf16 v[36:39], v[170:173], v[186:189], v[36:39]
	v_mfma_f32_16x16x32_bf16 v[24:27], v[162:165], v[194:197], v[24:27]
	v_mfma_f32_16x16x32_bf16 v[20:23], v[170:173], v[194:197], v[20:23]
	v_mfma_f32_16x16x32_bf16 v[8:11], v[162:165], v[224:227], v[8:11]
	v_mfma_f32_16x16x32_bf16 v[4:7], v[170:173], v[224:227], v[4:7]
	v_mfma_f32_16x16x32_bf16 v[56:59], v[166:169], v[182:185], v[56:59]
	v_mfma_f32_16x16x32_bf16 v[52:55], v[174:177], v[182:185], v[52:55]
	v_mfma_f32_16x16x32_bf16 v[40:43], v[166:169], v[190:193], v[40:43]
	v_mfma_f32_16x16x32_bf16 v[36:39], v[174:177], v[190:193], v[36:39]
	v_mfma_f32_16x16x32_bf16 v[24:27], v[166:169], v[206:209], v[24:27]
	v_mfma_f32_16x16x32_bf16 v[20:23], v[174:177], v[206:209], v[20:23]
	v_mfma_f32_16x16x32_bf16 v[8:11], v[166:169], v[228:231], v[8:11]
	v_mfma_f32_16x16x32_bf16 v[4:7], v[174:177], v[228:231], v[4:7]
	s_setprio 0
	s_barrier
	s_add_u32 s44, s44, 0x100
	s_addc_u32 s45, s45, 0
	s_add_u32 s67, s67, 0x100
	s_addc_u32 s68, s68, 0
	s_cmp_ge_i32 s69, s54
	s_mov_b32 s46, s69
	s_cbranch_scc0 .LBB0_1457

; #define PG8_STAGE(bufoff, gbase, voff) do { _Pragma("unroll") for (int _i = 0; _i < 2; ++_i) \
;         __builtin_amdgcn_global_load_lds((const unsigned*)((const char*)(gbase) + (voff)[_i]), (LAS unsigned*)(lds + (bufoff) + ldsw + _i * 8192), 16, 0, 0); } while (0)
; #define PG8_LDA(dst, b, h) do { _Pragma("unroll") for (int m = 0; m < 4; ++m) _Pragma("unroll") for (int k = 0; k < 2; ++k) dst[m][k] = *(const LAS bf16x8*)(lds + PG8_SA(b, h) + aoff + m * 2048 + k * 1024); } while (0)
; #define PG8_LDB(dst, b, h) do { _Pragma("unroll") for (int n = 0; n < 2; ++n) _Pragma("unroll") for (int k = 0; k < 2; ++k) dst[n][k] = *(const LAS bf16x8*)(lds + PG8_SB(b, h) + boff + n * 2048 + k * 1024); } while (0)
; #define PG8_MMA(ai, bj, At, Bt) do { __builtin_amdgcn_s_setprio(1); _Pragma("unroll") for (int m = 0; m < 4; ++m) _Pragma("unroll") for (int n = 0; n < 2; ++n) _Pragma("unroll") for (int k = 0; k < 2; ++k) \
;         acc[ai][bj][m][n] = __builtin_amdgcn_mfma_f32_16x16x32_bf16(Bt[n][k], At[m][k], acc[ai][bj][m][n], 0, 0, 0); __builtin_amdgcn_s_setprio(0); } while (0)
; #define PG8_WAIT_V(n) asm volatile("s_waitcnt vmcnt(" #n ")" ::: "memory")
; #define PG8_WAIT_L(n) asm volatile("s_waitcnt lgkmcnt(" #n ")" ::: "memory")
; #define PG8_BAR __builtin_amdgcn_s_barrier()
; #define PG8_WAIT_RELAX(flag, n) asm volatile("s_cmp_eq_u32 %0, 0\n\ts_cbranch_scc1 .Lrw%=\n\ts_waitcnt vmcnt(8)\n.Lrw%=:\n\ts_waitcnt vmcnt(%1)" :: "s"(flag), "n"(n) : "scc", "memory")
; #define PG8_SCHED __builtin_amdgcn_sched_barrier(0)
; template <class Epi, bool ALIGN_EPI = true>
; __device__ __forceinline__ void gemm_phase(LAS unsigned char* lds, const Gemm g, const Sched& S, const Epi& E) {
;     ...
;             PG8_LDB(B0, 0, 0); PG8_LDB(B1, 0, 1); PG8_SCHED; PG8_LDA(At, 0, 0); PG8_STAGE(PG8_SA(1, 1), a1 + hstepA, voffA);
;             if constexpr (Epi::NSTORES > 0) PG8_WAIT_RELAX(rflag, 8 + Epi::NSTORES); else PG8_WAIT_V(8);
;             PG8_WAIT_L(0); PG8_BAR; PG8_MMA(0, 0, At, B0); PG8_MMA(0, 1, At, B1); PG8_BAR; PG8_SCHED;
;             PG8_LDA(At, 0, 1); PG8_STAGE(PG8_SB(0, 0), b2, voffB); PG8_STAGE(PG8_SB(0, 1), b2 + hstepB, voffB); PG8_STAGE(PG8_SA(0, 0), a2, voffA);
;             if constexpr (Epi::NSTORES > 0) PG8_WAIT_RELAX(rflag, 8 + Epi::NSTORES); else PG8_WAIT_V(8);
;             PG8_WAIT_L(0); PG8_BAR; PG8_MMA(1, 0, At, B0); PG8_MMA(1, 1, At, B1); PG8_BAR; PG8_SCHED;
.Lrw16:
	s_waitcnt vmcnt(24)
	s_waitcnt lgkmcnt(0)
	s_barrier
	s_setprio 1
	s_waitcnt lgkmcnt(0)
	v_mfma_f32_16x16x32_bf16 v[124:127], v[146:149], v[178:181], v[124:127]
	v_mfma_f32_16x16x32_bf16 v[128:131], v[154:157], v[178:181], v[128:131]
	v_mfma_f32_16x16x32_bf16 v[112:115], v[146:149], v[186:189], v[112:115]
	v_mfma_f32_16x16x32_bf16 v[108:111], v[154:157], v[186:189], v[108:111]
	v_mfma_f32_16x16x32_bf16 v[96:99], v[146:149], v[194:197], v[96:99]
	v_mfma_f32_16x16x32_bf16 v[92:95], v[154:157], v[194:197], v[92:95]
	v_mfma_f32_16x16x32_bf16 v[80:83], v[146:149], v[224:227], v[80:83]
	v_mfma_f32_16x16x32_bf16 v[76:79], v[154:157], v[224:227], v[76:79]
	v_mfma_f32_16x16x32_bf16 v[124:127], v[150:153], v[182:185], v[124:127]
	v_mfma_f32_16x16x32_bf16 v[128:131], v[158:161], v[182:185], v[128:131]
	v_mfma_f32_16x16x32_bf16 v[112:115], v[150:153], v[190:193], v[112:115]
	v_mfma_f32_16x16x32_bf16 v[108:111], v[158:161], v[190:193], v[108:111]
	v_mfma_f32_16x16x32_bf16 v[96:99], v[150:153], v[206:209], v[96:99]
	v_mfma_f32_16x16x32_bf16 v[92:95], v[158:161], v[206:209], v[92:95]
	v_mfma_f32_16x16x32_bf16 v[80:83], v[150:153], v[228:231], v[80:83]
	v_mfma_f32_16x16x32_bf16 v[76:79], v[158:161], v[228:231], v[76:79]
	v_mfma_f32_16x16x32_bf16 v[120:123], v[162:165], v[178:181], v[120:123]
	v_mfma_f32_16x16x32_bf16 v[116:119], v[170:173], v[178:181], v[116:119]
	v_mfma_f32_16x16x32_bf16 v[104:107], v[162:165], v[186:189], v[104:107]
	v_mfma_f32_16x16x32_bf16 v[100:103], v[170:173], v[186:189], v[100:103]
	v_mfma_f32_16x16x32_bf16 v[88:91], v[162:165], v[194:197], v[88:91]
	v_mfma_f32_16x16x32_bf16 v[84:87], v[170:173], v[194:197], v[84:87]
	v_mfma_f32_16x16x32_bf16 v[72:75], v[162:165], v[224:227], v[72:75]
	v_mfma_f32_16x16x32_bf16 v[68:71], v[170:173], v[224:227], v[68:71]
	v_mfma_f32_16x16x32_bf16 v[120:123], v[166:169], v[182:185], v[120:123]
	v_mfma_f32_16x16x32_bf16 v[116:119], v[174:177], v[182:185], v[116:119]
	v_mfma_f32_16x16x32_bf16 v[104:107], v[166:169], v[190:193], v[104:107]
	v_mfma_f32_16x16x32_bf16 v[100:103], v[174:177], v[190:193], v[100:103]
	v_mfma_f32_16x16x32_bf16 v[88:91], v[166:169], v[206:209], v[88:91]
	v_mfma_f32_16x16x32_bf16 v[84:87], v[174:177], v[206:209], v[84:87]
	v_mfma_f32_16x16x32_bf16 v[72:75], v[166:169], v[228:231], v[72:75]
	v_mfma_f32_16x16x32_bf16 v[68:71], v[174:177], v[228:231], v[68:71]
	s_setprio 0
	s_barrier
	s_add_i32 s68, s68, s37
	s_mov_b32 m0, s68
	ds_read_b128 v[178:181], v144 offset:16384
	ds_read_b128 v[182:185], v144 offset:17408
	ds_read_b128 v[186:189], v144 offset:18432
	ds_read_b128 v[190:193], v144 offset:19456
	ds_read_b128 v[194:197], v144 offset:20480
	ds_read_b128 v[206:209], v144 offset:21504
	ds_read_b128 v[224:227], v144 offset:22528
	ds_read_b128 v[228:231], v144 offset:23552
	global_load_lds_dwordx4 v2, s[26:27]
	s_add_i32 m0, s68, 0x2000
	s_add_u32 s68, s26, 0x400000
	s_addc_u32 s69, s27, 0
	s_add_i32 s70, s70, s37
	global_load_lds_dwordx4 v132, s[26:27]
	s_mov_b32 m0, s70
	s_nop 0
	global_load_lds_dwordx4 v2, s[68:69]
	s_add_i32 m0, s70, 0x2000
	s_nop 0
	global_load_lds_dwordx4 v132, s[68:69]
	s_cmp_eq_u32 s71, 0
	s_cbranch_scc1 .Lrw17
	s_waitcnt vmcnt(6)
.Lrw17:
	s_waitcnt vmcnt(6)
	s_waitcnt lgkmcnt(0)
	s_barrier
	s_setprio 1
	s_waitcnt lgkmcnt(0)
	v_mfma_f32_16x16x32_bf16 v[64:67], v[146:149], v[178:181], v[64:67]
	v_mfma_f32_16x16x32_bf16 v[60:63], v[154:157], v[178:181], v[60:63]
	v_mfma_f32_16x16x32_bf16 v[48:51], v[146:149], v[186:189], v[48:51]
	v_mfma_f32_16x16x32_bf16 v[44:47], v[154:157], v[186:189], v[44:47]
	v_mfma_f32_16x16x32_bf16 v[32:35], v[146:149], v[194:197], v[32:35]
	v_mfma_f32_16x16x32_bf16 v[28:31], v[154:157], v[194:197], v[28:31]
	v_mfma_f32_16x16x32_bf16 v[16:19], v[146:149], v[224:227], v[16:19]
	v_mfma_f32_16x16x32_bf16 v[12:15], v[154:157], v[224:227], v[12:15]
	v_mfma_f32_16x16x32_bf16 v[64:67], v[150:153], v[182:185], v[64:67]
	v_mfma_f32_16x16x32_bf16 v[60:63], v[158:161], v[182:185], v[60:63]
	v_mfma_f32_16x16x32_bf16 v[48:51], v[150:153], v[190:193], v[48:51]
	v_mfma_f32_16x16x32_bf16 v[44:47], v[158:161], v[190:193], v[44:47]
	v_mfma_f32_16x16x32_bf16 v[32:35], v[150:153], v[206:209], v[32:35]
	v_mfma_f32_16x16x32_bf16 v[28:31], v[158:161], v[206:209], v[28:31]
	v_mfma_f32_16x16x32_bf16 v[16:19], v[150:153], v[228:231], v[16:19]
	v_mfma_f32_16x16x32_bf16 v[12:15], v[158:161], v[228:231], v[12:15]
	v_mfma_f32_16x16x32_bf16 v[56:59], v[162:165], v[178:181], v[56:59]
	v_mfma_f32_16x16x32_bf16 v[52:55], v[170:173], v[178:181], v[52:55]
	v_mfma_f32_16x16x32_bf16 v[40:43], v[162:165], v[186:189], v[40:43]
	v_mfma_f32_16x16x32_bf16 v[36:39], v[170:173], v[186:189], v[36:39]
	v_mfma_f32_16x16x32_bf16 v[24:27], v[162:165], v[194:197], v[24:27]
	v_mfma_f32_16x16x32_bf16 v[20:23], v[170:173], v[194:197], v[20:23]
	v_mfma_f32_16x16x32_bf16 v[8:11], v[162:165], v[224:227], v[8:11]
	v_mfma_f32_16x16x32_bf16 v[4:7], v[170:173], v[224:227], v[4:7]
	v_mfma_f32_16x16x32_bf16 v[56:59], v[166:169], v[182:185], v[56:59]
	v_mfma_f32_16x16x32_bf16 v[52:55], v[174:177], v[182:185], v[52:55]
	v_mfma_f32_16x16x32_bf16 v[40:43], v[166:169], v[190:193], v[40:43]
	v_mfma_f32_16x16x32_bf16 v[36:39], v[174:177], v[190:193], v[36:39]
	v_mfma_f32_16x16x32_bf16 v[24:27], v[166:169], v[206:209], v[24:27]
	v_mfma_f32_16x16x32_bf16 v[20:23], v[174:177], v[206:209], v[20:23]
	v_mfma_f32_16x16x32_bf16 v[8:11], v[166:169], v[228:231], v[8:11]
	v_mfma_f32_16x16x32_bf16 v[4:7], v[174:177], v[228:231], v[4:7]
	s_setprio 0
	s_barrier
; #define PG8_STAGE(bufoff, gbase, voff) do { _Pragma("unroll") for (int _i = 0; _i < 2; ++_i) \
;         __builtin_amdgcn_global_load_lds((const unsigned*)((const char*)(gbase) + (voff)[_i]), (LAS unsigned*)(lds + (bufoff) + ldsw + _i * 8192), 16, 0, 0); } while (0)
; #define PG8_LDA(dst, b, h) do { _Pragma("unroll") for (int m = 0; m < 4; ++m) _Pragma("unroll") for (int k = 0; k < 2; ++k) dst[m][k] = *(const LAS bf16x8*)(lds + PG8_SA(b, h) + aoff + m * 2048 + k * 1024); } while (0)
; #define PG8_LDB(dst, b, h) do { _Pragma("unroll") for (int n = 0; n < 2; ++n) _Pragma("unroll") for (int k = 0; k < 2; ++k) dst[n][k] = *(const LAS bf16x8*)(lds + PG8_SB(b, h) + boff + n * 2048 + k * 1024); } while (0)
; #define PG8_MMA(ai, bj, At, Bt) do { __builtin_amdgcn_s_setprio(1); _Pragma("unroll") for (int m = 0; m < 4; ++m) _Pragma("unroll") for (int n = 0; n < 2; ++n) _Pragma("unroll") for (int k = 0; k < 2; ++k) \
;         acc[ai][bj][m][n] = __builtin_amdgcn_mfma_f32_16x16x32_bf16(Bt[n][k], At[m][k], acc[ai][bj][m][n], 0, 0, 0); __builtin_amdgcn_s_setprio(0); } while (0)
; #define PG8_WAIT_V(n) asm volatile("s_waitcnt vmcnt(" #n ")" ::: "memory")
; #define PG8_WAIT_L(n) asm volatile("s_waitcnt lgkmcnt(" #n ")" ::: "memory")
; #define PG8_BAR __builtin_amdgcn_s_barrier()
; #define PG8_SCHED __builtin_amdgcn_sched_barrier(0)
; template <class Epi, bool ALIGN_EPI = true>
; __device__ __forceinline__ void gemm_phase(LAS unsigned char* lds, const Gemm g, const Sched& S, const Epi& E) {
;     ...
;             PG8_LDB(B0, 1, 0); PG8_LDB(B1, 1, 1); PG8_SCHED; PG8_LDA(At, 1, 0); PG8_STAGE(PG8_SA(0, 1), a2 + hstepA, voffA);
;             PG8_WAIT_V(8); PG8_WAIT_L(0); PG8_BAR; PG8_MMA(0, 0, At, B0); PG8_MMA(0, 1, At, B1); PG8_BAR; PG8_SCHED;
;             PG8_LDA(At, 1, 1); PG8_STAGE(PG8_SB(1, 0), b3, voffB); PG8_STAGE(PG8_SB(1, 1), b3 + hstepB, voffB); PG8_STAGE(PG8_SA(1, 0), a3, voffA);
;             PG8_WAIT_V(8); PG8_WAIT_L(0); PG8_BAR; PG8_MMA(1, 0, At, B0); PG8_MMA(1, 1, At, B1); PG8_BAR; PG8_SCHED;
	s_add_i32 s68, 0, 0x18000
	s_add_i32 s69, 0, 0x1c000
	v_add_u32_e32 v158, s68, v143
	v_add_u32_e32 v174, s69, v143
	ds_read_b128 v[146:149], v158
	ds_read_b128 v[150:153], v158 offset:1024
	ds_read_b128 v[154:157], v158 offset:2048
	ds_read_b128 v[158:161], v158 offset:3072
	ds_read_b128 v[162:165], v174
	ds_read_b128 v[166:169], v174 offset:1024
	ds_read_b128 v[170:173], v174 offset:2048
	ds_read_b128 v[174:177], v174 offset:3072
	s_add_u32 s44, s44, 0x80000
	s_addc_u32 s45, s45, 0
	s_mov_b32 m0, s48
	ds_read_b128 v[178:181], v144 offset:32768
	ds_read_b128 v[182:185], v144 offset:33792
	ds_read_b128 v[186:189], v144 offset:34816
	ds_read_b128 v[190:193], v144 offset:35840
	ds_read_b128 v[194:197], v144 offset:36864
	ds_read_b128 v[206:209], v144 offset:37888
	ds_read_b128 v[224:227], v144 offset:38912
	ds_read_b128 v[228:231], v144 offset:39936
	s_add_u32 s100, s44, 0xfff80000
	s_addc_u32 s101, s45, -1
	s_mov_b32 m0, s46
	s_nop 0
	global_load_lds_dwordx4 v136, s[100:101]
	s_mov_b32 m0, s47
	s_nop 0
	global_load_lds_dwordx4 v134, s[100:101]
	s_mov_b32 m0, s48
	s_nop 0
	global_load_lds_dwordx4 v136, s[44:45]
	s_mov_b32 m0, s49
	s_nop 0
	global_load_lds_dwordx4 v134, s[44:45]
	s_waitcnt vmcnt(8)
	s_waitcnt lgkmcnt(0)
	s_barrier
	s_setprio 1
	s_waitcnt lgkmcnt(0)
	v_mfma_f32_16x16x32_bf16 v[124:127], v[146:149], v[178:181], v[124:127]
	v_mfma_f32_16x16x32_bf16 v[128:131], v[154:157], v[178:181], v[128:131]
	v_mfma_f32_16x16x32_bf16 v[112:115], v[146:149], v[186:189], v[112:115]
	v_mfma_f32_16x16x32_bf16 v[108:111], v[154:157], v[186:189], v[108:111]
	v_mfma_f32_16x16x32_bf16 v[96:99], v[146:149], v[194:197], v[96:99]
	v_mfma_f32_16x16x32_bf16 v[92:95], v[154:157], v[194:197], v[92:95]
	v_mfma_f32_16x16x32_bf16 v[80:83], v[146:149], v[224:227], v[80:83]
	v_mfma_f32_16x16x32_bf16 v[76:79], v[154:157], v[224:227], v[76:79]
	v_mfma_f32_16x16x32_bf16 v[124:127], v[150:153], v[182:185], v[124:127]
	v_mfma_f32_16x16x32_bf16 v[128:131], v[158:161], v[182:185], v[128:131]
	v_mfma_f32_16x16x32_bf16 v[112:115], v[150:153], v[190:193], v[112:115]
	v_mfma_f32_16x16x32_bf16 v[108:111], v[158:161], v[190:193], v[108:111]
	v_mfma_f32_16x16x32_bf16 v[96:99], v[150:153], v[206:209], v[96:99]
	v_mfma_f32_16x16x32_bf16 v[92:95], v[158:161], v[206:209], v[92:95]
	v_mfma_f32_16x16x32_bf16 v[80:83], v[150:153], v[228:231], v[80:83]
	v_mfma_f32_16x16x32_bf16 v[76:79], v[158:161], v[228:231], v[76:79]
	v_mfma_f32_16x16x32_bf16 v[120:123], v[162:165], v[178:181], v[120:123]
	v_mfma_f32_16x16x32_bf16 v[116:119], v[170:173], v[178:181], v[116:119]
	v_mfma_f32_16x16x32_bf16 v[104:107], v[162:165], v[186:189], v[104:107]
	v_mfma_f32_16x16x32_bf16 v[100:103], v[170:173], v[186:189], v[100:103]
	v_mfma_f32_16x16x32_bf16 v[88:91], v[162:165], v[194:197], v[88:91]
	v_mfma_f32_16x16x32_bf16 v[84:87], v[170:173], v[194:197], v[84:87]
	v_mfma_f32_16x16x32_bf16 v[72:75], v[162:165], v[224:227], v[72:75]
	v_mfma_f32_16x16x32_bf16 v[68:71], v[170:173], v[224:227], v[68:71]
	v_mfma_f32_16x16x32_bf16 v[120:123], v[166:169], v[182:185], v[120:123]
	v_mfma_f32_16x16x32_bf16 v[116:119], v[174:177], v[182:185], v[116:119]
	v_mfma_f32_16x16x32_bf16 v[104:107], v[166:169], v[190:193], v[104:107]
	v_mfma_f32_16x16x32_bf16 v[100:103], v[174:177], v[190:193], v[100:103]
	v_mfma_f32_16x16x32_bf16 v[88:91], v[166:169], v[206:209], v[88:91]
	v_mfma_f32_16x16x32_bf16 v[84:87], v[174:177], v[206:209], v[84:87]
	v_mfma_f32_16x16x32_bf16 v[72:75], v[166:169], v[228:231], v[72:75]
	v_mfma_f32_16x16x32_bf16 v[68:71], v[174:177], v[228:231], v[68:71]
	s_setprio 0
	s_barrier
	s_add_u32 s100, s26, 0x80
	s_addc_u32 s101, s27, 0
	s_add_i32 s44, s68, s37
	s_mov_b32 m0, s44
	ds_read_b128 v[178:181], v144 offset:49152
	ds_read_b128 v[182:185], v144 offset:50176
	ds_read_b128 v[186:189], v144 offset:51200
	ds_read_b128 v[190:193], v144 offset:52224
	ds_read_b128 v[194:197], v144 offset:53248
	ds_read_b128 v[206:209], v144 offset:54272
	ds_read_b128 v[224:227], v144 offset:55296
	ds_read_b128 v[228:231], v144 offset:56320
	global_load_lds_dwordx4 v2, s[100:101]
	s_add_i32 m0, s44, 0x2000
	s_add_u32 s26, s26, 0x400080
	s_addc_u32 s27, s27, 0
	s_add_i32 s44, s69, s37
	global_load_lds_dwordx4 v132, s[100:101]
	s_mov_b32 m0, s44
	s_nop 0
	global_load_lds_dwordx4 v2, s[26:27]
	s_add_i32 m0, s44, 0x2000
	s_nop 0
	global_load_lds_dwordx4 v132, s[26:27]
	s_waitcnt vmcnt(6)
	s_waitcnt lgkmcnt(0)
	s_barrier
	s_setprio 1
	s_waitcnt lgkmcnt(0)
	v_mfma_f32_16x16x32_bf16 v[64:67], v[146:149], v[178:181], v[64:67]
	v_mfma_f32_16x16x32_bf16 v[60:63], v[154:157], v[178:181], v[60:63]
	v_mfma_f32_16x16x32_bf16 v[48:51], v[146:149], v[186:189], v[48:51]
	v_mfma_f32_16x16x32_bf16 v[44:47], v[154:157], v[186:189], v[44:47]
	v_mfma_f32_16x16x32_bf16 v[32:35], v[146:149], v[194:197], v[32:35]
	v_mfma_f32_16x16x32_bf16 v[28:31], v[154:157], v[194:197], v[28:31]
	v_mfma_f32_16x16x32_bf16 v[16:19], v[146:149], v[224:227], v[16:19]
	v_mfma_f32_16x16x32_bf16 v[12:15], v[154:157], v[224:227], v[12:15]
	v_mfma_f32_16x16x32_bf16 v[64:67], v[150:153], v[182:185], v[64:67]
	v_mfma_f32_16x16x32_bf16 v[60:63], v[158:161], v[182:185], v[60:63]
	v_mfma_f32_16x16x32_bf16 v[48:51], v[150:153], v[190:193], v[48:51]
	v_mfma_f32_16x16x32_bf16 v[44:47], v[158:161], v[190:193], v[44:47]
	v_mfma_f32_16x16x32_bf16 v[32:35], v[150:153], v[206:209], v[32:35]
	v_mfma_f32_16x16x32_bf16 v[28:31], v[158:161], v[206:209], v[28:31]
	v_mfma_f32_16x16x32_bf16 v[16:19], v[150:153], v[228:231], v[16:19]
	v_mfma_f32_16x16x32_bf16 v[12:15], v[158:161], v[228:231], v[12:15]
	v_mfma_f32_16x16x32_bf16 v[56:59], v[162:165], v[178:181], v[56:59]
	v_mfma_f32_16x16x32_bf16 v[52:55], v[170:173], v[178:181], v[52:55]
	v_mfma_f32_16x16x32_bf16 v[40:43], v[162:165], v[186:189], v[40:43]
	v_mfma_f32_16x16x32_bf16 v[36:39], v[170:173], v[186:189], v[36:39]
	v_mfma_f32_16x16x32_bf16 v[24:27], v[162:165], v[194:197], v[24:27]
	v_mfma_f32_16x16x32_bf16 v[20:23], v[170:173], v[194:197], v[20:23]
	v_mfma_f32_16x16x32_bf16 v[8:11], v[162:165], v[224:227], v[8:11]
	v_mfma_f32_16x16x32_bf16 v[4:7], v[170:173], v[224:227], v[4:7]
	v_mfma_f32_16x16x32_bf16 v[56:59], v[166:169], v[182:185], v[56:59]
	v_mfma_f32_16x16x32_bf16 v[52:55], v[174:177], v[182:185], v[52:55]
	v_mfma_f32_16x16x32_bf16 v[40:43], v[166:169], v[190:193], v[40:43]
	v_mfma_f32_16x16x32_bf16 v[36:39], v[174:177], v[190:193], v[36:39]
	v_mfma_f32_16x16x32_bf16 v[24:27], v[166:169], v[206:209], v[24:27]
	v_mfma_f32_16x16x32_bf16 v[20:23], v[174:177], v[206:209], v[20:23]
	v_mfma_f32_16x16x32_bf16 v[8:11], v[166:169], v[228:231], v[8:11]
	v_mfma_f32_16x16x32_bf16 v[4:7], v[174:177], v[228:231], v[4:7]
	s_setprio 0
	s_barrier
	s_add_u32 s42, s42, 0x100
	s_addc_u32 s43, s43, 0
	s_add_u32 s65, s65, 0x100
	s_addc_u32 s66, s66, 0
	s_cmp_ge_i32 s67, s52
	s_mov_b32 s44, s67
	s_cbranch_scc0 .LBB0_1479

; #define PG8_STAGE(bufoff, gbase, voff) do { _Pragma("unroll") for (int _i = 0; _i < 2; ++_i) \
;         __builtin_amdgcn_global_load_lds((const unsigned*)((const char*)(gbase) + (voff)[_i]), (LAS unsigned*)(lds + (bufoff) + ldsw + _i * 8192), 16, 0, 0); } while (0)
; #define PG8_LDA(dst, b, h) do { _Pragma("unroll") for (int m = 0; m < 4; ++m) _Pragma("unroll") for (int k = 0; k < 2; ++k) dst[m][k] = *(const LAS bf16x8*)(lds + PG8_SA(b, h) + aoff + m * 2048 + k * 1024); } while (0)
; #define PG8_LDB(dst, b, h) do { _Pragma("unroll") for (int n = 0; n < 2; ++n) _Pragma("unroll") for (int k = 0; k < 2; ++k) dst[n][k] = *(const LAS bf16x8*)(lds + PG8_SB(b, h) + boff + n * 2048 + k * 1024); } while (0)
; #define PG8_MMA(ai, bj, At, Bt) do { __builtin_amdgcn_s_setprio(1); _Pragma("unroll") for (int m = 0; m < 4; ++m) _Pragma("unroll") for (int n = 0; n < 2; ++n) _Pragma("unroll") for (int k = 0; k < 2; ++k) \
;         acc[ai][bj][m][n] = __builtin_amdgcn_mfma_f32_16x16x32_bf16(Bt[n][k], At[m][k], acc[ai][bj][m][n], 0, 0, 0); __builtin_amdgcn_s_setprio(0); } while (0)
; #define PG8_WAIT_V(n) asm volatile("s_waitcnt vmcnt(" #n ")" ::: "memory")
; #define PG8_WAIT_L(n) asm volatile("s_waitcnt lgkmcnt(" #n ")" ::: "memory")
; #define PG8_BAR __builtin_amdgcn_s_barrier()
; #define PG8_SCHED __builtin_amdgcn_sched_barrier(0)
; template <class Epi, bool ALIGN_EPI = true>
; __device__ __forceinline__ void gemm_phase(LAS unsigned char* lds, const Gemm g, const Sched& S, const Epi& E) {
;     ...
;             PG8_LDB(B0, 0, 0); PG8_LDB(B1, 0, 1); PG8_SCHED; PG8_LDA(At, 0, 0); PG8_STAGE(PG8_SA(1, 1), a1 + hstepA, voffA);
;             if constexpr (Epi::NSTORES > 0) PG8_WAIT_RELAX(rflag, 8 + Epi::NSTORES); else PG8_WAIT_V(8);
;             PG8_WAIT_L(0); PG8_BAR; PG8_MMA(0, 0, At, B0); PG8_MMA(0, 1, At, B1); PG8_BAR; PG8_SCHED;
;             PG8_LDA(At, 0, 1); PG8_STAGE(PG8_SB(0, 0), b2, voffB); PG8_STAGE(PG8_SB(0, 1), b2 + hstepB, voffB); PG8_STAGE(PG8_SA(0, 0), a2, voffA);
;             if constexpr (Epi::NSTORES > 0) PG8_WAIT_RELAX(rflag, 8 + Epi::NSTORES); else PG8_WAIT_V(8);
;             PG8_WAIT_L(0); PG8_BAR; PG8_MMA(1, 0, At, B0); PG8_MMA(1, 1, At, B1); PG8_BAR; PG8_SCHED;
;             PG8_LDB(B0, 1, 0); PG8_LDB(B1, 1, 1); PG8_SCHED; PG8_LDA(At, 1, 0); PG8_STAGE(PG8_SA(0, 1), a2 + hstepA, voffA);
.LBB0_1929:
	s_add_i32 s67, s48, 2
	s_add_u32 s49, s46, 0xfffc0080
	s_addc_u32 s50, s47, -1
	s_add_i32 s68, 0, 0x10000
	s_cmp_eq_u32 s59, s48
	s_cselect_b32 s51, s21, s50
	s_cselect_b32 s50, s23, s49
	v_add_u32_e32 v2, s68, v147
	s_cselect_b32 s49, s63, s66
	s_cselect_b32 s48, s64, s65
	s_add_i32 s70, 0, 0x14000
	ds_read_b128 v[150:153], v2
	ds_read_b128 v[154:157], v2 offset:1024
	ds_read_b128 v[158:161], v2 offset:2048
	ds_read_b128 v[162:165], v2 offset:3072
	v_add_u32_e32 v2, s70, v147
	ds_read_b128 v[166:169], v2
	ds_read_b128 v[170:173], v2 offset:1024
	ds_read_b128 v[174:177], v2 offset:2048
	ds_read_b128 v[178:181], v2 offset:3072
	s_add_i32 m0, s52, 0xc000
	ds_read_b128 v[182:185], v148
	ds_read_b128 v[186:189], v148 offset:1024
	ds_read_b128 v[190:193], v148 offset:2048
	ds_read_b128 v[194:197], v148 offset:3072
	ds_read_b128 v[206:209], v148 offset:4096
	ds_read_b128 v[224:227], v148 offset:5120
	ds_read_b128 v[228:231], v148 offset:6144
	ds_read_b128 v[232:235], v148 offset:7168
	s_add_u32 s100, s46, 0xfffc0000
	s_addc_u32 s101, s47, -1
	s_mov_b32 m0, s57
	s_nop 0
	global_load_lds_dwordx4 v142, s[100:101]
	s_mov_b32 m0, s58
	s_nop 0
	global_load_lds_dwordx4 v144, s[100:101]
	s_add_i32 m0, s52, 0xc000
	s_nop 0
	global_load_lds_dwordx4 v142, s[46:47]
	s_add_i32 m0, s52, 0xe000
	s_nop 0
	global_load_lds_dwordx4 v144, s[46:47]
	s_waitcnt vmcnt(8)
	s_waitcnt lgkmcnt(0)
	s_barrier
	s_setprio 1
	s_waitcnt lgkmcnt(0)
	v_mfma_f32_16x16x32_bf16 v[130:133], v[150:153], v[182:185], v[130:133]
	v_mfma_f32_16x16x32_bf16 v[126:129], v[158:161], v[182:185], v[126:129]
	v_mfma_f32_16x16x32_bf16 v[114:117], v[150:153], v[190:193], v[114:117]
	v_mfma_f32_16x16x32_bf16 v[110:113], v[158:161], v[190:193], v[110:113]
	v_mfma_f32_16x16x32_bf16 v[98:101], v[150:153], v[206:209], v[98:101]
	v_mfma_f32_16x16x32_bf16 v[94:97], v[158:161], v[206:209], v[94:97]
	v_mfma_f32_16x16x32_bf16 v[82:85], v[150:153], v[228:231], v[82:85]
	v_mfma_f32_16x16x32_bf16 v[78:81], v[158:161], v[228:231], v[78:81]
	v_mfma_f32_16x16x32_bf16 v[130:133], v[154:157], v[186:189], v[130:133]
	v_mfma_f32_16x16x32_bf16 v[126:129], v[162:165], v[186:189], v[126:129]
	v_mfma_f32_16x16x32_bf16 v[114:117], v[154:157], v[194:197], v[114:117]
	v_mfma_f32_16x16x32_bf16 v[110:113], v[162:165], v[194:197], v[110:113]
	v_mfma_f32_16x16x32_bf16 v[98:101], v[154:157], v[224:227], v[98:101]
	v_mfma_f32_16x16x32_bf16 v[94:97], v[162:165], v[224:227], v[94:97]
	v_mfma_f32_16x16x32_bf16 v[82:85], v[154:157], v[232:235], v[82:85]
	v_mfma_f32_16x16x32_bf16 v[78:81], v[162:165], v[232:235], v[78:81]
	v_mfma_f32_16x16x32_bf16 v[122:125], v[166:169], v[182:185], v[122:125]
	v_mfma_f32_16x16x32_bf16 v[118:121], v[174:177], v[182:185], v[118:121]
	v_mfma_f32_16x16x32_bf16 v[106:109], v[166:169], v[190:193], v[106:109]
	v_mfma_f32_16x16x32_bf16 v[102:105], v[174:177], v[190:193], v[102:105]
	v_mfma_f32_16x16x32_bf16 v[90:93], v[166:169], v[206:209], v[90:93]
	v_mfma_f32_16x16x32_bf16 v[86:89], v[174:177], v[206:209], v[86:89]
	v_mfma_f32_16x16x32_bf16 v[74:77], v[166:169], v[228:231], v[74:77]
	v_mfma_f32_16x16x32_bf16 v[70:73], v[174:177], v[228:231], v[70:73]
	v_mfma_f32_16x16x32_bf16 v[122:125], v[170:173], v[186:189], v[122:125]
	v_mfma_f32_16x16x32_bf16 v[118:121], v[178:181], v[186:189], v[118:121]
	v_mfma_f32_16x16x32_bf16 v[106:109], v[170:173], v[194:197], v[106:109]
	v_mfma_f32_16x16x32_bf16 v[102:105], v[178:181], v[194:197], v[102:105]
	v_mfma_f32_16x16x32_bf16 v[90:93], v[170:173], v[224:227], v[90:93]
	v_mfma_f32_16x16x32_bf16 v[86:89], v[178:181], v[224:227], v[86:89]
	v_mfma_f32_16x16x32_bf16 v[74:77], v[170:173], v[232:235], v[74:77]
	v_mfma_f32_16x16x32_bf16 v[70:73], v[178:181], v[232:235], v[70:73]
	s_setprio 0
	s_barrier
	s_add_i32 s68, s68, s37
	s_mov_b32 m0, s68
	ds_read_b128 v[182:185], v148 offset:16384
	ds_read_b128 v[186:189], v148 offset:17408
	ds_read_b128 v[190:193], v148 offset:18432
	ds_read_b128 v[194:197], v148 offset:19456
	ds_read_b128 v[206:209], v148 offset:20480
	ds_read_b128 v[224:227], v148 offset:21504
	ds_read_b128 v[228:231], v148 offset:22528
	ds_read_b128 v[232:235], v148 offset:23552
	global_load_lds_dwordx4 v138, s[48:49]
	s_add_i32 m0, s68, 0x2000
	s_add_u32 s68, s48, 0x40000
	s_addc_u32 s69, s49, 0
	s_add_i32 s70, s70, s37
	global_load_lds_dwordx4 v134, s[48:49]
	s_mov_b32 m0, s70
	s_nop 0
	global_load_lds_dwordx4 v138, s[68:69]
	s_add_i32 m0, s70, 0x2000
	s_nop 0
	global_load_lds_dwordx4 v134, s[68:69]
	s_waitcnt vmcnt(6)
	s_waitcnt lgkmcnt(0)
	s_barrier
; #define PG8_STAGE(bufoff, gbase, voff) do { _Pragma("unroll") for (int _i = 0; _i < 2; ++_i) \
;         __builtin_amdgcn_global_load_lds((const unsigned*)((const char*)(gbase) + (voff)[_i]), (LAS unsigned*)(lds + (bufoff) + ldsw + _i * 8192), 16, 0, 0); } while (0)
; #define PG8_LDA(dst, b, h) do { _Pragma("unroll") for (int m = 0; m < 4; ++m) _Pragma("unroll") for (int k = 0; k < 2; ++k) dst[m][k] = *(const LAS bf16x8*)(lds + PG8_SA(b, h) + aoff + m * 2048 + k * 1024); } while (0)
; #define PG8_LDB(dst, b, h) do { _Pragma("unroll") for (int n = 0; n < 2; ++n) _Pragma("unroll") for (int k = 0; k < 2; ++k) dst[n][k] = *(const LAS bf16x8*)(lds + PG8_SB(b, h) + boff + n * 2048 + k * 1024); } while (0)
; #define PG8_MMA(ai, bj, At, Bt) do { __builtin_amdgcn_s_setprio(1); _Pragma("unroll") for (int m = 0; m < 4; ++m) _Pragma("unroll") for (int n = 0; n < 2; ++n) _Pragma("unroll") for (int k = 0; k < 2; ++k) \
;         acc[ai][bj][m][n] = __builtin_amdgcn_mfma_f32_16x16x32_bf16(Bt[n][k], At[m][k], acc[ai][bj][m][n], 0, 0, 0); __builtin_amdgcn_s_setprio(0); } while (0)
; #define PG8_WAIT_V(n) asm volatile("s_waitcnt vmcnt(" #n ")" ::: "memory")
; #define PG8_WAIT_L(n) asm volatile("s_waitcnt lgkmcnt(" #n ")" ::: "memory")
; #define PG8_BAR __builtin_amdgcn_s_barrier()
; #define PG8_SCHED __builtin_amdgcn_sched_barrier(0)
; template <class Epi, bool ALIGN_EPI = true>
; __device__ __forceinline__ void gemm_phase(LAS unsigned char* lds, const Gemm g, const Sched& S, const Epi& E) {
;     ...
;             PG8_WAIT_L(0); PG8_BAR; PG8_MMA(1, 0, At, B0); PG8_MMA(1, 1, At, B1); PG8_BAR; PG8_SCHED;
;             PG8_LDB(B0, 1, 0); PG8_LDB(B1, 1, 1); PG8_SCHED; PG8_LDA(At, 1, 0); PG8_STAGE(PG8_SA(0, 1), a2 + hstepA, voffA);
;             PG8_WAIT_V(8); PG8_WAIT_L(0); PG8_BAR; PG8_MMA(0, 0, At, B0); PG8_MMA(0, 1, At, B1); PG8_BAR; PG8_SCHED;
	s_setprio 1
	s_waitcnt lgkmcnt(0)
	v_mfma_f32_16x16x32_bf16 v[66:69], v[150:153], v[182:185], v[66:69]
	v_mfma_f32_16x16x32_bf16 v[62:65], v[158:161], v[182:185], v[62:65]
	v_mfma_f32_16x16x32_bf16 v[50:53], v[150:153], v[190:193], v[50:53]
	v_mfma_f32_16x16x32_bf16 v[46:49], v[158:161], v[190:193], v[46:49]
	v_mfma_f32_16x16x32_bf16 v[34:37], v[150:153], v[206:209], v[34:37]
	v_mfma_f32_16x16x32_bf16 v[30:33], v[158:161], v[206:209], v[30:33]
	v_mfma_f32_16x16x32_bf16 v[18:21], v[150:153], v[228:231], v[18:21]
	v_mfma_f32_16x16x32_bf16 v[14:17], v[158:161], v[228:231], v[14:17]
	v_mfma_f32_16x16x32_bf16 v[66:69], v[154:157], v[186:189], v[66:69]
	v_mfma_f32_16x16x32_bf16 v[62:65], v[162:165], v[186:189], v[62:65]
	v_mfma_f32_16x16x32_bf16 v[50:53], v[154:157], v[194:197], v[50:53]
	v_mfma_f32_16x16x32_bf16 v[46:49], v[162:165], v[194:197], v[46:49]
	v_mfma_f32_16x16x32_bf16 v[34:37], v[154:157], v[224:227], v[34:37]
	v_mfma_f32_16x16x32_bf16 v[30:33], v[162:165], v[224:227], v[30:33]
	v_mfma_f32_16x16x32_bf16 v[18:21], v[154:157], v[232:235], v[18:21]
	v_mfma_f32_16x16x32_bf16 v[14:17], v[162:165], v[232:235], v[14:17]
	v_mfma_f32_16x16x32_bf16 v[58:61], v[166:169], v[182:185], v[58:61]
	v_mfma_f32_16x16x32_bf16 v[54:57], v[174:177], v[182:185], v[54:57]
	v_mfma_f32_16x16x32_bf16 v[42:45], v[166:169], v[190:193], v[42:45]
	v_mfma_f32_16x16x32_bf16 v[38:41], v[174:177], v[190:193], v[38:41]
	v_mfma_f32_16x16x32_bf16 v[26:29], v[166:169], v[206:209], v[26:29]
	v_mfma_f32_16x16x32_bf16 v[22:25], v[174:177], v[206:209], v[22:25]
	v_mfma_f32_16x16x32_bf16 v[10:13], v[166:169], v[228:231], v[10:13]
	v_mfma_f32_16x16x32_bf16 v[4:7], v[174:177], v[228:231], v[6:9]
	v_mfma_f32_16x16x32_bf16 v[58:61], v[170:173], v[186:189], v[58:61]
	v_mfma_f32_16x16x32_bf16 v[54:57], v[178:181], v[186:189], v[54:57]
	v_mfma_f32_16x16x32_bf16 v[42:45], v[170:173], v[194:197], v[42:45]
	v_mfma_f32_16x16x32_bf16 v[38:41], v[178:181], v[194:197], v[38:41]
	v_mfma_f32_16x16x32_bf16 v[26:29], v[170:173], v[224:227], v[26:29]
	v_mfma_f32_16x16x32_bf16 v[22:25], v[178:181], v[224:227], v[22:25]
	v_mfma_f32_16x16x32_bf16 v[10:13], v[170:173], v[232:235], v[10:13]
	v_mfma_f32_16x16x32_bf16 v[4:7], v[178:181], v[232:235], v[4:7]
	s_setprio 0
	s_barrier
	s_add_i32 s68, 0, 0x18000
	v_add_u32_e32 v2, s68, v147
	s_add_i32 s69, 0, 0x1c000
	ds_read_b128 v[150:153], v2
	ds_read_b128 v[154:157], v2 offset:1024
	ds_read_b128 v[158:161], v2 offset:2048
	ds_read_b128 v[162:165], v2 offset:3072
	v_add_u32_e32 v2, s69, v147
	ds_read_b128 v[166:169], v2
	ds_read_b128 v[170:173], v2 offset:1024
	ds_read_b128 v[174:177], v2 offset:2048
	ds_read_b128 v[178:181], v2 offset:3072
	s_add_u32 s50, s50, 0x40000
	s_addc_u32 s51, s51, 0
	s_mov_b32 m0, s54
	ds_read_b128 v[182:185], v148 offset:32768
	ds_read_b128 v[186:189], v148 offset:33792
	ds_read_b128 v[190:193], v148 offset:34816
	ds_read_b128 v[194:197], v148 offset:35840
	ds_read_b128 v[206:209], v148 offset:36864
	ds_read_b128 v[224:227], v148 offset:37888
	ds_read_b128 v[228:231], v148 offset:38912
	ds_read_b128 v[232:235], v148 offset:39936
	s_add_u32 s100, s50, 0xfffc0000
	s_addc_u32 s101, s51, -1
	s_mov_b32 m0, s52
	s_nop 0
	global_load_lds_dwordx4 v140, s[100:101]
	s_mov_b32 m0, s53
	s_nop 0
	global_load_lds_dwordx4 v136, s[100:101]
	s_mov_b32 m0, s54
	s_nop 0
	global_load_lds_dwordx4 v140, s[50:51]
	s_mov_b32 m0, s55
	s_nop 0
	global_load_lds_dwordx4 v136, s[50:51]
	s_waitcnt vmcnt(8)
	s_waitcnt lgkmcnt(0)
	s_barrier
; #define PG8_STAGE(bufoff, gbase, voff) do { _Pragma("unroll") for (int _i = 0; _i < 2; ++_i) \
;         __builtin_amdgcn_global_load_lds((const unsigned*)((const char*)(gbase) + (voff)[_i]), (LAS unsigned*)(lds + (bufoff) + ldsw + _i * 8192), 16, 0, 0); } while (0)
; #define PG8_LDA(dst, b, h) do { _Pragma("unroll") for (int m = 0; m < 4; ++m) _Pragma("unroll") for (int k = 0; k < 2; ++k) dst[m][k] = *(const LAS bf16x8*)(lds + PG8_SA(b, h) + aoff + m * 2048 + k * 1024); } while (0)
; #define PG8_MMA(ai, bj, At, Bt) do { __builtin_amdgcn_s_setprio(1); _Pragma("unroll") for (int m = 0; m < 4; ++m) _Pragma("unroll") for (int n = 0; n < 2; ++n) _Pragma("unroll") for (int k = 0; k < 2; ++k) \
;         acc[ai][bj][m][n] = __builtin_amdgcn_mfma_f32_16x16x32_bf16(Bt[n][k], At[m][k], acc[ai][bj][m][n], 0, 0, 0); __builtin_amdgcn_s_setprio(0); } while (0)
; #define PG8_WAIT_V(n) asm volatile("s_waitcnt vmcnt(" #n ")" ::: "memory")
; #define PG8_WAIT_L(n) asm volatile("s_waitcnt lgkmcnt(" #n ")" ::: "memory")
; #define PG8_BAR __builtin_amdgcn_s_barrier()
; #define PG8_SCHED __builtin_amdgcn_sched_barrier(0)
; template <class Epi, bool ALIGN_EPI = true>
; __device__ __forceinline__ void gemm_phase(LAS unsigned char* lds, const Gemm g, const Sched& S, const Epi& E) {
;     ...
;             PG8_WAIT_V(8); PG8_WAIT_L(0); PG8_BAR; PG8_MMA(0, 0, At, B0); PG8_MMA(0, 1, At, B1); PG8_BAR; PG8_SCHED;
;             PG8_LDA(At, 1, 1); PG8_STAGE(PG8_SB(1, 0), b3, voffB); PG8_STAGE(PG8_SB(1, 1), b3 + hstepB, voffB); PG8_STAGE(PG8_SA(1, 0), a3, voffA);
;             PG8_WAIT_V(8); PG8_WAIT_L(0); PG8_BAR; PG8_MMA(1, 0, At, B0); PG8_MMA(1, 1, At, B1); PG8_BAR; PG8_SCHED;
	s_setprio 1
	s_waitcnt lgkmcnt(0)
	v_mfma_f32_16x16x32_bf16 v[130:133], v[150:153], v[182:185], v[130:133]
	v_mfma_f32_16x16x32_bf16 v[126:129], v[158:161], v[182:185], v[126:129]
	v_mfma_f32_16x16x32_bf16 v[114:117], v[150:153], v[190:193], v[114:117]
	v_mfma_f32_16x16x32_bf16 v[110:113], v[158:161], v[190:193], v[110:113]
	v_mfma_f32_16x16x32_bf16 v[98:101], v[150:153], v[206:209], v[98:101]
	v_mfma_f32_16x16x32_bf16 v[94:97], v[158:161], v[206:209], v[94:97]
	v_mfma_f32_16x16x32_bf16 v[82:85], v[150:153], v[228:231], v[82:85]
	v_mfma_f32_16x16x32_bf16 v[78:81], v[158:161], v[228:231], v[78:81]
	v_mfma_f32_16x16x32_bf16 v[130:133], v[154:157], v[186:189], v[130:133]
	v_mfma_f32_16x16x32_bf16 v[126:129], v[162:165], v[186:189], v[126:129]
	v_mfma_f32_16x16x32_bf16 v[114:117], v[154:157], v[194:197], v[114:117]
	v_mfma_f32_16x16x32_bf16 v[110:113], v[162:165], v[194:197], v[110:113]
	v_mfma_f32_16x16x32_bf16 v[98:101], v[154:157], v[224:227], v[98:101]
	v_mfma_f32_16x16x32_bf16 v[94:97], v[162:165], v[224:227], v[94:97]
	v_mfma_f32_16x16x32_bf16 v[82:85], v[154:157], v[232:235], v[82:85]
	v_mfma_f32_16x16x32_bf16 v[78:81], v[162:165], v[232:235], v[78:81]
	v_mfma_f32_16x16x32_bf16 v[122:125], v[166:169], v[182:185], v[122:125]
	v_mfma_f32_16x16x32_bf16 v[118:121], v[174:177], v[182:185], v[118:121]
	v_mfma_f32_16x16x32_bf16 v[106:109], v[166:169], v[190:193], v[106:109]
	v_mfma_f32_16x16x32_bf16 v[102:105], v[174:177], v[190:193], v[102:105]
	v_mfma_f32_16x16x32_bf16 v[90:93], v[166:169], v[206:209], v[90:93]
	v_mfma_f32_16x16x32_bf16 v[86:89], v[174:177], v[206:209], v[86:89]
	v_mfma_f32_16x16x32_bf16 v[74:77], v[166:169], v[228:231], v[74:77]
	v_mfma_f32_16x16x32_bf16 v[70:73], v[174:177], v[228:231], v[70:73]
	v_mfma_f32_16x16x32_bf16 v[122:125], v[170:173], v[186:189], v[122:125]
	v_mfma_f32_16x16x32_bf16 v[118:121], v[178:181], v[186:189], v[118:121]
	v_mfma_f32_16x16x32_bf16 v[106:109], v[170:173], v[194:197], v[106:109]
	v_mfma_f32_16x16x32_bf16 v[102:105], v[178:181], v[194:197], v[102:105]
	v_mfma_f32_16x16x32_bf16 v[90:93], v[170:173], v[224:227], v[90:93]
	v_mfma_f32_16x16x32_bf16 v[86:89], v[178:181], v[224:227], v[86:89]
	v_mfma_f32_16x16x32_bf16 v[74:77], v[170:173], v[232:235], v[74:77]
	v_mfma_f32_16x16x32_bf16 v[70:73], v[178:181], v[232:235], v[70:73]
	s_setprio 0
	s_barrier
	s_add_u32 s100, s48, 0x80
	s_addc_u32 s101, s49, 0
	s_add_i32 s50, s68, s37
	s_mov_b32 m0, s50
	ds_read_b128 v[182:185], v148 offset:49152
	ds_read_b128 v[186:189], v148 offset:50176
	ds_read_b128 v[190:193], v148 offset:51200
	ds_read_b128 v[194:197], v148 offset:52224
	ds_read_b128 v[206:209], v148 offset:53248
	ds_read_b128 v[224:227], v148 offset:54272
	ds_read_b128 v[228:231], v148 offset:55296
	ds_read_b128 v[232:235], v148 offset:56320
	global_load_lds_dwordx4 v138, s[100:101]
	s_add_i32 m0, s50, 0x2000
	s_add_u32 s48, s48, 0x40080
	s_addc_u32 s49, s49, 0
	s_add_i32 s50, s69, s37
	global_load_lds_dwordx4 v134, s[100:101]
	s_mov_b32 m0, s50
	s_nop 0
	global_load_lds_dwordx4 v138, s[48:49]
	s_add_i32 m0, s50, 0x2000
	s_nop 0
	global_load_lds_dwordx4 v134, s[48:49]
	s_waitcnt vmcnt(6)
	s_waitcnt lgkmcnt(0)
	s_barrier
	s_setprio 1
	s_waitcnt lgkmcnt(0)
	v_mfma_f32_16x16x32_bf16 v[66:69], v[150:153], v[182:185], v[66:69]
	v_mfma_f32_16x16x32_bf16 v[62:65], v[158:161], v[182:185], v[62:65]
	v_mfma_f32_16x16x32_bf16 v[50:53], v[150:153], v[190:193], v[50:53]
	v_mfma_f32_16x16x32_bf16 v[46:49], v[158:161], v[190:193], v[46:49]
	v_mfma_f32_16x16x32_bf16 v[34:37], v[150:153], v[206:209], v[34:37]
	v_mfma_f32_16x16x32_bf16 v[30:33], v[158:161], v[206:209], v[30:33]
	v_mfma_f32_16x16x32_bf16 v[18:21], v[150:153], v[228:231], v[18:21]
	v_mfma_f32_16x16x32_bf16 v[14:17], v[158:161], v[228:231], v[14:17]
	v_mfma_f32_16x16x32_bf16 v[66:69], v[154:157], v[186:189], v[66:69]
	v_mfma_f32_16x16x32_bf16 v[62:65], v[162:165], v[186:189], v[62:65]
	v_mfma_f32_16x16x32_bf16 v[50:53], v[154:157], v[194:197], v[50:53]
	v_mfma_f32_16x16x32_bf16 v[46:49], v[162:165], v[194:197], v[46:49]
	v_mfma_f32_16x16x32_bf16 v[34:37], v[154:157], v[224:227], v[34:37]
	v_mfma_f32_16x16x32_bf16 v[30:33], v[162:165], v[224:227], v[30:33]
	v_mfma_f32_16x16x32_bf16 v[18:21], v[154:157], v[232:235], v[18:21]
	v_mfma_f32_16x16x32_bf16 v[14:17], v[162:165], v[232:235], v[14:17]
	v_mfma_f32_16x16x32_bf16 v[58:61], v[166:169], v[182:185], v[58:61]
	v_mfma_f32_16x16x32_bf16 v[54:57], v[174:177], v[182:185], v[54:57]
	v_mfma_f32_16x16x32_bf16 v[42:45], v[166:169], v[190:193], v[42:45]
	v_mfma_f32_16x16x32_bf16 v[38:41], v[174:177], v[190:193], v[38:41]
	v_mfma_f32_16x16x32_bf16 v[26:29], v[166:169], v[206:209], v[26:29]
	v_mfma_f32_16x16x32_bf16 v[22:25], v[174:177], v[206:209], v[22:25]
	v_mfma_f32_16x16x32_bf16 v[8:11], v[166:169], v[228:231], v[10:13]
	v_mfma_f32_16x16x32_bf16 v[4:7], v[174:177], v[228:231], v[4:7]
	v_mfma_f32_16x16x32_bf16 v[58:61], v[170:173], v[186:189], v[58:61]
	v_mfma_f32_16x16x32_bf16 v[54:57], v[178:181], v[186:189], v[54:57]
	v_mfma_f32_16x16x32_bf16 v[42:45], v[170:173], v[194:197], v[42:45]
	v_mfma_f32_16x16x32_bf16 v[38:41], v[178:181], v[194:197], v[38:41]
	v_mfma_f32_16x16x32_bf16 v[26:29], v[170:173], v[224:227], v[26:29]
	v_mfma_f32_16x16x32_bf16 v[22:25], v[178:181], v[224:227], v[22:25]
	v_mfma_f32_16x16x32_bf16 v[10:13], v[170:173], v[232:235], v[8:11]
	v_mfma_f32_16x16x32_bf16 v[6:9], v[178:181], v[232:235], v[4:7]
	s_setprio 0
	s_barrier
	s_add_u32 s46, s46, 0x100
	s_addc_u32 s47, s47, 0
	s_add_u32 s65, s65, 0x100
	s_addc_u32 s66, s66, 0
	s_cmp_ge_i32 s67, s56
	s_mov_b32 s48, s67
	s_cbranch_scc0 .LBB0_1929

; #define PG8_STAGE(bufoff, gbase, voff) do { _Pragma("unroll") for (int _i = 0; _i < 2; ++_i) \
;         __builtin_amdgcn_global_load_lds((const unsigned*)((const char*)(gbase) + (voff)[_i]), (LAS unsigned*)(lds + (bufoff) + ldsw + _i * 8192), 16, 0, 0); } while (0)
; #define PG8_LDA(dst, b, h) do { _Pragma("unroll") for (int m = 0; m < 4; ++m) _Pragma("unroll") for (int k = 0; k < 2; ++k) dst[m][k] = *(const LAS bf16x8*)(lds + PG8_SA(b, h) + aoff + m * 2048 + k * 1024); } while (0)
; #define PG8_LDB(dst, b, h) do { _Pragma("unroll") for (int n = 0; n < 2; ++n) _Pragma("unroll") for (int k = 0; k < 2; ++k) dst[n][k] = *(const LAS bf16x8*)(lds + PG8_SB(b, h) + boff + n * 2048 + k * 1024); } while (0)
; #define PG8_MMA(ai, bj, At, Bt) do { __builtin_amdgcn_s_setprio(1); _Pragma("unroll") for (int m = 0; m < 4; ++m) _Pragma("unroll") for (int n = 0; n < 2; ++n) _Pragma("unroll") for (int k = 0; k < 2; ++k) \
;         acc[ai][bj][m][n] = __builtin_amdgcn_mfma_f32_16x16x32_bf16(Bt[n][k], At[m][k], acc[ai][bj][m][n], 0, 0, 0); __builtin_amdgcn_s_setprio(0); } while (0)
; #define PG8_WAIT_V(n) asm volatile("s_waitcnt vmcnt(" #n ")" ::: "memory")
; #define PG8_WAIT_L(n) asm volatile("s_waitcnt lgkmcnt(" #n ")" ::: "memory")
; #define PG8_BAR __builtin_amdgcn_s_barrier()
; #define PG8_WAIT_RELAX(flag, n) asm volatile("s_cmp_eq_u32 %0, 0\n\ts_cbranch_scc1 .Lrw%=\n\ts_waitcnt vmcnt(8)\n.Lrw%=:\n\ts_waitcnt vmcnt(%1)" :: "s"(flag), "n"(n) : "scc", "memory")
; #define PG8_SCHED __builtin_amdgcn_sched_barrier(0)
; template <class Epi, bool ALIGN_EPI = true>
; __device__ __forceinline__ void gemm_phase(LAS unsigned char* lds, const Gemm g, const Sched& S, const Epi& E) {
;     ...
;             PG8_LDB(B0, 0, 0); PG8_LDB(B1, 0, 1); PG8_SCHED; PG8_LDA(At, 0, 0); PG8_STAGE(PG8_SA(1, 1), a1 + hstepA, voffA);
;             if constexpr (Epi::NSTORES > 0) PG8_WAIT_RELAX(rflag, 8 + Epi::NSTORES); else PG8_WAIT_V(8);
;             PG8_WAIT_L(0); PG8_BAR; PG8_MMA(0, 0, At, B0); PG8_MMA(0, 1, At, B1); PG8_BAR; PG8_SCHED;
;             PG8_LDA(At, 0, 1); PG8_STAGE(PG8_SB(0, 0), b2, voffB); PG8_STAGE(PG8_SB(0, 1), b2 + hstepB, voffB); PG8_STAGE(PG8_SA(0, 0), a2, voffA);
;             if constexpr (Epi::NSTORES > 0) PG8_WAIT_RELAX(rflag, 8 + Epi::NSTORES); else PG8_WAIT_V(8);
;             PG8_WAIT_L(0); PG8_BAR; PG8_MMA(1, 0, At, B0); PG8_MMA(1, 1, At, B1); PG8_BAR; PG8_SCHED;
.Lrw18:
	s_waitcnt vmcnt(16)
	s_waitcnt lgkmcnt(0)
	s_barrier
	s_setprio 1
	s_waitcnt lgkmcnt(0)
	v_mfma_f32_16x16x32_bf16 v[130:133], v[146:149], v[182:185], v[130:133]
	v_mfma_f32_16x16x32_bf16 v[126:129], v[158:161], v[182:185], v[126:129]
	v_mfma_f32_16x16x32_bf16 v[122:125], v[146:149], v[190:193], v[122:125]
	v_mfma_f32_16x16x32_bf16 v[118:121], v[158:161], v[190:193], v[118:121]
	v_mfma_f32_16x16x32_bf16 v[114:117], v[146:149], v[206:209], v[114:117]
	v_mfma_f32_16x16x32_bf16 v[110:113], v[158:161], v[206:209], v[110:113]
	v_mfma_f32_16x16x32_bf16 v[106:109], v[146:149], v[228:231], v[106:109]
	v_mfma_f32_16x16x32_bf16 v[102:105], v[158:161], v[228:231], v[102:105]
	v_mfma_f32_16x16x32_bf16 v[130:133], v[154:157], v[186:189], v[130:133]
	v_mfma_f32_16x16x32_bf16 v[126:129], v[162:165], v[186:189], v[126:129]
	v_mfma_f32_16x16x32_bf16 v[122:125], v[154:157], v[194:197], v[122:125]
	v_mfma_f32_16x16x32_bf16 v[118:121], v[162:165], v[194:197], v[118:121]
	v_mfma_f32_16x16x32_bf16 v[114:117], v[154:157], v[224:227], v[114:117]
	v_mfma_f32_16x16x32_bf16 v[110:113], v[162:165], v[224:227], v[110:113]
	v_mfma_f32_16x16x32_bf16 v[106:109], v[154:157], v[232:235], v[106:109]
	v_mfma_f32_16x16x32_bf16 v[102:105], v[162:165], v[232:235], v[102:105]
	v_mfma_f32_16x16x32_bf16 v[98:101], v[166:169], v[182:185], v[98:101]
	v_mfma_f32_16x16x32_bf16 v[94:97], v[174:177], v[182:185], v[94:97]
	v_mfma_f32_16x16x32_bf16 v[90:93], v[166:169], v[190:193], v[90:93]
	v_mfma_f32_16x16x32_bf16 v[86:89], v[174:177], v[190:193], v[86:89]
	v_mfma_f32_16x16x32_bf16 v[82:85], v[166:169], v[206:209], v[82:85]
	v_mfma_f32_16x16x32_bf16 v[78:81], v[174:177], v[206:209], v[78:81]
	v_mfma_f32_16x16x32_bf16 v[74:77], v[166:169], v[228:231], v[74:77]
	v_mfma_f32_16x16x32_bf16 v[70:73], v[174:177], v[228:231], v[70:73]
	v_mfma_f32_16x16x32_bf16 v[98:101], v[170:173], v[186:189], v[98:101]
	v_mfma_f32_16x16x32_bf16 v[94:97], v[178:181], v[186:189], v[94:97]
	v_mfma_f32_16x16x32_bf16 v[90:93], v[170:173], v[194:197], v[90:93]
	v_mfma_f32_16x16x32_bf16 v[86:89], v[178:181], v[194:197], v[86:89]
	v_mfma_f32_16x16x32_bf16 v[82:85], v[170:173], v[224:227], v[82:85]
	v_mfma_f32_16x16x32_bf16 v[78:81], v[178:181], v[224:227], v[78:81]
	v_mfma_f32_16x16x32_bf16 v[74:77], v[170:173], v[232:235], v[74:77]
	v_mfma_f32_16x16x32_bf16 v[70:73], v[178:181], v[232:235], v[70:73]
	s_setprio 0
	s_barrier
	s_add_i32 s70, s70, s35
	s_mov_b32 m0, s70
	ds_read_b128 v[182:185], v152 offset:16384
	ds_read_b128 v[186:189], v152 offset:17408
	ds_read_b128 v[190:193], v152 offset:18432
	ds_read_b128 v[194:197], v152 offset:19456
	ds_read_b128 v[206:209], v152 offset:20480
	ds_read_b128 v[224:227], v152 offset:21504
	ds_read_b128 v[228:231], v152 offset:22528
	ds_read_b128 v[232:235], v152 offset:23552
	global_load_lds_dwordx4 v136, s[46:47]
	s_add_i32 m0, s70, 0x2000
	s_add_u32 s70, s46, 0x80000
	s_addc_u32 s71, s47, 0
	s_add_i32 s72, s72, s35
	global_load_lds_dwordx4 v140, s[46:47]
	s_mov_b32 m0, s72
	s_nop 0
	global_load_lds_dwordx4 v136, s[70:71]
	s_add_i32 m0, s72, 0x2000
	s_nop 0
	global_load_lds_dwordx4 v140, s[70:71]
	s_cmp_eq_u32 s73, 0
	s_cbranch_scc1 .Lrw19
	s_waitcnt vmcnt(6)
.Lrw19:
	s_waitcnt vmcnt(6)
	s_waitcnt lgkmcnt(0)
	s_barrier
	s_setprio 1
	s_waitcnt lgkmcnt(0)
	v_mfma_f32_16x16x32_bf16 v[66:69], v[146:149], v[182:185], v[66:69]
	v_mfma_f32_16x16x32_bf16 v[62:65], v[158:161], v[182:185], v[62:65]
	v_mfma_f32_16x16x32_bf16 v[58:61], v[146:149], v[190:193], v[58:61]
	v_mfma_f32_16x16x32_bf16 v[54:57], v[158:161], v[190:193], v[54:57]
	v_mfma_f32_16x16x32_bf16 v[50:53], v[146:149], v[206:209], v[50:53]
	v_mfma_f32_16x16x32_bf16 v[46:49], v[158:161], v[206:209], v[46:49]
	v_mfma_f32_16x16x32_bf16 v[42:45], v[146:149], v[228:231], v[42:45]
	v_mfma_f32_16x16x32_bf16 v[38:41], v[158:161], v[228:231], v[38:41]
	v_mfma_f32_16x16x32_bf16 v[66:69], v[154:157], v[186:189], v[66:69]
	v_mfma_f32_16x16x32_bf16 v[62:65], v[162:165], v[186:189], v[62:65]
	v_mfma_f32_16x16x32_bf16 v[58:61], v[154:157], v[194:197], v[58:61]
	v_mfma_f32_16x16x32_bf16 v[54:57], v[162:165], v[194:197], v[54:57]
	v_mfma_f32_16x16x32_bf16 v[50:53], v[154:157], v[224:227], v[50:53]
	v_mfma_f32_16x16x32_bf16 v[46:49], v[162:165], v[224:227], v[46:49]
	v_mfma_f32_16x16x32_bf16 v[42:45], v[154:157], v[232:235], v[42:45]
	v_mfma_f32_16x16x32_bf16 v[38:41], v[162:165], v[232:235], v[38:41]
	v_mfma_f32_16x16x32_bf16 v[34:37], v[166:169], v[182:185], v[34:37]
	v_mfma_f32_16x16x32_bf16 v[30:33], v[174:177], v[182:185], v[30:33]
	v_mfma_f32_16x16x32_bf16 v[26:29], v[166:169], v[190:193], v[26:29]
	v_mfma_f32_16x16x32_bf16 v[22:25], v[174:177], v[190:193], v[22:25]
	v_mfma_f32_16x16x32_bf16 v[18:21], v[166:169], v[206:209], v[18:21]
	v_mfma_f32_16x16x32_bf16 v[14:17], v[174:177], v[206:209], v[14:17]
	v_mfma_f32_16x16x32_bf16 v[10:13], v[166:169], v[228:231], v[10:13]
	v_mfma_f32_16x16x32_bf16 v[4:7], v[174:177], v[228:231], v[6:9]
	v_mfma_f32_16x16x32_bf16 v[34:37], v[170:173], v[186:189], v[34:37]
	v_mfma_f32_16x16x32_bf16 v[30:33], v[178:181], v[186:189], v[30:33]
	v_mfma_f32_16x16x32_bf16 v[26:29], v[170:173], v[194:197], v[26:29]
	v_mfma_f32_16x16x32_bf16 v[22:25], v[178:181], v[194:197], v[22:25]
	v_mfma_f32_16x16x32_bf16 v[18:21], v[170:173], v[224:227], v[18:21]
	v_mfma_f32_16x16x32_bf16 v[14:17], v[178:181], v[224:227], v[14:17]
	v_mfma_f32_16x16x32_bf16 v[10:13], v[170:173], v[232:235], v[10:13]
	v_mfma_f32_16x16x32_bf16 v[4:7], v[178:181], v[232:235], v[4:7]
	s_setprio 0
	s_barrier
; #define PG8_STAGE(bufoff, gbase, voff) do { _Pragma("unroll") for (int _i = 0; _i < 2; ++_i) \
;         __builtin_amdgcn_global_load_lds((const unsigned*)((const char*)(gbase) + (voff)[_i]), (LAS unsigned*)(lds + (bufoff) + ldsw + _i * 8192), 16, 0, 0); } while (0)
; #define PG8_LDA(dst, b, h) do { _Pragma("unroll") for (int m = 0; m < 4; ++m) _Pragma("unroll") for (int k = 0; k < 2; ++k) dst[m][k] = *(const LAS bf16x8*)(lds + PG8_SA(b, h) + aoff + m * 2048 + k * 1024); } while (0)
; #define PG8_LDB(dst, b, h) do { _Pragma("unroll") for (int n = 0; n < 2; ++n) _Pragma("unroll") for (int k = 0; k < 2; ++k) dst[n][k] = *(const LAS bf16x8*)(lds + PG8_SB(b, h) + boff + n * 2048 + k * 1024); } while (0)
; #define PG8_MMA(ai, bj, At, Bt) do { __builtin_amdgcn_s_setprio(1); _Pragma("unroll") for (int m = 0; m < 4; ++m) _Pragma("unroll") for (int n = 0; n < 2; ++n) _Pragma("unroll") for (int k = 0; k < 2; ++k) \
;         acc[ai][bj][m][n] = __builtin_amdgcn_mfma_f32_16x16x32_bf16(Bt[n][k], At[m][k], acc[ai][bj][m][n], 0, 0, 0); __builtin_amdgcn_s_setprio(0); } while (0)
; #define PG8_WAIT_V(n) asm volatile("s_waitcnt vmcnt(" #n ")" ::: "memory")
; #define PG8_WAIT_L(n) asm volatile("s_waitcnt lgkmcnt(" #n ")" ::: "memory")
; #define PG8_BAR __builtin_amdgcn_s_barrier()
; #define PG8_SCHED __builtin_amdgcn_sched_barrier(0)
; template <class Epi, bool ALIGN_EPI = true>
; __device__ __forceinline__ void gemm_phase(LAS unsigned char* lds, const Gemm g, const Sched& S, const Epi& E) {
;     ...
;             PG8_LDB(B0, 1, 0); PG8_LDB(B1, 1, 1); PG8_SCHED; PG8_LDA(At, 1, 0); PG8_STAGE(PG8_SA(0, 1), a2 + hstepA, voffA);
;             PG8_WAIT_V(8); PG8_WAIT_L(0); PG8_BAR; PG8_MMA(0, 0, At, B0); PG8_MMA(0, 1, At, B1); PG8_BAR; PG8_SCHED;
;             PG8_LDA(At, 1, 1); PG8_STAGE(PG8_SB(1, 0), b3, voffB); PG8_STAGE(PG8_SB(1, 1), b3 + hstepB, voffB); PG8_STAGE(PG8_SA(1, 0), a3, voffA);
;             PG8_WAIT_V(8); PG8_WAIT_L(0); PG8_BAR; PG8_MMA(1, 0, At, B0); PG8_MMA(1, 1, At, B1); PG8_BAR; PG8_SCHED;
	s_add_i32 s70, 0, 0x18000
	v_add_u32_e32 v8, s70, v151
	s_add_i32 s71, 0, 0x1c000
	ds_read_b128 v[146:149], v8
	ds_read_b128 v[154:157], v8 offset:1024
	ds_read_b128 v[158:161], v8 offset:2048
	ds_read_b128 v[162:165], v8 offset:3072
	v_add_u32_e32 v8, s71, v151
	ds_read_b128 v[166:169], v8
	ds_read_b128 v[170:173], v8 offset:1024
	ds_read_b128 v[174:177], v8 offset:2048
	ds_read_b128 v[178:181], v8 offset:3072
	s_add_u32 s48, s48, 0x80000
	s_addc_u32 s49, s49, 0
	s_mov_b32 m0, s50
	ds_read_b128 v[182:185], v152 offset:32768
	ds_read_b128 v[186:189], v152 offset:33792
	ds_read_b128 v[190:193], v152 offset:34816
	ds_read_b128 v[194:197], v152 offset:35840
	ds_read_b128 v[206:209], v152 offset:36864
	ds_read_b128 v[224:227], v152 offset:37888
	ds_read_b128 v[228:231], v152 offset:38912
	ds_read_b128 v[232:235], v152 offset:39936
	s_add_u32 s100, s48, 0xfff80000
	s_addc_u32 s101, s49, -1
	s_mov_b32 m0, s36
	s_nop 0
	global_load_lds_dwordx4 v134, s[100:101]
	s_mov_b32 m0, s37
	s_nop 0
	global_load_lds_dwordx4 v138, s[100:101]
	s_mov_b32 m0, s50
	s_nop 0
	global_load_lds_dwordx4 v134, s[48:49]
	s_mov_b32 m0, s51
	s_nop 0
	global_load_lds_dwordx4 v138, s[48:49]
	s_waitcnt vmcnt(8)
	s_waitcnt lgkmcnt(0)
	s_barrier
	s_setprio 1
	s_waitcnt lgkmcnt(0)
	v_mfma_f32_16x16x32_bf16 v[130:133], v[146:149], v[182:185], v[130:133]
	v_mfma_f32_16x16x32_bf16 v[126:129], v[158:161], v[182:185], v[126:129]
	v_mfma_f32_16x16x32_bf16 v[122:125], v[146:149], v[190:193], v[122:125]
	v_mfma_f32_16x16x32_bf16 v[118:121], v[158:161], v[190:193], v[118:121]
	v_mfma_f32_16x16x32_bf16 v[114:117], v[146:149], v[206:209], v[114:117]
	v_mfma_f32_16x16x32_bf16 v[110:113], v[158:161], v[206:209], v[110:113]
	v_mfma_f32_16x16x32_bf16 v[106:109], v[146:149], v[228:231], v[106:109]
	v_mfma_f32_16x16x32_bf16 v[102:105], v[158:161], v[228:231], v[102:105]
	v_mfma_f32_16x16x32_bf16 v[130:133], v[154:157], v[186:189], v[130:133]
	v_mfma_f32_16x16x32_bf16 v[126:129], v[162:165], v[186:189], v[126:129]
	v_mfma_f32_16x16x32_bf16 v[122:125], v[154:157], v[194:197], v[122:125]
	v_mfma_f32_16x16x32_bf16 v[118:121], v[162:165], v[194:197], v[118:121]
	v_mfma_f32_16x16x32_bf16 v[114:117], v[154:157], v[224:227], v[114:117]
	v_mfma_f32_16x16x32_bf16 v[110:113], v[162:165], v[224:227], v[110:113]
	v_mfma_f32_16x16x32_bf16 v[106:109], v[154:157], v[232:235], v[106:109]
	v_mfma_f32_16x16x32_bf16 v[102:105], v[162:165], v[232:235], v[102:105]
	v_mfma_f32_16x16x32_bf16 v[98:101], v[166:169], v[182:185], v[98:101]
	v_mfma_f32_16x16x32_bf16 v[94:97], v[174:177], v[182:185], v[94:97]
	v_mfma_f32_16x16x32_bf16 v[90:93], v[166:169], v[190:193], v[90:93]
	v_mfma_f32_16x16x32_bf16 v[86:89], v[174:177], v[190:193], v[86:89]
	v_mfma_f32_16x16x32_bf16 v[82:85], v[166:169], v[206:209], v[82:85]
	v_mfma_f32_16x16x32_bf16 v[78:81], v[174:177], v[206:209], v[78:81]
	v_mfma_f32_16x16x32_bf16 v[74:77], v[166:169], v[228:231], v[74:77]
	v_mfma_f32_16x16x32_bf16 v[70:73], v[174:177], v[228:231], v[70:73]
	v_mfma_f32_16x16x32_bf16 v[98:101], v[170:173], v[186:189], v[98:101]
	v_mfma_f32_16x16x32_bf16 v[94:97], v[178:181], v[186:189], v[94:97]
	v_mfma_f32_16x16x32_bf16 v[90:93], v[170:173], v[194:197], v[90:93]
	v_mfma_f32_16x16x32_bf16 v[86:89], v[178:181], v[194:197], v[86:89]
	v_mfma_f32_16x16x32_bf16 v[82:85], v[170:173], v[224:227], v[82:85]
	v_mfma_f32_16x16x32_bf16 v[78:81], v[178:181], v[224:227], v[78:81]
	v_mfma_f32_16x16x32_bf16 v[74:77], v[170:173], v[232:235], v[74:77]
	v_mfma_f32_16x16x32_bf16 v[70:73], v[178:181], v[232:235], v[70:73]
	s_setprio 0
	s_barrier
	s_add_u32 s100, s46, 0x80
	s_addc_u32 s101, s47, 0
	s_add_i32 s48, s70, s35
	s_mov_b32 m0, s48
	ds_read_b128 v[182:185], v152 offset:49152
	ds_read_b128 v[186:189], v152 offset:50176
	ds_read_b128 v[190:193], v152 offset:51200
	ds_read_b128 v[194:197], v152 offset:52224
	ds_read_b128 v[206:209], v152 offset:53248
	ds_read_b128 v[224:227], v152 offset:54272
	ds_read_b128 v[228:231], v152 offset:55296
	ds_read_b128 v[232:235], v152 offset:56320
	global_load_lds_dwordx4 v136, s[100:101]
	s_add_i32 m0, s48, 0x2000
	s_add_u32 s46, s46, 0x80080
	s_addc_u32 s47, s47, 0
	s_add_i32 s48, s71, s35
	global_load_lds_dwordx4 v140, s[100:101]
	s_mov_b32 m0, s48
	s_nop 0
	global_load_lds_dwordx4 v136, s[46:47]
	s_add_i32 m0, s48, 0x2000
	s_nop 0
	global_load_lds_dwordx4 v140, s[46:47]
	s_waitcnt vmcnt(6)
	s_waitcnt lgkmcnt(0)
	s_barrier
	s_setprio 1
	s_waitcnt lgkmcnt(0)
	v_mfma_f32_16x16x32_bf16 v[66:69], v[146:149], v[182:185], v[66:69]
	v_mfma_f32_16x16x32_bf16 v[62:65], v[158:161], v[182:185], v[62:65]
	v_mfma_f32_16x16x32_bf16 v[58:61], v[146:149], v[190:193], v[58:61]
	v_mfma_f32_16x16x32_bf16 v[54:57], v[158:161], v[190:193], v[54:57]
	v_mfma_f32_16x16x32_bf16 v[50:53], v[146:149], v[206:209], v[50:53]
	v_mfma_f32_16x16x32_bf16 v[46:49], v[158:161], v[206:209], v[46:49]
	v_mfma_f32_16x16x32_bf16 v[42:45], v[146:149], v[228:231], v[42:45]
	v_mfma_f32_16x16x32_bf16 v[38:41], v[158:161], v[228:231], v[38:41]
	v_mfma_f32_16x16x32_bf16 v[66:69], v[154:157], v[186:189], v[66:69]
	v_mfma_f32_16x16x32_bf16 v[62:65], v[162:165], v[186:189], v[62:65]
	v_mfma_f32_16x16x32_bf16 v[58:61], v[154:157], v[194:197], v[58:61]
	v_mfma_f32_16x16x32_bf16 v[54:57], v[162:165], v[194:197], v[54:57]
	v_mfma_f32_16x16x32_bf16 v[50:53], v[154:157], v[224:227], v[50:53]
	v_mfma_f32_16x16x32_bf16 v[46:49], v[162:165], v[224:227], v[46:49]
	v_mfma_f32_16x16x32_bf16 v[42:45], v[154:157], v[232:235], v[42:45]
	v_mfma_f32_16x16x32_bf16 v[38:41], v[162:165], v[232:235], v[38:41]
	v_mfma_f32_16x16x32_bf16 v[34:37], v[166:169], v[182:185], v[34:37]
	v_mfma_f32_16x16x32_bf16 v[30:33], v[174:177], v[182:185], v[30:33]
	v_mfma_f32_16x16x32_bf16 v[26:29], v[166:169], v[190:193], v[26:29]
	v_mfma_f32_16x16x32_bf16 v[22:25], v[174:177], v[190:193], v[22:25]
	v_mfma_f32_16x16x32_bf16 v[18:21], v[166:169], v[206:209], v[18:21]
	v_mfma_f32_16x16x32_bf16 v[14:17], v[174:177], v[206:209], v[14:17]
	v_mfma_f32_16x16x32_bf16 v[8:11], v[166:169], v[228:231], v[10:13]
	v_mfma_f32_16x16x32_bf16 v[4:7], v[174:177], v[228:231], v[4:7]
	v_mfma_f32_16x16x32_bf16 v[34:37], v[170:173], v[186:189], v[34:37]
	v_mfma_f32_16x16x32_bf16 v[30:33], v[178:181], v[186:189], v[30:33]
	v_mfma_f32_16x16x32_bf16 v[26:29], v[170:173], v[194:197], v[26:29]
	v_mfma_f32_16x16x32_bf16 v[22:25], v[178:181], v[194:197], v[22:25]
	v_mfma_f32_16x16x32_bf16 v[18:21], v[170:173], v[224:227], v[18:21]
	v_mfma_f32_16x16x32_bf16 v[14:17], v[178:181], v[224:227], v[14:17]
	v_mfma_f32_16x16x32_bf16 v[10:13], v[170:173], v[232:235], v[8:11]
	v_mfma_f32_16x16x32_bf16 v[6:9], v[178:181], v[232:235], v[4:7]
	s_setprio 0
	s_barrier
	s_add_u32 s26, s26, 0x100
	s_addc_u32 s27, s27, 0
	s_add_u32 s67, s67, 0x100
	s_addc_u32 s68, s68, 0
	s_cmp_ge_i32 s69, s54
	s_mov_b32 s46, s69
	s_cbranch_scc0 .LBB0_2023
	s_mov_b32 s72, 0x8000

; #define PG8_STAGE(bufoff, gbase, voff) do { _Pragma("unroll") for (int _i = 0; _i < 2; ++_i) \
;         __builtin_amdgcn_global_load_lds((const unsigned*)((const char*)(gbase) + (voff)[_i]), (LAS unsigned*)(lds + (bufoff) + ldsw + _i * 8192), 16, 0, 0); } while (0)
; #define PG8_LDA(dst, b, h) do { _Pragma("unroll") for (int m = 0; m < 4; ++m) _Pragma("unroll") for (int k = 0; k < 2; ++k) dst[m][k] = *(const LAS bf16x8*)(lds + PG8_SA(b, h) + aoff + m * 2048 + k * 1024); } while (0)
; #define PG8_LDB(dst, b, h) do { _Pragma("unroll") for (int n = 0; n < 2; ++n) _Pragma("unroll") for (int k = 0; k < 2; ++k) dst[n][k] = *(const LAS bf16x8*)(lds + PG8_SB(b, h) + boff + n * 2048 + k * 1024); } while (0)
; #define PG8_MMA(ai, bj, At, Bt) do { __builtin_amdgcn_s_setprio(1); _Pragma("unroll") for (int m = 0; m < 4; ++m) _Pragma("unroll") for (int n = 0; n < 2; ++n) _Pragma("unroll") for (int k = 0; k < 2; ++k) \
;         acc[ai][bj][m][n] = __builtin_amdgcn_mfma_f32_16x16x32_bf16(Bt[n][k], At[m][k], acc[ai][bj][m][n], 0, 0, 0); __builtin_amdgcn_s_setprio(0); } while (0)
; #define PG8_WAIT_V(n) asm volatile("s_waitcnt vmcnt(" #n ")" ::: "memory")
; #define PG8_WAIT_L(n) asm volatile("s_waitcnt lgkmcnt(" #n ")" ::: "memory")
; #define PG8_BAR __builtin_amdgcn_s_barrier()
; #define PG8_SCHED __builtin_amdgcn_sched_barrier(0)
; template <class Epi, bool ALIGN_EPI = true>
; __device__ __forceinline__ void gemm_phase(LAS unsigned char* lds, const Gemm g, const Sched& S, const Epi& E) {
;     ...
;             PG8_LDB(B0, 0, 0); PG8_LDB(B1, 0, 1); PG8_SCHED; PG8_LDA(At, 0, 0); PG8_STAGE(PG8_SA(1, 1), a1 + hstepA, voffA);
;             if constexpr (Epi::NSTORES > 0) PG8_WAIT_RELAX(rflag, 8 + Epi::NSTORES); else PG8_WAIT_V(8);
;             PG8_WAIT_L(0); PG8_BAR; PG8_MMA(0, 0, At, B0); PG8_MMA(0, 1, At, B1); PG8_BAR; PG8_SCHED;
;             PG8_LDA(At, 0, 1); PG8_STAGE(PG8_SB(0, 0), b2, voffB); PG8_STAGE(PG8_SB(0, 1), b2 + hstepB, voffB); PG8_STAGE(PG8_SA(0, 0), a2, voffA);
;             if constexpr (Epi::NSTORES > 0) PG8_WAIT_RELAX(rflag, 8 + Epi::NSTORES); else PG8_WAIT_V(8);
;             PG8_WAIT_L(0); PG8_BAR; PG8_MMA(1, 0, At, B0); PG8_MMA(1, 1, At, B1); PG8_BAR; PG8_SCHED;
;             PG8_LDB(B0, 1, 0); PG8_LDB(B1, 1, 1); PG8_SCHED; PG8_LDA(At, 1, 0); PG8_STAGE(PG8_SA(0, 1), a2 + hstepA, voffA);
.LBB0_2287:
	s_add_i32 s69, s44, 2
	s_add_u32 s42, s48, 0x100
	s_addc_u32 s43, s49, 0
	s_add_i32 s70, 0, 0x10000
	s_cmp_eq_u32 s57, s44
	s_cselect_b32 s47, s63, s43
	s_cselect_b32 s46, s64, s42
	v_add_u32_e32 v2, s70, v147
	s_cselect_b32 s45, s65, s68
	s_cselect_b32 s44, s66, s67
	s_add_i32 s71, 0, 0x14000
	ds_read_b128 v[150:153], v2
	ds_read_b128 v[154:157], v2 offset:1024
	ds_read_b128 v[158:161], v2 offset:2048
	ds_read_b128 v[162:165], v2 offset:3072
	v_add_u32_e32 v2, s71, v147
	ds_read_b128 v[166:169], v2
	ds_read_b128 v[170:173], v2 offset:1024
	ds_read_b128 v[174:177], v2 offset:2048
	ds_read_b128 v[178:181], v2 offset:3072
	s_add_i32 m0, s50, 0xc000
	ds_read_b128 v[182:185], v148
	ds_read_b128 v[186:189], v148 offset:1024
	ds_read_b128 v[190:193], v148 offset:2048
	ds_read_b128 v[194:197], v148 offset:3072
	ds_read_b128 v[206:209], v148 offset:4096
	ds_read_b128 v[224:227], v148 offset:5120
	ds_read_b128 v[228:231], v148 offset:6144
	ds_read_b128 v[232:235], v148 offset:7168
	s_add_u32 s100, s48, 0xffea0000
	s_addc_u32 s101, s49, -1
	s_mov_b32 m0, s55
	s_nop 0
	global_load_lds_dwordx4 v142, s[100:101]
	s_mov_b32 m0, s56
	s_nop 0
	global_load_lds_dwordx4 v144, s[100:101]
	s_add_i32 m0, s50, 0xc000
	s_nop 0
	global_load_lds_dwordx4 v142, s[48:49]
	s_add_i32 m0, s50, 0xe000
	s_nop 0
	global_load_lds_dwordx4 v144, s[48:49]
	s_waitcnt vmcnt(8)
	s_waitcnt lgkmcnt(0)
	s_barrier
	s_setprio 1
	s_waitcnt lgkmcnt(0)
	v_mfma_f32_16x16x32_bf16 v[130:133], v[150:153], v[182:185], v[130:133]
	v_mfma_f32_16x16x32_bf16 v[126:129], v[158:161], v[182:185], v[126:129]
	v_mfma_f32_16x16x32_bf16 v[114:117], v[150:153], v[190:193], v[114:117]
	v_mfma_f32_16x16x32_bf16 v[110:113], v[158:161], v[190:193], v[110:113]
	v_mfma_f32_16x16x32_bf16 v[98:101], v[150:153], v[206:209], v[98:101]
	v_mfma_f32_16x16x32_bf16 v[94:97], v[158:161], v[206:209], v[94:97]
	v_mfma_f32_16x16x32_bf16 v[82:85], v[150:153], v[228:231], v[82:85]
	v_mfma_f32_16x16x32_bf16 v[78:81], v[158:161], v[228:231], v[78:81]
	v_mfma_f32_16x16x32_bf16 v[130:133], v[154:157], v[186:189], v[130:133]
	v_mfma_f32_16x16x32_bf16 v[126:129], v[162:165], v[186:189], v[126:129]
	v_mfma_f32_16x16x32_bf16 v[114:117], v[154:157], v[194:197], v[114:117]
	v_mfma_f32_16x16x32_bf16 v[110:113], v[162:165], v[194:197], v[110:113]
	v_mfma_f32_16x16x32_bf16 v[98:101], v[154:157], v[224:227], v[98:101]
	v_mfma_f32_16x16x32_bf16 v[94:97], v[162:165], v[224:227], v[94:97]
	v_mfma_f32_16x16x32_bf16 v[82:85], v[154:157], v[232:235], v[82:85]
	v_mfma_f32_16x16x32_bf16 v[78:81], v[162:165], v[232:235], v[78:81]
	v_mfma_f32_16x16x32_bf16 v[122:125], v[166:169], v[182:185], v[122:125]
	v_mfma_f32_16x16x32_bf16 v[118:121], v[174:177], v[182:185], v[118:121]
	v_mfma_f32_16x16x32_bf16 v[106:109], v[166:169], v[190:193], v[106:109]
	v_mfma_f32_16x16x32_bf16 v[102:105], v[174:177], v[190:193], v[102:105]
	v_mfma_f32_16x16x32_bf16 v[90:93], v[166:169], v[206:209], v[90:93]
	v_mfma_f32_16x16x32_bf16 v[86:89], v[174:177], v[206:209], v[86:89]
	v_mfma_f32_16x16x32_bf16 v[74:77], v[166:169], v[228:231], v[74:77]
	v_mfma_f32_16x16x32_bf16 v[70:73], v[174:177], v[228:231], v[70:73]
	v_mfma_f32_16x16x32_bf16 v[122:125], v[170:173], v[186:189], v[122:125]
	v_mfma_f32_16x16x32_bf16 v[118:121], v[178:181], v[186:189], v[118:121]
	v_mfma_f32_16x16x32_bf16 v[106:109], v[170:173], v[194:197], v[106:109]
	v_mfma_f32_16x16x32_bf16 v[102:105], v[178:181], v[194:197], v[102:105]
	v_mfma_f32_16x16x32_bf16 v[90:93], v[170:173], v[224:227], v[90:93]
	v_mfma_f32_16x16x32_bf16 v[86:89], v[178:181], v[224:227], v[86:89]
	v_mfma_f32_16x16x32_bf16 v[74:77], v[170:173], v[232:235], v[74:77]
	v_mfma_f32_16x16x32_bf16 v[70:73], v[178:181], v[232:235], v[70:73]
	s_setprio 0
	s_barrier
	s_add_i32 s48, s70, s37
	s_mov_b32 m0, s48
	ds_read_b128 v[182:185], v148 offset:16384
	ds_read_b128 v[186:189], v148 offset:17408
	ds_read_b128 v[190:193], v148 offset:18432
	ds_read_b128 v[194:197], v148 offset:19456
	ds_read_b128 v[206:209], v148 offset:20480
	ds_read_b128 v[224:227], v148 offset:21504
	ds_read_b128 v[228:231], v148 offset:22528
	ds_read_b128 v[232:235], v148 offset:23552
	global_load_lds_dwordx4 v138, s[44:45]
	s_add_i32 m0, s48, 0x2000
	s_add_u32 s48, s44, 0x160000
	s_addc_u32 s49, s45, 0
	s_add_i32 s70, s71, s37
	global_load_lds_dwordx4 v134, s[44:45]
	s_mov_b32 m0, s70
	s_nop 0
	global_load_lds_dwordx4 v138, s[48:49]
	s_add_i32 m0, s70, 0x2000
	s_nop 0
	global_load_lds_dwordx4 v134, s[48:49]
	s_waitcnt vmcnt(6)
	s_waitcnt lgkmcnt(0)
	s_barrier
; #define PG8_STAGE(bufoff, gbase, voff) do { _Pragma("unroll") for (int _i = 0; _i < 2; ++_i) \
;         __builtin_amdgcn_global_load_lds((const unsigned*)((const char*)(gbase) + (voff)[_i]), (LAS unsigned*)(lds + (bufoff) + ldsw + _i * 8192), 16, 0, 0); } while (0)
; #define PG8_LDA(dst, b, h) do { _Pragma("unroll") for (int m = 0; m < 4; ++m) _Pragma("unroll") for (int k = 0; k < 2; ++k) dst[m][k] = *(const LAS bf16x8*)(lds + PG8_SA(b, h) + aoff + m * 2048 + k * 1024); } while (0)
; #define PG8_LDB(dst, b, h) do { _Pragma("unroll") for (int n = 0; n < 2; ++n) _Pragma("unroll") for (int k = 0; k < 2; ++k) dst[n][k] = *(const LAS bf16x8*)(lds + PG8_SB(b, h) + boff + n * 2048 + k * 1024); } while (0)
; #define PG8_MMA(ai, bj, At, Bt) do { __builtin_amdgcn_s_setprio(1); _Pragma("unroll") for (int m = 0; m < 4; ++m) _Pragma("unroll") for (int n = 0; n < 2; ++n) _Pragma("unroll") for (int k = 0; k < 2; ++k) \
;         acc[ai][bj][m][n] = __builtin_amdgcn_mfma_f32_16x16x32_bf16(Bt[n][k], At[m][k], acc[ai][bj][m][n], 0, 0, 0); __builtin_amdgcn_s_setprio(0); } while (0)
; #define PG8_WAIT_V(n) asm volatile("s_waitcnt vmcnt(" #n ")" ::: "memory")
; #define PG8_WAIT_L(n) asm volatile("s_waitcnt lgkmcnt(" #n ")" ::: "memory")
; #define PG8_BAR __builtin_amdgcn_s_barrier()
; #define PG8_SCHED __builtin_amdgcn_sched_barrier(0)
; template <class Epi, bool ALIGN_EPI = true>
; __device__ __forceinline__ void gemm_phase(LAS unsigned char* lds, const Gemm g, const Sched& S, const Epi& E) {
;     ...
;             PG8_WAIT_L(0); PG8_BAR; PG8_MMA(1, 0, At, B0); PG8_MMA(1, 1, At, B1); PG8_BAR; PG8_SCHED;
;             PG8_LDB(B0, 1, 0); PG8_LDB(B1, 1, 1); PG8_SCHED; PG8_LDA(At, 1, 0); PG8_STAGE(PG8_SA(0, 1), a2 + hstepA, voffA);
;             PG8_WAIT_V(8); PG8_WAIT_L(0); PG8_BAR; PG8_MMA(0, 0, At, B0); PG8_MMA(0, 1, At, B1); PG8_BAR; PG8_SCHED;
	s_setprio 1
	s_waitcnt lgkmcnt(0)
	v_mfma_f32_16x16x32_bf16 v[66:69], v[150:153], v[182:185], v[66:69]
	v_mfma_f32_16x16x32_bf16 v[62:65], v[158:161], v[182:185], v[62:65]
	v_mfma_f32_16x16x32_bf16 v[50:53], v[150:153], v[190:193], v[50:53]
	v_mfma_f32_16x16x32_bf16 v[46:49], v[158:161], v[190:193], v[46:49]
	v_mfma_f32_16x16x32_bf16 v[34:37], v[150:153], v[206:209], v[34:37]
	v_mfma_f32_16x16x32_bf16 v[30:33], v[158:161], v[206:209], v[30:33]
	v_mfma_f32_16x16x32_bf16 v[18:21], v[150:153], v[228:231], v[18:21]
	v_mfma_f32_16x16x32_bf16 v[14:17], v[158:161], v[228:231], v[14:17]
	v_mfma_f32_16x16x32_bf16 v[66:69], v[154:157], v[186:189], v[66:69]
	v_mfma_f32_16x16x32_bf16 v[62:65], v[162:165], v[186:189], v[62:65]
	v_mfma_f32_16x16x32_bf16 v[50:53], v[154:157], v[194:197], v[50:53]
	v_mfma_f32_16x16x32_bf16 v[46:49], v[162:165], v[194:197], v[46:49]
	v_mfma_f32_16x16x32_bf16 v[34:37], v[154:157], v[224:227], v[34:37]
	v_mfma_f32_16x16x32_bf16 v[30:33], v[162:165], v[224:227], v[30:33]
	v_mfma_f32_16x16x32_bf16 v[18:21], v[154:157], v[232:235], v[18:21]
	v_mfma_f32_16x16x32_bf16 v[14:17], v[162:165], v[232:235], v[14:17]
	v_mfma_f32_16x16x32_bf16 v[58:61], v[166:169], v[182:185], v[58:61]
	v_mfma_f32_16x16x32_bf16 v[54:57], v[174:177], v[182:185], v[54:57]
	v_mfma_f32_16x16x32_bf16 v[42:45], v[166:169], v[190:193], v[42:45]
	v_mfma_f32_16x16x32_bf16 v[38:41], v[174:177], v[190:193], v[38:41]
	v_mfma_f32_16x16x32_bf16 v[26:29], v[166:169], v[206:209], v[26:29]
	v_mfma_f32_16x16x32_bf16 v[22:25], v[174:177], v[206:209], v[22:25]
	v_mfma_f32_16x16x32_bf16 v[10:13], v[166:169], v[228:231], v[10:13]
	v_mfma_f32_16x16x32_bf16 v[4:7], v[174:177], v[228:231], v[6:9]
	v_mfma_f32_16x16x32_bf16 v[58:61], v[170:173], v[186:189], v[58:61]
	v_mfma_f32_16x16x32_bf16 v[54:57], v[178:181], v[186:189], v[54:57]
	v_mfma_f32_16x16x32_bf16 v[42:45], v[170:173], v[194:197], v[42:45]
	v_mfma_f32_16x16x32_bf16 v[38:41], v[178:181], v[194:197], v[38:41]
	v_mfma_f32_16x16x32_bf16 v[26:29], v[170:173], v[224:227], v[26:29]
	v_mfma_f32_16x16x32_bf16 v[22:25], v[178:181], v[224:227], v[22:25]
	v_mfma_f32_16x16x32_bf16 v[10:13], v[170:173], v[232:235], v[10:13]
	v_mfma_f32_16x16x32_bf16 v[4:7], v[178:181], v[232:235], v[4:7]
	s_setprio 0
	s_barrier
	s_add_i32 s48, 0, 0x18000
	v_add_u32_e32 v2, s48, v147
	s_add_i32 s49, 0, 0x1c000
	ds_read_b128 v[150:153], v2
	ds_read_b128 v[154:157], v2 offset:1024
	ds_read_b128 v[158:161], v2 offset:2048
	ds_read_b128 v[162:165], v2 offset:3072
	v_add_u32_e32 v2, s49, v147
	ds_read_b128 v[166:169], v2
	ds_read_b128 v[170:173], v2 offset:1024
	ds_read_b128 v[174:177], v2 offset:2048
	ds_read_b128 v[178:181], v2 offset:3072
	s_add_u32 s46, s46, 0x160000
	s_addc_u32 s47, s47, 0
	s_mov_b32 m0, s52
	ds_read_b128 v[182:185], v148 offset:32768
	ds_read_b128 v[186:189], v148 offset:33792
	ds_read_b128 v[190:193], v148 offset:34816
	ds_read_b128 v[194:197], v148 offset:35840
	ds_read_b128 v[206:209], v148 offset:36864
	ds_read_b128 v[224:227], v148 offset:37888
	ds_read_b128 v[228:231], v148 offset:38912
	ds_read_b128 v[232:235], v148 offset:39936
	s_add_u32 s100, s46, 0xffea0000
	s_addc_u32 s101, s47, -1
	s_mov_b32 m0, s50
	s_nop 0
	global_load_lds_dwordx4 v140, s[100:101]
	s_mov_b32 m0, s51
	s_nop 0
	global_load_lds_dwordx4 v136, s[100:101]
	s_mov_b32 m0, s52
	s_nop 0
	global_load_lds_dwordx4 v140, s[46:47]
	s_mov_b32 m0, s53
	s_nop 0
	global_load_lds_dwordx4 v136, s[46:47]
	s_waitcnt vmcnt(8)
	s_waitcnt lgkmcnt(0)
	s_barrier
; #define PG8_STAGE(bufoff, gbase, voff) do { _Pragma("unroll") for (int _i = 0; _i < 2; ++_i) \
;         __builtin_amdgcn_global_load_lds((const unsigned*)((const char*)(gbase) + (voff)[_i]), (LAS unsigned*)(lds + (bufoff) + ldsw + _i * 8192), 16, 0, 0); } while (0)
; #define PG8_LDA(dst, b, h) do { _Pragma("unroll") for (int m = 0; m < 4; ++m) _Pragma("unroll") for (int k = 0; k < 2; ++k) dst[m][k] = *(const LAS bf16x8*)(lds + PG8_SA(b, h) + aoff + m * 2048 + k * 1024); } while (0)
; #define PG8_MMA(ai, bj, At, Bt) do { __builtin_amdgcn_s_setprio(1); _Pragma("unroll") for (int m = 0; m < 4; ++m) _Pragma("unroll") for (int n = 0; n < 2; ++n) _Pragma("unroll") for (int k = 0; k < 2; ++k) \
;         acc[ai][bj][m][n] = __builtin_amdgcn_mfma_f32_16x16x32_bf16(Bt[n][k], At[m][k], acc[ai][bj][m][n], 0, 0, 0); __builtin_amdgcn_s_setprio(0); } while (0)
; #define PG8_WAIT_V(n) asm volatile("s_waitcnt vmcnt(" #n ")" ::: "memory")
; #define PG8_WAIT_L(n) asm volatile("s_waitcnt lgkmcnt(" #n ")" ::: "memory")
; #define PG8_BAR __builtin_amdgcn_s_barrier()
; #define PG8_SCHED __builtin_amdgcn_sched_barrier(0)
; template <class Epi, bool ALIGN_EPI = true>
; __device__ __forceinline__ void gemm_phase(LAS unsigned char* lds, const Gemm g, const Sched& S, const Epi& E) {
;     ...
;             PG8_WAIT_V(8); PG8_WAIT_L(0); PG8_BAR; PG8_MMA(0, 0, At, B0); PG8_MMA(0, 1, At, B1); PG8_BAR; PG8_SCHED;
;             PG8_LDA(At, 1, 1); PG8_STAGE(PG8_SB(1, 0), b3, voffB); PG8_STAGE(PG8_SB(1, 1), b3 + hstepB, voffB); PG8_STAGE(PG8_SA(1, 0), a3, voffA);
;             PG8_WAIT_V(8); PG8_WAIT_L(0); PG8_BAR; PG8_MMA(1, 0, At, B0); PG8_MMA(1, 1, At, B1); PG8_BAR; PG8_SCHED;
	s_setprio 1
	s_waitcnt lgkmcnt(0)
	v_mfma_f32_16x16x32_bf16 v[130:133], v[150:153], v[182:185], v[130:133]
	v_mfma_f32_16x16x32_bf16 v[126:129], v[158:161], v[182:185], v[126:129]
	v_mfma_f32_16x16x32_bf16 v[114:117], v[150:153], v[190:193], v[114:117]
	v_mfma_f32_16x16x32_bf16 v[110:113], v[158:161], v[190:193], v[110:113]
	v_mfma_f32_16x16x32_bf16 v[98:101], v[150:153], v[206:209], v[98:101]
	v_mfma_f32_16x16x32_bf16 v[94:97], v[158:161], v[206:209], v[94:97]
	v_mfma_f32_16x16x32_bf16 v[82:85], v[150:153], v[228:231], v[82:85]
	v_mfma_f32_16x16x32_bf16 v[78:81], v[158:161], v[228:231], v[78:81]
	v_mfma_f32_16x16x32_bf16 v[130:133], v[154:157], v[186:189], v[130:133]
	v_mfma_f32_16x16x32_bf16 v[126:129], v[162:165], v[186:189], v[126:129]
	v_mfma_f32_16x16x32_bf16 v[114:117], v[154:157], v[194:197], v[114:117]
	v_mfma_f32_16x16x32_bf16 v[110:113], v[162:165], v[194:197], v[110:113]
	v_mfma_f32_16x16x32_bf16 v[98:101], v[154:157], v[224:227], v[98:101]
	v_mfma_f32_16x16x32_bf16 v[94:97], v[162:165], v[224:227], v[94:97]
	v_mfma_f32_16x16x32_bf16 v[82:85], v[154:157], v[232:235], v[82:85]
	v_mfma_f32_16x16x32_bf16 v[78:81], v[162:165], v[232:235], v[78:81]
	v_mfma_f32_16x16x32_bf16 v[122:125], v[166:169], v[182:185], v[122:125]
	v_mfma_f32_16x16x32_bf16 v[118:121], v[174:177], v[182:185], v[118:121]
	v_mfma_f32_16x16x32_bf16 v[106:109], v[166:169], v[190:193], v[106:109]
	v_mfma_f32_16x16x32_bf16 v[102:105], v[174:177], v[190:193], v[102:105]
	v_mfma_f32_16x16x32_bf16 v[90:93], v[166:169], v[206:209], v[90:93]
	v_mfma_f32_16x16x32_bf16 v[86:89], v[174:177], v[206:209], v[86:89]
	v_mfma_f32_16x16x32_bf16 v[74:77], v[166:169], v[228:231], v[74:77]
	v_mfma_f32_16x16x32_bf16 v[70:73], v[174:177], v[228:231], v[70:73]
	v_mfma_f32_16x16x32_bf16 v[122:125], v[170:173], v[186:189], v[122:125]
	v_mfma_f32_16x16x32_bf16 v[118:121], v[178:181], v[186:189], v[118:121]
	v_mfma_f32_16x16x32_bf16 v[106:109], v[170:173], v[194:197], v[106:109]
	v_mfma_f32_16x16x32_bf16 v[102:105], v[178:181], v[194:197], v[102:105]
	v_mfma_f32_16x16x32_bf16 v[90:93], v[170:173], v[224:227], v[90:93]
	v_mfma_f32_16x16x32_bf16 v[86:89], v[178:181], v[224:227], v[86:89]
	v_mfma_f32_16x16x32_bf16 v[74:77], v[170:173], v[232:235], v[74:77]
	v_mfma_f32_16x16x32_bf16 v[70:73], v[178:181], v[232:235], v[70:73]
	s_setprio 0
	s_barrier
	s_add_u32 s100, s44, 0x80
	s_addc_u32 s101, s45, 0
	s_add_i32 s46, s48, s37
	s_mov_b32 m0, s46
	ds_read_b128 v[182:185], v148 offset:49152
	ds_read_b128 v[186:189], v148 offset:50176
	ds_read_b128 v[190:193], v148 offset:51200
	ds_read_b128 v[194:197], v148 offset:52224
	ds_read_b128 v[206:209], v148 offset:53248
	ds_read_b128 v[224:227], v148 offset:54272
	ds_read_b128 v[228:231], v148 offset:55296
	ds_read_b128 v[232:235], v148 offset:56320
	global_load_lds_dwordx4 v138, s[100:101]
	s_add_i32 m0, s46, 0x2000
	s_add_u32 s44, s44, 0x160080
	s_addc_u32 s45, s45, 0
	s_add_i32 s46, s49, s37
	global_load_lds_dwordx4 v134, s[100:101]
	s_mov_b32 m0, s46
	s_nop 0
	global_load_lds_dwordx4 v138, s[44:45]
	s_add_i32 m0, s46, 0x2000
	s_nop 0
	global_load_lds_dwordx4 v134, s[44:45]
	s_waitcnt vmcnt(6)
	s_waitcnt lgkmcnt(0)
	s_barrier
	s_setprio 1
	s_waitcnt lgkmcnt(0)
	v_mfma_f32_16x16x32_bf16 v[66:69], v[150:153], v[182:185], v[66:69]
	v_mfma_f32_16x16x32_bf16 v[62:65], v[158:161], v[182:185], v[62:65]
	v_mfma_f32_16x16x32_bf16 v[50:53], v[150:153], v[190:193], v[50:53]
	v_mfma_f32_16x16x32_bf16 v[46:49], v[158:161], v[190:193], v[46:49]
	v_mfma_f32_16x16x32_bf16 v[34:37], v[150:153], v[206:209], v[34:37]
	v_mfma_f32_16x16x32_bf16 v[30:33], v[158:161], v[206:209], v[30:33]
	v_mfma_f32_16x16x32_bf16 v[18:21], v[150:153], v[228:231], v[18:21]
	v_mfma_f32_16x16x32_bf16 v[14:17], v[158:161], v[228:231], v[14:17]
	v_mfma_f32_16x16x32_bf16 v[66:69], v[154:157], v[186:189], v[66:69]
	v_mfma_f32_16x16x32_bf16 v[62:65], v[162:165], v[186:189], v[62:65]
	v_mfma_f32_16x16x32_bf16 v[50:53], v[154:157], v[194:197], v[50:53]
	v_mfma_f32_16x16x32_bf16 v[46:49], v[162:165], v[194:197], v[46:49]
	v_mfma_f32_16x16x32_bf16 v[34:37], v[154:157], v[224:227], v[34:37]
	v_mfma_f32_16x16x32_bf16 v[30:33], v[162:165], v[224:227], v[30:33]
	v_mfma_f32_16x16x32_bf16 v[18:21], v[154:157], v[232:235], v[18:21]
	v_mfma_f32_16x16x32_bf16 v[14:17], v[162:165], v[232:235], v[14:17]
	v_mfma_f32_16x16x32_bf16 v[58:61], v[166:169], v[182:185], v[58:61]
	v_mfma_f32_16x16x32_bf16 v[54:57], v[174:177], v[182:185], v[54:57]
	v_mfma_f32_16x16x32_bf16 v[42:45], v[166:169], v[190:193], v[42:45]
	v_mfma_f32_16x16x32_bf16 v[38:41], v[174:177], v[190:193], v[38:41]
	v_mfma_f32_16x16x32_bf16 v[26:29], v[166:169], v[206:209], v[26:29]
	v_mfma_f32_16x16x32_bf16 v[22:25], v[174:177], v[206:209], v[22:25]
	v_mfma_f32_16x16x32_bf16 v[8:11], v[166:169], v[228:231], v[10:13]
	v_mfma_f32_16x16x32_bf16 v[4:7], v[174:177], v[228:231], v[4:7]
	v_mfma_f32_16x16x32_bf16 v[58:61], v[170:173], v[186:189], v[58:61]
	v_mfma_f32_16x16x32_bf16 v[54:57], v[178:181], v[186:189], v[54:57]
	v_mfma_f32_16x16x32_bf16 v[42:45], v[170:173], v[194:197], v[42:45]
	v_mfma_f32_16x16x32_bf16 v[38:41], v[178:181], v[194:197], v[38:41]
	v_mfma_f32_16x16x32_bf16 v[26:29], v[170:173], v[224:227], v[26:29]
	v_mfma_f32_16x16x32_bf16 v[22:25], v[178:181], v[224:227], v[22:25]
	v_mfma_f32_16x16x32_bf16 v[10:13], v[170:173], v[232:235], v[8:11]
	v_mfma_f32_16x16x32_bf16 v[6:9], v[178:181], v[232:235], v[4:7]
	s_setprio 0
	s_barrier
	s_add_u32 s67, s67, 0x100
	s_addc_u32 s68, s68, 0
	s_cmp_ge_i32 s69, s54
	s_mov_b64 s[48:49], s[42:43]
	s_mov_b32 s44, s69
	s_cbranch_scc0 .LBB0_2287
